# r5 + s_setprio: one wave of every SIMD pair runs the GEMM K-loops at raised issue priority (de-phases the pair)
# speedup vs baseline: 1.0037x; 1.0037x over previous
; DI int tid512() { int t = threadIdx_x_raw(); asm volatile("" : "+v"(t)); return t; }
; #define G_LOADA(kt_) { _Pragma("unroll") for (int i = 0; i < 4; ++i) ra[i] = al(lrow + 64 * i, (kt_) * 64 + lck * 8); }
; #define G_LOADB(kt_) { _Pragma("unroll") for (int i = 0; i < 4; ++i) rb[i] = bl(lrow + 64 * i, (kt_) * 64 + lck * 8); }
; #define G_STOREA(buf_) { bf16_t* nA = sA + (buf_) * 256 * GLD; _Pragma("unroll") for (int i = 0; i < 4; ++i) *(u32x4*)(nA + (lrow + 64 * i) * GLD + lck * 8) = ra[i]; }
; #define G_STOREB(buf_) { bf16_t* nB = sB + (buf_) * 256 * GLD; _Pragma("unroll") for (int i = 0; i < 4; ++i) *(u32x4*)(nB + (lrow + 64 * i) * GLD + lck * 8) = rb[i]; }
; template <class AL, class BL, class EP>
; DI void gemm_tile256(AL al, BL bl, EP ep, int K, char* smem) {
;   bf16_t* sA = (bf16_t*)smem;
;   bf16_t* sB = sA + 2 * 256 * GLD;
;   const int tid = tid512(), lane = tid & 63, w = tid >> 6, wm = w >> 2, wn = w & 3, r = lane & 31, h = lane >> 5;
;   const int lrow = tid >> 3, lck = tid & 7;
;   f32x16 acc[4][2];
; #pragma unroll
;   for (int i = 0; i < 4; ++i)
; #pragma unroll
;     for (int j = 0; j < 2; ++j)
; #pragma unroll
;       for (int q = 0; q < 16; ++q) acc[i][j][q] = 0.f;
;   u32x4 ra[4], rb[4];
;   const int KT = K >> 6;
;     ...
;   G_LOADA(0); G_LOADB(0);
;   __syncthreads();
;   G_STOREA(0); G_STOREB(0);
;   if (KT > 1) G_LOADB(1);
;   __syncthreads();
;   DI u32x4 operator()(int r, int k) const {
;     int row = row0 + r;
;     row = row < nrows ? row : nrows - 1;
;     return ldg16(base + (size_t)row * ld + k);
.LBB0_154:
	s_cmp_gt_i32 s38, 1
	s_cbranch_scc1 .LBB0_164
	s_cmp_lg_u32 s38, 1
	s_mov_b64 s[0:1], -1
	s_cbranch_scc0 .LBB0_162
	v_mov_b32_e32 v32, v196
	s_nop 0
	v_ashrrev_i32_e32 v33, 3, v32
	v_add_u32_e32 v12, v33, v168
	v_add_u32_e32 v28, v33, v169
	v_lshlrev_b32_e32 v0, 4, v32
	v_add_u32_e32 v10, 0x80, v12
	v_add_u32_e32 v26, 0x80, v28
	v_and_b32_e32 v128, 0x70, v0
	v_min_i32_e32 v0, 0x7fff, v12
	v_min_i32_e32 v10, 0x7fff, v10
	v_min_i32_e32 v16, 0x79f, v28
	v_min_i32_e32 v26, 0x79f, v26
	v_ashrrev_i32_e32 v1, 31, v0
	v_ashrrev_i32_e32 v11, 31, v10
	v_ashrrev_i32_e32 v17, 31, v16
	v_ashrrev_i32_e32 v27, 31, v26
	v_lshl_add_u64 v[8:9], s[52:53], 0, v[128:129]
	v_lshlrev_b64 v[0:1], 11, v[0:1]
	v_lshlrev_b64 v[10:11], 11, v[10:11]
	v_lshl_add_u64 v[24:25], s[90:91], 0, v[128:129]
	v_lshlrev_b64 v[16:17], 11, v[16:17]
	v_lshlrev_b64 v[26:27], 11, v[26:27]
	v_lshl_add_u64 v[134:135], v[8:9], 0, v[0:1]
	v_add_u32_e32 v0, 64, v12
	v_lshl_add_u64 v[138:139], v[8:9], 0, v[10:11]
	v_add_u32_e32 v10, 0xc0, v12
	v_lshl_add_u64 v[142:143], v[24:25], 0, v[16:17]
	v_add_u32_e32 v16, 64, v28
	v_lshl_add_u64 v[146:147], v[24:25], 0, v[26:27]
	v_add_u32_e32 v26, 0xc0, v28
	v_min_i32_e32 v0, 0x7fff, v0
	v_min_i32_e32 v10, 0x7fff, v10
	v_min_i32_e32 v16, 0x79f, v16
	v_min_i32_e32 v26, 0x79f, v26
	v_ashrrev_i32_e32 v1, 31, v0
	v_ashrrev_i32_e32 v11, 31, v10
	v_ashrrev_i32_e32 v17, 31, v16
	v_ashrrev_i32_e32 v27, 31, v26
	v_lshlrev_b64 v[0:1], 11, v[0:1]
	v_lshlrev_b64 v[10:11], 11, v[10:11]
	v_lshlrev_b64 v[16:17], 11, v[16:17]
	v_lshlrev_b64 v[26:27], 11, v[26:27]
	v_lshl_add_u64 v[136:137], v[8:9], 0, v[0:1]
	v_lshl_add_u64 v[140:141], v[8:9], 0, v[10:11]
	v_lshl_add_u64 v[144:145], v[24:25], 0, v[16:17]
	v_lshl_add_u64 v[148:149], v[24:25], 0, v[26:27]
	v_mad_u64_u32 v[132:133], s[0:1], v33, s41, v[128:129]
	v_add_u32_e32 v173, 0x12000, v132
	v_bfe_u32 v128, v32, 6, 2
	v_add_u32_e32 v172, 0x1b000, v132
	v_and_b32_e32 v1, 31, v32
	v_ashrrev_i32_e32 v0, 1, v32
	v_and_or_b32 v133, v0, s42, v1
	v_lshrrev_b32_e32 v0, 2, v32
	v_and_b32_e32 v170, 8, v0
	v_lshlrev_b32_e32 v0, 1, v170
	v_mad_u64_u32 v[130:131], s[0:1], v133, s41, v[0:1]
	v_lshl_or_b32 v1, v128, 6, v1
	v_mul_u32_u24_e32 v1, 0x48, v1
	v_lshl_add_u32 v0, v1, 1, v0
	v_add_u32_e32 v171, 0x12000, v0
	v_add_u32_e32 v131, 0x1b000, v0
	s_nop 0
	s_nop 0
	s_nop 0
	s_nop 0
	s_nop 0
	s_nop 0
	v_lshrrev_b32_e32 v231, 6, v196
	s_mov_b32 s38, 64
	v_readfirstlane_b32 s32, v231
	s_mov_b32 s39, 0
	s_mov_b32 s48, 0x40000
	s_mov_b32 s49, 0
	v_bfe_u32 v240, v196, 2, 4
	s_lshl_b32 s54, s32, 3
	v_add_u32_e32 v240, s54, v240
	s_mov_b32 s54, 0x800
	v_mul_lo_u32 v240, v240, s54
	v_bfe_u32 v231, v196, 4, 2
	v_and_b32_e32 v241, 3, v196
	v_xor_b32_e32 v231, v241, v231
	v_lshl_add_u32 v240, v231, 4, v240
	v_mov_b32_e32 v241, 0
	v_readlane_b32 s50, v134, 0
	v_readlane_b32 s51, v135, 0
	s_nop 1
	v_lshl_add_u64 v[232:233], s[50:51], 0, v[240:241]
	v_lshl_add_u64 v[234:235], v[232:233], 0, s[48:49]
	v_readlane_b32 s50, v142, 0
	v_readlane_b32 s51, v143, 0
	s_nop 1
	v_lshl_add_u64 v[236:237], s[50:51], 0, v[240:241]
	v_lshl_add_u64 v[238:239], v[236:237], 0, s[48:49]
	v_and_b32_e32 v240, 31, v196
	v_bfe_u32 v231, v196, 2, 2
	v_bfe_u32 v241, v196, 5, 1
	v_xor_b32_e32 v231, v241, v231
	v_lshlrev_b32_e32 v231, 4, v231
	v_lshl_or_b32 v240, v240, 6, v231
	s_lshr_b32 s54, s32, 2
	s_lshl_b32 s54, s54, 13
	v_add_u32_e32 v132, s54, v240
	s_and_b32 s54, s32, 3
	s_lshl_b32 s54, s54, 12
	s_add_u32 s54, s54, 0x4000
	v_add_u32_e32 v197, s54, v240
	v_xor_b32_e32 v171, 0x20, v132
	v_xor_b32_e32 v198, 0x20, v197
	v_add_u32_e32 v199, 0x10000, v132
	v_add_u32_e32 v225, 0x10000, v197
	v_add_u32_e32 v227, 0x20000, v132
	v_add_u32_e32 v229, 0x20000, v197
	v_add_u32_e32 v224, 0x10000, v171
	v_add_u32_e32 v226, 0x10000, v198
	v_add_u32_e32 v228, 0x20000, v171
	v_add_u32_e32 v230, 0x20000, v198
	s_lshl_b32 s32, s32, 10
	s_waitcnt lgkmcnt(0)
	s_barrier
	s_add_u32 m0, s32, 0x0
	s_nop 0
	global_load_lds_dwordx4 v[232:233], off
	v_lshl_add_u64 v[232:233], v[232:233], 0, s[38:39]
	s_add_u32 m0, s32, 0x4000
	s_nop 0
	global_load_lds_dwordx4 v[236:237], off
	v_lshl_add_u64 v[236:237], v[236:237], 0, s[38:39]
	s_add_u32 m0, s32, 0x2000
	s_nop 0
	global_load_lds_dwordx4 v[234:235], off
	v_lshl_add_u64 v[234:235], v[234:235], 0, s[38:39]
	s_add_u32 m0, s32, 0x6000
	s_nop 0
	global_load_lds_dwordx4 v[238:239], off
	v_lshl_add_u64 v[238:239], v[238:239], 0, s[38:39]
	s_add_u32 m0, s32, 0x8000
	s_nop 0
	global_load_lds_dwordx4 v[232:233], off
	v_lshl_add_u64 v[232:233], v[232:233], 0, s[38:39]
	s_add_u32 m0, s32, 0xc000
	s_nop 0
	global_load_lds_dwordx4 v[236:237], off
	v_lshl_add_u64 v[236:237], v[236:237], 0, s[38:39]
	s_add_u32 m0, s32, 0xa000
	s_nop 0
	global_load_lds_dwordx4 v[234:235], off
	v_lshl_add_u64 v[234:235], v[234:235], 0, s[38:39]
	s_add_u32 m0, s32, 0xe000
	s_nop 0
	global_load_lds_dwordx4 v[238:239], off
	v_lshl_add_u64 v[238:239], v[238:239], 0, s[38:39]
	s_add_u32 m0, s32, 0x10000
	s_nop 0
	global_load_lds_dwordx4 v[232:233], off
	v_lshl_add_u64 v[232:233], v[232:233], 0, s[38:39]
	s_add_u32 m0, s32, 0x14000
	s_nop 0
	global_load_lds_dwordx4 v[236:237], off
	v_lshl_add_u64 v[236:237], v[236:237], 0, s[38:39]
	s_add_u32 m0, s32, 0x12000
	s_nop 0
	global_load_lds_dwordx4 v[234:235], off
	v_lshl_add_u64 v[234:235], v[234:235], 0, s[38:39]
	s_add_u32 m0, s32, 0x16000
	s_nop 0
	global_load_lds_dwordx4 v[238:239], off
	v_lshl_add_u64 v[238:239], v[238:239], 0, s[38:39]
	s_add_u32 m0, s32, 0x18000
	s_nop 0
	global_load_lds_dwordx4 v[232:233], off
	v_lshl_add_u64 v[232:233], v[232:233], 0, s[38:39]
	s_add_u32 m0, s32, 0x1c000
	s_nop 0
; #define G_LOADA(kt_) { _Pragma("unroll") for (int i = 0; i < 4; ++i) ra[i] = al(lrow + 64 * i, (kt_) * 64 + lck * 8); }
; #define G_LOADB(kt_) { _Pragma("unroll") for (int i = 0; i < 4; ++i) rb[i] = bl(lrow + 64 * i, (kt_) * 64 + lck * 8); }
; #define G_STOREA(buf_) { bf16_t* nA = sA + (buf_) * 256 * GLD; _Pragma("unroll") for (int i = 0; i < 4; ++i) *(u32x4*)(nA + (lrow + 64 * i) * GLD + lck * 8) = ra[i]; }
; #define G_STOREB(buf_) { bf16_t* nB = sB + (buf_) * 256 * GLD; _Pragma("unroll") for (int i = 0; i < 4; ++i) *(u32x4*)(nB + (lrow + 64 * i) * GLD + lck * 8) = rb[i]; }
; template <class AL, class BL, class EP>
; DI void gemm_tile256(AL al, BL bl, EP ep, int K, char* smem) {
;     ...
; #pragma unroll
;   for (int i = 0; i < 4; ++i)
; #pragma unroll
;     for (int j = 0; j < 2; ++j)
; #pragma unroll
;       for (int q = 0; q < 16; ++q) acc[i][j][q] = 0.f;
;     ...
;   G_LOADA(0); G_LOADB(0);
;   __syncthreads();
;   G_STOREA(0); G_STOREB(0);
;   if (KT > 1) G_LOADB(1);
;   __syncthreads();
;   for (int kt = 0; kt < KT; kt += 2) {
;     G_STEP(0, kt);
;     if (kt + 1 >= KT) break;
;     G_STEP(1, kt + 1);
;   }
	global_load_lds_dwordx4 v[236:237], off
	v_lshl_add_u64 v[236:237], v[236:237], 0, s[38:39]
	s_add_u32 m0, s32, 0x1a000
	s_nop 0
	global_load_lds_dwordx4 v[234:235], off
	v_lshl_add_u64 v[234:235], v[234:235], 0, s[38:39]
	s_add_u32 m0, s32, 0x1e000
	s_nop 0
	global_load_lds_dwordx4 v[238:239], off
	v_lshl_add_u64 v[238:239], v[238:239], 0, s[38:39]
	s_add_u32 m0, s32, 0x20000
	s_nop 0
	global_load_lds_dwordx4 v[232:233], off
	v_lshl_add_u64 v[232:233], v[232:233], 0, s[38:39]
	s_add_u32 m0, s32, 0x24000
	s_nop 0
	global_load_lds_dwordx4 v[236:237], off
	v_lshl_add_u64 v[236:237], v[236:237], 0, s[38:39]
	v_mov_b64_e32 v[112:113], 0
	v_mov_b64_e32 v[114:115], 0
	v_mov_b64_e32 v[116:117], 0
	v_mov_b64_e32 v[118:119], 0
	v_mov_b64_e32 v[120:121], 0
	v_mov_b64_e32 v[122:123], 0
	v_mov_b64_e32 v[124:125], 0
	v_mov_b64_e32 v[126:127], 0
	v_mov_b64_e32 v[96:97], 0
	v_mov_b64_e32 v[98:99], 0
	v_mov_b64_e32 v[100:101], 0
	v_mov_b64_e32 v[102:103], 0
	v_mov_b64_e32 v[104:105], 0
	v_mov_b64_e32 v[106:107], 0
	v_mov_b64_e32 v[108:109], 0
	v_mov_b64_e32 v[110:111], 0
	v_mov_b64_e32 v[80:81], 0
	v_mov_b64_e32 v[82:83], 0
	v_mov_b64_e32 v[84:85], 0
	v_mov_b64_e32 v[86:87], 0
	v_mov_b64_e32 v[88:89], 0
	v_mov_b64_e32 v[90:91], 0
	v_mov_b64_e32 v[92:93], 0
	v_mov_b64_e32 v[94:95], 0
	v_mov_b64_e32 v[64:65], 0
	v_mov_b64_e32 v[66:67], 0
	v_mov_b64_e32 v[68:69], 0
	v_mov_b64_e32 v[70:71], 0
	v_mov_b64_e32 v[72:73], 0
	v_mov_b64_e32 v[74:75], 0
	v_mov_b64_e32 v[76:77], 0
	v_mov_b64_e32 v[78:79], 0
	v_mov_b64_e32 v[48:49], 0
	v_mov_b64_e32 v[50:51], 0
	v_mov_b64_e32 v[52:53], 0
	v_mov_b64_e32 v[54:55], 0
	v_mov_b64_e32 v[56:57], 0
	v_mov_b64_e32 v[58:59], 0
	v_mov_b64_e32 v[60:61], 0
	v_mov_b64_e32 v[62:63], 0
	v_mov_b64_e32 v[32:33], 0
	v_mov_b64_e32 v[34:35], 0
	v_mov_b64_e32 v[36:37], 0
	v_mov_b64_e32 v[38:39], 0
	v_mov_b64_e32 v[40:41], 0
	v_mov_b64_e32 v[42:43], 0
	v_mov_b64_e32 v[44:45], 0
	v_mov_b64_e32 v[46:47], 0
	v_mov_b64_e32 v[16:17], 0
	v_mov_b64_e32 v[18:19], 0
	v_mov_b64_e32 v[20:21], 0
	v_mov_b64_e32 v[22:23], 0
	v_mov_b64_e32 v[24:25], 0
	v_mov_b64_e32 v[26:27], 0
	v_mov_b64_e32 v[28:29], 0
	v_mov_b64_e32 v[30:31], 0
	v_mov_b64_e32 v[0:1], 0
	v_mov_b64_e32 v[2:3], 0
	v_mov_b64_e32 v[4:5], 0
	v_mov_b64_e32 v[6:7], 0
	v_mov_b64_e32 v[8:9], 0
	v_mov_b64_e32 v[10:11], 0
	v_mov_b64_e32 v[12:13], 0
	v_mov_b64_e32 v[14:15], 0
	s_lshr_b32 s54, s32, 2
	s_xor_b32 s54, s54, s32
	s_bitcmp1_b32 s54, 10
	s_cbranch_scc0 .Lgk_ph1_np
	s_setprio 1
.Lgk_ph1_np:
	s_mov_b32 s54, 5
	s_waitcnt vmcnt(14)
	s_barrier
	ds_read_b128 v[208:211], v197
	ds_read_b128 v[172:175], v132
	ds_read_b128 v[212:215], v197 offset:2048
	ds_read_b128 v[176:179], v132 offset:2048
	ds_read_b128 v[180:183], v132 offset:4096
	ds_read_b128 v[184:187], v132 offset:6144
.Lgk_ph1_loop:
	s_waitcnt lgkmcnt(0)
	v_mfma_f32_32x32x16_bf16 v[112:127], v[208:211], v[172:175], v[112:127]
	ds_read_b128 v[216:219], v198
	ds_read_b128 v[188:191], v171
	v_mfma_f32_32x32x16_bf16 v[96:111], v[212:215], v[172:175], v[96:111]
	ds_read_b128 v[220:223], v198 offset:2048
	ds_read_b128 v[192:195], v171 offset:2048
	v_mfma_f32_32x32x16_bf16 v[80:95], v[208:211], v[176:179], v[80:95]
	ds_read_b128 v[200:203], v171 offset:4096
	ds_read_b128 v[204:207], v171 offset:6144
	v_mfma_f32_32x32x16_bf16 v[64:79], v[212:215], v[176:179], v[64:79]
	s_add_u32 m0, s32, 0x22000
	s_nop 0
	global_load_lds_dwordx4 v[234:235], off
	v_lshl_add_u64 v[234:235], v[234:235], 0, s[38:39]
	v_mfma_f32_32x32x16_bf16 v[48:63], v[208:211], v[180:183], v[48:63]
	v_mfma_f32_32x32x16_bf16 v[32:47], v[212:215], v[180:183], v[32:47]
	v_mfma_f32_32x32x16_bf16 v[16:31], v[208:211], v[184:187], v[16:31]
	v_mfma_f32_32x32x16_bf16 v[0:15], v[212:215], v[184:187], v[0:15]
	s_add_u32 m0, s32, 0x26000
	s_nop 0
	global_load_lds_dwordx4 v[238:239], off
	v_lshl_add_u64 v[238:239], v[238:239], 0, s[38:39]
	s_waitcnt lgkmcnt(0)
	s_waitcnt vmcnt(12)
	s_barrier
	s_waitcnt lgkmcnt(0)
	v_mfma_f32_32x32x16_bf16 v[112:127], v[216:219], v[188:191], v[112:127]
	ds_read_b128 v[208:211], v197 offset:32768
	ds_read_b128 v[172:175], v132 offset:32768
	v_mfma_f32_32x32x16_bf16 v[96:111], v[220:223], v[188:191], v[96:111]
	ds_read_b128 v[212:215], v197 offset:34816
	ds_read_b128 v[176:179], v132 offset:34816
	v_mfma_f32_32x32x16_bf16 v[80:95], v[216:219], v[192:195], v[80:95]
	ds_read_b128 v[180:183], v132 offset:36864
	ds_read_b128 v[184:187], v132 offset:38912
	v_mfma_f32_32x32x16_bf16 v[64:79], v[220:223], v[192:195], v[64:79]
	s_add_u32 m0, s32, 0x0
	s_nop 0
	global_load_lds_dwordx4 v[232:233], off
	v_lshl_add_u64 v[232:233], v[232:233], 0, s[38:39]
	v_mfma_f32_32x32x16_bf16 v[48:63], v[216:219], v[200:203], v[48:63]
	v_mfma_f32_32x32x16_bf16 v[32:47], v[220:223], v[200:203], v[32:47]
	v_mfma_f32_32x32x16_bf16 v[16:31], v[216:219], v[204:207], v[16:31]
	v_mfma_f32_32x32x16_bf16 v[0:15], v[220:223], v[204:207], v[0:15]
	s_add_u32 m0, s32, 0x4000
	s_nop 0
	global_load_lds_dwordx4 v[236:237], off
	v_lshl_add_u64 v[236:237], v[236:237], 0, s[38:39]
	s_waitcnt lgkmcnt(0)
	v_mfma_f32_32x32x16_bf16 v[112:127], v[208:211], v[172:175], v[112:127]
	ds_read_b128 v[216:219], v198 offset:32768
	ds_read_b128 v[188:191], v171 offset:32768
	v_mfma_f32_32x32x16_bf16 v[96:111], v[212:215], v[172:175], v[96:111]
	ds_read_b128 v[220:223], v198 offset:34816
	ds_read_b128 v[192:195], v171 offset:34816
	v_mfma_f32_32x32x16_bf16 v[80:95], v[208:211], v[176:179], v[80:95]
	ds_read_b128 v[200:203], v171 offset:36864
	ds_read_b128 v[204:207], v171 offset:38912
	v_mfma_f32_32x32x16_bf16 v[64:79], v[212:215], v[176:179], v[64:79]
	s_add_u32 m0, s32, 0x2000
	s_nop 0
	global_load_lds_dwordx4 v[234:235], off
	v_lshl_add_u64 v[234:235], v[234:235], 0, s[38:39]
	v_mfma_f32_32x32x16_bf16 v[48:63], v[208:211], v[180:183], v[48:63]
	v_mfma_f32_32x32x16_bf16 v[32:47], v[212:215], v[180:183], v[32:47]
	v_mfma_f32_32x32x16_bf16 v[16:31], v[208:211], v[184:187], v[16:31]
	v_mfma_f32_32x32x16_bf16 v[0:15], v[212:215], v[184:187], v[0:15]
	s_add_u32 m0, s32, 0x6000
	s_nop 0
	global_load_lds_dwordx4 v[238:239], off
	v_lshl_add_u64 v[238:239], v[238:239], 0, s[38:39]
	s_waitcnt lgkmcnt(0)
	s_waitcnt vmcnt(12)
	s_barrier
	s_waitcnt lgkmcnt(0)
	v_mfma_f32_32x32x16_bf16 v[112:127], v[216:219], v[188:191], v[112:127]
	ds_read_b128 v[208:211], v225
	ds_read_b128 v[172:175], v199
	v_mfma_f32_32x32x16_bf16 v[96:111], v[220:223], v[188:191], v[96:111]
	ds_read_b128 v[212:215], v225 offset:2048
	ds_read_b128 v[176:179], v199 offset:2048
	v_mfma_f32_32x32x16_bf16 v[80:95], v[216:219], v[192:195], v[80:95]
	ds_read_b128 v[180:183], v199 offset:4096
	ds_read_b128 v[184:187], v199 offset:6144
	v_mfma_f32_32x32x16_bf16 v[64:79], v[220:223], v[192:195], v[64:79]
	s_add_u32 m0, s32, 0x8000
	s_nop 0
	global_load_lds_dwordx4 v[232:233], off
	v_lshl_add_u64 v[232:233], v[232:233], 0, s[38:39]
	v_mfma_f32_32x32x16_bf16 v[48:63], v[216:219], v[200:203], v[48:63]
	v_mfma_f32_32x32x16_bf16 v[32:47], v[220:223], v[200:203], v[32:47]
	v_mfma_f32_32x32x16_bf16 v[16:31], v[216:219], v[204:207], v[16:31]
	v_mfma_f32_32x32x16_bf16 v[0:15], v[220:223], v[204:207], v[0:15]
	s_add_u32 m0, s32, 0xc000
	s_nop 0
	global_load_lds_dwordx4 v[236:237], off
	v_lshl_add_u64 v[236:237], v[236:237], 0, s[38:39]
	s_waitcnt lgkmcnt(0)
	v_mfma_f32_32x32x16_bf16 v[112:127], v[208:211], v[172:175], v[112:127]
	ds_read_b128 v[216:219], v226
	ds_read_b128 v[188:191], v224
	v_mfma_f32_32x32x16_bf16 v[96:111], v[212:215], v[172:175], v[96:111]
	ds_read_b128 v[220:223], v226 offset:2048
	ds_read_b128 v[192:195], v224 offset:2048
	v_mfma_f32_32x32x16_bf16 v[80:95], v[208:211], v[176:179], v[80:95]
	ds_read_b128 v[200:203], v224 offset:4096
	ds_read_b128 v[204:207], v224 offset:6144
	v_mfma_f32_32x32x16_bf16 v[64:79], v[212:215], v[176:179], v[64:79]
	s_add_u32 m0, s32, 0xa000
	s_nop 0
	global_load_lds_dwordx4 v[234:235], off
	v_lshl_add_u64 v[234:235], v[234:235], 0, s[38:39]
	v_mfma_f32_32x32x16_bf16 v[48:63], v[208:211], v[180:183], v[48:63]
	v_mfma_f32_32x32x16_bf16 v[32:47], v[212:215], v[180:183], v[32:47]
	v_mfma_f32_32x32x16_bf16 v[16:31], v[208:211], v[184:187], v[16:31]
	v_mfma_f32_32x32x16_bf16 v[0:15], v[212:215], v[184:187], v[0:15]
	s_add_u32 m0, s32, 0xe000
	s_nop 0
	global_load_lds_dwordx4 v[238:239], off
	v_lshl_add_u64 v[238:239], v[238:239], 0, s[38:39]
	s_waitcnt lgkmcnt(0)
	s_waitcnt vmcnt(12)
	s_barrier
	s_waitcnt lgkmcnt(0)
	v_mfma_f32_32x32x16_bf16 v[112:127], v[216:219], v[188:191], v[112:127]
	ds_read_b128 v[208:211], v225 offset:32768
	ds_read_b128 v[172:175], v199 offset:32768
	v_mfma_f32_32x32x16_bf16 v[96:111], v[220:223], v[188:191], v[96:111]
	ds_read_b128 v[212:215], v225 offset:34816
	ds_read_b128 v[176:179], v199 offset:34816
	v_mfma_f32_32x32x16_bf16 v[80:95], v[216:219], v[192:195], v[80:95]
	ds_read_b128 v[180:183], v199 offset:36864
	ds_read_b128 v[184:187], v199 offset:38912
	v_mfma_f32_32x32x16_bf16 v[64:79], v[220:223], v[192:195], v[64:79]
	s_add_u32 m0, s32, 0x10000
	s_nop 0
	global_load_lds_dwordx4 v[232:233], off
	v_lshl_add_u64 v[232:233], v[232:233], 0, s[38:39]
	v_mfma_f32_32x32x16_bf16 v[48:63], v[216:219], v[200:203], v[48:63]
	v_mfma_f32_32x32x16_bf16 v[32:47], v[220:223], v[200:203], v[32:47]
	v_mfma_f32_32x32x16_bf16 v[16:31], v[216:219], v[204:207], v[16:31]
	v_mfma_f32_32x32x16_bf16 v[0:15], v[220:223], v[204:207], v[0:15]
	s_add_u32 m0, s32, 0x14000
	s_nop 0
	global_load_lds_dwordx4 v[236:237], off
	v_lshl_add_u64 v[236:237], v[236:237], 0, s[38:39]
	s_waitcnt lgkmcnt(0)
	v_mfma_f32_32x32x16_bf16 v[112:127], v[208:211], v[172:175], v[112:127]
	ds_read_b128 v[216:219], v226 offset:32768
	ds_read_b128 v[188:191], v224 offset:32768
	v_mfma_f32_32x32x16_bf16 v[96:111], v[212:215], v[172:175], v[96:111]
	ds_read_b128 v[220:223], v226 offset:34816
	ds_read_b128 v[192:195], v224 offset:34816
	v_mfma_f32_32x32x16_bf16 v[80:95], v[208:211], v[176:179], v[80:95]
	ds_read_b128 v[200:203], v224 offset:36864
	ds_read_b128 v[204:207], v224 offset:38912
	v_mfma_f32_32x32x16_bf16 v[64:79], v[212:215], v[176:179], v[64:79]
	s_add_u32 m0, s32, 0x12000
	s_nop 0
	global_load_lds_dwordx4 v[234:235], off
	v_lshl_add_u64 v[234:235], v[234:235], 0, s[38:39]
	v_mfma_f32_32x32x16_bf16 v[48:63], v[208:211], v[180:183], v[48:63]
	v_mfma_f32_32x32x16_bf16 v[32:47], v[212:215], v[180:183], v[32:47]
	v_mfma_f32_32x32x16_bf16 v[16:31], v[208:211], v[184:187], v[16:31]
	v_mfma_f32_32x32x16_bf16 v[0:15], v[212:215], v[184:187], v[0:15]
	s_add_u32 m0, s32, 0x16000
	s_nop 0
	global_load_lds_dwordx4 v[238:239], off
	v_lshl_add_u64 v[238:239], v[238:239], 0, s[38:39]
	s_waitcnt lgkmcnt(0)
	s_waitcnt vmcnt(12)
	s_barrier
	s_waitcnt lgkmcnt(0)
	v_mfma_f32_32x32x16_bf16 v[112:127], v[216:219], v[188:191], v[112:127]
	ds_read_b128 v[208:211], v229
	ds_read_b128 v[172:175], v227
	v_mfma_f32_32x32x16_bf16 v[96:111], v[220:223], v[188:191], v[96:111]
	ds_read_b128 v[212:215], v229 offset:2048
	ds_read_b128 v[176:179], v227 offset:2048
	v_mfma_f32_32x32x16_bf16 v[80:95], v[216:219], v[192:195], v[80:95]
	ds_read_b128 v[180:183], v227 offset:4096
	ds_read_b128 v[184:187], v227 offset:6144
	v_mfma_f32_32x32x16_bf16 v[64:79], v[220:223], v[192:195], v[64:79]
	s_add_u32 m0, s32, 0x18000
	s_nop 0
	global_load_lds_dwordx4 v[232:233], off
	v_lshl_add_u64 v[232:233], v[232:233], 0, s[38:39]
	v_mfma_f32_32x32x16_bf16 v[48:63], v[216:219], v[200:203], v[48:63]
	v_mfma_f32_32x32x16_bf16 v[32:47], v[220:223], v[200:203], v[32:47]
	v_mfma_f32_32x32x16_bf16 v[16:31], v[216:219], v[204:207], v[16:31]
	v_mfma_f32_32x32x16_bf16 v[0:15], v[220:223], v[204:207], v[0:15]
	s_add_u32 m0, s32, 0x1c000
	s_nop 0
	global_load_lds_dwordx4 v[236:237], off
	v_lshl_add_u64 v[236:237], v[236:237], 0, s[38:39]
	s_waitcnt lgkmcnt(0)
	v_mfma_f32_32x32x16_bf16 v[112:127], v[208:211], v[172:175], v[112:127]
	ds_read_b128 v[216:219], v230
	ds_read_b128 v[188:191], v228
	v_mfma_f32_32x32x16_bf16 v[96:111], v[212:215], v[172:175], v[96:111]
	ds_read_b128 v[220:223], v230 offset:2048
	ds_read_b128 v[192:195], v228 offset:2048
	v_mfma_f32_32x32x16_bf16 v[80:95], v[208:211], v[176:179], v[80:95]
	ds_read_b128 v[200:203], v228 offset:4096
	ds_read_b128 v[204:207], v228 offset:6144
	v_mfma_f32_32x32x16_bf16 v[64:79], v[212:215], v[176:179], v[64:79]
	s_add_u32 m0, s32, 0x1a000
	s_nop 0
	global_load_lds_dwordx4 v[234:235], off
	v_lshl_add_u64 v[234:235], v[234:235], 0, s[38:39]
	v_mfma_f32_32x32x16_bf16 v[48:63], v[208:211], v[180:183], v[48:63]
	v_mfma_f32_32x32x16_bf16 v[32:47], v[212:215], v[180:183], v[32:47]
	v_mfma_f32_32x32x16_bf16 v[16:31], v[208:211], v[184:187], v[16:31]
	v_mfma_f32_32x32x16_bf16 v[0:15], v[212:215], v[184:187], v[0:15]
	s_add_u32 m0, s32, 0x1e000
	s_nop 0
	global_load_lds_dwordx4 v[238:239], off
	v_lshl_add_u64 v[238:239], v[238:239], 0, s[38:39]
	s_waitcnt lgkmcnt(0)
	s_waitcnt vmcnt(12)
	s_barrier
; #define G_LOADA(kt_) { _Pragma("unroll") for (int i = 0; i < 4; ++i) ra[i] = al(lrow + 64 * i, (kt_) * 64 + lck * 8); }
; #define G_LOADB(kt_) { _Pragma("unroll") for (int i = 0; i < 4; ++i) rb[i] = bl(lrow + 64 * i, (kt_) * 64 + lck * 8); }
; #define G_STOREA(buf_) { bf16_t* nA = sA + (buf_) * 256 * GLD; _Pragma("unroll") for (int i = 0; i < 4; ++i) *(u32x4*)(nA + (lrow + 64 * i) * GLD + lck * 8) = ra[i]; }
; #define G_STOREB(buf_) { bf16_t* nB = sB + (buf_) * 256 * GLD; _Pragma("unroll") for (int i = 0; i < 4; ++i) *(u32x4*)(nB + (lrow + 64 * i) * GLD + lck * 8) = rb[i]; }
; template <class AL, class BL, class EP>
; DI void gemm_tile256(AL al, BL bl, EP ep, int K, char* smem) {
;     ...
;   G_LOADA(0); G_LOADB(0);
;   __syncthreads();
;   G_STOREA(0); G_STOREB(0);
;   if (KT > 1) G_LOADB(1);
;   __syncthreads();
;   for (int kt = 0; kt < KT; kt += 2) {
;     G_STEP(0, kt);
;     if (kt + 1 >= KT) break;
;     G_STEP(1, kt + 1);
;   }
	s_waitcnt lgkmcnt(0)
	v_mfma_f32_32x32x16_bf16 v[112:127], v[216:219], v[188:191], v[112:127]
	ds_read_b128 v[208:211], v197
	ds_read_b128 v[172:175], v132
	v_mfma_f32_32x32x16_bf16 v[96:111], v[220:223], v[188:191], v[96:111]
	ds_read_b128 v[212:215], v197 offset:2048
	ds_read_b128 v[176:179], v132 offset:2048
	v_mfma_f32_32x32x16_bf16 v[80:95], v[216:219], v[192:195], v[80:95]
	ds_read_b128 v[180:183], v132 offset:4096
	ds_read_b128 v[184:187], v132 offset:6144
	v_mfma_f32_32x32x16_bf16 v[64:79], v[220:223], v[192:195], v[64:79]
	s_add_u32 m0, s32, 0x20000
	s_nop 0
	global_load_lds_dwordx4 v[232:233], off
	v_lshl_add_u64 v[232:233], v[232:233], 0, s[38:39]
	v_mfma_f32_32x32x16_bf16 v[48:63], v[216:219], v[200:203], v[48:63]
	v_mfma_f32_32x32x16_bf16 v[32:47], v[220:223], v[200:203], v[32:47]
	v_mfma_f32_32x32x16_bf16 v[16:31], v[216:219], v[204:207], v[16:31]
	v_mfma_f32_32x32x16_bf16 v[0:15], v[220:223], v[204:207], v[0:15]
	s_add_u32 m0, s32, 0x24000
	s_nop 0
	global_load_lds_dwordx4 v[236:237], off
	v_lshl_add_u64 v[236:237], v[236:237], 0, s[38:39]
	s_sub_u32 s54, s54, 1
	s_cmp_lg_u32 s54, 0
	s_cbranch_scc1 .Lgk_ph1_loop
	s_waitcnt lgkmcnt(0)
	v_mfma_f32_32x32x16_bf16 v[112:127], v[208:211], v[172:175], v[112:127]
	ds_read_b128 v[216:219], v198
	ds_read_b128 v[188:191], v171
	v_mfma_f32_32x32x16_bf16 v[96:111], v[212:215], v[172:175], v[96:111]
	ds_read_b128 v[220:223], v198 offset:2048
	ds_read_b128 v[192:195], v171 offset:2048
	v_mfma_f32_32x32x16_bf16 v[80:95], v[208:211], v[176:179], v[80:95]
	ds_read_b128 v[200:203], v171 offset:4096
	ds_read_b128 v[204:207], v171 offset:6144
	v_mfma_f32_32x32x16_bf16 v[64:79], v[212:215], v[176:179], v[64:79]
	s_add_u32 m0, s32, 0x22000
	s_nop 0
	global_load_lds_dwordx4 v[234:235], off
	v_lshl_add_u64 v[234:235], v[234:235], 0, s[38:39]
	v_mfma_f32_32x32x16_bf16 v[48:63], v[208:211], v[180:183], v[48:63]
	v_mfma_f32_32x32x16_bf16 v[32:47], v[212:215], v[180:183], v[32:47]
	v_mfma_f32_32x32x16_bf16 v[16:31], v[208:211], v[184:187], v[16:31]
	v_mfma_f32_32x32x16_bf16 v[0:15], v[212:215], v[184:187], v[0:15]
	s_add_u32 m0, s32, 0x26000
	s_nop 0
	global_load_lds_dwordx4 v[238:239], off
	v_lshl_add_u64 v[238:239], v[238:239], 0, s[38:39]
	s_waitcnt lgkmcnt(0)
	s_waitcnt vmcnt(12)
	s_barrier
	s_waitcnt lgkmcnt(0)
	v_mfma_f32_32x32x16_bf16 v[112:127], v[216:219], v[188:191], v[112:127]
	ds_read_b128 v[208:211], v197 offset:32768
	ds_read_b128 v[172:175], v132 offset:32768
	v_mfma_f32_32x32x16_bf16 v[96:111], v[220:223], v[188:191], v[96:111]
	ds_read_b128 v[212:215], v197 offset:34816
	ds_read_b128 v[176:179], v132 offset:34816
	v_mfma_f32_32x32x16_bf16 v[80:95], v[216:219], v[192:195], v[80:95]
	ds_read_b128 v[180:183], v132 offset:36864
	ds_read_b128 v[184:187], v132 offset:38912
	v_mfma_f32_32x32x16_bf16 v[64:79], v[220:223], v[192:195], v[64:79]
	s_add_u32 m0, s32, 0x0
	s_nop 0
	global_load_lds_dwordx4 v[232:233], off
	v_lshl_add_u64 v[232:233], v[232:233], 0, s[38:39]
	v_mfma_f32_32x32x16_bf16 v[48:63], v[216:219], v[200:203], v[48:63]
	v_mfma_f32_32x32x16_bf16 v[32:47], v[220:223], v[200:203], v[32:47]
	v_mfma_f32_32x32x16_bf16 v[16:31], v[216:219], v[204:207], v[16:31]
	v_mfma_f32_32x32x16_bf16 v[0:15], v[220:223], v[204:207], v[0:15]
	s_add_u32 m0, s32, 0x4000
	s_nop 0
	global_load_lds_dwordx4 v[236:237], off
	v_lshl_add_u64 v[236:237], v[236:237], 0, s[38:39]
	s_waitcnt lgkmcnt(0)
	v_mfma_f32_32x32x16_bf16 v[112:127], v[208:211], v[172:175], v[112:127]
	ds_read_b128 v[216:219], v198 offset:32768
	ds_read_b128 v[188:191], v171 offset:32768
	v_mfma_f32_32x32x16_bf16 v[96:111], v[212:215], v[172:175], v[96:111]
	ds_read_b128 v[220:223], v198 offset:34816
	ds_read_b128 v[192:195], v171 offset:34816
	v_mfma_f32_32x32x16_bf16 v[80:95], v[208:211], v[176:179], v[80:95]
	ds_read_b128 v[200:203], v171 offset:36864
	ds_read_b128 v[204:207], v171 offset:38912
	v_mfma_f32_32x32x16_bf16 v[64:79], v[212:215], v[176:179], v[64:79]
	s_add_u32 m0, s32, 0x2000
	s_nop 0
	global_load_lds_dwordx4 v[234:235], off
	v_lshl_add_u64 v[234:235], v[234:235], 0, s[38:39]
	v_mfma_f32_32x32x16_bf16 v[48:63], v[208:211], v[180:183], v[48:63]
	v_mfma_f32_32x32x16_bf16 v[32:47], v[212:215], v[180:183], v[32:47]
	v_mfma_f32_32x32x16_bf16 v[16:31], v[208:211], v[184:187], v[16:31]
	v_mfma_f32_32x32x16_bf16 v[0:15], v[212:215], v[184:187], v[0:15]
	s_add_u32 m0, s32, 0x6000
	s_nop 0
	global_load_lds_dwordx4 v[238:239], off
	v_lshl_add_u64 v[238:239], v[238:239], 0, s[38:39]
	s_waitcnt lgkmcnt(0)
	s_waitcnt vmcnt(12)
	s_barrier
	s_waitcnt lgkmcnt(0)
	v_mfma_f32_32x32x16_bf16 v[112:127], v[216:219], v[188:191], v[112:127]
	ds_read_b128 v[208:211], v225
	ds_read_b128 v[172:175], v199
	v_mfma_f32_32x32x16_bf16 v[96:111], v[220:223], v[188:191], v[96:111]
	ds_read_b128 v[212:215], v225 offset:2048
	ds_read_b128 v[176:179], v199 offset:2048
	v_mfma_f32_32x32x16_bf16 v[80:95], v[216:219], v[192:195], v[80:95]
	ds_read_b128 v[180:183], v199 offset:4096
	ds_read_b128 v[184:187], v199 offset:6144
	v_mfma_f32_32x32x16_bf16 v[64:79], v[220:223], v[192:195], v[64:79]
	s_add_u32 m0, s32, 0x8000
	s_nop 0
	global_load_lds_dwordx4 v[232:233], off
	v_lshl_add_u64 v[232:233], v[232:233], 0, s[38:39]
	v_mfma_f32_32x32x16_bf16 v[48:63], v[216:219], v[200:203], v[48:63]
	v_mfma_f32_32x32x16_bf16 v[32:47], v[220:223], v[200:203], v[32:47]
	v_mfma_f32_32x32x16_bf16 v[16:31], v[216:219], v[204:207], v[16:31]
	v_mfma_f32_32x32x16_bf16 v[0:15], v[220:223], v[204:207], v[0:15]
	s_add_u32 m0, s32, 0xc000
	s_nop 0
	global_load_lds_dwordx4 v[236:237], off
	v_lshl_add_u64 v[236:237], v[236:237], 0, s[38:39]
	s_waitcnt lgkmcnt(0)
	v_mfma_f32_32x32x16_bf16 v[112:127], v[208:211], v[172:175], v[112:127]
	ds_read_b128 v[216:219], v226
	ds_read_b128 v[188:191], v224
	v_mfma_f32_32x32x16_bf16 v[96:111], v[212:215], v[172:175], v[96:111]
	ds_read_b128 v[220:223], v226 offset:2048
	ds_read_b128 v[192:195], v224 offset:2048
	v_mfma_f32_32x32x16_bf16 v[80:95], v[208:211], v[176:179], v[80:95]
	ds_read_b128 v[200:203], v224 offset:4096
	ds_read_b128 v[204:207], v224 offset:6144
	v_mfma_f32_32x32x16_bf16 v[64:79], v[212:215], v[176:179], v[64:79]
	s_add_u32 m0, s32, 0xa000
	s_nop 0
	global_load_lds_dwordx4 v[234:235], off
	v_lshl_add_u64 v[234:235], v[234:235], 0, s[38:39]
	v_mfma_f32_32x32x16_bf16 v[48:63], v[208:211], v[180:183], v[48:63]
	v_mfma_f32_32x32x16_bf16 v[32:47], v[212:215], v[180:183], v[32:47]
	v_mfma_f32_32x32x16_bf16 v[16:31], v[208:211], v[184:187], v[16:31]
	v_mfma_f32_32x32x16_bf16 v[0:15], v[212:215], v[184:187], v[0:15]
	s_add_u32 m0, s32, 0xe000
	s_nop 0
	global_load_lds_dwordx4 v[238:239], off
	v_lshl_add_u64 v[238:239], v[238:239], 0, s[38:39]
	s_waitcnt lgkmcnt(0)
	s_waitcnt vmcnt(12)
	s_barrier
; #define G_LOADA(kt_) { _Pragma("unroll") for (int i = 0; i < 4; ++i) ra[i] = al(lrow + 64 * i, (kt_) * 64 + lck * 8); }
; #define G_LOADB(kt_) { _Pragma("unroll") for (int i = 0; i < 4; ++i) rb[i] = bl(lrow + 64 * i, (kt_) * 64 + lck * 8); }
; #define G_STOREA(buf_) { bf16_t* nA = sA + (buf_) * 256 * GLD; _Pragma("unroll") for (int i = 0; i < 4; ++i) *(u32x4*)(nA + (lrow + 64 * i) * GLD + lck * 8) = ra[i]; }
; #define G_STOREB(buf_) { bf16_t* nB = sB + (buf_) * 256 * GLD; _Pragma("unroll") for (int i = 0; i < 4; ++i) *(u32x4*)(nB + (lrow + 64 * i) * GLD + lck * 8) = rb[i]; }
; template <class AL, class BL, class EP>
; DI void gemm_tile256(AL al, BL bl, EP ep, int K, char* smem) {
;     ...
;   G_LOADA(0); G_LOADB(0);
;   __syncthreads();
;   G_STOREA(0); G_STOREB(0);
;   if (KT > 1) G_LOADB(1);
;   __syncthreads();
;   for (int kt = 0; kt < KT; kt += 2) {
;     G_STEP(0, kt);
;     if (kt + 1 >= KT) break;
;     G_STEP(1, kt + 1);
;   }
	s_waitcnt lgkmcnt(0)
	v_mfma_f32_32x32x16_bf16 v[112:127], v[216:219], v[188:191], v[112:127]
	ds_read_b128 v[208:211], v225 offset:32768
	ds_read_b128 v[172:175], v199 offset:32768
	v_mfma_f32_32x32x16_bf16 v[96:111], v[220:223], v[188:191], v[96:111]
	ds_read_b128 v[212:215], v225 offset:34816
	ds_read_b128 v[176:179], v199 offset:34816
	v_mfma_f32_32x32x16_bf16 v[80:95], v[216:219], v[192:195], v[80:95]
	ds_read_b128 v[180:183], v199 offset:36864
	ds_read_b128 v[184:187], v199 offset:38912
	v_mfma_f32_32x32x16_bf16 v[64:79], v[220:223], v[192:195], v[64:79]
	v_mfma_f32_32x32x16_bf16 v[48:63], v[216:219], v[200:203], v[48:63]
	v_mfma_f32_32x32x16_bf16 v[32:47], v[220:223], v[200:203], v[32:47]
	v_mfma_f32_32x32x16_bf16 v[16:31], v[216:219], v[204:207], v[16:31]
	v_mfma_f32_32x32x16_bf16 v[0:15], v[220:223], v[204:207], v[0:15]
	s_waitcnt lgkmcnt(0)
	v_mfma_f32_32x32x16_bf16 v[112:127], v[208:211], v[172:175], v[112:127]
	ds_read_b128 v[216:219], v226 offset:32768
	ds_read_b128 v[188:191], v224 offset:32768
	v_mfma_f32_32x32x16_bf16 v[96:111], v[212:215], v[172:175], v[96:111]
	ds_read_b128 v[220:223], v226 offset:34816
	ds_read_b128 v[192:195], v224 offset:34816
	v_mfma_f32_32x32x16_bf16 v[80:95], v[208:211], v[176:179], v[80:95]
	ds_read_b128 v[200:203], v224 offset:36864
	ds_read_b128 v[204:207], v224 offset:38912
	v_mfma_f32_32x32x16_bf16 v[64:79], v[212:215], v[176:179], v[64:79]
	v_mfma_f32_32x32x16_bf16 v[48:63], v[208:211], v[180:183], v[48:63]
	v_mfma_f32_32x32x16_bf16 v[32:47], v[212:215], v[180:183], v[32:47]
	v_mfma_f32_32x32x16_bf16 v[16:31], v[208:211], v[184:187], v[16:31]
	v_mfma_f32_32x32x16_bf16 v[0:15], v[212:215], v[184:187], v[0:15]
	s_waitcnt lgkmcnt(0)
	s_waitcnt vmcnt(8)
	s_barrier
	s_waitcnt lgkmcnt(0)
	v_mfma_f32_32x32x16_bf16 v[112:127], v[216:219], v[188:191], v[112:127]
	ds_read_b128 v[208:211], v229
	ds_read_b128 v[172:175], v227
	v_mfma_f32_32x32x16_bf16 v[96:111], v[220:223], v[188:191], v[96:111]
	ds_read_b128 v[212:215], v229 offset:2048
	ds_read_b128 v[176:179], v227 offset:2048
	v_mfma_f32_32x32x16_bf16 v[80:95], v[216:219], v[192:195], v[80:95]
	ds_read_b128 v[180:183], v227 offset:4096
	ds_read_b128 v[184:187], v227 offset:6144
	v_mfma_f32_32x32x16_bf16 v[64:79], v[220:223], v[192:195], v[64:79]
	v_mfma_f32_32x32x16_bf16 v[48:63], v[216:219], v[200:203], v[48:63]
	v_mfma_f32_32x32x16_bf16 v[32:47], v[220:223], v[200:203], v[32:47]
	v_mfma_f32_32x32x16_bf16 v[16:31], v[216:219], v[204:207], v[16:31]
	v_mfma_f32_32x32x16_bf16 v[0:15], v[220:223], v[204:207], v[0:15]
	s_waitcnt lgkmcnt(0)
	v_mfma_f32_32x32x16_bf16 v[112:127], v[208:211], v[172:175], v[112:127]
	ds_read_b128 v[216:219], v230
	ds_read_b128 v[188:191], v228
	v_mfma_f32_32x32x16_bf16 v[96:111], v[212:215], v[172:175], v[96:111]
	ds_read_b128 v[220:223], v230 offset:2048
	ds_read_b128 v[192:195], v228 offset:2048
	v_mfma_f32_32x32x16_bf16 v[80:95], v[208:211], v[176:179], v[80:95]
	ds_read_b128 v[200:203], v228 offset:4096
	ds_read_b128 v[204:207], v228 offset:6144
	v_mfma_f32_32x32x16_bf16 v[64:79], v[212:215], v[176:179], v[64:79]
	v_mfma_f32_32x32x16_bf16 v[48:63], v[208:211], v[180:183], v[48:63]
	v_mfma_f32_32x32x16_bf16 v[32:47], v[212:215], v[180:183], v[32:47]
	v_mfma_f32_32x32x16_bf16 v[16:31], v[208:211], v[184:187], v[16:31]
	v_mfma_f32_32x32x16_bf16 v[0:15], v[212:215], v[184:187], v[0:15]
	s_waitcnt lgkmcnt(0)
	s_waitcnt vmcnt(4)
	s_barrier
	s_waitcnt lgkmcnt(0)
	v_mfma_f32_32x32x16_bf16 v[112:127], v[216:219], v[188:191], v[112:127]
	ds_read_b128 v[208:211], v197
	ds_read_b128 v[172:175], v132
	v_mfma_f32_32x32x16_bf16 v[96:111], v[220:223], v[188:191], v[96:111]
	ds_read_b128 v[212:215], v197 offset:2048
	ds_read_b128 v[176:179], v132 offset:2048
	v_mfma_f32_32x32x16_bf16 v[80:95], v[216:219], v[192:195], v[80:95]
	ds_read_b128 v[180:183], v132 offset:4096
	ds_read_b128 v[184:187], v132 offset:6144
	v_mfma_f32_32x32x16_bf16 v[64:79], v[220:223], v[192:195], v[64:79]
	v_mfma_f32_32x32x16_bf16 v[48:63], v[216:219], v[200:203], v[48:63]
	v_mfma_f32_32x32x16_bf16 v[32:47], v[220:223], v[200:203], v[32:47]
	v_mfma_f32_32x32x16_bf16 v[16:31], v[216:219], v[204:207], v[16:31]
	v_mfma_f32_32x32x16_bf16 v[0:15], v[220:223], v[204:207], v[0:15]
	s_waitcnt lgkmcnt(0)
	v_mfma_f32_32x32x16_bf16 v[112:127], v[208:211], v[172:175], v[112:127]
	ds_read_b128 v[216:219], v198
	ds_read_b128 v[188:191], v171
	v_mfma_f32_32x32x16_bf16 v[96:111], v[212:215], v[172:175], v[96:111]
	ds_read_b128 v[220:223], v198 offset:2048
	ds_read_b128 v[192:195], v171 offset:2048
	v_mfma_f32_32x32x16_bf16 v[80:95], v[208:211], v[176:179], v[80:95]
	ds_read_b128 v[200:203], v171 offset:4096
	ds_read_b128 v[204:207], v171 offset:6144
	v_mfma_f32_32x32x16_bf16 v[64:79], v[212:215], v[176:179], v[64:79]
	v_mfma_f32_32x32x16_bf16 v[48:63], v[208:211], v[180:183], v[48:63]
	v_mfma_f32_32x32x16_bf16 v[32:47], v[212:215], v[180:183], v[32:47]
	v_mfma_f32_32x32x16_bf16 v[16:31], v[208:211], v[184:187], v[16:31]
	v_mfma_f32_32x32x16_bf16 v[0:15], v[212:215], v[184:187], v[0:15]
	s_waitcnt lgkmcnt(0)
	s_waitcnt vmcnt(0)
	s_barrier
; DI unsigned pack2(float a, float b) { f2_t f = {a, b}; bf2_t r = __builtin_convertvector(f, bf2_t); return __builtin_bit_cast(unsigned, r); }
; template <class AL, class BL, class EP>
; DI void gemm_tile256(AL al, BL bl, EP ep, int K, char* smem) {
;     ...
;   if constexpr (EP::kBf16) {
;     bf16_t* sCb = (bf16_t*)smem;
; #pragma unroll
;     for (int i = 0; i < 4; ++i)
; #pragma unroll
;       for (int j = 0; j < 2; ++j)
; #pragma unroll
;         for (int g = 0; g < 4; ++g) {
;           u32x2 v = {pack2(acc[i][j][4 * g], acc[i][j][4 * g + 1]), pack2(acc[i][j][4 * g + 2], acc[i][j][4 * g + 3])};
;           *(u32x2*)(sCb + (128 * wm + 32 * i + r) * BLD + 64 * wn + 32 * j + 8 * g + 4 * h) = v;
;         }
;     __syncthreads();
	s_waitcnt lgkmcnt(0)
	v_mfma_f32_32x32x16_bf16 v[112:127], v[216:219], v[188:191], v[112:127]
	ds_read_b128 v[208:211], v197 offset:32768
	ds_read_b128 v[172:175], v132 offset:32768
	v_mfma_f32_32x32x16_bf16 v[96:111], v[220:223], v[188:191], v[96:111]
	ds_read_b128 v[212:215], v197 offset:34816
	ds_read_b128 v[176:179], v132 offset:34816
	v_mfma_f32_32x32x16_bf16 v[80:95], v[216:219], v[192:195], v[80:95]
	ds_read_b128 v[180:183], v132 offset:36864
	ds_read_b128 v[184:187], v132 offset:38912
	v_mfma_f32_32x32x16_bf16 v[64:79], v[220:223], v[192:195], v[64:79]
	v_mfma_f32_32x32x16_bf16 v[48:63], v[216:219], v[200:203], v[48:63]
	v_mfma_f32_32x32x16_bf16 v[32:47], v[220:223], v[200:203], v[32:47]
	v_mfma_f32_32x32x16_bf16 v[16:31], v[216:219], v[204:207], v[16:31]
	v_mfma_f32_32x32x16_bf16 v[0:15], v[220:223], v[204:207], v[0:15]
	s_waitcnt lgkmcnt(0)
	v_mfma_f32_32x32x16_bf16 v[112:127], v[208:211], v[172:175], v[112:127]
	ds_read_b128 v[216:219], v198 offset:32768
	ds_read_b128 v[188:191], v171 offset:32768
	v_mfma_f32_32x32x16_bf16 v[96:111], v[212:215], v[172:175], v[96:111]
	ds_read_b128 v[220:223], v198 offset:34816
	ds_read_b128 v[192:195], v171 offset:34816
	v_mfma_f32_32x32x16_bf16 v[80:95], v[208:211], v[176:179], v[80:95]
	ds_read_b128 v[200:203], v171 offset:36864
	ds_read_b128 v[204:207], v171 offset:38912
	v_mfma_f32_32x32x16_bf16 v[64:79], v[212:215], v[176:179], v[64:79]
	v_mfma_f32_32x32x16_bf16 v[48:63], v[208:211], v[180:183], v[48:63]
	v_mfma_f32_32x32x16_bf16 v[32:47], v[212:215], v[180:183], v[32:47]
	v_mfma_f32_32x32x16_bf16 v[16:31], v[208:211], v[184:187], v[16:31]
	v_mfma_f32_32x32x16_bf16 v[0:15], v[212:215], v[184:187], v[0:15]
	s_waitcnt lgkmcnt(0)
	s_waitcnt lgkmcnt(0)
	v_mfma_f32_32x32x16_bf16 v[112:127], v[216:219], v[188:191], v[112:127]
	v_mfma_f32_32x32x16_bf16 v[96:111], v[220:223], v[188:191], v[96:111]
	v_mfma_f32_32x32x16_bf16 v[80:95], v[216:219], v[192:195], v[80:95]
	v_mfma_f32_32x32x16_bf16 v[64:79], v[220:223], v[192:195], v[64:79]
	v_mfma_f32_32x32x16_bf16 v[48:63], v[216:219], v[200:203], v[48:63]
	v_mfma_f32_32x32x16_bf16 v[32:47], v[220:223], v[200:203], v[32:47]
	v_mfma_f32_32x32x16_bf16 v[16:31], v[216:219], v[204:207], v[16:31]
	v_mfma_f32_32x32x16_bf16 v[0:15], v[220:223], v[204:207], v[0:15]
	s_nop 15
	s_nop 3
	s_setprio 0
	v_lshl_or_b32 v128, v128, 7, v170
	s_waitcnt lgkmcnt(4)
	v_mad_u64_u32 v[130:131], s[0:1], v133, s43, v[128:129]
	s_waitcnt lgkmcnt(0)
	s_barrier
	s_nop 8
	v_cvt_pk_bf16_f32 v112, v112, v113
	v_cvt_pk_bf16_f32 v113, v114, v115
	v_cvt_pk_bf16_f32 v114, v116, v117
	v_cvt_pk_bf16_f32 v115, v118, v119
	ds_write2_b64 v130, v[112:113], v[114:115] offset1:2
	v_cvt_pk_bf16_f32 v112, v120, v121
	v_cvt_pk_bf16_f32 v113, v122, v123
	v_cvt_pk_bf16_f32 v114, v124, v125
	s_nop 3
	v_cvt_pk_bf16_f32 v16, v16, v17
	v_cvt_pk_bf16_f32 v17, v18, v19
	v_cvt_pk_bf16_f32 v18, v20, v21
	v_add_u32_e32 v20, 0xc000, v130
	v_cvt_pk_bf16_f32 v19, v22, v23
	v_cvt_pk_bf16_f32 v115, v126, v127
	ds_write2_b64 v20, v[16:17], v[18:19] offset0:192 offset1:194
	v_cvt_pk_bf16_f32 v0, v0, v1
	v_cvt_pk_bf16_f32 v1, v2, v3
	v_cvt_pk_bf16_f32 v2, v4, v5
	v_cvt_pk_bf16_f32 v3, v6, v7
	ds_write2_b64 v20, v[0:1], v[2:3] offset0:200 offset1:202
	v_cvt_pk_bf16_f32 v0, v8, v9
	v_cvt_pk_bf16_f32 v1, v10, v11
	s_nop 3
	v_cvt_pk_bf16_f32 v96, v96, v97
	v_cvt_pk_bf16_f32 v97, v98, v99
	v_cvt_pk_bf16_f32 v98, v100, v101
	v_cvt_pk_bf16_f32 v99, v102, v103
	v_cvt_pk_bf16_f32 v2, v12, v13
	v_cvt_pk_bf16_f32 v3, v14, v15
	ds_write2_b64 v130, v[96:97], v[98:99] offset0:8 offset1:10
	v_cvt_pk_bf16_f32 v80, v80, v81
	v_cvt_pk_bf16_f32 v81, v82, v83
	v_cvt_pk_bf16_f32 v82, v84, v85
	v_cvt_pk_bf16_f32 v83, v86, v87
	v_add_u32_e32 v84, 0x4000, v130
	v_cvt_pk_bf16_f32 v96, v104, v105
	v_cvt_pk_bf16_f32 v97, v106, v107
	s_nop 3
	v_cvt_pk_bf16_f32 v64, v64, v65
	v_cvt_pk_bf16_f32 v65, v66, v67
	v_cvt_pk_bf16_f32 v66, v68, v69
	v_cvt_pk_bf16_f32 v67, v70, v71
	v_cvt_pk_bf16_f32 v98, v108, v109
	v_cvt_pk_bf16_f32 v99, v110, v111
	ds_write2_b64 v84, v[80:81], v[82:83] offset0:64 offset1:66
	v_cvt_pk_bf16_f32 v48, v48, v49
	v_cvt_pk_bf16_f32 v49, v50, v51
	v_cvt_pk_bf16_f32 v50, v52, v53
	v_cvt_pk_bf16_f32 v51, v54, v55
	v_add_u32_e32 v52, 0x8000, v130
	v_cvt_pk_bf16_f32 v80, v88, v89
	v_cvt_pk_bf16_f32 v81, v90, v91
	s_nop 4
	v_cvt_pk_bf16_f32 v32, v32, v33
	v_cvt_pk_bf16_f32 v33, v34, v35
	v_cvt_pk_bf16_f32 v34, v36, v37
	v_cvt_pk_bf16_f32 v35, v38, v39
	v_cvt_pk_bf16_f32 v82, v92, v93
	v_cvt_pk_bf16_f32 v83, v94, v95
	ds_write2_b64 v84, v[64:65], v[66:67] offset0:72 offset1:74
	v_cvt_pk_bf16_f32 v64, v72, v73
	v_cvt_pk_bf16_f32 v65, v74, v75
	v_cvt_pk_bf16_f32 v66, v76, v77
	v_cvt_pk_bf16_f32 v67, v78, v79
	ds_write2_b64 v52, v[48:49], v[50:51] offset0:128 offset1:130
	v_cvt_pk_bf16_f32 v48, v56, v57
	v_cvt_pk_bf16_f32 v49, v58, v59
	v_cvt_pk_bf16_f32 v50, v60, v61
	v_cvt_pk_bf16_f32 v51, v62, v63
	ds_write2_b64 v52, v[32:33], v[34:35] offset0:136 offset1:138
	v_cvt_pk_bf16_f32 v32, v40, v41
	v_cvt_pk_bf16_f32 v33, v42, v43
	v_cvt_pk_bf16_f32 v34, v44, v45
	v_cvt_pk_bf16_f32 v35, v46, v47
	v_cvt_pk_bf16_f32 v16, v24, v25
	v_cvt_pk_bf16_f32 v17, v26, v27
	v_cvt_pk_bf16_f32 v18, v28, v29
	v_cvt_pk_bf16_f32 v19, v30, v31
	ds_write2_b64 v20, v[0:1], v[2:3] offset0:204 offset1:206
	v_mov_b32_e32 v2, v196
	ds_write2_b64 v130, v[112:113], v[114:115] offset0:4 offset1:6
	ds_write2_b64 v130, v[96:97], v[98:99] offset0:12 offset1:14
	ds_write2_b64 v84, v[80:81], v[82:83] offset0:68 offset1:70
	ds_write2_b64 v84, v[64:65], v[66:67] offset0:76 offset1:78
	ds_write2_b64 v52, v[48:49], v[50:51] offset0:132 offset1:134
	ds_write2_b64 v52, v[32:33], v[34:35] offset0:140 offset1:142
	ds_write2_b64 v20, v[16:17], v[18:19] offset0:196 offset1:198
	s_waitcnt lgkmcnt(0)
	s_barrier
; DI int tid512() { int t = threadIdx_x_raw(); asm volatile("" : "+v"(t)); return t; }
;   DI void operator()(const bf16_t* sCb) const {
;     for (int id = tid512(); id < 8192; id += 512) {
;       int row = id >> 5, c8 = (id & 31) * 8, n = n0 + c8;
;       if (n < N) *(u32x4*)(dst + (size_t)(m0 + row) * ld + n) = *(const u32x4*)(sCb + row * BLD + c8);
;     }
;   }
	s_nop 0
	v_cmp_gt_i32_e32 vcc, s44, v2
	s_and_saveexec_b64 s[0:1], vcc
	s_cbranch_execz .LBB0_161
	v_lshlrev_b32_e32 v3, 3, v2
	v_and_b32_e32 v1, 0xf8, v3
	v_or_b32_e32 v0, v1, v169
	v_cmp_gt_i32_e32 vcc, s45, v0
	s_and_saveexec_b64 s[38:39], vcc
	s_cbranch_execz .Lep_done_161
	v_ashrrev_i32_e32 v8, 5, v2
	v_mul_lo_u32 v4, v8, s43
	v_lshl_add_u32 v1, v1, 1, v4
	v_add_u32_e32 v10, 0x10800, v1
	ds_read_b128 v[64:67], v1
	ds_read_b128 v[68:71], v1 offset:8448
	ds_read_b128 v[72:75], v1 offset:16896
	ds_read_b128 v[76:79], v1 offset:25344
	ds_read_b128 v[80:83], v1 offset:33792
	ds_read_b128 v[84:87], v1 offset:42240
	ds_read_b128 v[88:91], v1 offset:50688
	ds_read_b128 v[92:95], v1 offset:59136
	ds_read_b128 v[96:99], v10
	ds_read_b128 v[100:103], v10 offset:8448
	ds_read_b128 v[104:107], v10 offset:16896
	ds_read_b128 v[108:111], v10 offset:25344
	ds_read_b128 v[112:115], v10 offset:33792
	ds_read_b128 v[116:119], v10 offset:42240
	ds_read_b128 v[120:123], v10 offset:50688
	ds_read_b128 v[124:127], v10 offset:59136
	v_and_b32_e32 v1, 0xf8, v3
	v_or_b32_e32 v0, v1, v169
	v_ashrrev_i32_e32 v8, 5, v2
	v_add_u32_e32 v1, v8, v168
	v_mov_b64_e32 v[8:9], s[72:73]
	v_mad_i64_i32 v[8:9], s[48:49], v1, s46, v[8:9]
	v_ashrrev_i32_e32 v1, 31, v0
	v_lshl_add_u64 v[0:1], v[0:1], 1, v[8:9]
	s_waitcnt lgkmcnt(15)
	global_store_dwordx4 v[0:1], v[64:67], off
	v_add_u32_e32 v2, 0x200, v2
	v_and_b32_e32 v1, 0xf8, v3
	v_or_b32_e32 v0, v1, v169
	v_ashrrev_i32_e32 v8, 5, v2
	v_add_u32_e32 v1, v8, v168
	v_mov_b64_e32 v[8:9], s[72:73]
	v_mad_i64_i32 v[8:9], s[48:49], v1, s46, v[8:9]
	v_ashrrev_i32_e32 v1, 31, v0
	v_lshl_add_u64 v[0:1], v[0:1], 1, v[8:9]
	s_waitcnt lgkmcnt(14)
	global_store_dwordx4 v[0:1], v[68:71], off
	v_add_u32_e32 v2, 0x200, v2
	v_and_b32_e32 v1, 0xf8, v3
	v_or_b32_e32 v0, v1, v169
	v_ashrrev_i32_e32 v8, 5, v2
	v_add_u32_e32 v1, v8, v168
	v_mov_b64_e32 v[8:9], s[72:73]
	v_mad_i64_i32 v[8:9], s[48:49], v1, s46, v[8:9]
	v_ashrrev_i32_e32 v1, 31, v0
	v_lshl_add_u64 v[0:1], v[0:1], 1, v[8:9]
	s_waitcnt lgkmcnt(13)
	global_store_dwordx4 v[0:1], v[72:75], off
	v_add_u32_e32 v2, 0x200, v2
	v_and_b32_e32 v1, 0xf8, v3
	v_or_b32_e32 v0, v1, v169
	v_ashrrev_i32_e32 v8, 5, v2
	v_add_u32_e32 v1, v8, v168
	v_mov_b64_e32 v[8:9], s[72:73]
	v_mad_i64_i32 v[8:9], s[48:49], v1, s46, v[8:9]
	v_ashrrev_i32_e32 v1, 31, v0
	v_lshl_add_u64 v[0:1], v[0:1], 1, v[8:9]
	s_waitcnt lgkmcnt(12)
	global_store_dwordx4 v[0:1], v[76:79], off
	v_add_u32_e32 v2, 0x200, v2
	v_and_b32_e32 v1, 0xf8, v3
	v_or_b32_e32 v0, v1, v169
	v_ashrrev_i32_e32 v8, 5, v2
	v_add_u32_e32 v1, v8, v168
	v_mov_b64_e32 v[8:9], s[72:73]
	v_mad_i64_i32 v[8:9], s[48:49], v1, s46, v[8:9]
	v_ashrrev_i32_e32 v1, 31, v0
	v_lshl_add_u64 v[0:1], v[0:1], 1, v[8:9]
	s_waitcnt lgkmcnt(11)
	global_store_dwordx4 v[0:1], v[80:83], off
	v_add_u32_e32 v2, 0x200, v2
	v_and_b32_e32 v1, 0xf8, v3
	v_or_b32_e32 v0, v1, v169
	v_ashrrev_i32_e32 v8, 5, v2
	v_add_u32_e32 v1, v8, v168
	v_mov_b64_e32 v[8:9], s[72:73]
	v_mad_i64_i32 v[8:9], s[48:49], v1, s46, v[8:9]
	v_ashrrev_i32_e32 v1, 31, v0
	v_lshl_add_u64 v[0:1], v[0:1], 1, v[8:9]
	s_waitcnt lgkmcnt(10)
	global_store_dwordx4 v[0:1], v[84:87], off
	v_add_u32_e32 v2, 0x200, v2
	v_and_b32_e32 v1, 0xf8, v3
	v_or_b32_e32 v0, v1, v169
	v_ashrrev_i32_e32 v8, 5, v2
	v_add_u32_e32 v1, v8, v168
	v_mov_b64_e32 v[8:9], s[72:73]
	v_mad_i64_i32 v[8:9], s[48:49], v1, s46, v[8:9]
	v_ashrrev_i32_e32 v1, 31, v0
	v_lshl_add_u64 v[0:1], v[0:1], 1, v[8:9]
	s_waitcnt lgkmcnt(9)
	global_store_dwordx4 v[0:1], v[88:91], off
	v_add_u32_e32 v2, 0x200, v2
	v_and_b32_e32 v1, 0xf8, v3
	v_or_b32_e32 v0, v1, v169
	v_ashrrev_i32_e32 v8, 5, v2
	v_add_u32_e32 v1, v8, v168
	v_mov_b64_e32 v[8:9], s[72:73]
	v_mad_i64_i32 v[8:9], s[48:49], v1, s46, v[8:9]
	v_ashrrev_i32_e32 v1, 31, v0
	v_lshl_add_u64 v[0:1], v[0:1], 1, v[8:9]
	s_waitcnt lgkmcnt(8)
	global_store_dwordx4 v[0:1], v[92:95], off
	v_add_u32_e32 v2, 0x200, v2
	v_and_b32_e32 v1, 0xf8, v3
	v_or_b32_e32 v0, v1, v169
	v_ashrrev_i32_e32 v8, 5, v2
	v_add_u32_e32 v1, v8, v168
	v_mov_b64_e32 v[8:9], s[72:73]
	v_mad_i64_i32 v[8:9], s[48:49], v1, s46, v[8:9]
	v_ashrrev_i32_e32 v1, 31, v0
	v_lshl_add_u64 v[0:1], v[0:1], 1, v[8:9]
	s_waitcnt lgkmcnt(7)
	global_store_dwordx4 v[0:1], v[96:99], off
	v_add_u32_e32 v2, 0x200, v2
	v_and_b32_e32 v1, 0xf8, v3
	v_or_b32_e32 v0, v1, v169
	v_ashrrev_i32_e32 v8, 5, v2
	v_add_u32_e32 v1, v8, v168
	v_mov_b64_e32 v[8:9], s[72:73]
	v_mad_i64_i32 v[8:9], s[48:49], v1, s46, v[8:9]
	v_ashrrev_i32_e32 v1, 31, v0
	v_lshl_add_u64 v[0:1], v[0:1], 1, v[8:9]
	s_waitcnt lgkmcnt(6)
	global_store_dwordx4 v[0:1], v[100:103], off
	v_add_u32_e32 v2, 0x200, v2
	v_and_b32_e32 v1, 0xf8, v3
	v_or_b32_e32 v0, v1, v169
	v_ashrrev_i32_e32 v8, 5, v2
	v_add_u32_e32 v1, v8, v168
	v_mov_b64_e32 v[8:9], s[72:73]
	v_mad_i64_i32 v[8:9], s[48:49], v1, s46, v[8:9]
	v_ashrrev_i32_e32 v1, 31, v0
	v_lshl_add_u64 v[0:1], v[0:1], 1, v[8:9]
	s_waitcnt lgkmcnt(5)
	global_store_dwordx4 v[0:1], v[104:107], off
	v_add_u32_e32 v2, 0x200, v2
	v_and_b32_e32 v1, 0xf8, v3
	v_or_b32_e32 v0, v1, v169
	v_ashrrev_i32_e32 v8, 5, v2
	v_add_u32_e32 v1, v8, v168
	v_mov_b64_e32 v[8:9], s[72:73]
	v_mad_i64_i32 v[8:9], s[48:49], v1, s46, v[8:9]
	v_ashrrev_i32_e32 v1, 31, v0
	v_lshl_add_u64 v[0:1], v[0:1], 1, v[8:9]
	s_waitcnt lgkmcnt(4)
	global_store_dwordx4 v[0:1], v[108:111], off
	v_add_u32_e32 v2, 0x200, v2
	v_and_b32_e32 v1, 0xf8, v3
	v_or_b32_e32 v0, v1, v169
	v_ashrrev_i32_e32 v8, 5, v2
	v_add_u32_e32 v1, v8, v168
	v_mov_b64_e32 v[8:9], s[72:73]
	v_mad_i64_i32 v[8:9], s[48:49], v1, s46, v[8:9]
	v_ashrrev_i32_e32 v1, 31, v0
	v_lshl_add_u64 v[0:1], v[0:1], 1, v[8:9]
	s_waitcnt lgkmcnt(3)
	global_store_dwordx4 v[0:1], v[112:115], off
	v_add_u32_e32 v2, 0x200, v2
	v_and_b32_e32 v1, 0xf8, v3
	v_or_b32_e32 v0, v1, v169
	v_ashrrev_i32_e32 v8, 5, v2
	v_add_u32_e32 v1, v8, v168
	v_mov_b64_e32 v[8:9], s[72:73]
	v_mad_i64_i32 v[8:9], s[48:49], v1, s46, v[8:9]
	v_ashrrev_i32_e32 v1, 31, v0
	v_lshl_add_u64 v[0:1], v[0:1], 1, v[8:9]
	s_waitcnt lgkmcnt(2)
	global_store_dwordx4 v[0:1], v[116:119], off
	v_add_u32_e32 v2, 0x200, v2
	v_and_b32_e32 v1, 0xf8, v3
	v_or_b32_e32 v0, v1, v169
	v_ashrrev_i32_e32 v8, 5, v2
	v_add_u32_e32 v1, v8, v168
	v_mov_b64_e32 v[8:9], s[72:73]
	v_mad_i64_i32 v[8:9], s[48:49], v1, s46, v[8:9]
	v_ashrrev_i32_e32 v1, 31, v0
	v_lshl_add_u64 v[0:1], v[0:1], 1, v[8:9]
	s_waitcnt lgkmcnt(1)
	global_store_dwordx4 v[0:1], v[120:123], off
	v_add_u32_e32 v2, 0x200, v2
	v_and_b32_e32 v1, 0xf8, v3
	v_or_b32_e32 v0, v1, v169
	v_ashrrev_i32_e32 v8, 5, v2
	v_add_u32_e32 v1, v8, v168
	v_mov_b64_e32 v[8:9], s[72:73]
	v_mad_i64_i32 v[8:9], s[48:49], v1, s46, v[8:9]
	v_ashrrev_i32_e32 v1, 31, v0
	v_lshl_add_u64 v[0:1], v[0:1], 1, v[8:9]
	s_waitcnt lgkmcnt(0)
	global_store_dwordx4 v[0:1], v[124:127], off

; DI int tid512() { int t = threadIdx_x_raw(); asm volatile("" : "+v"(t)); return t; }
; #define G_LOADA(kt_) { _Pragma("unroll") for (int i = 0; i < 4; ++i) ra[i] = al(lrow + 64 * i, (kt_) * 64 + lck * 8); }
; #define G_LOADB(kt_) { _Pragma("unroll") for (int i = 0; i < 4; ++i) rb[i] = bl(lrow + 64 * i, (kt_) * 64 + lck * 8); }
; #define G_STOREA(buf_) { bf16_t* nA = sA + (buf_) * 256 * GLD; _Pragma("unroll") for (int i = 0; i < 4; ++i) *(u32x4*)(nA + (lrow + 64 * i) * GLD + lck * 8) = ra[i]; }
; #define G_STOREB(buf_) { bf16_t* nB = sB + (buf_) * 256 * GLD; _Pragma("unroll") for (int i = 0; i < 4; ++i) *(u32x4*)(nB + (lrow + 64 * i) * GLD + lck * 8) = rb[i]; }
; template <class AL, class BL, class EP>
; DI void gemm_tile256(AL al, BL bl, EP ep, int K, char* smem) {
;   bf16_t* sA = (bf16_t*)smem;
;   bf16_t* sB = sA + 2 * 256 * GLD;
;   const int tid = tid512(), lane = tid & 63, w = tid >> 6, wm = w >> 2, wn = w & 3, r = lane & 31, h = lane >> 5;
;   const int lrow = tid >> 3, lck = tid & 7;
;   f32x16 acc[4][2];
; #pragma unroll
;   for (int i = 0; i < 4; ++i)
; #pragma unroll
;     for (int j = 0; j < 2; ++j)
; #pragma unroll
;       for (int q = 0; q < 16; ++q) acc[i][j][q] = 0.f;
;   u32x4 ra[4], rb[4];
;   const int KT = K >> 6;
;     ...
;   G_LOADA(0); G_LOADB(0);
;   __syncthreads();
;   G_STOREA(0); G_STOREB(0);
;   if (KT > 1) G_LOADB(1);
;   __syncthreads();
;   DI u32x4 operator()(int r, int k) const {
;     int row = row0 + r;
;     row = row < nrows ? row : nrows - 1;
;     return ldg16(base + (size_t)row * ld + k);
.LBB0_438:
	s_cmp_lg_u32 s6, 1
	s_mov_b64 s[2:3], -1
	s_cbranch_scc0 .LBB0_445
	v_mov_b32_e32 v32, v196
	s_nop 0
	v_ashrrev_i32_e32 v33, 3, v32
	v_add_u32_e32 v12, s18, v33
	v_add_u32_e32 v28, s17, v33
	v_lshlrev_b32_e32 v0, 4, v32
	v_add_u32_e32 v10, 0x80, v12
	v_add_u32_e32 v26, 0x80, v28
	v_and_b32_e32 v128, 0x70, v0
	v_min_i32_e32 v0, 0x7fff, v12
	v_min_i32_e32 v10, 0x7fff, v10
	v_min_i32_e32 v16, 0x3ff, v28
	v_min_i32_e32 v26, 0x3ff, v26
	v_ashrrev_i32_e32 v1, 31, v0
	v_ashrrev_i32_e32 v11, 31, v10
	v_ashrrev_i32_e32 v17, 31, v16
	v_ashrrev_i32_e32 v27, 31, v26
	v_lshl_add_u64 v[8:9], s[38:39], 0, v[128:129]
	v_lshlrev_b64 v[0:1], 11, v[0:1]
	v_lshlrev_b64 v[10:11], 11, v[10:11]
	v_lshl_add_u64 v[24:25], s[0:1], 0, v[128:129]
	v_lshlrev_b64 v[16:17], 11, v[16:17]
	v_lshlrev_b64 v[26:27], 11, v[26:27]
	v_lshl_add_u64 v[134:135], v[8:9], 0, v[0:1]
	v_add_u32_e32 v0, 64, v12
	v_lshl_add_u64 v[138:139], v[8:9], 0, v[10:11]
	v_add_u32_e32 v10, 0xc0, v12
	v_lshl_add_u64 v[142:143], v[24:25], 0, v[16:17]
	v_add_u32_e32 v16, 64, v28
	v_lshl_add_u64 v[146:147], v[24:25], 0, v[26:27]
	v_add_u32_e32 v26, 0xc0, v28
	v_min_i32_e32 v0, 0x7fff, v0
	v_min_i32_e32 v10, 0x7fff, v10
	v_min_i32_e32 v16, 0x3ff, v16
	v_min_i32_e32 v26, 0x3ff, v26
	v_ashrrev_i32_e32 v1, 31, v0
	v_ashrrev_i32_e32 v11, 31, v10
	v_ashrrev_i32_e32 v17, 31, v16
	v_ashrrev_i32_e32 v27, 31, v26
	v_lshlrev_b64 v[0:1], 11, v[0:1]
	v_lshlrev_b64 v[10:11], 11, v[10:11]
	v_lshlrev_b64 v[16:17], 11, v[16:17]
	v_lshlrev_b64 v[26:27], 11, v[26:27]
	v_lshl_add_u64 v[136:137], v[8:9], 0, v[0:1]
	v_lshl_add_u64 v[140:141], v[8:9], 0, v[10:11]
	v_lshl_add_u64 v[144:145], v[24:25], 0, v[16:17]
	v_lshl_add_u64 v[148:149], v[24:25], 0, v[26:27]
	v_mad_u64_u32 v[132:133], s[2:3], v33, s11, v[128:129]
	v_add_u32_e32 v153, 0x12000, v132
	v_bfe_u32 v128, v32, 6, 2
	v_add_u32_e32 v152, 0x1b000, v132
	v_and_b32_e32 v1, 31, v32
	v_ashrrev_i32_e32 v0, 1, v32
	v_and_or_b32 v133, v0, s12, v1
	v_lshrrev_b32_e32 v0, 2, v32
	v_and_b32_e32 v150, 8, v0
	v_lshlrev_b32_e32 v0, 1, v150
	v_mad_u64_u32 v[130:131], s[2:3], v133, s11, v[0:1]
	v_lshl_or_b32 v1, v128, 6, v1
	v_mul_u32_u24_e32 v1, 0x48, v1
	v_lshl_add_u32 v0, v1, 1, v0
	v_add_u32_e32 v151, 0x12000, v0
	v_add_u32_e32 v131, 0x1b000, v0
	s_nop 0
	s_nop 0
	s_nop 0
	s_nop 0
	s_nop 0
	s_nop 0
	v_lshrrev_b32_e32 v222, 6, v196
	s_mov_b32 s4, 64
	v_readfirstlane_b32 s19, v222
	s_mov_b32 s5, 0
	s_mov_b32 s6, 0x40000
	s_mov_b32 s7, 0
	v_bfe_u32 v220, v196, 2, 4
	s_lshl_b32 s23, s19, 3
	v_add_u32_e32 v220, s23, v220
	s_mov_b32 s23, 0x800
	v_mul_lo_u32 v220, v220, s23
	v_bfe_u32 v222, v196, 4, 2
	v_and_b32_e32 v221, 3, v196
	v_xor_b32_e32 v222, v221, v222
	v_lshl_add_u32 v220, v222, 4, v220
	v_mov_b32_e32 v221, 0
	v_readlane_b32 s20, v134, 0
	v_readlane_b32 s21, v135, 0
	s_nop 1
	v_lshl_add_u64 v[212:213], s[20:21], 0, v[220:221]
	v_lshl_add_u64 v[214:215], v[212:213], 0, s[6:7]
	v_readlane_b32 s20, v142, 0
	v_readlane_b32 s21, v143, 0
	s_nop 1
	v_lshl_add_u64 v[216:217], s[20:21], 0, v[220:221]
	v_lshl_add_u64 v[218:219], v[216:217], 0, s[6:7]
	v_and_b32_e32 v220, 31, v196
	v_bfe_u32 v222, v196, 2, 2
	v_bfe_u32 v221, v196, 5, 1
	v_xor_b32_e32 v222, v221, v222
	v_lshlrev_b32_e32 v222, 4, v222
	v_lshl_or_b32 v220, v220, 6, v222
	s_lshr_b32 s23, s19, 2
	s_lshl_b32 s23, s23, 13
	v_add_u32_e32 v132, s23, v220
	s_and_b32 s23, s19, 3
	s_lshl_b32 s23, s23, 12
	s_add_u32 s23, s23, 0x4000
	v_add_u32_e32 v198, s23, v220
	v_xor_b32_e32 v151, 0x20, v132
	v_xor_b32_e32 v199, 0x20, v198
	v_add_u32_e32 v204, 0x10000, v132
	v_add_u32_e32 v206, 0x10000, v198
	v_add_u32_e32 v208, 0x20000, v132
	v_add_u32_e32 v210, 0x20000, v198
	v_add_u32_e32 v205, 0x10000, v151
	v_add_u32_e32 v207, 0x10000, v199
	v_add_u32_e32 v209, 0x20000, v151
	v_add_u32_e32 v211, 0x20000, v199
	s_lshl_b32 s19, s19, 10
	s_waitcnt lgkmcnt(0)
	s_barrier
	s_add_u32 m0, s19, 0x0
	s_nop 0
	global_load_lds_dwordx4 v[212:213], off
	v_lshl_add_u64 v[212:213], v[212:213], 0, s[4:5]
	s_add_u32 m0, s19, 0x4000
	s_nop 0
	global_load_lds_dwordx4 v[216:217], off
	v_lshl_add_u64 v[216:217], v[216:217], 0, s[4:5]
	s_add_u32 m0, s19, 0x2000
	s_nop 0
	global_load_lds_dwordx4 v[214:215], off
	v_lshl_add_u64 v[214:215], v[214:215], 0, s[4:5]
	s_add_u32 m0, s19, 0x6000
	s_nop 0
	global_load_lds_dwordx4 v[218:219], off
	v_lshl_add_u64 v[218:219], v[218:219], 0, s[4:5]
	s_add_u32 m0, s19, 0x8000
	s_nop 0
	global_load_lds_dwordx4 v[212:213], off
	v_lshl_add_u64 v[212:213], v[212:213], 0, s[4:5]
	s_add_u32 m0, s19, 0xc000
	s_nop 0
	global_load_lds_dwordx4 v[216:217], off
	v_lshl_add_u64 v[216:217], v[216:217], 0, s[4:5]
	s_add_u32 m0, s19, 0xa000
	s_nop 0
	global_load_lds_dwordx4 v[214:215], off
	v_lshl_add_u64 v[214:215], v[214:215], 0, s[4:5]
	s_add_u32 m0, s19, 0xe000
	s_nop 0
	global_load_lds_dwordx4 v[218:219], off
	v_lshl_add_u64 v[218:219], v[218:219], 0, s[4:5]
	s_add_u32 m0, s19, 0x10000
	s_nop 0
	global_load_lds_dwordx4 v[212:213], off
	v_lshl_add_u64 v[212:213], v[212:213], 0, s[4:5]
	s_add_u32 m0, s19, 0x14000
	s_nop 0
	global_load_lds_dwordx4 v[216:217], off
	v_lshl_add_u64 v[216:217], v[216:217], 0, s[4:5]
	s_add_u32 m0, s19, 0x12000
	s_nop 0
	global_load_lds_dwordx4 v[214:215], off
	v_lshl_add_u64 v[214:215], v[214:215], 0, s[4:5]
	s_add_u32 m0, s19, 0x16000
	s_nop 0
	global_load_lds_dwordx4 v[218:219], off
	v_lshl_add_u64 v[218:219], v[218:219], 0, s[4:5]
	s_add_u32 m0, s19, 0x18000
	s_nop 0
	global_load_lds_dwordx4 v[212:213], off
	v_lshl_add_u64 v[212:213], v[212:213], 0, s[4:5]
	s_add_u32 m0, s19, 0x1c000
	s_nop 0
	global_load_lds_dwordx4 v[216:217], off
	v_lshl_add_u64 v[216:217], v[216:217], 0, s[4:5]
; #define G_LOADA(kt_) { _Pragma("unroll") for (int i = 0; i < 4; ++i) ra[i] = al(lrow + 64 * i, (kt_) * 64 + lck * 8); }
; #define G_LOADB(kt_) { _Pragma("unroll") for (int i = 0; i < 4; ++i) rb[i] = bl(lrow + 64 * i, (kt_) * 64 + lck * 8); }
; #define G_STOREA(buf_) { bf16_t* nA = sA + (buf_) * 256 * GLD; _Pragma("unroll") for (int i = 0; i < 4; ++i) *(u32x4*)(nA + (lrow + 64 * i) * GLD + lck * 8) = ra[i]; }
; #define G_STOREB(buf_) { bf16_t* nB = sB + (buf_) * 256 * GLD; _Pragma("unroll") for (int i = 0; i < 4; ++i) *(u32x4*)(nB + (lrow + 64 * i) * GLD + lck * 8) = rb[i]; }
; template <class AL, class BL, class EP>
; DI void gemm_tile256(AL al, BL bl, EP ep, int K, char* smem) {
;     ...
; #pragma unroll
;   for (int i = 0; i < 4; ++i)
; #pragma unroll
;     for (int j = 0; j < 2; ++j)
; #pragma unroll
;       for (int q = 0; q < 16; ++q) acc[i][j][q] = 0.f;
;     ...
;   G_LOADA(0); G_LOADB(0);
;   __syncthreads();
;   G_STOREA(0); G_STOREB(0);
;   if (KT > 1) G_LOADB(1);
;   __syncthreads();
;   for (int kt = 0; kt < KT; kt += 2) {
;     G_STEP(0, kt);
;     if (kt + 1 >= KT) break;
;     G_STEP(1, kt + 1);
;   }
	s_add_u32 m0, s19, 0x1a000
	s_nop 0
	global_load_lds_dwordx4 v[214:215], off
	v_lshl_add_u64 v[214:215], v[214:215], 0, s[4:5]
	s_add_u32 m0, s19, 0x1e000
	s_nop 0
	global_load_lds_dwordx4 v[218:219], off
	v_lshl_add_u64 v[218:219], v[218:219], 0, s[4:5]
	s_add_u32 m0, s19, 0x20000
	s_nop 0
	global_load_lds_dwordx4 v[212:213], off
	v_lshl_add_u64 v[212:213], v[212:213], 0, s[4:5]
	s_add_u32 m0, s19, 0x24000
	s_nop 0
	global_load_lds_dwordx4 v[216:217], off
	v_lshl_add_u64 v[216:217], v[216:217], 0, s[4:5]
	v_mov_b64_e32 v[112:113], 0
	v_mov_b64_e32 v[114:115], 0
	v_mov_b64_e32 v[116:117], 0
	v_mov_b64_e32 v[118:119], 0
	v_mov_b64_e32 v[120:121], 0
	v_mov_b64_e32 v[122:123], 0
	v_mov_b64_e32 v[124:125], 0
	v_mov_b64_e32 v[126:127], 0
	v_mov_b64_e32 v[96:97], 0
	v_mov_b64_e32 v[98:99], 0
	v_mov_b64_e32 v[100:101], 0
	v_mov_b64_e32 v[102:103], 0
	v_mov_b64_e32 v[104:105], 0
	v_mov_b64_e32 v[106:107], 0
	v_mov_b64_e32 v[108:109], 0
	v_mov_b64_e32 v[110:111], 0
	v_mov_b64_e32 v[80:81], 0
	v_mov_b64_e32 v[82:83], 0
	v_mov_b64_e32 v[84:85], 0
	v_mov_b64_e32 v[86:87], 0
	v_mov_b64_e32 v[88:89], 0
	v_mov_b64_e32 v[90:91], 0
	v_mov_b64_e32 v[92:93], 0
	v_mov_b64_e32 v[94:95], 0
	v_mov_b64_e32 v[64:65], 0
	v_mov_b64_e32 v[66:67], 0
	v_mov_b64_e32 v[68:69], 0
	v_mov_b64_e32 v[70:71], 0
	v_mov_b64_e32 v[72:73], 0
	v_mov_b64_e32 v[74:75], 0
	v_mov_b64_e32 v[76:77], 0
	v_mov_b64_e32 v[78:79], 0
	v_mov_b64_e32 v[48:49], 0
	v_mov_b64_e32 v[50:51], 0
	v_mov_b64_e32 v[52:53], 0
	v_mov_b64_e32 v[54:55], 0
	v_mov_b64_e32 v[56:57], 0
	v_mov_b64_e32 v[58:59], 0
	v_mov_b64_e32 v[60:61], 0
	v_mov_b64_e32 v[62:63], 0
	v_mov_b64_e32 v[32:33], 0
	v_mov_b64_e32 v[34:35], 0
	v_mov_b64_e32 v[36:37], 0
	v_mov_b64_e32 v[38:39], 0
	v_mov_b64_e32 v[40:41], 0
	v_mov_b64_e32 v[42:43], 0
	v_mov_b64_e32 v[44:45], 0
	v_mov_b64_e32 v[46:47], 0
	v_mov_b64_e32 v[16:17], 0
	v_mov_b64_e32 v[18:19], 0
	v_mov_b64_e32 v[20:21], 0
	v_mov_b64_e32 v[22:23], 0
	v_mov_b64_e32 v[24:25], 0
	v_mov_b64_e32 v[26:27], 0
	v_mov_b64_e32 v[28:29], 0
	v_mov_b64_e32 v[30:31], 0
	v_mov_b64_e32 v[0:1], 0
	v_mov_b64_e32 v[2:3], 0
	v_mov_b64_e32 v[4:5], 0
	v_mov_b64_e32 v[6:7], 0
	v_mov_b64_e32 v[8:9], 0
	v_mov_b64_e32 v[10:11], 0
	v_mov_b64_e32 v[12:13], 0
	v_mov_b64_e32 v[14:15], 0
	s_lshr_b32 s23, s19, 2
	s_xor_b32 s23, s23, s19
	s_bitcmp1_b32 s23, 10
	s_cbranch_scc0 .Lgk_ph4_np
	s_setprio 1
.Lgk_ph4_np:
	s_mov_b32 s23, 5
	s_waitcnt vmcnt(14)
	s_barrier
	ds_read_b128 v[184:187], v198
	ds_read_b128 v[152:155], v132
	ds_read_b128 v[188:191], v198 offset:2048
	ds_read_b128 v[156:159], v132 offset:2048
	ds_read_b128 v[160:163], v132 offset:4096
	ds_read_b128 v[164:167], v132 offset:6144
.Lgk_ph4_loop:
	s_waitcnt lgkmcnt(0)
	v_mfma_f32_32x32x16_bf16 v[112:127], v[184:187], v[152:155], v[112:127]
	ds_read_b128 v[192:195], v199
	ds_read_b128 v[168:171], v151
	v_mfma_f32_32x32x16_bf16 v[96:111], v[188:191], v[152:155], v[96:111]
	ds_read_b128 v[200:203], v199 offset:2048
	ds_read_b128 v[172:175], v151 offset:2048
	v_mfma_f32_32x32x16_bf16 v[80:95], v[184:187], v[156:159], v[80:95]
	ds_read_b128 v[176:179], v151 offset:4096
	ds_read_b128 v[180:183], v151 offset:6144
	v_mfma_f32_32x32x16_bf16 v[64:79], v[188:191], v[156:159], v[64:79]
	s_add_u32 m0, s19, 0x22000
	s_nop 0
	global_load_lds_dwordx4 v[214:215], off
	v_lshl_add_u64 v[214:215], v[214:215], 0, s[4:5]
	v_mfma_f32_32x32x16_bf16 v[48:63], v[184:187], v[160:163], v[48:63]
	v_mfma_f32_32x32x16_bf16 v[32:47], v[188:191], v[160:163], v[32:47]
	v_mfma_f32_32x32x16_bf16 v[16:31], v[184:187], v[164:167], v[16:31]
	v_mfma_f32_32x32x16_bf16 v[0:15], v[188:191], v[164:167], v[0:15]
	s_add_u32 m0, s19, 0x26000
	s_nop 0
	global_load_lds_dwordx4 v[218:219], off
	v_lshl_add_u64 v[218:219], v[218:219], 0, s[4:5]
	s_waitcnt lgkmcnt(0)
	s_waitcnt vmcnt(12)
	s_barrier
	s_waitcnt lgkmcnt(0)
	v_mfma_f32_32x32x16_bf16 v[112:127], v[192:195], v[168:171], v[112:127]
	ds_read_b128 v[184:187], v198 offset:32768
	ds_read_b128 v[152:155], v132 offset:32768
	v_mfma_f32_32x32x16_bf16 v[96:111], v[200:203], v[168:171], v[96:111]
	ds_read_b128 v[188:191], v198 offset:34816
	ds_read_b128 v[156:159], v132 offset:34816
	v_mfma_f32_32x32x16_bf16 v[80:95], v[192:195], v[172:175], v[80:95]
	ds_read_b128 v[160:163], v132 offset:36864
	ds_read_b128 v[164:167], v132 offset:38912
	v_mfma_f32_32x32x16_bf16 v[64:79], v[200:203], v[172:175], v[64:79]
	s_add_u32 m0, s19, 0x0
	s_nop 0
	global_load_lds_dwordx4 v[212:213], off
	v_lshl_add_u64 v[212:213], v[212:213], 0, s[4:5]
	v_mfma_f32_32x32x16_bf16 v[48:63], v[192:195], v[176:179], v[48:63]
	v_mfma_f32_32x32x16_bf16 v[32:47], v[200:203], v[176:179], v[32:47]
	v_mfma_f32_32x32x16_bf16 v[16:31], v[192:195], v[180:183], v[16:31]
	v_mfma_f32_32x32x16_bf16 v[0:15], v[200:203], v[180:183], v[0:15]
	s_add_u32 m0, s19, 0x4000
	s_nop 0
	global_load_lds_dwordx4 v[216:217], off
	v_lshl_add_u64 v[216:217], v[216:217], 0, s[4:5]
	s_waitcnt lgkmcnt(0)
	v_mfma_f32_32x32x16_bf16 v[112:127], v[184:187], v[152:155], v[112:127]
	ds_read_b128 v[192:195], v199 offset:32768
	ds_read_b128 v[168:171], v151 offset:32768
	v_mfma_f32_32x32x16_bf16 v[96:111], v[188:191], v[152:155], v[96:111]
	ds_read_b128 v[200:203], v199 offset:34816
	ds_read_b128 v[172:175], v151 offset:34816
	v_mfma_f32_32x32x16_bf16 v[80:95], v[184:187], v[156:159], v[80:95]
	ds_read_b128 v[176:179], v151 offset:36864
	ds_read_b128 v[180:183], v151 offset:38912
	v_mfma_f32_32x32x16_bf16 v[64:79], v[188:191], v[156:159], v[64:79]
	s_add_u32 m0, s19, 0x2000
	s_nop 0
	global_load_lds_dwordx4 v[214:215], off
	v_lshl_add_u64 v[214:215], v[214:215], 0, s[4:5]
	v_mfma_f32_32x32x16_bf16 v[48:63], v[184:187], v[160:163], v[48:63]
	v_mfma_f32_32x32x16_bf16 v[32:47], v[188:191], v[160:163], v[32:47]
	v_mfma_f32_32x32x16_bf16 v[16:31], v[184:187], v[164:167], v[16:31]
	v_mfma_f32_32x32x16_bf16 v[0:15], v[188:191], v[164:167], v[0:15]
	s_add_u32 m0, s19, 0x6000
	s_nop 0
	global_load_lds_dwordx4 v[218:219], off
	v_lshl_add_u64 v[218:219], v[218:219], 0, s[4:5]
	s_waitcnt lgkmcnt(0)
	s_waitcnt vmcnt(12)
	s_barrier
; #define G_LOADA(kt_) { _Pragma("unroll") for (int i = 0; i < 4; ++i) ra[i] = al(lrow + 64 * i, (kt_) * 64 + lck * 8); }
; #define G_LOADB(kt_) { _Pragma("unroll") for (int i = 0; i < 4; ++i) rb[i] = bl(lrow + 64 * i, (kt_) * 64 + lck * 8); }
; #define G_STOREA(buf_) { bf16_t* nA = sA + (buf_) * 256 * GLD; _Pragma("unroll") for (int i = 0; i < 4; ++i) *(u32x4*)(nA + (lrow + 64 * i) * GLD + lck * 8) = ra[i]; }
; #define G_STOREB(buf_) { bf16_t* nB = sB + (buf_) * 256 * GLD; _Pragma("unroll") for (int i = 0; i < 4; ++i) *(u32x4*)(nB + (lrow + 64 * i) * GLD + lck * 8) = rb[i]; }
; template <class AL, class BL, class EP>
; DI void gemm_tile256(AL al, BL bl, EP ep, int K, char* smem) {
;     ...
;   G_LOADA(0); G_LOADB(0);
;   __syncthreads();
;   G_STOREA(0); G_STOREB(0);
;   if (KT > 1) G_LOADB(1);
;   __syncthreads();
;   for (int kt = 0; kt < KT; kt += 2) {
;     G_STEP(0, kt);
;     if (kt + 1 >= KT) break;
;     G_STEP(1, kt + 1);
;   }
	s_waitcnt lgkmcnt(0)
	v_mfma_f32_32x32x16_bf16 v[112:127], v[192:195], v[168:171], v[112:127]
	ds_read_b128 v[184:187], v206
	ds_read_b128 v[152:155], v204
	v_mfma_f32_32x32x16_bf16 v[96:111], v[200:203], v[168:171], v[96:111]
	ds_read_b128 v[188:191], v206 offset:2048
	ds_read_b128 v[156:159], v204 offset:2048
	v_mfma_f32_32x32x16_bf16 v[80:95], v[192:195], v[172:175], v[80:95]
	ds_read_b128 v[160:163], v204 offset:4096
	ds_read_b128 v[164:167], v204 offset:6144
	v_mfma_f32_32x32x16_bf16 v[64:79], v[200:203], v[172:175], v[64:79]
	s_add_u32 m0, s19, 0x8000
	s_nop 0
	global_load_lds_dwordx4 v[212:213], off
	v_lshl_add_u64 v[212:213], v[212:213], 0, s[4:5]
	v_mfma_f32_32x32x16_bf16 v[48:63], v[192:195], v[176:179], v[48:63]
	v_mfma_f32_32x32x16_bf16 v[32:47], v[200:203], v[176:179], v[32:47]
	v_mfma_f32_32x32x16_bf16 v[16:31], v[192:195], v[180:183], v[16:31]
	v_mfma_f32_32x32x16_bf16 v[0:15], v[200:203], v[180:183], v[0:15]
	s_add_u32 m0, s19, 0xc000
	s_nop 0
	global_load_lds_dwordx4 v[216:217], off
	v_lshl_add_u64 v[216:217], v[216:217], 0, s[4:5]
	s_waitcnt lgkmcnt(0)
	v_mfma_f32_32x32x16_bf16 v[112:127], v[184:187], v[152:155], v[112:127]
	ds_read_b128 v[192:195], v207
	ds_read_b128 v[168:171], v205
	v_mfma_f32_32x32x16_bf16 v[96:111], v[188:191], v[152:155], v[96:111]
	ds_read_b128 v[200:203], v207 offset:2048
	ds_read_b128 v[172:175], v205 offset:2048
	v_mfma_f32_32x32x16_bf16 v[80:95], v[184:187], v[156:159], v[80:95]
	ds_read_b128 v[176:179], v205 offset:4096
	ds_read_b128 v[180:183], v205 offset:6144
	v_mfma_f32_32x32x16_bf16 v[64:79], v[188:191], v[156:159], v[64:79]
	s_add_u32 m0, s19, 0xa000
	s_nop 0
	global_load_lds_dwordx4 v[214:215], off
	v_lshl_add_u64 v[214:215], v[214:215], 0, s[4:5]
	v_mfma_f32_32x32x16_bf16 v[48:63], v[184:187], v[160:163], v[48:63]
	v_mfma_f32_32x32x16_bf16 v[32:47], v[188:191], v[160:163], v[32:47]
	v_mfma_f32_32x32x16_bf16 v[16:31], v[184:187], v[164:167], v[16:31]
	v_mfma_f32_32x32x16_bf16 v[0:15], v[188:191], v[164:167], v[0:15]
	s_add_u32 m0, s19, 0xe000
	s_nop 0
	global_load_lds_dwordx4 v[218:219], off
	v_lshl_add_u64 v[218:219], v[218:219], 0, s[4:5]
	s_waitcnt lgkmcnt(0)
	s_waitcnt vmcnt(12)
	s_barrier
	s_waitcnt lgkmcnt(0)
	v_mfma_f32_32x32x16_bf16 v[112:127], v[192:195], v[168:171], v[112:127]
	ds_read_b128 v[184:187], v206 offset:32768
	ds_read_b128 v[152:155], v204 offset:32768
	v_mfma_f32_32x32x16_bf16 v[96:111], v[200:203], v[168:171], v[96:111]
	ds_read_b128 v[188:191], v206 offset:34816
	ds_read_b128 v[156:159], v204 offset:34816
	v_mfma_f32_32x32x16_bf16 v[80:95], v[192:195], v[172:175], v[80:95]
	ds_read_b128 v[160:163], v204 offset:36864
	ds_read_b128 v[164:167], v204 offset:38912
	v_mfma_f32_32x32x16_bf16 v[64:79], v[200:203], v[172:175], v[64:79]
	s_add_u32 m0, s19, 0x10000
	s_nop 0
	global_load_lds_dwordx4 v[212:213], off
	v_lshl_add_u64 v[212:213], v[212:213], 0, s[4:5]
	v_mfma_f32_32x32x16_bf16 v[48:63], v[192:195], v[176:179], v[48:63]
	v_mfma_f32_32x32x16_bf16 v[32:47], v[200:203], v[176:179], v[32:47]
	v_mfma_f32_32x32x16_bf16 v[16:31], v[192:195], v[180:183], v[16:31]
	v_mfma_f32_32x32x16_bf16 v[0:15], v[200:203], v[180:183], v[0:15]
	s_add_u32 m0, s19, 0x14000
	s_nop 0
	global_load_lds_dwordx4 v[216:217], off
	v_lshl_add_u64 v[216:217], v[216:217], 0, s[4:5]
	s_waitcnt lgkmcnt(0)
	v_mfma_f32_32x32x16_bf16 v[112:127], v[184:187], v[152:155], v[112:127]
	ds_read_b128 v[192:195], v207 offset:32768
	ds_read_b128 v[168:171], v205 offset:32768
	v_mfma_f32_32x32x16_bf16 v[96:111], v[188:191], v[152:155], v[96:111]
	ds_read_b128 v[200:203], v207 offset:34816
	ds_read_b128 v[172:175], v205 offset:34816
	v_mfma_f32_32x32x16_bf16 v[80:95], v[184:187], v[156:159], v[80:95]
	ds_read_b128 v[176:179], v205 offset:36864
	ds_read_b128 v[180:183], v205 offset:38912
	v_mfma_f32_32x32x16_bf16 v[64:79], v[188:191], v[156:159], v[64:79]
	s_add_u32 m0, s19, 0x12000
	s_nop 0
	global_load_lds_dwordx4 v[214:215], off
	v_lshl_add_u64 v[214:215], v[214:215], 0, s[4:5]
	v_mfma_f32_32x32x16_bf16 v[48:63], v[184:187], v[160:163], v[48:63]
	v_mfma_f32_32x32x16_bf16 v[32:47], v[188:191], v[160:163], v[32:47]
	v_mfma_f32_32x32x16_bf16 v[16:31], v[184:187], v[164:167], v[16:31]
	v_mfma_f32_32x32x16_bf16 v[0:15], v[188:191], v[164:167], v[0:15]
	s_add_u32 m0, s19, 0x16000
	s_nop 0
	global_load_lds_dwordx4 v[218:219], off
	v_lshl_add_u64 v[218:219], v[218:219], 0, s[4:5]
	s_waitcnt lgkmcnt(0)
	s_waitcnt vmcnt(12)
	s_barrier
	s_waitcnt lgkmcnt(0)
	v_mfma_f32_32x32x16_bf16 v[112:127], v[192:195], v[168:171], v[112:127]
	ds_read_b128 v[184:187], v210
	ds_read_b128 v[152:155], v208
	v_mfma_f32_32x32x16_bf16 v[96:111], v[200:203], v[168:171], v[96:111]
	ds_read_b128 v[188:191], v210 offset:2048
	ds_read_b128 v[156:159], v208 offset:2048
	v_mfma_f32_32x32x16_bf16 v[80:95], v[192:195], v[172:175], v[80:95]
	ds_read_b128 v[160:163], v208 offset:4096
	ds_read_b128 v[164:167], v208 offset:6144
	v_mfma_f32_32x32x16_bf16 v[64:79], v[200:203], v[172:175], v[64:79]
	s_add_u32 m0, s19, 0x18000
	s_nop 0
	global_load_lds_dwordx4 v[212:213], off
	v_lshl_add_u64 v[212:213], v[212:213], 0, s[4:5]
	v_mfma_f32_32x32x16_bf16 v[48:63], v[192:195], v[176:179], v[48:63]
	v_mfma_f32_32x32x16_bf16 v[32:47], v[200:203], v[176:179], v[32:47]
	v_mfma_f32_32x32x16_bf16 v[16:31], v[192:195], v[180:183], v[16:31]
	v_mfma_f32_32x32x16_bf16 v[0:15], v[200:203], v[180:183], v[0:15]
	s_add_u32 m0, s19, 0x1c000
	s_nop 0
	global_load_lds_dwordx4 v[216:217], off
	v_lshl_add_u64 v[216:217], v[216:217], 0, s[4:5]
	s_waitcnt lgkmcnt(0)
	v_mfma_f32_32x32x16_bf16 v[112:127], v[184:187], v[152:155], v[112:127]
	ds_read_b128 v[192:195], v211
	ds_read_b128 v[168:171], v209
	v_mfma_f32_32x32x16_bf16 v[96:111], v[188:191], v[152:155], v[96:111]
	ds_read_b128 v[200:203], v211 offset:2048
	ds_read_b128 v[172:175], v209 offset:2048
	v_mfma_f32_32x32x16_bf16 v[80:95], v[184:187], v[156:159], v[80:95]
	ds_read_b128 v[176:179], v209 offset:4096
	ds_read_b128 v[180:183], v209 offset:6144
	v_mfma_f32_32x32x16_bf16 v[64:79], v[188:191], v[156:159], v[64:79]
	s_add_u32 m0, s19, 0x1a000
	s_nop 0
	global_load_lds_dwordx4 v[214:215], off
	v_lshl_add_u64 v[214:215], v[214:215], 0, s[4:5]
	v_mfma_f32_32x32x16_bf16 v[48:63], v[184:187], v[160:163], v[48:63]
	v_mfma_f32_32x32x16_bf16 v[32:47], v[188:191], v[160:163], v[32:47]
	v_mfma_f32_32x32x16_bf16 v[16:31], v[184:187], v[164:167], v[16:31]
	v_mfma_f32_32x32x16_bf16 v[0:15], v[188:191], v[164:167], v[0:15]
	s_add_u32 m0, s19, 0x1e000
	s_nop 0
	global_load_lds_dwordx4 v[218:219], off
	v_lshl_add_u64 v[218:219], v[218:219], 0, s[4:5]
	s_waitcnt lgkmcnt(0)
	s_waitcnt vmcnt(12)
	s_barrier
; #define G_LOADA(kt_) { _Pragma("unroll") for (int i = 0; i < 4; ++i) ra[i] = al(lrow + 64 * i, (kt_) * 64 + lck * 8); }
; #define G_LOADB(kt_) { _Pragma("unroll") for (int i = 0; i < 4; ++i) rb[i] = bl(lrow + 64 * i, (kt_) * 64 + lck * 8); }
; #define G_STOREA(buf_) { bf16_t* nA = sA + (buf_) * 256 * GLD; _Pragma("unroll") for (int i = 0; i < 4; ++i) *(u32x4*)(nA + (lrow + 64 * i) * GLD + lck * 8) = ra[i]; }
; #define G_STOREB(buf_) { bf16_t* nB = sB + (buf_) * 256 * GLD; _Pragma("unroll") for (int i = 0; i < 4; ++i) *(u32x4*)(nB + (lrow + 64 * i) * GLD + lck * 8) = rb[i]; }
; template <class AL, class BL, class EP>
; DI void gemm_tile256(AL al, BL bl, EP ep, int K, char* smem) {
;     ...
;   G_LOADA(0); G_LOADB(0);
;   __syncthreads();
;   G_STOREA(0); G_STOREB(0);
;   if (KT > 1) G_LOADB(1);
;   __syncthreads();
;   for (int kt = 0; kt < KT; kt += 2) {
;     G_STEP(0, kt);
;     if (kt + 1 >= KT) break;
;     G_STEP(1, kt + 1);
;   }
	s_waitcnt lgkmcnt(0)
	v_mfma_f32_32x32x16_bf16 v[112:127], v[192:195], v[168:171], v[112:127]
	ds_read_b128 v[184:187], v198
	ds_read_b128 v[152:155], v132
	v_mfma_f32_32x32x16_bf16 v[96:111], v[200:203], v[168:171], v[96:111]
	ds_read_b128 v[188:191], v198 offset:2048
	ds_read_b128 v[156:159], v132 offset:2048
	v_mfma_f32_32x32x16_bf16 v[80:95], v[192:195], v[172:175], v[80:95]
	ds_read_b128 v[160:163], v132 offset:4096
	ds_read_b128 v[164:167], v132 offset:6144
	v_mfma_f32_32x32x16_bf16 v[64:79], v[200:203], v[172:175], v[64:79]
	s_add_u32 m0, s19, 0x20000
	s_nop 0
	global_load_lds_dwordx4 v[212:213], off
	v_lshl_add_u64 v[212:213], v[212:213], 0, s[4:5]
	v_mfma_f32_32x32x16_bf16 v[48:63], v[192:195], v[176:179], v[48:63]
	v_mfma_f32_32x32x16_bf16 v[32:47], v[200:203], v[176:179], v[32:47]
	v_mfma_f32_32x32x16_bf16 v[16:31], v[192:195], v[180:183], v[16:31]
	v_mfma_f32_32x32x16_bf16 v[0:15], v[200:203], v[180:183], v[0:15]
	s_add_u32 m0, s19, 0x24000
	s_nop 0
	global_load_lds_dwordx4 v[216:217], off
	v_lshl_add_u64 v[216:217], v[216:217], 0, s[4:5]
	s_sub_u32 s23, s23, 1
	s_cmp_lg_u32 s23, 0
	s_cbranch_scc1 .Lgk_ph4_loop
	s_waitcnt lgkmcnt(0)
	v_mfma_f32_32x32x16_bf16 v[112:127], v[184:187], v[152:155], v[112:127]
	ds_read_b128 v[192:195], v199
	ds_read_b128 v[168:171], v151
	v_mfma_f32_32x32x16_bf16 v[96:111], v[188:191], v[152:155], v[96:111]
	ds_read_b128 v[200:203], v199 offset:2048
	ds_read_b128 v[172:175], v151 offset:2048
	v_mfma_f32_32x32x16_bf16 v[80:95], v[184:187], v[156:159], v[80:95]
	ds_read_b128 v[176:179], v151 offset:4096
	ds_read_b128 v[180:183], v151 offset:6144
	v_mfma_f32_32x32x16_bf16 v[64:79], v[188:191], v[156:159], v[64:79]
	s_add_u32 m0, s19, 0x22000
	s_nop 0
	global_load_lds_dwordx4 v[214:215], off
	v_lshl_add_u64 v[214:215], v[214:215], 0, s[4:5]
	v_mfma_f32_32x32x16_bf16 v[48:63], v[184:187], v[160:163], v[48:63]
	v_mfma_f32_32x32x16_bf16 v[32:47], v[188:191], v[160:163], v[32:47]
	v_mfma_f32_32x32x16_bf16 v[16:31], v[184:187], v[164:167], v[16:31]
	v_mfma_f32_32x32x16_bf16 v[0:15], v[188:191], v[164:167], v[0:15]
	s_add_u32 m0, s19, 0x26000
	s_nop 0
	global_load_lds_dwordx4 v[218:219], off
	v_lshl_add_u64 v[218:219], v[218:219], 0, s[4:5]
	s_waitcnt lgkmcnt(0)
	s_waitcnt vmcnt(12)
	s_barrier
	s_waitcnt lgkmcnt(0)
	v_mfma_f32_32x32x16_bf16 v[112:127], v[192:195], v[168:171], v[112:127]
	ds_read_b128 v[184:187], v198 offset:32768
	ds_read_b128 v[152:155], v132 offset:32768
	v_mfma_f32_32x32x16_bf16 v[96:111], v[200:203], v[168:171], v[96:111]
	ds_read_b128 v[188:191], v198 offset:34816
	ds_read_b128 v[156:159], v132 offset:34816
	v_mfma_f32_32x32x16_bf16 v[80:95], v[192:195], v[172:175], v[80:95]
	ds_read_b128 v[160:163], v132 offset:36864
	ds_read_b128 v[164:167], v132 offset:38912
	v_mfma_f32_32x32x16_bf16 v[64:79], v[200:203], v[172:175], v[64:79]
	s_add_u32 m0, s19, 0x0
	s_nop 0
	global_load_lds_dwordx4 v[212:213], off
	v_lshl_add_u64 v[212:213], v[212:213], 0, s[4:5]
	v_mfma_f32_32x32x16_bf16 v[48:63], v[192:195], v[176:179], v[48:63]
	v_mfma_f32_32x32x16_bf16 v[32:47], v[200:203], v[176:179], v[32:47]
	v_mfma_f32_32x32x16_bf16 v[16:31], v[192:195], v[180:183], v[16:31]
	v_mfma_f32_32x32x16_bf16 v[0:15], v[200:203], v[180:183], v[0:15]
	s_add_u32 m0, s19, 0x4000
	s_nop 0
	global_load_lds_dwordx4 v[216:217], off
	v_lshl_add_u64 v[216:217], v[216:217], 0, s[4:5]
	s_waitcnt lgkmcnt(0)
	v_mfma_f32_32x32x16_bf16 v[112:127], v[184:187], v[152:155], v[112:127]
	ds_read_b128 v[192:195], v199 offset:32768
	ds_read_b128 v[168:171], v151 offset:32768
	v_mfma_f32_32x32x16_bf16 v[96:111], v[188:191], v[152:155], v[96:111]
	ds_read_b128 v[200:203], v199 offset:34816
	ds_read_b128 v[172:175], v151 offset:34816
	v_mfma_f32_32x32x16_bf16 v[80:95], v[184:187], v[156:159], v[80:95]
	ds_read_b128 v[176:179], v151 offset:36864
	ds_read_b128 v[180:183], v151 offset:38912
	v_mfma_f32_32x32x16_bf16 v[64:79], v[188:191], v[156:159], v[64:79]
	s_add_u32 m0, s19, 0x2000
	s_nop 0
	global_load_lds_dwordx4 v[214:215], off
	v_lshl_add_u64 v[214:215], v[214:215], 0, s[4:5]
	v_mfma_f32_32x32x16_bf16 v[48:63], v[184:187], v[160:163], v[48:63]
	v_mfma_f32_32x32x16_bf16 v[32:47], v[188:191], v[160:163], v[32:47]
	v_mfma_f32_32x32x16_bf16 v[16:31], v[184:187], v[164:167], v[16:31]
	v_mfma_f32_32x32x16_bf16 v[0:15], v[188:191], v[164:167], v[0:15]
	s_add_u32 m0, s19, 0x6000
	s_nop 0
	global_load_lds_dwordx4 v[218:219], off
	v_lshl_add_u64 v[218:219], v[218:219], 0, s[4:5]
	s_waitcnt lgkmcnt(0)
	s_waitcnt vmcnt(12)
	s_barrier
	s_waitcnt lgkmcnt(0)
	v_mfma_f32_32x32x16_bf16 v[112:127], v[192:195], v[168:171], v[112:127]
	ds_read_b128 v[184:187], v206
	ds_read_b128 v[152:155], v204
	v_mfma_f32_32x32x16_bf16 v[96:111], v[200:203], v[168:171], v[96:111]
	ds_read_b128 v[188:191], v206 offset:2048
	ds_read_b128 v[156:159], v204 offset:2048
	v_mfma_f32_32x32x16_bf16 v[80:95], v[192:195], v[172:175], v[80:95]
	ds_read_b128 v[160:163], v204 offset:4096
	ds_read_b128 v[164:167], v204 offset:6144
	v_mfma_f32_32x32x16_bf16 v[64:79], v[200:203], v[172:175], v[64:79]
	s_add_u32 m0, s19, 0x8000
	s_nop 0
	global_load_lds_dwordx4 v[212:213], off
	v_lshl_add_u64 v[212:213], v[212:213], 0, s[4:5]
	v_mfma_f32_32x32x16_bf16 v[48:63], v[192:195], v[176:179], v[48:63]
	v_mfma_f32_32x32x16_bf16 v[32:47], v[200:203], v[176:179], v[32:47]
	v_mfma_f32_32x32x16_bf16 v[16:31], v[192:195], v[180:183], v[16:31]
	v_mfma_f32_32x32x16_bf16 v[0:15], v[200:203], v[180:183], v[0:15]
	s_add_u32 m0, s19, 0xc000
	s_nop 0
	global_load_lds_dwordx4 v[216:217], off
	v_lshl_add_u64 v[216:217], v[216:217], 0, s[4:5]
	s_waitcnt lgkmcnt(0)
	v_mfma_f32_32x32x16_bf16 v[112:127], v[184:187], v[152:155], v[112:127]
	ds_read_b128 v[192:195], v207
	ds_read_b128 v[168:171], v205
	v_mfma_f32_32x32x16_bf16 v[96:111], v[188:191], v[152:155], v[96:111]
	ds_read_b128 v[200:203], v207 offset:2048
	ds_read_b128 v[172:175], v205 offset:2048
	v_mfma_f32_32x32x16_bf16 v[80:95], v[184:187], v[156:159], v[80:95]
	ds_read_b128 v[176:179], v205 offset:4096
	ds_read_b128 v[180:183], v205 offset:6144
	v_mfma_f32_32x32x16_bf16 v[64:79], v[188:191], v[156:159], v[64:79]
	s_add_u32 m0, s19, 0xa000
	s_nop 0
	global_load_lds_dwordx4 v[214:215], off
	v_lshl_add_u64 v[214:215], v[214:215], 0, s[4:5]
	v_mfma_f32_32x32x16_bf16 v[48:63], v[184:187], v[160:163], v[48:63]
	v_mfma_f32_32x32x16_bf16 v[32:47], v[188:191], v[160:163], v[32:47]
	v_mfma_f32_32x32x16_bf16 v[16:31], v[184:187], v[164:167], v[16:31]
	v_mfma_f32_32x32x16_bf16 v[0:15], v[188:191], v[164:167], v[0:15]
	s_add_u32 m0, s19, 0xe000
	s_nop 0
	global_load_lds_dwordx4 v[218:219], off
	v_lshl_add_u64 v[218:219], v[218:219], 0, s[4:5]
	s_waitcnt lgkmcnt(0)
	s_waitcnt vmcnt(12)
	s_barrier
; #define G_LOADA(kt_) { _Pragma("unroll") for (int i = 0; i < 4; ++i) ra[i] = al(lrow + 64 * i, (kt_) * 64 + lck * 8); }
; #define G_LOADB(kt_) { _Pragma("unroll") for (int i = 0; i < 4; ++i) rb[i] = bl(lrow + 64 * i, (kt_) * 64 + lck * 8); }
; #define G_STOREA(buf_) { bf16_t* nA = sA + (buf_) * 256 * GLD; _Pragma("unroll") for (int i = 0; i < 4; ++i) *(u32x4*)(nA + (lrow + 64 * i) * GLD + lck * 8) = ra[i]; }
; #define G_STOREB(buf_) { bf16_t* nB = sB + (buf_) * 256 * GLD; _Pragma("unroll") for (int i = 0; i < 4; ++i) *(u32x4*)(nB + (lrow + 64 * i) * GLD + lck * 8) = rb[i]; }
; template <class AL, class BL, class EP>
; DI void gemm_tile256(AL al, BL bl, EP ep, int K, char* smem) {
;     ...
;   G_LOADA(0); G_LOADB(0);
;   __syncthreads();
;   G_STOREA(0); G_STOREB(0);
;   if (KT > 1) G_LOADB(1);
;   __syncthreads();
;   for (int kt = 0; kt < KT; kt += 2) {
;     G_STEP(0, kt);
;     if (kt + 1 >= KT) break;
;     G_STEP(1, kt + 1);
;   }
	s_waitcnt lgkmcnt(0)
	v_mfma_f32_32x32x16_bf16 v[112:127], v[192:195], v[168:171], v[112:127]
	ds_read_b128 v[184:187], v206 offset:32768
	ds_read_b128 v[152:155], v204 offset:32768
	v_mfma_f32_32x32x16_bf16 v[96:111], v[200:203], v[168:171], v[96:111]
	ds_read_b128 v[188:191], v206 offset:34816
	ds_read_b128 v[156:159], v204 offset:34816
	v_mfma_f32_32x32x16_bf16 v[80:95], v[192:195], v[172:175], v[80:95]
	ds_read_b128 v[160:163], v204 offset:36864
	ds_read_b128 v[164:167], v204 offset:38912
	v_mfma_f32_32x32x16_bf16 v[64:79], v[200:203], v[172:175], v[64:79]
	v_mfma_f32_32x32x16_bf16 v[48:63], v[192:195], v[176:179], v[48:63]
	v_mfma_f32_32x32x16_bf16 v[32:47], v[200:203], v[176:179], v[32:47]
	v_mfma_f32_32x32x16_bf16 v[16:31], v[192:195], v[180:183], v[16:31]
	v_mfma_f32_32x32x16_bf16 v[0:15], v[200:203], v[180:183], v[0:15]
	s_waitcnt lgkmcnt(0)
	v_mfma_f32_32x32x16_bf16 v[112:127], v[184:187], v[152:155], v[112:127]
	ds_read_b128 v[192:195], v207 offset:32768
	ds_read_b128 v[168:171], v205 offset:32768
	v_mfma_f32_32x32x16_bf16 v[96:111], v[188:191], v[152:155], v[96:111]
	ds_read_b128 v[200:203], v207 offset:34816
	ds_read_b128 v[172:175], v205 offset:34816
	v_mfma_f32_32x32x16_bf16 v[80:95], v[184:187], v[156:159], v[80:95]
	ds_read_b128 v[176:179], v205 offset:36864
	ds_read_b128 v[180:183], v205 offset:38912
	v_mfma_f32_32x32x16_bf16 v[64:79], v[188:191], v[156:159], v[64:79]
	v_mfma_f32_32x32x16_bf16 v[48:63], v[184:187], v[160:163], v[48:63]
	v_mfma_f32_32x32x16_bf16 v[32:47], v[188:191], v[160:163], v[32:47]
	v_mfma_f32_32x32x16_bf16 v[16:31], v[184:187], v[164:167], v[16:31]
	v_mfma_f32_32x32x16_bf16 v[0:15], v[188:191], v[164:167], v[0:15]
	s_waitcnt lgkmcnt(0)
	s_waitcnt vmcnt(8)
	s_barrier
	s_waitcnt lgkmcnt(0)
	v_mfma_f32_32x32x16_bf16 v[112:127], v[192:195], v[168:171], v[112:127]
	ds_read_b128 v[184:187], v210
	ds_read_b128 v[152:155], v208
	v_mfma_f32_32x32x16_bf16 v[96:111], v[200:203], v[168:171], v[96:111]
	ds_read_b128 v[188:191], v210 offset:2048
	ds_read_b128 v[156:159], v208 offset:2048
	v_mfma_f32_32x32x16_bf16 v[80:95], v[192:195], v[172:175], v[80:95]
	ds_read_b128 v[160:163], v208 offset:4096
	ds_read_b128 v[164:167], v208 offset:6144
	v_mfma_f32_32x32x16_bf16 v[64:79], v[200:203], v[172:175], v[64:79]
	v_mfma_f32_32x32x16_bf16 v[48:63], v[192:195], v[176:179], v[48:63]
	v_mfma_f32_32x32x16_bf16 v[32:47], v[200:203], v[176:179], v[32:47]
	v_mfma_f32_32x32x16_bf16 v[16:31], v[192:195], v[180:183], v[16:31]
	v_mfma_f32_32x32x16_bf16 v[0:15], v[200:203], v[180:183], v[0:15]
	s_waitcnt lgkmcnt(0)
	v_mfma_f32_32x32x16_bf16 v[112:127], v[184:187], v[152:155], v[112:127]
	ds_read_b128 v[192:195], v211
	ds_read_b128 v[168:171], v209
	v_mfma_f32_32x32x16_bf16 v[96:111], v[188:191], v[152:155], v[96:111]
	ds_read_b128 v[200:203], v211 offset:2048
	ds_read_b128 v[172:175], v209 offset:2048
	v_mfma_f32_32x32x16_bf16 v[80:95], v[184:187], v[156:159], v[80:95]
	ds_read_b128 v[176:179], v209 offset:4096
	ds_read_b128 v[180:183], v209 offset:6144
	v_mfma_f32_32x32x16_bf16 v[64:79], v[188:191], v[156:159], v[64:79]
	v_mfma_f32_32x32x16_bf16 v[48:63], v[184:187], v[160:163], v[48:63]
	v_mfma_f32_32x32x16_bf16 v[32:47], v[188:191], v[160:163], v[32:47]
	v_mfma_f32_32x32x16_bf16 v[16:31], v[184:187], v[164:167], v[16:31]
	v_mfma_f32_32x32x16_bf16 v[0:15], v[188:191], v[164:167], v[0:15]
	s_waitcnt lgkmcnt(0)
	s_waitcnt vmcnt(4)
	s_barrier
	s_waitcnt lgkmcnt(0)
	v_mfma_f32_32x32x16_bf16 v[112:127], v[192:195], v[168:171], v[112:127]
	ds_read_b128 v[184:187], v198
	ds_read_b128 v[152:155], v132
	v_mfma_f32_32x32x16_bf16 v[96:111], v[200:203], v[168:171], v[96:111]
	ds_read_b128 v[188:191], v198 offset:2048
	ds_read_b128 v[156:159], v132 offset:2048
	v_mfma_f32_32x32x16_bf16 v[80:95], v[192:195], v[172:175], v[80:95]
	ds_read_b128 v[160:163], v132 offset:4096
	ds_read_b128 v[164:167], v132 offset:6144
	v_mfma_f32_32x32x16_bf16 v[64:79], v[200:203], v[172:175], v[64:79]
	v_mfma_f32_32x32x16_bf16 v[48:63], v[192:195], v[176:179], v[48:63]
	v_mfma_f32_32x32x16_bf16 v[32:47], v[200:203], v[176:179], v[32:47]
	v_mfma_f32_32x32x16_bf16 v[16:31], v[192:195], v[180:183], v[16:31]
	v_mfma_f32_32x32x16_bf16 v[0:15], v[200:203], v[180:183], v[0:15]
	s_waitcnt lgkmcnt(0)
	v_mfma_f32_32x32x16_bf16 v[112:127], v[184:187], v[152:155], v[112:127]
	ds_read_b128 v[192:195], v199
	ds_read_b128 v[168:171], v151
	v_mfma_f32_32x32x16_bf16 v[96:111], v[188:191], v[152:155], v[96:111]
	ds_read_b128 v[200:203], v199 offset:2048
	ds_read_b128 v[172:175], v151 offset:2048
	v_mfma_f32_32x32x16_bf16 v[80:95], v[184:187], v[156:159], v[80:95]
	ds_read_b128 v[176:179], v151 offset:4096
	ds_read_b128 v[180:183], v151 offset:6144
	v_mfma_f32_32x32x16_bf16 v[64:79], v[188:191], v[156:159], v[64:79]
	v_mfma_f32_32x32x16_bf16 v[48:63], v[184:187], v[160:163], v[48:63]
	v_mfma_f32_32x32x16_bf16 v[32:47], v[188:191], v[160:163], v[32:47]
	v_mfma_f32_32x32x16_bf16 v[16:31], v[184:187], v[164:167], v[16:31]
	v_mfma_f32_32x32x16_bf16 v[0:15], v[188:191], v[164:167], v[0:15]
	s_waitcnt lgkmcnt(0)
	s_waitcnt vmcnt(0)
	s_barrier
; DI unsigned pack2(float a, float b) { f2_t f = {a, b}; bf2_t r = __builtin_convertvector(f, bf2_t); return __builtin_bit_cast(unsigned, r); }
; #define G_LOADA(kt_) { _Pragma("unroll") for (int i = 0; i < 4; ++i) ra[i] = al(lrow + 64 * i, (kt_) * 64 + lck * 8); }
; #define G_LOADB(kt_) { _Pragma("unroll") for (int i = 0; i < 4; ++i) rb[i] = bl(lrow + 64 * i, (kt_) * 64 + lck * 8); }
; #define G_STOREA(buf_) { bf16_t* nA = sA + (buf_) * 256 * GLD; _Pragma("unroll") for (int i = 0; i < 4; ++i) *(u32x4*)(nA + (lrow + 64 * i) * GLD + lck * 8) = ra[i]; }
; #define G_STOREB(buf_) { bf16_t* nB = sB + (buf_) * 256 * GLD; _Pragma("unroll") for (int i = 0; i < 4; ++i) *(u32x4*)(nB + (lrow + 64 * i) * GLD + lck * 8) = rb[i]; }
; template <class AL, class BL, class EP>
; DI void gemm_tile256(AL al, BL bl, EP ep, int K, char* smem) {
;     ...
;   G_LOADA(0); G_LOADB(0);
;   __syncthreads();
;   G_STOREA(0); G_STOREB(0);
;   if (KT > 1) G_LOADB(1);
;   __syncthreads();
;   for (int kt = 0; kt < KT; kt += 2) {
;     G_STEP(0, kt);
;     if (kt + 1 >= KT) break;
;     G_STEP(1, kt + 1);
;   }
;     ...
;   if constexpr (EP::kBf16) {
;     bf16_t* sCb = (bf16_t*)smem;
; #pragma unroll
;     for (int i = 0; i < 4; ++i)
; #pragma unroll
;       for (int j = 0; j < 2; ++j)
; #pragma unroll
;         for (int g = 0; g < 4; ++g) {
;           u32x2 v = {pack2(acc[i][j][4 * g], acc[i][j][4 * g + 1]), pack2(acc[i][j][4 * g + 2], acc[i][j][4 * g + 3])};
;           *(u32x2*)(sCb + (128 * wm + 32 * i + r) * BLD + 64 * wn + 32 * j + 8 * g + 4 * h) = v;
;         }
;     __syncthreads();
	s_waitcnt lgkmcnt(0)
	v_mfma_f32_32x32x16_bf16 v[112:127], v[192:195], v[168:171], v[112:127]
	ds_read_b128 v[184:187], v198 offset:32768
	ds_read_b128 v[152:155], v132 offset:32768
	v_mfma_f32_32x32x16_bf16 v[96:111], v[200:203], v[168:171], v[96:111]
	ds_read_b128 v[188:191], v198 offset:34816
	ds_read_b128 v[156:159], v132 offset:34816
	v_mfma_f32_32x32x16_bf16 v[80:95], v[192:195], v[172:175], v[80:95]
	ds_read_b128 v[160:163], v132 offset:36864
	ds_read_b128 v[164:167], v132 offset:38912
	v_mfma_f32_32x32x16_bf16 v[64:79], v[200:203], v[172:175], v[64:79]
	v_mfma_f32_32x32x16_bf16 v[48:63], v[192:195], v[176:179], v[48:63]
	v_mfma_f32_32x32x16_bf16 v[32:47], v[200:203], v[176:179], v[32:47]
	v_mfma_f32_32x32x16_bf16 v[16:31], v[192:195], v[180:183], v[16:31]
	v_mfma_f32_32x32x16_bf16 v[0:15], v[200:203], v[180:183], v[0:15]
	s_waitcnt lgkmcnt(0)
	v_mfma_f32_32x32x16_bf16 v[112:127], v[184:187], v[152:155], v[112:127]
	ds_read_b128 v[192:195], v199 offset:32768
	ds_read_b128 v[168:171], v151 offset:32768
	v_mfma_f32_32x32x16_bf16 v[96:111], v[188:191], v[152:155], v[96:111]
	ds_read_b128 v[200:203], v199 offset:34816
	ds_read_b128 v[172:175], v151 offset:34816
	v_mfma_f32_32x32x16_bf16 v[80:95], v[184:187], v[156:159], v[80:95]
	ds_read_b128 v[176:179], v151 offset:36864
	ds_read_b128 v[180:183], v151 offset:38912
	v_mfma_f32_32x32x16_bf16 v[64:79], v[188:191], v[156:159], v[64:79]
	v_mfma_f32_32x32x16_bf16 v[48:63], v[184:187], v[160:163], v[48:63]
	v_mfma_f32_32x32x16_bf16 v[32:47], v[188:191], v[160:163], v[32:47]
	v_mfma_f32_32x32x16_bf16 v[16:31], v[184:187], v[164:167], v[16:31]
	v_mfma_f32_32x32x16_bf16 v[0:15], v[188:191], v[164:167], v[0:15]
	s_waitcnt lgkmcnt(0)
	s_waitcnt lgkmcnt(0)
	v_mfma_f32_32x32x16_bf16 v[112:127], v[192:195], v[168:171], v[112:127]
	v_mfma_f32_32x32x16_bf16 v[96:111], v[200:203], v[168:171], v[96:111]
	v_mfma_f32_32x32x16_bf16 v[80:95], v[192:195], v[172:175], v[80:95]
	v_mfma_f32_32x32x16_bf16 v[64:79], v[200:203], v[172:175], v[64:79]
	v_mfma_f32_32x32x16_bf16 v[48:63], v[192:195], v[176:179], v[48:63]
	v_mfma_f32_32x32x16_bf16 v[32:47], v[200:203], v[176:179], v[32:47]
	v_mfma_f32_32x32x16_bf16 v[16:31], v[192:195], v[180:183], v[16:31]
	v_mfma_f32_32x32x16_bf16 v[0:15], v[200:203], v[180:183], v[0:15]
	s_nop 15
	s_nop 3
	s_setprio 0
	v_lshl_or_b32 v128, v128, 7, v150
	s_waitcnt lgkmcnt(4)
	v_mad_u64_u32 v[130:131], s[2:3], v133, s13, v[128:129]
	s_waitcnt lgkmcnt(0)
	s_barrier
	s_nop 8
	v_cvt_pk_bf16_f32 v112, v112, v113
	v_cvt_pk_bf16_f32 v113, v114, v115
	v_cvt_pk_bf16_f32 v114, v116, v117
	v_cvt_pk_bf16_f32 v115, v118, v119
	ds_write2_b64 v130, v[112:113], v[114:115] offset1:2
	v_cvt_pk_bf16_f32 v112, v120, v121
	v_cvt_pk_bf16_f32 v113, v122, v123
	v_cvt_pk_bf16_f32 v114, v124, v125
	s_nop 3
	v_cvt_pk_bf16_f32 v16, v16, v17
	v_cvt_pk_bf16_f32 v17, v18, v19
	v_cvt_pk_bf16_f32 v18, v20, v21
	v_add_u32_e32 v20, 0xc000, v130
	v_cvt_pk_bf16_f32 v19, v22, v23
	v_cvt_pk_bf16_f32 v115, v126, v127
	ds_write2_b64 v20, v[16:17], v[18:19] offset0:192 offset1:194
	v_cvt_pk_bf16_f32 v0, v0, v1
	v_cvt_pk_bf16_f32 v1, v2, v3
	v_cvt_pk_bf16_f32 v2, v4, v5
	v_cvt_pk_bf16_f32 v3, v6, v7
	ds_write2_b64 v20, v[0:1], v[2:3] offset0:200 offset1:202
	v_cvt_pk_bf16_f32 v0, v8, v9
	v_cvt_pk_bf16_f32 v1, v10, v11
	s_nop 3
	v_cvt_pk_bf16_f32 v96, v96, v97
	v_cvt_pk_bf16_f32 v97, v98, v99
	v_cvt_pk_bf16_f32 v98, v100, v101
	v_cvt_pk_bf16_f32 v99, v102, v103
	v_cvt_pk_bf16_f32 v2, v12, v13
	v_cvt_pk_bf16_f32 v3, v14, v15
	ds_write2_b64 v130, v[96:97], v[98:99] offset0:8 offset1:10
	v_cvt_pk_bf16_f32 v80, v80, v81
	v_cvt_pk_bf16_f32 v81, v82, v83
	v_cvt_pk_bf16_f32 v82, v84, v85
	v_cvt_pk_bf16_f32 v83, v86, v87
	v_add_u32_e32 v84, 0x4000, v130
	v_cvt_pk_bf16_f32 v96, v104, v105
	v_cvt_pk_bf16_f32 v97, v106, v107
	s_nop 3
	v_cvt_pk_bf16_f32 v64, v64, v65
	v_cvt_pk_bf16_f32 v65, v66, v67
	v_cvt_pk_bf16_f32 v66, v68, v69
	v_cvt_pk_bf16_f32 v67, v70, v71
	v_cvt_pk_bf16_f32 v98, v108, v109
	v_cvt_pk_bf16_f32 v99, v110, v111
	ds_write2_b64 v84, v[80:81], v[82:83] offset0:64 offset1:66
	v_cvt_pk_bf16_f32 v48, v48, v49
	v_cvt_pk_bf16_f32 v49, v50, v51
	v_cvt_pk_bf16_f32 v50, v52, v53
	v_cvt_pk_bf16_f32 v51, v54, v55
	v_add_u32_e32 v52, 0x8000, v130
	v_cvt_pk_bf16_f32 v80, v88, v89
	v_cvt_pk_bf16_f32 v81, v90, v91
	s_nop 4
	v_cvt_pk_bf16_f32 v32, v32, v33
	v_cvt_pk_bf16_f32 v33, v34, v35
	v_cvt_pk_bf16_f32 v34, v36, v37
	v_cvt_pk_bf16_f32 v35, v38, v39
	v_cvt_pk_bf16_f32 v82, v92, v93
	v_cvt_pk_bf16_f32 v83, v94, v95
	ds_write2_b64 v84, v[64:65], v[66:67] offset0:72 offset1:74
	v_cvt_pk_bf16_f32 v64, v72, v73
	v_cvt_pk_bf16_f32 v65, v74, v75
	v_cvt_pk_bf16_f32 v66, v76, v77
	v_cvt_pk_bf16_f32 v67, v78, v79
	ds_write2_b64 v52, v[48:49], v[50:51] offset0:128 offset1:130
	v_cvt_pk_bf16_f32 v48, v56, v57
	v_cvt_pk_bf16_f32 v49, v58, v59
	v_cvt_pk_bf16_f32 v50, v60, v61
	v_cvt_pk_bf16_f32 v51, v62, v63
	ds_write2_b64 v52, v[32:33], v[34:35] offset0:136 offset1:138
	v_cvt_pk_bf16_f32 v32, v40, v41
	v_cvt_pk_bf16_f32 v33, v42, v43
	v_cvt_pk_bf16_f32 v34, v44, v45
	v_cvt_pk_bf16_f32 v35, v46, v47
	v_cvt_pk_bf16_f32 v16, v24, v25
	v_cvt_pk_bf16_f32 v17, v26, v27
	v_cvt_pk_bf16_f32 v18, v28, v29
	v_cvt_pk_bf16_f32 v19, v30, v31
	ds_write2_b64 v20, v[0:1], v[2:3] offset0:204 offset1:206
	v_mov_b32_e32 v2, v196
	ds_write2_b64 v130, v[112:113], v[114:115] offset0:4 offset1:6
	ds_write2_b64 v130, v[96:97], v[98:99] offset0:12 offset1:14
	ds_write2_b64 v84, v[80:81], v[82:83] offset0:68 offset1:70
	ds_write2_b64 v84, v[64:65], v[66:67] offset0:76 offset1:78
	ds_write2_b64 v52, v[48:49], v[50:51] offset0:132 offset1:134
	ds_write2_b64 v52, v[32:33], v[34:35] offset0:140 offset1:142
	ds_write2_b64 v20, v[16:17], v[18:19] offset0:196 offset1:198
	s_waitcnt lgkmcnt(0)
	s_barrier
; DI int tid512() { int t = threadIdx_x_raw(); asm volatile("" : "+v"(t)); return t; }
;   DI void operator()(const bf16_t* sCb) const {
;     for (int id = tid512(); id < 8192; id += 512) {
;       int row = id >> 5, c8 = (id & 31) * 8, n = n0 + c8;
;       if (n < N) *(u32x4*)(dst + (size_t)(m0 + row) * ld + n) = *(const u32x4*)(sCb + row * BLD + c8);
	s_nop 0
	v_cmp_gt_i32_e32 vcc, s14, v2
	s_and_saveexec_b64 s[2:3], vcc
	s_cbranch_execz .LBB0_444
	v_lshlrev_b32_e32 v3, 3, v2
	v_and_b32_e32 v1, 0xf8, v3
	v_or_b32_e32 v0, s17, v1
	v_cmp_gt_i32_e32 vcc, s15, v0
	s_and_saveexec_b64 s[6:7], vcc
	s_cbranch_execz .Lep_done_444
; DI int tid512() { int t = threadIdx_x_raw(); asm volatile("" : "+v"(t)); return t; }
;   DI void operator()(const bf16_t* sCb) const {
;     for (int id = tid512(); id < 8192; id += 512) {
;       int row = id >> 5, c8 = (id & 31) * 8, n = n0 + c8;
;       if (n < N) *(u32x4*)(dst + (size_t)(m0 + row) * ld + n) = *(const u32x4*)(sCb + row * BLD + c8);
;     }
	v_ashrrev_i32_e32 v8, 5, v2
	v_mul_lo_u32 v4, v8, s13
	v_lshl_add_u32 v1, v1, 1, v4
	v_add_u32_e32 v10, 0x10800, v1
	ds_read_b128 v[64:67], v1
	ds_read_b128 v[68:71], v1 offset:8448
	ds_read_b128 v[72:75], v1 offset:16896
	ds_read_b128 v[76:79], v1 offset:25344
	ds_read_b128 v[80:83], v1 offset:33792
	ds_read_b128 v[84:87], v1 offset:42240
	ds_read_b128 v[88:91], v1 offset:50688
	ds_read_b128 v[92:95], v1 offset:59136
	ds_read_b128 v[96:99], v10
	ds_read_b128 v[100:103], v10 offset:8448
	ds_read_b128 v[104:107], v10 offset:16896
	ds_read_b128 v[108:111], v10 offset:25344
	ds_read_b128 v[112:115], v10 offset:33792
	ds_read_b128 v[116:119], v10 offset:42240
	ds_read_b128 v[120:123], v10 offset:50688
	ds_read_b128 v[124:127], v10 offset:59136
	v_and_b32_e32 v1, 0xf8, v3
	v_or_b32_e32 v0, s17, v1
	v_ashrrev_i32_e32 v8, 5, v2
	v_add_u32_e32 v8, s18, v8
	v_ashrrev_i32_e32 v9, 31, v8
	v_lshlrev_b64 v[8:9], 11, v[8:9]
	v_lshl_add_u64 v[8:9], s[8:9], 0, v[8:9]
	v_ashrrev_i32_e32 v1, 31, v0
	v_lshl_add_u64 v[0:1], v[0:1], 1, v[8:9]
	s_waitcnt lgkmcnt(15)
	global_store_dwordx4 v[0:1], v[64:67], off
	v_add_u32_e32 v2, 0x200, v2
	v_and_b32_e32 v1, 0xf8, v3
	v_or_b32_e32 v0, s17, v1
	v_ashrrev_i32_e32 v8, 5, v2
	v_add_u32_e32 v8, s18, v8
	v_ashrrev_i32_e32 v9, 31, v8
	v_lshlrev_b64 v[8:9], 11, v[8:9]
	v_lshl_add_u64 v[8:9], s[8:9], 0, v[8:9]
	v_ashrrev_i32_e32 v1, 31, v0
	v_lshl_add_u64 v[0:1], v[0:1], 1, v[8:9]
	s_waitcnt lgkmcnt(14)
	global_store_dwordx4 v[0:1], v[68:71], off
	v_add_u32_e32 v2, 0x200, v2
	v_and_b32_e32 v1, 0xf8, v3
	v_or_b32_e32 v0, s17, v1
	v_ashrrev_i32_e32 v8, 5, v2
	v_add_u32_e32 v8, s18, v8
	v_ashrrev_i32_e32 v9, 31, v8
	v_lshlrev_b64 v[8:9], 11, v[8:9]
	v_lshl_add_u64 v[8:9], s[8:9], 0, v[8:9]
	v_ashrrev_i32_e32 v1, 31, v0
	v_lshl_add_u64 v[0:1], v[0:1], 1, v[8:9]
	s_waitcnt lgkmcnt(13)
	global_store_dwordx4 v[0:1], v[72:75], off
	v_add_u32_e32 v2, 0x200, v2
	v_and_b32_e32 v1, 0xf8, v3
	v_or_b32_e32 v0, s17, v1
	v_ashrrev_i32_e32 v8, 5, v2
	v_add_u32_e32 v8, s18, v8
	v_ashrrev_i32_e32 v9, 31, v8
	v_lshlrev_b64 v[8:9], 11, v[8:9]
	v_lshl_add_u64 v[8:9], s[8:9], 0, v[8:9]
	v_ashrrev_i32_e32 v1, 31, v0
	v_lshl_add_u64 v[0:1], v[0:1], 1, v[8:9]
	s_waitcnt lgkmcnt(12)
	global_store_dwordx4 v[0:1], v[76:79], off
	v_add_u32_e32 v2, 0x200, v2
	v_and_b32_e32 v1, 0xf8, v3
	v_or_b32_e32 v0, s17, v1
	v_ashrrev_i32_e32 v8, 5, v2
	v_add_u32_e32 v8, s18, v8
	v_ashrrev_i32_e32 v9, 31, v8
	v_lshlrev_b64 v[8:9], 11, v[8:9]
	v_lshl_add_u64 v[8:9], s[8:9], 0, v[8:9]
	v_ashrrev_i32_e32 v1, 31, v0
	v_lshl_add_u64 v[0:1], v[0:1], 1, v[8:9]
	s_waitcnt lgkmcnt(11)
	global_store_dwordx4 v[0:1], v[80:83], off
	v_add_u32_e32 v2, 0x200, v2
	v_and_b32_e32 v1, 0xf8, v3
	v_or_b32_e32 v0, s17, v1
	v_ashrrev_i32_e32 v8, 5, v2
	v_add_u32_e32 v8, s18, v8
	v_ashrrev_i32_e32 v9, 31, v8
	v_lshlrev_b64 v[8:9], 11, v[8:9]
	v_lshl_add_u64 v[8:9], s[8:9], 0, v[8:9]
	v_ashrrev_i32_e32 v1, 31, v0
	v_lshl_add_u64 v[0:1], v[0:1], 1, v[8:9]
	s_waitcnt lgkmcnt(10)
	global_store_dwordx4 v[0:1], v[84:87], off
	v_add_u32_e32 v2, 0x200, v2
	v_and_b32_e32 v1, 0xf8, v3
	v_or_b32_e32 v0, s17, v1
	v_ashrrev_i32_e32 v8, 5, v2
	v_add_u32_e32 v8, s18, v8
	v_ashrrev_i32_e32 v9, 31, v8
	v_lshlrev_b64 v[8:9], 11, v[8:9]
	v_lshl_add_u64 v[8:9], s[8:9], 0, v[8:9]
	v_ashrrev_i32_e32 v1, 31, v0
	v_lshl_add_u64 v[0:1], v[0:1], 1, v[8:9]
	s_waitcnt lgkmcnt(9)
	global_store_dwordx4 v[0:1], v[88:91], off
	v_add_u32_e32 v2, 0x200, v2
	v_and_b32_e32 v1, 0xf8, v3
	v_or_b32_e32 v0, s17, v1
	v_ashrrev_i32_e32 v8, 5, v2
	v_add_u32_e32 v8, s18, v8
	v_ashrrev_i32_e32 v9, 31, v8
	v_lshlrev_b64 v[8:9], 11, v[8:9]
	v_lshl_add_u64 v[8:9], s[8:9], 0, v[8:9]
	v_ashrrev_i32_e32 v1, 31, v0
	v_lshl_add_u64 v[0:1], v[0:1], 1, v[8:9]
	s_waitcnt lgkmcnt(8)
	global_store_dwordx4 v[0:1], v[92:95], off
	v_add_u32_e32 v2, 0x200, v2
	v_and_b32_e32 v1, 0xf8, v3
	v_or_b32_e32 v0, s17, v1
	v_ashrrev_i32_e32 v8, 5, v2
	v_add_u32_e32 v8, s18, v8
	v_ashrrev_i32_e32 v9, 31, v8
	v_lshlrev_b64 v[8:9], 11, v[8:9]
	v_lshl_add_u64 v[8:9], s[8:9], 0, v[8:9]
	v_ashrrev_i32_e32 v1, 31, v0
	v_lshl_add_u64 v[0:1], v[0:1], 1, v[8:9]
	s_waitcnt lgkmcnt(7)
	global_store_dwordx4 v[0:1], v[96:99], off
	v_add_u32_e32 v2, 0x200, v2
	v_and_b32_e32 v1, 0xf8, v3
	v_or_b32_e32 v0, s17, v1
	v_ashrrev_i32_e32 v8, 5, v2
	v_add_u32_e32 v8, s18, v8
	v_ashrrev_i32_e32 v9, 31, v8
	v_lshlrev_b64 v[8:9], 11, v[8:9]
	v_lshl_add_u64 v[8:9], s[8:9], 0, v[8:9]
	v_ashrrev_i32_e32 v1, 31, v0
	v_lshl_add_u64 v[0:1], v[0:1], 1, v[8:9]
	s_waitcnt lgkmcnt(6)
	global_store_dwordx4 v[0:1], v[100:103], off
	v_add_u32_e32 v2, 0x200, v2
	v_and_b32_e32 v1, 0xf8, v3
	v_or_b32_e32 v0, s17, v1
	v_ashrrev_i32_e32 v8, 5, v2
	v_add_u32_e32 v8, s18, v8
	v_ashrrev_i32_e32 v9, 31, v8
	v_lshlrev_b64 v[8:9], 11, v[8:9]
	v_lshl_add_u64 v[8:9], s[8:9], 0, v[8:9]
	v_ashrrev_i32_e32 v1, 31, v0
	v_lshl_add_u64 v[0:1], v[0:1], 1, v[8:9]
	s_waitcnt lgkmcnt(5)
	global_store_dwordx4 v[0:1], v[104:107], off
	v_add_u32_e32 v2, 0x200, v2
	v_and_b32_e32 v1, 0xf8, v3
	v_or_b32_e32 v0, s17, v1
	v_ashrrev_i32_e32 v8, 5, v2
	v_add_u32_e32 v8, s18, v8
	v_ashrrev_i32_e32 v9, 31, v8
	v_lshlrev_b64 v[8:9], 11, v[8:9]
	v_lshl_add_u64 v[8:9], s[8:9], 0, v[8:9]
	v_ashrrev_i32_e32 v1, 31, v0
	v_lshl_add_u64 v[0:1], v[0:1], 1, v[8:9]
	s_waitcnt lgkmcnt(4)
	global_store_dwordx4 v[0:1], v[108:111], off
	v_add_u32_e32 v2, 0x200, v2
	v_and_b32_e32 v1, 0xf8, v3
	v_or_b32_e32 v0, s17, v1
	v_ashrrev_i32_e32 v8, 5, v2
	v_add_u32_e32 v8, s18, v8
	v_ashrrev_i32_e32 v9, 31, v8
	v_lshlrev_b64 v[8:9], 11, v[8:9]
	v_lshl_add_u64 v[8:9], s[8:9], 0, v[8:9]
	v_ashrrev_i32_e32 v1, 31, v0
	v_lshl_add_u64 v[0:1], v[0:1], 1, v[8:9]
	s_waitcnt lgkmcnt(3)
	global_store_dwordx4 v[0:1], v[112:115], off
	v_add_u32_e32 v2, 0x200, v2
	v_and_b32_e32 v1, 0xf8, v3
	v_or_b32_e32 v0, s17, v1
	v_ashrrev_i32_e32 v8, 5, v2
	v_add_u32_e32 v8, s18, v8
	v_ashrrev_i32_e32 v9, 31, v8
	v_lshlrev_b64 v[8:9], 11, v[8:9]
	v_lshl_add_u64 v[8:9], s[8:9], 0, v[8:9]
	v_ashrrev_i32_e32 v1, 31, v0
	v_lshl_add_u64 v[0:1], v[0:1], 1, v[8:9]
	s_waitcnt lgkmcnt(2)
	global_store_dwordx4 v[0:1], v[116:119], off
	v_add_u32_e32 v2, 0x200, v2
	v_and_b32_e32 v1, 0xf8, v3
	v_or_b32_e32 v0, s17, v1
	v_ashrrev_i32_e32 v8, 5, v2
	v_add_u32_e32 v8, s18, v8
	v_ashrrev_i32_e32 v9, 31, v8
	v_lshlrev_b64 v[8:9], 11, v[8:9]
	v_lshl_add_u64 v[8:9], s[8:9], 0, v[8:9]
	v_ashrrev_i32_e32 v1, 31, v0
	v_lshl_add_u64 v[0:1], v[0:1], 1, v[8:9]
	s_waitcnt lgkmcnt(1)
	global_store_dwordx4 v[0:1], v[120:123], off
	v_add_u32_e32 v2, 0x200, v2
	v_and_b32_e32 v1, 0xf8, v3
	v_or_b32_e32 v0, s17, v1
	v_ashrrev_i32_e32 v8, 5, v2
	v_add_u32_e32 v8, s18, v8
	v_ashrrev_i32_e32 v9, 31, v8
	v_lshlrev_b64 v[8:9], 11, v[8:9]
	v_lshl_add_u64 v[8:9], s[8:9], 0, v[8:9]
	v_ashrrev_i32_e32 v1, 31, v0
	v_lshl_add_u64 v[0:1], v[0:1], 1, v[8:9]
	s_waitcnt lgkmcnt(0)
	global_store_dwordx4 v[0:1], v[124:127], off

;   DI u32x4 operator()(int r, int k) const {
;     int row = row0 + r;
;     row = row < nrows ? row : nrows - 1;
;     return ldg16(base + (size_t)row * ld + k);
;   }
; DI void phase_ffn_up256(const Sched& sc, const Params& p, int layer, char* smem) {
;     ...
;   for (int round = 0;; ++round) {
;     int mt = 0, nt = 0;
;     const int st = sched_tile(sc, round, 128, 22, mt, nt);
;     if (st == 2) break;
;     if (st == 1) continue;
;     LoadRows al{H, 1024, mt * 256, T};
;     LoadRows bl{Wt, 1024, nt * 256, 5632};
;     EpFfnUp256 ep{p.ffn_conv + (size_t)layer * 3 * DFF, (bf16_t*)(p.ws + OFF_HID), (bf16_t*)(p.ws + OFF_HG), (bf16_t*)(p.ws + OFF_HU), mt, nt * 128};
;     gemm_tile256(al, bl, ep, 1024, smem);
.LBB0_541:
	v_cmp_ne_u32_e32 vcc, 1, v0
	s_mov_b64 s[0:1], -1
	s_cbranch_vccz .LBB0_556
	v_mov_b32_e32 v32, v196
	s_nop 0
	v_ashrrev_i32_e32 v33, 3, v32
	v_lshl_add_u32 v12, v130, 8, v33
	v_lshlrev_b32_e32 v0, 4, v32
	v_add_u32_e32 v10, 0x80, v12
	v_lshl_add_u32 v28, v131, 8, v33
	v_and_b32_e32 v128, 0x70, v0
	v_min_i32_e32 v0, 0x7fff, v12
	v_min_i32_e32 v10, 0x7fff, v10
	v_add_u32_e32 v26, 0x80, v28
	v_ashrrev_i32_e32 v1, 31, v0
	v_ashrrev_i32_e32 v11, 31, v10
	v_min_i32_e32 v16, 0x15ff, v28
	v_min_i32_e32 v26, 0x15ff, v26
	v_lshl_add_u64 v[8:9], s[84:85], 0, v[128:129]
	v_lshlrev_b64 v[0:1], 11, v[0:1]
	v_lshlrev_b64 v[10:11], 11, v[10:11]
	v_ashrrev_i32_e32 v17, 31, v16
	v_ashrrev_i32_e32 v27, 31, v26
	v_lshl_add_u64 v[136:137], v[8:9], 0, v[0:1]
	v_add_u32_e32 v0, 64, v12
	v_lshl_add_u64 v[140:141], v[8:9], 0, v[10:11]
	v_add_u32_e32 v10, 0xc0, v12
	v_lshlrev_b64 v[190:191], 11, v[16:17]
	v_add_u32_e32 v16, 64, v28
	v_lshlrev_b64 v[194:195], 11, v[26:27]
	v_add_u32_e32 v26, 0xc0, v28
	v_min_i32_e32 v0, 0x7fff, v0
	v_min_i32_e32 v10, 0x7fff, v10
	v_min_i32_e32 v16, 0x15ff, v16
	v_min_i32_e32 v26, 0x15ff, v26
	v_ashrrev_i32_e32 v1, 31, v0
	v_ashrrev_i32_e32 v11, 31, v10
	v_lshl_add_u64 v[24:25], s[2:3], 0, v[128:129]
	v_ashrrev_i32_e32 v17, 31, v16
	v_ashrrev_i32_e32 v27, 31, v26
	v_lshlrev_b64 v[0:1], 11, v[0:1]
	v_lshlrev_b64 v[10:11], 11, v[10:11]
	v_lshl_add_u64 v[144:145], v[24:25], 0, v[190:191]
	v_lshlrev_b64 v[192:193], 11, v[16:17]
	v_lshl_add_u64 v[148:149], v[24:25], 0, v[194:195]
	v_lshlrev_b64 v[198:199], 11, v[26:27]
	v_lshl_add_u64 v[138:139], v[8:9], 0, v[0:1]
	v_lshl_add_u64 v[142:143], v[8:9], 0, v[10:11]
	v_lshl_add_u64 v[146:147], v[24:25], 0, v[192:193]
	v_lshl_add_u64 v[150:151], v[24:25], 0, v[198:199]
	v_mad_u64_u32 v[134:135], s[0:1], v33, s19, v[128:129]
	v_add_u32_e32 v157, 0x12000, v134
	v_bfe_u32 v135, v32, 6, 2
	v_add_u32_e32 v156, 0x1b000, v134
	v_and_b32_e32 v1, 31, v32
	v_ashrrev_i32_e32 v0, 1, v32
	v_and_or_b32 v153, v0, s20, v1
	v_lshrrev_b32_e32 v0, 2, v32
	v_and_b32_e32 v154, 8, v0
	v_lshlrev_b32_e32 v0, 1, v154
	v_mad_u64_u32 v[132:133], s[0:1], v153, s19, v[0:1]
	v_lshl_or_b32 v1, v135, 6, v1
	v_mul_u32_u24_e32 v1, 0x48, v1
	v_lshl_add_u32 v0, v1, 1, v0
	v_add_u32_e32 v155, 0x12000, v0
	v_add_u32_e32 v133, 0x1b000, v0
	v_lshl_add_u64 v[198:199], s[2:3], 0, v[198:199]
	v_or_b32_e32 v128, 0x100, v128
	v_lshl_add_u64 v[192:193], s[2:3], 0, v[192:193]
	v_lshl_add_u64 v[190:191], s[2:3], 0, v[190:191]
	v_lshl_add_u64 v[206:207], v[198:199], 0, v[128:129]
	v_lshl_add_u64 v[194:195], s[2:3], 0, v[194:195]
	v_lshl_add_u64 v[198:199], v[192:193], 0, v[128:129]
	v_lshl_add_u64 v[190:191], v[190:191], 0, v[128:129]
	v_lshl_add_u64 v[194:195], v[194:195], 0, v[128:129]
	s_nop 0
	s_nop 0
	s_nop 0
	s_nop 0
	s_nop 0
	s_nop 0
	s_nop 0
	s_nop 0
	s_nop 0
	v_lshrrev_b32_e32 v226, 6, v196
	s_mov_b32 s10, 64
	v_readfirstlane_b32 s29, v226
	s_mov_b32 s11, 0
	s_mov_b32 s14, 0x40000
	s_mov_b32 s15, 0
	v_bfe_u32 v224, v196, 2, 4
	s_lshl_b32 s30, s29, 3
	v_add_u32_e32 v224, s30, v224
	s_mov_b32 s30, 0x800
	v_mul_lo_u32 v224, v224, s30
	v_bfe_u32 v226, v196, 4, 2
	v_and_b32_e32 v225, 3, v196
	v_xor_b32_e32 v226, v225, v226
	v_lshl_add_u32 v224, v226, 4, v224
	v_mov_b32_e32 v225, 0
	v_readlane_b32 s16, v136, 0
	v_readlane_b32 s17, v137, 0
	s_nop 1
	v_lshl_add_u64 v[216:217], s[16:17], 0, v[224:225]
	v_lshl_add_u64 v[218:219], v[216:217], 0, s[14:15]
	v_readlane_b32 s16, v144, 0
	v_readlane_b32 s17, v145, 0
	s_nop 1
	v_lshl_add_u64 v[220:221], s[16:17], 0, v[224:225]
	v_lshl_add_u64 v[222:223], v[220:221], 0, s[14:15]
	v_and_b32_e32 v224, 31, v196
	v_bfe_u32 v226, v196, 2, 2
	v_bfe_u32 v225, v196, 5, 1
	v_xor_b32_e32 v226, v225, v226
	v_lshlrev_b32_e32 v226, 4, v226
	v_lshl_or_b32 v224, v224, 6, v226
	s_lshr_b32 s30, s29, 2
	s_lshl_b32 s30, s30, 13
	v_add_u32_e32 v134, s30, v224
	s_and_b32 s30, s29, 3
	s_lshl_b32 s30, s30, 12
	s_add_u32 s30, s30, 0x4000
	v_add_u32_e32 v198, s30, v224
	v_xor_b32_e32 v155, 0x20, v134
	v_xor_b32_e32 v199, 0x20, v198
	v_add_u32_e32 v208, 0x10000, v134
	v_add_u32_e32 v210, 0x10000, v198
	v_add_u32_e32 v212, 0x20000, v134
	v_add_u32_e32 v214, 0x20000, v198
	v_add_u32_e32 v209, 0x10000, v155
	v_add_u32_e32 v211, 0x10000, v199
	v_add_u32_e32 v213, 0x20000, v155
	v_add_u32_e32 v215, 0x20000, v199
	s_lshl_b32 s29, s29, 10
	s_waitcnt lgkmcnt(0)
	s_barrier
; #define G_LOADA(kt_) { _Pragma("unroll") for (int i = 0; i < 4; ++i) ra[i] = al(lrow + 64 * i, (kt_) * 64 + lck * 8); }
; #define G_LOADB(kt_) { _Pragma("unroll") for (int i = 0; i < 4; ++i) rb[i] = bl(lrow + 64 * i, (kt_) * 64 + lck * 8); }
; #define G_STOREA(buf_) { bf16_t* nA = sA + (buf_) * 256 * GLD; _Pragma("unroll") for (int i = 0; i < 4; ++i) *(u32x4*)(nA + (lrow + 64 * i) * GLD + lck * 8) = ra[i]; }
; #define G_STOREB(buf_) { bf16_t* nB = sB + (buf_) * 256 * GLD; _Pragma("unroll") for (int i = 0; i < 4; ++i) *(u32x4*)(nB + (lrow + 64 * i) * GLD + lck * 8) = rb[i]; }
; template <class AL, class BL, class EP>
; DI void gemm_tile256(AL al, BL bl, EP ep, int K, char* smem) {
;     ...
; #pragma unroll
;   for (int i = 0; i < 4; ++i)
; #pragma unroll
;     for (int j = 0; j < 2; ++j)
; #pragma unroll
;       for (int q = 0; q < 16; ++q) acc[i][j][q] = 0.f;
;   u32x4 ra[4], rb[4];
;   const int KT = K >> 6;
;     ...
;   G_LOADA(0); G_LOADB(0);
;   __syncthreads();
;   G_STOREA(0); G_STOREB(0);
;   if (KT > 1) G_LOADB(1);
;   __syncthreads();
	s_add_u32 m0, s29, 0x0
	s_nop 0
	global_load_lds_dwordx4 v[216:217], off
	v_lshl_add_u64 v[216:217], v[216:217], 0, s[10:11]
	s_add_u32 m0, s29, 0x4000
	s_nop 0
	global_load_lds_dwordx4 v[220:221], off
	v_lshl_add_u64 v[220:221], v[220:221], 0, s[10:11]
	s_add_u32 m0, s29, 0x2000
	s_nop 0
	global_load_lds_dwordx4 v[218:219], off
	v_lshl_add_u64 v[218:219], v[218:219], 0, s[10:11]
	s_add_u32 m0, s29, 0x6000
	s_nop 0
	global_load_lds_dwordx4 v[222:223], off
	v_lshl_add_u64 v[222:223], v[222:223], 0, s[10:11]
	s_add_u32 m0, s29, 0x8000
	s_nop 0
	global_load_lds_dwordx4 v[216:217], off
	v_lshl_add_u64 v[216:217], v[216:217], 0, s[10:11]
	s_add_u32 m0, s29, 0xc000
	s_nop 0
	global_load_lds_dwordx4 v[220:221], off
	v_lshl_add_u64 v[220:221], v[220:221], 0, s[10:11]
	s_add_u32 m0, s29, 0xa000
	s_nop 0
	global_load_lds_dwordx4 v[218:219], off
	v_lshl_add_u64 v[218:219], v[218:219], 0, s[10:11]
	s_add_u32 m0, s29, 0xe000
	s_nop 0
	global_load_lds_dwordx4 v[222:223], off
	v_lshl_add_u64 v[222:223], v[222:223], 0, s[10:11]
	s_add_u32 m0, s29, 0x10000
	s_nop 0
	global_load_lds_dwordx4 v[216:217], off
	v_lshl_add_u64 v[216:217], v[216:217], 0, s[10:11]
	s_add_u32 m0, s29, 0x14000
	s_nop 0
	global_load_lds_dwordx4 v[220:221], off
	v_lshl_add_u64 v[220:221], v[220:221], 0, s[10:11]
	s_add_u32 m0, s29, 0x12000
	s_nop 0
	global_load_lds_dwordx4 v[218:219], off
	v_lshl_add_u64 v[218:219], v[218:219], 0, s[10:11]
	s_add_u32 m0, s29, 0x16000
	s_nop 0
	global_load_lds_dwordx4 v[222:223], off
	v_lshl_add_u64 v[222:223], v[222:223], 0, s[10:11]
	s_add_u32 m0, s29, 0x18000
	s_nop 0
	global_load_lds_dwordx4 v[216:217], off
	v_lshl_add_u64 v[216:217], v[216:217], 0, s[10:11]
	s_add_u32 m0, s29, 0x1c000
	s_nop 0
	global_load_lds_dwordx4 v[220:221], off
	v_lshl_add_u64 v[220:221], v[220:221], 0, s[10:11]
	s_add_u32 m0, s29, 0x1a000
	s_nop 0
	global_load_lds_dwordx4 v[218:219], off
	v_lshl_add_u64 v[218:219], v[218:219], 0, s[10:11]
	s_add_u32 m0, s29, 0x1e000
	s_nop 0
	global_load_lds_dwordx4 v[222:223], off
	v_lshl_add_u64 v[222:223], v[222:223], 0, s[10:11]
	s_add_u32 m0, s29, 0x20000
	s_nop 0
	global_load_lds_dwordx4 v[216:217], off
	v_lshl_add_u64 v[216:217], v[216:217], 0, s[10:11]
	s_add_u32 m0, s29, 0x24000
	s_nop 0
	global_load_lds_dwordx4 v[220:221], off
	v_lshl_add_u64 v[220:221], v[220:221], 0, s[10:11]
	v_mov_b64_e32 v[112:113], 0
	v_mov_b64_e32 v[114:115], 0
	v_mov_b64_e32 v[116:117], 0
	v_mov_b64_e32 v[118:119], 0
	v_mov_b64_e32 v[120:121], 0
	v_mov_b64_e32 v[122:123], 0
	v_mov_b64_e32 v[124:125], 0
	v_mov_b64_e32 v[126:127], 0
	v_mov_b64_e32 v[96:97], 0
	v_mov_b64_e32 v[98:99], 0
	v_mov_b64_e32 v[100:101], 0
	v_mov_b64_e32 v[102:103], 0
	v_mov_b64_e32 v[104:105], 0
	v_mov_b64_e32 v[106:107], 0
	v_mov_b64_e32 v[108:109], 0
	v_mov_b64_e32 v[110:111], 0
	v_mov_b64_e32 v[80:81], 0
	v_mov_b64_e32 v[82:83], 0
	v_mov_b64_e32 v[84:85], 0
	v_mov_b64_e32 v[86:87], 0
	v_mov_b64_e32 v[88:89], 0
	v_mov_b64_e32 v[90:91], 0
	v_mov_b64_e32 v[92:93], 0
	v_mov_b64_e32 v[94:95], 0
	v_mov_b64_e32 v[64:65], 0
	v_mov_b64_e32 v[66:67], 0
	v_mov_b64_e32 v[68:69], 0
	v_mov_b64_e32 v[70:71], 0
	v_mov_b64_e32 v[72:73], 0
	v_mov_b64_e32 v[74:75], 0
	v_mov_b64_e32 v[76:77], 0
	v_mov_b64_e32 v[78:79], 0
	v_mov_b64_e32 v[48:49], 0
	v_mov_b64_e32 v[50:51], 0
	v_mov_b64_e32 v[52:53], 0
	v_mov_b64_e32 v[54:55], 0
	v_mov_b64_e32 v[56:57], 0
	v_mov_b64_e32 v[58:59], 0
	v_mov_b64_e32 v[60:61], 0
	v_mov_b64_e32 v[62:63], 0
	v_mov_b64_e32 v[32:33], 0
	v_mov_b64_e32 v[34:35], 0
	v_mov_b64_e32 v[36:37], 0
	v_mov_b64_e32 v[38:39], 0
	v_mov_b64_e32 v[40:41], 0
	v_mov_b64_e32 v[42:43], 0
	v_mov_b64_e32 v[44:45], 0
	v_mov_b64_e32 v[46:47], 0
	v_mov_b64_e32 v[16:17], 0
	v_mov_b64_e32 v[18:19], 0
	v_mov_b64_e32 v[20:21], 0
	v_mov_b64_e32 v[22:23], 0
	v_mov_b64_e32 v[24:25], 0
	v_mov_b64_e32 v[26:27], 0
	v_mov_b64_e32 v[28:29], 0
	v_mov_b64_e32 v[30:31], 0
	v_mov_b64_e32 v[0:1], 0
	v_mov_b64_e32 v[2:3], 0
	v_mov_b64_e32 v[4:5], 0
	v_mov_b64_e32 v[6:7], 0
	v_mov_b64_e32 v[8:9], 0
	v_mov_b64_e32 v[10:11], 0
	v_mov_b64_e32 v[12:13], 0
	v_mov_b64_e32 v[14:15], 0
	s_lshr_b32 s30, s29, 2
	s_xor_b32 s30, s30, s29
	s_bitcmp1_b32 s30, 10
	s_cbranch_scc0 .Lgk_ph6_np
	s_setprio 1
.Lgk_ph6_np:
	s_mov_b32 s30, 5
	s_waitcnt vmcnt(14)
	s_barrier
	ds_read_b128 v[188:191], v198
	ds_read_b128 v[156:159], v134
	ds_read_b128 v[192:195], v198 offset:2048
	ds_read_b128 v[160:163], v134 offset:2048
	ds_read_b128 v[164:167], v134 offset:4096
	ds_read_b128 v[168:171], v134 offset:6144
; #define G_LOADA(kt_) { _Pragma("unroll") for (int i = 0; i < 4; ++i) ra[i] = al(lrow + 64 * i, (kt_) * 64 + lck * 8); }
; #define G_LOADB(kt_) { _Pragma("unroll") for (int i = 0; i < 4; ++i) rb[i] = bl(lrow + 64 * i, (kt_) * 64 + lck * 8); }
; #define G_STOREA(buf_) { bf16_t* nA = sA + (buf_) * 256 * GLD; _Pragma("unroll") for (int i = 0; i < 4; ++i) *(u32x4*)(nA + (lrow + 64 * i) * GLD + lck * 8) = ra[i]; }
; #define G_STOREB(buf_) { bf16_t* nB = sB + (buf_) * 256 * GLD; _Pragma("unroll") for (int i = 0; i < 4; ++i) *(u32x4*)(nB + (lrow + 64 * i) * GLD + lck * 8) = rb[i]; }
; template <class AL, class BL, class EP>
; DI void gemm_tile256(AL al, BL bl, EP ep, int K, char* smem) {
;     ...
;   G_LOADA(0); G_LOADB(0);
;   __syncthreads();
;   G_STOREA(0); G_STOREB(0);
;   if (KT > 1) G_LOADB(1);
;   __syncthreads();
;   for (int kt = 0; kt < KT; kt += 2) {
;     G_STEP(0, kt);
;     if (kt + 1 >= KT) break;
;     G_STEP(1, kt + 1);
;   }
.Lgk_ph6_loop:
	s_waitcnt lgkmcnt(0)
	v_mfma_f32_32x32x16_bf16 v[112:127], v[188:191], v[156:159], v[112:127]
	ds_read_b128 v[200:203], v199
	ds_read_b128 v[172:175], v155
	v_mfma_f32_32x32x16_bf16 v[96:111], v[192:195], v[156:159], v[96:111]
	ds_read_b128 v[204:207], v199 offset:2048
	ds_read_b128 v[176:179], v155 offset:2048
	v_mfma_f32_32x32x16_bf16 v[80:95], v[188:191], v[160:163], v[80:95]
	ds_read_b128 v[180:183], v155 offset:4096
	ds_read_b128 v[184:187], v155 offset:6144
	v_mfma_f32_32x32x16_bf16 v[64:79], v[192:195], v[160:163], v[64:79]
	s_add_u32 m0, s29, 0x22000
	s_nop 0
	global_load_lds_dwordx4 v[218:219], off
	v_lshl_add_u64 v[218:219], v[218:219], 0, s[10:11]
	v_mfma_f32_32x32x16_bf16 v[48:63], v[188:191], v[164:167], v[48:63]
	v_mfma_f32_32x32x16_bf16 v[32:47], v[192:195], v[164:167], v[32:47]
	v_mfma_f32_32x32x16_bf16 v[16:31], v[188:191], v[168:171], v[16:31]
	v_mfma_f32_32x32x16_bf16 v[0:15], v[192:195], v[168:171], v[0:15]
	s_add_u32 m0, s29, 0x26000
	s_nop 0
	global_load_lds_dwordx4 v[222:223], off
	v_lshl_add_u64 v[222:223], v[222:223], 0, s[10:11]
	s_waitcnt lgkmcnt(0)
	s_waitcnt vmcnt(12)
	s_barrier
	s_waitcnt lgkmcnt(0)
	v_mfma_f32_32x32x16_bf16 v[112:127], v[200:203], v[172:175], v[112:127]
	ds_read_b128 v[188:191], v198 offset:32768
	ds_read_b128 v[156:159], v134 offset:32768
	v_mfma_f32_32x32x16_bf16 v[96:111], v[204:207], v[172:175], v[96:111]
	ds_read_b128 v[192:195], v198 offset:34816
	ds_read_b128 v[160:163], v134 offset:34816
	v_mfma_f32_32x32x16_bf16 v[80:95], v[200:203], v[176:179], v[80:95]
	ds_read_b128 v[164:167], v134 offset:36864
	ds_read_b128 v[168:171], v134 offset:38912
	v_mfma_f32_32x32x16_bf16 v[64:79], v[204:207], v[176:179], v[64:79]
	s_add_u32 m0, s29, 0x0
	s_nop 0
	global_load_lds_dwordx4 v[216:217], off
	v_lshl_add_u64 v[216:217], v[216:217], 0, s[10:11]
	v_mfma_f32_32x32x16_bf16 v[48:63], v[200:203], v[180:183], v[48:63]
	v_mfma_f32_32x32x16_bf16 v[32:47], v[204:207], v[180:183], v[32:47]
	v_mfma_f32_32x32x16_bf16 v[16:31], v[200:203], v[184:187], v[16:31]
	v_mfma_f32_32x32x16_bf16 v[0:15], v[204:207], v[184:187], v[0:15]
	s_add_u32 m0, s29, 0x4000
	s_nop 0
	global_load_lds_dwordx4 v[220:221], off
	v_lshl_add_u64 v[220:221], v[220:221], 0, s[10:11]
	s_waitcnt lgkmcnt(0)
	v_mfma_f32_32x32x16_bf16 v[112:127], v[188:191], v[156:159], v[112:127]
	ds_read_b128 v[200:203], v199 offset:32768
	ds_read_b128 v[172:175], v155 offset:32768
	v_mfma_f32_32x32x16_bf16 v[96:111], v[192:195], v[156:159], v[96:111]
	ds_read_b128 v[204:207], v199 offset:34816
	ds_read_b128 v[176:179], v155 offset:34816
	v_mfma_f32_32x32x16_bf16 v[80:95], v[188:191], v[160:163], v[80:95]
	ds_read_b128 v[180:183], v155 offset:36864
	ds_read_b128 v[184:187], v155 offset:38912
	v_mfma_f32_32x32x16_bf16 v[64:79], v[192:195], v[160:163], v[64:79]
	s_add_u32 m0, s29, 0x2000
	s_nop 0
	global_load_lds_dwordx4 v[218:219], off
	v_lshl_add_u64 v[218:219], v[218:219], 0, s[10:11]
	v_mfma_f32_32x32x16_bf16 v[48:63], v[188:191], v[164:167], v[48:63]
	v_mfma_f32_32x32x16_bf16 v[32:47], v[192:195], v[164:167], v[32:47]
	v_mfma_f32_32x32x16_bf16 v[16:31], v[188:191], v[168:171], v[16:31]
	v_mfma_f32_32x32x16_bf16 v[0:15], v[192:195], v[168:171], v[0:15]
	s_add_u32 m0, s29, 0x6000
	s_nop 0
	global_load_lds_dwordx4 v[222:223], off
	v_lshl_add_u64 v[222:223], v[222:223], 0, s[10:11]
	s_waitcnt lgkmcnt(0)
	s_waitcnt vmcnt(12)
	s_barrier
	s_waitcnt lgkmcnt(0)
	v_mfma_f32_32x32x16_bf16 v[112:127], v[200:203], v[172:175], v[112:127]
	ds_read_b128 v[188:191], v210
	ds_read_b128 v[156:159], v208
	v_mfma_f32_32x32x16_bf16 v[96:111], v[204:207], v[172:175], v[96:111]
	ds_read_b128 v[192:195], v210 offset:2048
	ds_read_b128 v[160:163], v208 offset:2048
	v_mfma_f32_32x32x16_bf16 v[80:95], v[200:203], v[176:179], v[80:95]
	ds_read_b128 v[164:167], v208 offset:4096
	ds_read_b128 v[168:171], v208 offset:6144
	v_mfma_f32_32x32x16_bf16 v[64:79], v[204:207], v[176:179], v[64:79]
	s_add_u32 m0, s29, 0x8000
	s_nop 0
	global_load_lds_dwordx4 v[216:217], off
	v_lshl_add_u64 v[216:217], v[216:217], 0, s[10:11]
	v_mfma_f32_32x32x16_bf16 v[48:63], v[200:203], v[180:183], v[48:63]
	v_mfma_f32_32x32x16_bf16 v[32:47], v[204:207], v[180:183], v[32:47]
	v_mfma_f32_32x32x16_bf16 v[16:31], v[200:203], v[184:187], v[16:31]
	v_mfma_f32_32x32x16_bf16 v[0:15], v[204:207], v[184:187], v[0:15]
	s_add_u32 m0, s29, 0xc000
	s_nop 0
	global_load_lds_dwordx4 v[220:221], off
	v_lshl_add_u64 v[220:221], v[220:221], 0, s[10:11]
	s_waitcnt lgkmcnt(0)
	v_mfma_f32_32x32x16_bf16 v[112:127], v[188:191], v[156:159], v[112:127]
	ds_read_b128 v[200:203], v211
	ds_read_b128 v[172:175], v209
	v_mfma_f32_32x32x16_bf16 v[96:111], v[192:195], v[156:159], v[96:111]
	ds_read_b128 v[204:207], v211 offset:2048
	ds_read_b128 v[176:179], v209 offset:2048
	v_mfma_f32_32x32x16_bf16 v[80:95], v[188:191], v[160:163], v[80:95]
	ds_read_b128 v[180:183], v209 offset:4096
	ds_read_b128 v[184:187], v209 offset:6144
	v_mfma_f32_32x32x16_bf16 v[64:79], v[192:195], v[160:163], v[64:79]
	s_add_u32 m0, s29, 0xa000
	s_nop 0
	global_load_lds_dwordx4 v[218:219], off
	v_lshl_add_u64 v[218:219], v[218:219], 0, s[10:11]
	v_mfma_f32_32x32x16_bf16 v[48:63], v[188:191], v[164:167], v[48:63]
	v_mfma_f32_32x32x16_bf16 v[32:47], v[192:195], v[164:167], v[32:47]
	v_mfma_f32_32x32x16_bf16 v[16:31], v[188:191], v[168:171], v[16:31]
	v_mfma_f32_32x32x16_bf16 v[0:15], v[192:195], v[168:171], v[0:15]
	s_add_u32 m0, s29, 0xe000
	s_nop 0
	global_load_lds_dwordx4 v[222:223], off
	v_lshl_add_u64 v[222:223], v[222:223], 0, s[10:11]
	s_waitcnt lgkmcnt(0)
	s_waitcnt vmcnt(12)
	s_barrier
; #define G_LOADA(kt_) { _Pragma("unroll") for (int i = 0; i < 4; ++i) ra[i] = al(lrow + 64 * i, (kt_) * 64 + lck * 8); }
; #define G_LOADB(kt_) { _Pragma("unroll") for (int i = 0; i < 4; ++i) rb[i] = bl(lrow + 64 * i, (kt_) * 64 + lck * 8); }
; #define G_STOREA(buf_) { bf16_t* nA = sA + (buf_) * 256 * GLD; _Pragma("unroll") for (int i = 0; i < 4; ++i) *(u32x4*)(nA + (lrow + 64 * i) * GLD + lck * 8) = ra[i]; }
; #define G_STOREB(buf_) { bf16_t* nB = sB + (buf_) * 256 * GLD; _Pragma("unroll") for (int i = 0; i < 4; ++i) *(u32x4*)(nB + (lrow + 64 * i) * GLD + lck * 8) = rb[i]; }
; template <class AL, class BL, class EP>
; DI void gemm_tile256(AL al, BL bl, EP ep, int K, char* smem) {
;     ...
;   G_LOADA(0); G_LOADB(0);
;   __syncthreads();
;   G_STOREA(0); G_STOREB(0);
;   if (KT > 1) G_LOADB(1);
;   __syncthreads();
;   for (int kt = 0; kt < KT; kt += 2) {
;     G_STEP(0, kt);
;     if (kt + 1 >= KT) break;
;     G_STEP(1, kt + 1);
;   }
	s_waitcnt lgkmcnt(0)
	v_mfma_f32_32x32x16_bf16 v[112:127], v[200:203], v[172:175], v[112:127]
	ds_read_b128 v[188:191], v210 offset:32768
	ds_read_b128 v[156:159], v208 offset:32768
	v_mfma_f32_32x32x16_bf16 v[96:111], v[204:207], v[172:175], v[96:111]
	ds_read_b128 v[192:195], v210 offset:34816
	ds_read_b128 v[160:163], v208 offset:34816
	v_mfma_f32_32x32x16_bf16 v[80:95], v[200:203], v[176:179], v[80:95]
	ds_read_b128 v[164:167], v208 offset:36864
	ds_read_b128 v[168:171], v208 offset:38912
	v_mfma_f32_32x32x16_bf16 v[64:79], v[204:207], v[176:179], v[64:79]
	s_add_u32 m0, s29, 0x10000
	s_nop 0
	global_load_lds_dwordx4 v[216:217], off
	v_lshl_add_u64 v[216:217], v[216:217], 0, s[10:11]
	v_mfma_f32_32x32x16_bf16 v[48:63], v[200:203], v[180:183], v[48:63]
	v_mfma_f32_32x32x16_bf16 v[32:47], v[204:207], v[180:183], v[32:47]
	v_mfma_f32_32x32x16_bf16 v[16:31], v[200:203], v[184:187], v[16:31]
	v_mfma_f32_32x32x16_bf16 v[0:15], v[204:207], v[184:187], v[0:15]
	s_add_u32 m0, s29, 0x14000
	s_nop 0
	global_load_lds_dwordx4 v[220:221], off
	v_lshl_add_u64 v[220:221], v[220:221], 0, s[10:11]
	s_waitcnt lgkmcnt(0)
	v_mfma_f32_32x32x16_bf16 v[112:127], v[188:191], v[156:159], v[112:127]
	ds_read_b128 v[200:203], v211 offset:32768
	ds_read_b128 v[172:175], v209 offset:32768
	v_mfma_f32_32x32x16_bf16 v[96:111], v[192:195], v[156:159], v[96:111]
	ds_read_b128 v[204:207], v211 offset:34816
	ds_read_b128 v[176:179], v209 offset:34816
	v_mfma_f32_32x32x16_bf16 v[80:95], v[188:191], v[160:163], v[80:95]
	ds_read_b128 v[180:183], v209 offset:36864
	ds_read_b128 v[184:187], v209 offset:38912
	v_mfma_f32_32x32x16_bf16 v[64:79], v[192:195], v[160:163], v[64:79]
	s_add_u32 m0, s29, 0x12000
	s_nop 0
	global_load_lds_dwordx4 v[218:219], off
	v_lshl_add_u64 v[218:219], v[218:219], 0, s[10:11]
	v_mfma_f32_32x32x16_bf16 v[48:63], v[188:191], v[164:167], v[48:63]
	v_mfma_f32_32x32x16_bf16 v[32:47], v[192:195], v[164:167], v[32:47]
	v_mfma_f32_32x32x16_bf16 v[16:31], v[188:191], v[168:171], v[16:31]
	v_mfma_f32_32x32x16_bf16 v[0:15], v[192:195], v[168:171], v[0:15]
	s_add_u32 m0, s29, 0x16000
	s_nop 0
	global_load_lds_dwordx4 v[222:223], off
	v_lshl_add_u64 v[222:223], v[222:223], 0, s[10:11]
	s_waitcnt lgkmcnt(0)
	s_waitcnt vmcnt(12)
	s_barrier
	s_waitcnt lgkmcnt(0)
	v_mfma_f32_32x32x16_bf16 v[112:127], v[200:203], v[172:175], v[112:127]
	ds_read_b128 v[188:191], v214
	ds_read_b128 v[156:159], v212
	v_mfma_f32_32x32x16_bf16 v[96:111], v[204:207], v[172:175], v[96:111]
	ds_read_b128 v[192:195], v214 offset:2048
	ds_read_b128 v[160:163], v212 offset:2048
	v_mfma_f32_32x32x16_bf16 v[80:95], v[200:203], v[176:179], v[80:95]
	ds_read_b128 v[164:167], v212 offset:4096
	ds_read_b128 v[168:171], v212 offset:6144
	v_mfma_f32_32x32x16_bf16 v[64:79], v[204:207], v[176:179], v[64:79]
	s_add_u32 m0, s29, 0x18000
	s_nop 0
	global_load_lds_dwordx4 v[216:217], off
	v_lshl_add_u64 v[216:217], v[216:217], 0, s[10:11]
	v_mfma_f32_32x32x16_bf16 v[48:63], v[200:203], v[180:183], v[48:63]
	v_mfma_f32_32x32x16_bf16 v[32:47], v[204:207], v[180:183], v[32:47]
	v_mfma_f32_32x32x16_bf16 v[16:31], v[200:203], v[184:187], v[16:31]
	v_mfma_f32_32x32x16_bf16 v[0:15], v[204:207], v[184:187], v[0:15]
	s_add_u32 m0, s29, 0x1c000
	s_nop 0
	global_load_lds_dwordx4 v[220:221], off
	v_lshl_add_u64 v[220:221], v[220:221], 0, s[10:11]
	s_waitcnt lgkmcnt(0)
	v_mfma_f32_32x32x16_bf16 v[112:127], v[188:191], v[156:159], v[112:127]
	ds_read_b128 v[200:203], v215
	ds_read_b128 v[172:175], v213
	v_mfma_f32_32x32x16_bf16 v[96:111], v[192:195], v[156:159], v[96:111]
	ds_read_b128 v[204:207], v215 offset:2048
	ds_read_b128 v[176:179], v213 offset:2048
	v_mfma_f32_32x32x16_bf16 v[80:95], v[188:191], v[160:163], v[80:95]
	ds_read_b128 v[180:183], v213 offset:4096
	ds_read_b128 v[184:187], v213 offset:6144
	v_mfma_f32_32x32x16_bf16 v[64:79], v[192:195], v[160:163], v[64:79]
	s_add_u32 m0, s29, 0x1a000
	s_nop 0
	global_load_lds_dwordx4 v[218:219], off
	v_lshl_add_u64 v[218:219], v[218:219], 0, s[10:11]
	v_mfma_f32_32x32x16_bf16 v[48:63], v[188:191], v[164:167], v[48:63]
	v_mfma_f32_32x32x16_bf16 v[32:47], v[192:195], v[164:167], v[32:47]
	v_mfma_f32_32x32x16_bf16 v[16:31], v[188:191], v[168:171], v[16:31]
	v_mfma_f32_32x32x16_bf16 v[0:15], v[192:195], v[168:171], v[0:15]
	s_add_u32 m0, s29, 0x1e000
	s_nop 0
	global_load_lds_dwordx4 v[222:223], off
	v_lshl_add_u64 v[222:223], v[222:223], 0, s[10:11]
	s_waitcnt lgkmcnt(0)
	s_waitcnt vmcnt(12)
	s_barrier
	s_waitcnt lgkmcnt(0)
	v_mfma_f32_32x32x16_bf16 v[112:127], v[200:203], v[172:175], v[112:127]
	ds_read_b128 v[188:191], v198
	ds_read_b128 v[156:159], v134
	v_mfma_f32_32x32x16_bf16 v[96:111], v[204:207], v[172:175], v[96:111]
	ds_read_b128 v[192:195], v198 offset:2048
	ds_read_b128 v[160:163], v134 offset:2048
	v_mfma_f32_32x32x16_bf16 v[80:95], v[200:203], v[176:179], v[80:95]
	ds_read_b128 v[164:167], v134 offset:4096
	ds_read_b128 v[168:171], v134 offset:6144
	v_mfma_f32_32x32x16_bf16 v[64:79], v[204:207], v[176:179], v[64:79]
	s_add_u32 m0, s29, 0x20000
	s_nop 0
	global_load_lds_dwordx4 v[216:217], off
	v_lshl_add_u64 v[216:217], v[216:217], 0, s[10:11]
	v_mfma_f32_32x32x16_bf16 v[48:63], v[200:203], v[180:183], v[48:63]
	v_mfma_f32_32x32x16_bf16 v[32:47], v[204:207], v[180:183], v[32:47]
	v_mfma_f32_32x32x16_bf16 v[16:31], v[200:203], v[184:187], v[16:31]
	v_mfma_f32_32x32x16_bf16 v[0:15], v[204:207], v[184:187], v[0:15]
	s_add_u32 m0, s29, 0x24000
	s_nop 0
	global_load_lds_dwordx4 v[220:221], off
	v_lshl_add_u64 v[220:221], v[220:221], 0, s[10:11]
	s_sub_u32 s30, s30, 1
	s_cmp_lg_u32 s30, 0
	s_cbranch_scc1 .Lgk_ph6_loop
; #define G_LOADA(kt_) { _Pragma("unroll") for (int i = 0; i < 4; ++i) ra[i] = al(lrow + 64 * i, (kt_) * 64 + lck * 8); }
; #define G_LOADB(kt_) { _Pragma("unroll") for (int i = 0; i < 4; ++i) rb[i] = bl(lrow + 64 * i, (kt_) * 64 + lck * 8); }
; #define G_STOREA(buf_) { bf16_t* nA = sA + (buf_) * 256 * GLD; _Pragma("unroll") for (int i = 0; i < 4; ++i) *(u32x4*)(nA + (lrow + 64 * i) * GLD + lck * 8) = ra[i]; }
; #define G_STOREB(buf_) { bf16_t* nB = sB + (buf_) * 256 * GLD; _Pragma("unroll") for (int i = 0; i < 4; ++i) *(u32x4*)(nB + (lrow + 64 * i) * GLD + lck * 8) = rb[i]; }
; template <class AL, class BL, class EP>
; DI void gemm_tile256(AL al, BL bl, EP ep, int K, char* smem) {
;     ...
;   G_LOADA(0); G_LOADB(0);
;   __syncthreads();
;   G_STOREA(0); G_STOREB(0);
;   if (KT > 1) G_LOADB(1);
;   __syncthreads();
;   for (int kt = 0; kt < KT; kt += 2) {
;     G_STEP(0, kt);
;     if (kt + 1 >= KT) break;
;     G_STEP(1, kt + 1);
;   }
	s_waitcnt lgkmcnt(0)
	v_mfma_f32_32x32x16_bf16 v[112:127], v[188:191], v[156:159], v[112:127]
	ds_read_b128 v[200:203], v199
	ds_read_b128 v[172:175], v155
	v_mfma_f32_32x32x16_bf16 v[96:111], v[192:195], v[156:159], v[96:111]
	ds_read_b128 v[204:207], v199 offset:2048
	ds_read_b128 v[176:179], v155 offset:2048
	v_mfma_f32_32x32x16_bf16 v[80:95], v[188:191], v[160:163], v[80:95]
	ds_read_b128 v[180:183], v155 offset:4096
	ds_read_b128 v[184:187], v155 offset:6144
	v_mfma_f32_32x32x16_bf16 v[64:79], v[192:195], v[160:163], v[64:79]
	s_add_u32 m0, s29, 0x22000
	s_nop 0
	global_load_lds_dwordx4 v[218:219], off
	v_lshl_add_u64 v[218:219], v[218:219], 0, s[10:11]
	v_mfma_f32_32x32x16_bf16 v[48:63], v[188:191], v[164:167], v[48:63]
	v_mfma_f32_32x32x16_bf16 v[32:47], v[192:195], v[164:167], v[32:47]
	v_mfma_f32_32x32x16_bf16 v[16:31], v[188:191], v[168:171], v[16:31]
	v_mfma_f32_32x32x16_bf16 v[0:15], v[192:195], v[168:171], v[0:15]
	s_add_u32 m0, s29, 0x26000
	s_nop 0
	global_load_lds_dwordx4 v[222:223], off
	v_lshl_add_u64 v[222:223], v[222:223], 0, s[10:11]
	s_waitcnt lgkmcnt(0)
	s_waitcnt vmcnt(12)
	s_barrier
	s_waitcnt lgkmcnt(0)
	v_mfma_f32_32x32x16_bf16 v[112:127], v[200:203], v[172:175], v[112:127]
	ds_read_b128 v[188:191], v198 offset:32768
	ds_read_b128 v[156:159], v134 offset:32768
	v_mfma_f32_32x32x16_bf16 v[96:111], v[204:207], v[172:175], v[96:111]
	ds_read_b128 v[192:195], v198 offset:34816
	ds_read_b128 v[160:163], v134 offset:34816
	v_mfma_f32_32x32x16_bf16 v[80:95], v[200:203], v[176:179], v[80:95]
	ds_read_b128 v[164:167], v134 offset:36864
	ds_read_b128 v[168:171], v134 offset:38912
	v_mfma_f32_32x32x16_bf16 v[64:79], v[204:207], v[176:179], v[64:79]
	s_add_u32 m0, s29, 0x0
	s_nop 0
	global_load_lds_dwordx4 v[216:217], off
	v_lshl_add_u64 v[216:217], v[216:217], 0, s[10:11]
	v_mfma_f32_32x32x16_bf16 v[48:63], v[200:203], v[180:183], v[48:63]
	v_mfma_f32_32x32x16_bf16 v[32:47], v[204:207], v[180:183], v[32:47]
	v_mfma_f32_32x32x16_bf16 v[16:31], v[200:203], v[184:187], v[16:31]
	v_mfma_f32_32x32x16_bf16 v[0:15], v[204:207], v[184:187], v[0:15]
	s_add_u32 m0, s29, 0x4000
	s_nop 0
	global_load_lds_dwordx4 v[220:221], off
	v_lshl_add_u64 v[220:221], v[220:221], 0, s[10:11]
	s_waitcnt lgkmcnt(0)
	v_mfma_f32_32x32x16_bf16 v[112:127], v[188:191], v[156:159], v[112:127]
	ds_read_b128 v[200:203], v199 offset:32768
	ds_read_b128 v[172:175], v155 offset:32768
	v_mfma_f32_32x32x16_bf16 v[96:111], v[192:195], v[156:159], v[96:111]
	ds_read_b128 v[204:207], v199 offset:34816
	ds_read_b128 v[176:179], v155 offset:34816
	v_mfma_f32_32x32x16_bf16 v[80:95], v[188:191], v[160:163], v[80:95]
	ds_read_b128 v[180:183], v155 offset:36864
	ds_read_b128 v[184:187], v155 offset:38912
	v_mfma_f32_32x32x16_bf16 v[64:79], v[192:195], v[160:163], v[64:79]
	s_add_u32 m0, s29, 0x2000
	s_nop 0
	global_load_lds_dwordx4 v[218:219], off
	v_lshl_add_u64 v[218:219], v[218:219], 0, s[10:11]
	v_mfma_f32_32x32x16_bf16 v[48:63], v[188:191], v[164:167], v[48:63]
	v_mfma_f32_32x32x16_bf16 v[32:47], v[192:195], v[164:167], v[32:47]
	v_mfma_f32_32x32x16_bf16 v[16:31], v[188:191], v[168:171], v[16:31]
	v_mfma_f32_32x32x16_bf16 v[0:15], v[192:195], v[168:171], v[0:15]
	s_add_u32 m0, s29, 0x6000
	s_nop 0
	global_load_lds_dwordx4 v[222:223], off
	v_lshl_add_u64 v[222:223], v[222:223], 0, s[10:11]
	s_waitcnt lgkmcnt(0)
	s_waitcnt vmcnt(12)
	s_barrier
	s_waitcnt lgkmcnt(0)
	v_mfma_f32_32x32x16_bf16 v[112:127], v[200:203], v[172:175], v[112:127]
	ds_read_b128 v[188:191], v210
	ds_read_b128 v[156:159], v208
	v_mfma_f32_32x32x16_bf16 v[96:111], v[204:207], v[172:175], v[96:111]
	ds_read_b128 v[192:195], v210 offset:2048
	ds_read_b128 v[160:163], v208 offset:2048
	v_mfma_f32_32x32x16_bf16 v[80:95], v[200:203], v[176:179], v[80:95]
	ds_read_b128 v[164:167], v208 offset:4096
	ds_read_b128 v[168:171], v208 offset:6144
	v_mfma_f32_32x32x16_bf16 v[64:79], v[204:207], v[176:179], v[64:79]
	s_add_u32 m0, s29, 0x8000
	s_nop 0
	global_load_lds_dwordx4 v[216:217], off
	v_lshl_add_u64 v[216:217], v[216:217], 0, s[10:11]
	v_mfma_f32_32x32x16_bf16 v[48:63], v[200:203], v[180:183], v[48:63]
	v_mfma_f32_32x32x16_bf16 v[32:47], v[204:207], v[180:183], v[32:47]
	v_mfma_f32_32x32x16_bf16 v[16:31], v[200:203], v[184:187], v[16:31]
	v_mfma_f32_32x32x16_bf16 v[0:15], v[204:207], v[184:187], v[0:15]
	s_add_u32 m0, s29, 0xc000
	s_nop 0
	global_load_lds_dwordx4 v[220:221], off
	v_lshl_add_u64 v[220:221], v[220:221], 0, s[10:11]
	s_waitcnt lgkmcnt(0)
	v_mfma_f32_32x32x16_bf16 v[112:127], v[188:191], v[156:159], v[112:127]
	ds_read_b128 v[200:203], v211
	ds_read_b128 v[172:175], v209
	v_mfma_f32_32x32x16_bf16 v[96:111], v[192:195], v[156:159], v[96:111]
	ds_read_b128 v[204:207], v211 offset:2048
	ds_read_b128 v[176:179], v209 offset:2048
	v_mfma_f32_32x32x16_bf16 v[80:95], v[188:191], v[160:163], v[80:95]
	ds_read_b128 v[180:183], v209 offset:4096
	ds_read_b128 v[184:187], v209 offset:6144
	v_mfma_f32_32x32x16_bf16 v[64:79], v[192:195], v[160:163], v[64:79]
	s_add_u32 m0, s29, 0xa000
	s_nop 0
	global_load_lds_dwordx4 v[218:219], off
	v_lshl_add_u64 v[218:219], v[218:219], 0, s[10:11]
	v_mfma_f32_32x32x16_bf16 v[48:63], v[188:191], v[164:167], v[48:63]
	v_mfma_f32_32x32x16_bf16 v[32:47], v[192:195], v[164:167], v[32:47]
	v_mfma_f32_32x32x16_bf16 v[16:31], v[188:191], v[168:171], v[16:31]
	v_mfma_f32_32x32x16_bf16 v[0:15], v[192:195], v[168:171], v[0:15]
	s_add_u32 m0, s29, 0xe000
	s_nop 0
	global_load_lds_dwordx4 v[222:223], off
	v_lshl_add_u64 v[222:223], v[222:223], 0, s[10:11]
	s_waitcnt lgkmcnt(0)
	s_waitcnt vmcnt(12)
	s_barrier
; #define G_LOADA(kt_) { _Pragma("unroll") for (int i = 0; i < 4; ++i) ra[i] = al(lrow + 64 * i, (kt_) * 64 + lck * 8); }
; #define G_LOADB(kt_) { _Pragma("unroll") for (int i = 0; i < 4; ++i) rb[i] = bl(lrow + 64 * i, (kt_) * 64 + lck * 8); }
; #define G_STOREA(buf_) { bf16_t* nA = sA + (buf_) * 256 * GLD; _Pragma("unroll") for (int i = 0; i < 4; ++i) *(u32x4*)(nA + (lrow + 64 * i) * GLD + lck * 8) = ra[i]; }
; #define G_STOREB(buf_) { bf16_t* nB = sB + (buf_) * 256 * GLD; _Pragma("unroll") for (int i = 0; i < 4; ++i) *(u32x4*)(nB + (lrow + 64 * i) * GLD + lck * 8) = rb[i]; }
; template <class AL, class BL, class EP>
; DI void gemm_tile256(AL al, BL bl, EP ep, int K, char* smem) {
;     ...
;   G_LOADA(0); G_LOADB(0);
;   __syncthreads();
;   G_STOREA(0); G_STOREB(0);
;   if (KT > 1) G_LOADB(1);
;   __syncthreads();
;   for (int kt = 0; kt < KT; kt += 2) {
;     G_STEP(0, kt);
;     if (kt + 1 >= KT) break;
;     G_STEP(1, kt + 1);
;   }
	s_waitcnt lgkmcnt(0)
	v_mfma_f32_32x32x16_bf16 v[112:127], v[200:203], v[172:175], v[112:127]
	ds_read_b128 v[188:191], v210 offset:32768
	ds_read_b128 v[156:159], v208 offset:32768
	v_mfma_f32_32x32x16_bf16 v[96:111], v[204:207], v[172:175], v[96:111]
	ds_read_b128 v[192:195], v210 offset:34816
	ds_read_b128 v[160:163], v208 offset:34816
	v_mfma_f32_32x32x16_bf16 v[80:95], v[200:203], v[176:179], v[80:95]
	ds_read_b128 v[164:167], v208 offset:36864
	ds_read_b128 v[168:171], v208 offset:38912
	v_mfma_f32_32x32x16_bf16 v[64:79], v[204:207], v[176:179], v[64:79]
	v_mfma_f32_32x32x16_bf16 v[48:63], v[200:203], v[180:183], v[48:63]
	v_mfma_f32_32x32x16_bf16 v[32:47], v[204:207], v[180:183], v[32:47]
	v_mfma_f32_32x32x16_bf16 v[16:31], v[200:203], v[184:187], v[16:31]
	v_mfma_f32_32x32x16_bf16 v[0:15], v[204:207], v[184:187], v[0:15]
	s_waitcnt lgkmcnt(0)
	v_mfma_f32_32x32x16_bf16 v[112:127], v[188:191], v[156:159], v[112:127]
	ds_read_b128 v[200:203], v211 offset:32768
	ds_read_b128 v[172:175], v209 offset:32768
	v_mfma_f32_32x32x16_bf16 v[96:111], v[192:195], v[156:159], v[96:111]
	ds_read_b128 v[204:207], v211 offset:34816
	ds_read_b128 v[176:179], v209 offset:34816
	v_mfma_f32_32x32x16_bf16 v[80:95], v[188:191], v[160:163], v[80:95]
	ds_read_b128 v[180:183], v209 offset:36864
	ds_read_b128 v[184:187], v209 offset:38912
	v_mfma_f32_32x32x16_bf16 v[64:79], v[192:195], v[160:163], v[64:79]
	v_mfma_f32_32x32x16_bf16 v[48:63], v[188:191], v[164:167], v[48:63]
	v_mfma_f32_32x32x16_bf16 v[32:47], v[192:195], v[164:167], v[32:47]
	v_mfma_f32_32x32x16_bf16 v[16:31], v[188:191], v[168:171], v[16:31]
	v_mfma_f32_32x32x16_bf16 v[0:15], v[192:195], v[168:171], v[0:15]
	s_waitcnt lgkmcnt(0)
	s_waitcnt vmcnt(8)
	s_barrier
	s_waitcnt lgkmcnt(0)
	v_mfma_f32_32x32x16_bf16 v[112:127], v[200:203], v[172:175], v[112:127]
	ds_read_b128 v[188:191], v214
	ds_read_b128 v[156:159], v212
	v_mfma_f32_32x32x16_bf16 v[96:111], v[204:207], v[172:175], v[96:111]
	ds_read_b128 v[192:195], v214 offset:2048
	ds_read_b128 v[160:163], v212 offset:2048
	v_mfma_f32_32x32x16_bf16 v[80:95], v[200:203], v[176:179], v[80:95]
	ds_read_b128 v[164:167], v212 offset:4096
	ds_read_b128 v[168:171], v212 offset:6144
	v_mfma_f32_32x32x16_bf16 v[64:79], v[204:207], v[176:179], v[64:79]
	v_mfma_f32_32x32x16_bf16 v[48:63], v[200:203], v[180:183], v[48:63]
	v_mfma_f32_32x32x16_bf16 v[32:47], v[204:207], v[180:183], v[32:47]
	v_mfma_f32_32x32x16_bf16 v[16:31], v[200:203], v[184:187], v[16:31]
	v_mfma_f32_32x32x16_bf16 v[0:15], v[204:207], v[184:187], v[0:15]
	s_waitcnt lgkmcnt(0)
	v_mfma_f32_32x32x16_bf16 v[112:127], v[188:191], v[156:159], v[112:127]
	ds_read_b128 v[200:203], v215
	ds_read_b128 v[172:175], v213
	v_mfma_f32_32x32x16_bf16 v[96:111], v[192:195], v[156:159], v[96:111]
	ds_read_b128 v[204:207], v215 offset:2048
	ds_read_b128 v[176:179], v213 offset:2048
	v_mfma_f32_32x32x16_bf16 v[80:95], v[188:191], v[160:163], v[80:95]
	ds_read_b128 v[180:183], v213 offset:4096
	ds_read_b128 v[184:187], v213 offset:6144
	v_mfma_f32_32x32x16_bf16 v[64:79], v[192:195], v[160:163], v[64:79]
	v_mfma_f32_32x32x16_bf16 v[48:63], v[188:191], v[164:167], v[48:63]
	v_mfma_f32_32x32x16_bf16 v[32:47], v[192:195], v[164:167], v[32:47]
	v_mfma_f32_32x32x16_bf16 v[16:31], v[188:191], v[168:171], v[16:31]
	v_mfma_f32_32x32x16_bf16 v[0:15], v[192:195], v[168:171], v[0:15]
	s_waitcnt lgkmcnt(0)
	s_waitcnt vmcnt(4)
	s_barrier
	s_waitcnt lgkmcnt(0)
	v_mfma_f32_32x32x16_bf16 v[112:127], v[200:203], v[172:175], v[112:127]
	ds_read_b128 v[188:191], v198
	ds_read_b128 v[156:159], v134
	v_mfma_f32_32x32x16_bf16 v[96:111], v[204:207], v[172:175], v[96:111]
	ds_read_b128 v[192:195], v198 offset:2048
	ds_read_b128 v[160:163], v134 offset:2048
	v_mfma_f32_32x32x16_bf16 v[80:95], v[200:203], v[176:179], v[80:95]
	ds_read_b128 v[164:167], v134 offset:4096
	ds_read_b128 v[168:171], v134 offset:6144
	v_mfma_f32_32x32x16_bf16 v[64:79], v[204:207], v[176:179], v[64:79]
	v_mfma_f32_32x32x16_bf16 v[48:63], v[200:203], v[180:183], v[48:63]
	v_mfma_f32_32x32x16_bf16 v[32:47], v[204:207], v[180:183], v[32:47]
	v_mfma_f32_32x32x16_bf16 v[16:31], v[200:203], v[184:187], v[16:31]
	v_mfma_f32_32x32x16_bf16 v[0:15], v[204:207], v[184:187], v[0:15]
	s_waitcnt lgkmcnt(0)
	v_mfma_f32_32x32x16_bf16 v[112:127], v[188:191], v[156:159], v[112:127]
	ds_read_b128 v[200:203], v199
	ds_read_b128 v[172:175], v155
	v_mfma_f32_32x32x16_bf16 v[96:111], v[192:195], v[156:159], v[96:111]
	ds_read_b128 v[204:207], v199 offset:2048
	ds_read_b128 v[176:179], v155 offset:2048
	v_mfma_f32_32x32x16_bf16 v[80:95], v[188:191], v[160:163], v[80:95]
	ds_read_b128 v[180:183], v155 offset:4096
	ds_read_b128 v[184:187], v155 offset:6144
	v_mfma_f32_32x32x16_bf16 v[64:79], v[192:195], v[160:163], v[64:79]
	v_mfma_f32_32x32x16_bf16 v[48:63], v[188:191], v[164:167], v[48:63]
	v_mfma_f32_32x32x16_bf16 v[32:47], v[192:195], v[164:167], v[32:47]
	v_mfma_f32_32x32x16_bf16 v[16:31], v[188:191], v[168:171], v[16:31]
	v_mfma_f32_32x32x16_bf16 v[0:15], v[192:195], v[168:171], v[0:15]
	s_waitcnt lgkmcnt(0)
	s_waitcnt vmcnt(0)
	s_barrier
; DI unsigned pack2(float a, float b) { f2_t f = {a, b}; bf2_t r = __builtin_convertvector(f, bf2_t); return __builtin_bit_cast(unsigned, r); }
; template <class AL, class BL, class EP>
; DI void gemm_tile256(AL al, BL bl, EP ep, int K, char* smem) {
;     ...
;         for (int g = 0; g < 4; ++g) {
;           u32x2 v = {pack2(acc[i][j][4 * g], acc[i][j][4 * g + 1]), pack2(acc[i][j][4 * g + 2], acc[i][j][4 * g + 3])};
;           *(u32x2*)(sCb + (128 * wm + 32 * i + r) * BLD + 64 * wn + 32 * j + 8 * g + 4 * h) = v;
;         }
;     __syncthreads();
	s_waitcnt lgkmcnt(0)
	v_mfma_f32_32x32x16_bf16 v[112:127], v[200:203], v[172:175], v[112:127]
	ds_read_b128 v[188:191], v198 offset:32768
	ds_read_b128 v[156:159], v134 offset:32768
	v_mfma_f32_32x32x16_bf16 v[96:111], v[204:207], v[172:175], v[96:111]
	ds_read_b128 v[192:195], v198 offset:34816
	ds_read_b128 v[160:163], v134 offset:34816
	v_mfma_f32_32x32x16_bf16 v[80:95], v[200:203], v[176:179], v[80:95]
	ds_read_b128 v[164:167], v134 offset:36864
	ds_read_b128 v[168:171], v134 offset:38912
	v_mfma_f32_32x32x16_bf16 v[64:79], v[204:207], v[176:179], v[64:79]
	v_mfma_f32_32x32x16_bf16 v[48:63], v[200:203], v[180:183], v[48:63]
	v_mfma_f32_32x32x16_bf16 v[32:47], v[204:207], v[180:183], v[32:47]
	v_mfma_f32_32x32x16_bf16 v[16:31], v[200:203], v[184:187], v[16:31]
	v_mfma_f32_32x32x16_bf16 v[0:15], v[204:207], v[184:187], v[0:15]
	s_waitcnt lgkmcnt(0)
	v_mfma_f32_32x32x16_bf16 v[112:127], v[188:191], v[156:159], v[112:127]
	ds_read_b128 v[200:203], v199 offset:32768
	ds_read_b128 v[172:175], v155 offset:32768
	v_mfma_f32_32x32x16_bf16 v[96:111], v[192:195], v[156:159], v[96:111]
	ds_read_b128 v[204:207], v199 offset:34816
	ds_read_b128 v[176:179], v155 offset:34816
	v_mfma_f32_32x32x16_bf16 v[80:95], v[188:191], v[160:163], v[80:95]
	ds_read_b128 v[180:183], v155 offset:36864
	ds_read_b128 v[184:187], v155 offset:38912
	v_mfma_f32_32x32x16_bf16 v[64:79], v[192:195], v[160:163], v[64:79]
	v_mfma_f32_32x32x16_bf16 v[48:63], v[188:191], v[164:167], v[48:63]
	v_mfma_f32_32x32x16_bf16 v[32:47], v[192:195], v[164:167], v[32:47]
	v_mfma_f32_32x32x16_bf16 v[16:31], v[188:191], v[168:171], v[16:31]
	v_mfma_f32_32x32x16_bf16 v[0:15], v[192:195], v[168:171], v[0:15]
	s_waitcnt lgkmcnt(0)
	s_waitcnt lgkmcnt(0)
	v_mfma_f32_32x32x16_bf16 v[112:127], v[200:203], v[172:175], v[112:127]
	v_mfma_f32_32x32x16_bf16 v[96:111], v[204:207], v[172:175], v[96:111]
	v_mfma_f32_32x32x16_bf16 v[80:95], v[200:203], v[176:179], v[80:95]
	v_mfma_f32_32x32x16_bf16 v[64:79], v[204:207], v[176:179], v[64:79]
	v_mfma_f32_32x32x16_bf16 v[48:63], v[200:203], v[180:183], v[48:63]
	v_mfma_f32_32x32x16_bf16 v[32:47], v[204:207], v[180:183], v[32:47]
	v_mfma_f32_32x32x16_bf16 v[16:31], v[200:203], v[184:187], v[16:31]
	v_mfma_f32_32x32x16_bf16 v[0:15], v[204:207], v[184:187], v[0:15]
	s_nop 15
	s_nop 3
	s_setprio 0
	s_waitcnt lgkmcnt(4)
	v_lshl_or_b32 v128, v135, 7, v154
	v_mad_u64_u32 v[132:133], s[0:1], v153, s21, v[128:129]
	s_waitcnt lgkmcnt(0)
	s_barrier
; DI unsigned pack2(float a, float b) { f2_t f = {a, b}; bf2_t r = __builtin_convertvector(f, bf2_t); return __builtin_bit_cast(unsigned, r); }
; DI int tid512() { int t = threadIdx_x_raw(); asm volatile("" : "+v"(t)); return t; }
; template <class AL, class BL, class EP>
; DI void gemm_tile256(AL al, BL bl, EP ep, int K, char* smem) {
;     ...
;         for (int g = 0; g < 4; ++g) {
;           u32x2 v = {pack2(acc[i][j][4 * g], acc[i][j][4 * g + 1]), pack2(acc[i][j][4 * g + 2], acc[i][j][4 * g + 3])};
;           *(u32x2*)(sCb + (128 * wm + 32 * i + r) * BLD + 64 * wn + 32 * j + 8 * g + 4 * h) = v;
;         }
;     __syncthreads();
;   DI void operator()(const bf16_t* sCb) const {
;     const int t = tid512(), hf = (t >> 3) & 1, c8 = (t & 7) * 8;
;     const int cb = c0 + 64 * hf;
;     const bf16_t* base = sCb + 128 * hf;
;     float w0[8], w1[8], w2[8];
;     ld8f(conv + cb + c8, w0); ld8f(conv + DFF + cb + c8, w1); ld8f(conv + 2 * DFF + cb + c8, w2);
;     for (int rr = t >> 4; rr < 254; rr += 32) {
;       const int row = rr + 1;
;       float gm[8], g0[8], gp[8], uu[8], v[8];
;       ld8b(base + (row - 1) * BLD + c8, gm); ld8b(base + row * BLD + c8, g0); ld8b(base + (row + 1) * BLD + c8, gp); ld8b(base + row * BLD + 64 + c8, uu);
; #pragma unroll
;       for (int j = 0; j < 8; ++j) v[j] = gelu_gate(w0[j] * gm[j] + w1[j] * g0[j] + w2[j] * gp[j], uu[j]);
;       store8(hid + ((size_t)mt * 256 + row) * DFF + cb + c8, v);
	v_lshlrev_b32_e32 v131, 7, v131
	v_bfe_u32 v200, v196, 3, 1
	v_lshlrev_b32_e32 v200, 6, v200
	v_or_b32_e32 v200, v200, v131
	v_ashrrev_i32_e32 v201, 31, v200
	v_lshlrev_b64 v[200:201], 2, v[200:201]
	v_lshlrev_b32_e32 v202, 3, v196
	v_and_b32_e32 v202, 56, v202
	v_lshlrev_b32_e32 v202, 2, v202
	v_mov_b32_e32 v203, 0
	v_lshl_add_u64 v[204:205], s[6:7], 0, v[200:201]
	v_lshl_add_u64 v[204:205], v[204:205], 0, v[202:203]
	v_lshl_add_u64 v[206:207], s[4:5], 0, v[200:201]
	v_lshl_add_u64 v[206:207], v[206:207], 0, v[202:203]
	v_lshl_add_u64 v[240:241], s[86:87], 0, v[200:201]
	v_lshl_add_u64 v[240:241], v[240:241], 0, v[202:203]
	global_load_dwordx4 v[208:211], v[204:205], off
	global_load_dwordx4 v[212:215], v[204:205], off offset:16
	global_load_dwordx4 v[216:219], v[206:207], off
	global_load_dwordx4 v[220:223], v[206:207], off offset:16
	global_load_dwordx4 v[224:227], v[240:241], off
	global_load_dwordx4 v[228:231], v[240:241], off offset:16
	s_nop 5
	v_cvt_pk_bf16_f32 v112, v112, v113
	v_cvt_pk_bf16_f32 v113, v114, v115
	v_cvt_pk_bf16_f32 v114, v116, v117
	v_cvt_pk_bf16_f32 v115, v118, v119
	ds_write2_b64 v132, v[112:113], v[114:115] offset1:2
	v_cvt_pk_bf16_f32 v112, v120, v121
	v_cvt_pk_bf16_f32 v113, v122, v123
	v_cvt_pk_bf16_f32 v96, v96, v97
	v_cvt_pk_bf16_f32 v97, v98, v99
	v_cvt_pk_bf16_f32 v98, v100, v101
	v_cvt_pk_bf16_f32 v99, v102, v103
	v_cvt_pk_bf16_f32 v114, v124, v125
	v_cvt_pk_bf16_f32 v115, v126, v127
	ds_write2_b64 v132, v[96:97], v[98:99] offset0:8 offset1:10
	s_nop 3
	v_cvt_pk_bf16_f32 v80, v80, v81
	v_cvt_pk_bf16_f32 v81, v82, v83
	v_cvt_pk_bf16_f32 v82, v84, v85
	v_cvt_pk_bf16_f32 v83, v86, v87
	v_add_u32_e32 v84, 0x4000, v132
	v_cvt_pk_bf16_f32 v96, v104, v105
	v_cvt_pk_bf16_f32 v97, v106, v107
	v_cvt_pk_bf16_f32 v64, v64, v65
	v_cvt_pk_bf16_f32 v65, v66, v67
	v_cvt_pk_bf16_f32 v66, v68, v69
	v_cvt_pk_bf16_f32 v67, v70, v71
	v_cvt_pk_bf16_f32 v98, v108, v109
	v_cvt_pk_bf16_f32 v99, v110, v111
	ds_write2_b64 v84, v[80:81], v[82:83] offset0:64 offset1:66
	s_nop 3
	v_cvt_pk_bf16_f32 v48, v48, v49
	v_cvt_pk_bf16_f32 v49, v50, v51
	v_cvt_pk_bf16_f32 v50, v52, v53
	v_cvt_pk_bf16_f32 v51, v54, v55
	v_add_u32_e32 v52, 0x8000, v132
	v_cvt_pk_bf16_f32 v80, v88, v89
	v_cvt_pk_bf16_f32 v81, v90, v91
	v_cvt_pk_bf16_f32 v32, v32, v33
	v_cvt_pk_bf16_f32 v33, v34, v35
	v_cvt_pk_bf16_f32 v34, v36, v37
	v_cvt_pk_bf16_f32 v35, v38, v39
	v_cvt_pk_bf16_f32 v82, v92, v93
	v_cvt_pk_bf16_f32 v83, v94, v95
	ds_write2_b64 v84, v[64:65], v[66:67] offset0:72 offset1:74
	s_nop 3
	v_cvt_pk_bf16_f32 v16, v16, v17
	v_cvt_pk_bf16_f32 v17, v18, v19
	v_cvt_pk_bf16_f32 v18, v20, v21
	v_cvt_pk_bf16_f32 v19, v22, v23
	v_add_u32_e32 v20, 0xc000, v132
	v_cvt_pk_bf16_f32 v64, v72, v73
	v_cvt_pk_bf16_f32 v65, v74, v75
	s_nop 0
	v_cvt_pk_bf16_f32 v0, v0, v1
	v_cvt_pk_bf16_f32 v1, v2, v3
	v_cvt_pk_bf16_f32 v2, v4, v5
	v_cvt_pk_bf16_f32 v3, v6, v7
	v_cvt_pk_bf16_f32 v66, v76, v77
	v_cvt_pk_bf16_f32 v67, v78, v79
	ds_write2_b64 v52, v[48:49], v[50:51] offset0:128 offset1:130
	v_cvt_pk_bf16_f32 v48, v56, v57
	v_cvt_pk_bf16_f32 v49, v58, v59
	v_cvt_pk_bf16_f32 v50, v60, v61
	v_cvt_pk_bf16_f32 v51, v62, v63
	ds_write2_b64 v52, v[32:33], v[34:35] offset0:136 offset1:138
	v_cvt_pk_bf16_f32 v32, v40, v41
	v_cvt_pk_bf16_f32 v33, v42, v43
	v_cvt_pk_bf16_f32 v34, v44, v45
	v_cvt_pk_bf16_f32 v35, v46, v47
	ds_write2_b64 v20, v[16:17], v[18:19] offset0:192 offset1:194
	v_cvt_pk_bf16_f32 v16, v24, v25
	v_cvt_pk_bf16_f32 v17, v26, v27
	v_cvt_pk_bf16_f32 v18, v28, v29
	v_cvt_pk_bf16_f32 v19, v30, v31
	ds_write2_b64 v20, v[0:1], v[2:3] offset0:200 offset1:202
	v_cvt_pk_bf16_f32 v0, v8, v9
	v_cvt_pk_bf16_f32 v1, v10, v11
	v_cvt_pk_bf16_f32 v2, v12, v13
	v_cvt_pk_bf16_f32 v3, v14, v15
	v_mov_b32_e32 v29, v196
	ds_write2_b64 v132, v[112:113], v[114:115] offset0:4 offset1:6
	ds_write2_b64 v132, v[96:97], v[98:99] offset0:12 offset1:14
	ds_write2_b64 v84, v[80:81], v[82:83] offset0:68 offset1:70
	ds_write2_b64 v84, v[64:65], v[66:67] offset0:76 offset1:78
	ds_write2_b64 v52, v[48:49], v[50:51] offset0:132 offset1:134
	ds_write2_b64 v52, v[32:33], v[34:35] offset0:140 offset1:142
	ds_write2_b64 v20, v[16:17], v[18:19] offset0:196 offset1:198
	ds_write2_b64 v20, v[0:1], v[2:3] offset0:204 offset1:206
	s_waitcnt lgkmcnt(0)
	s_barrier
	s_nop 0
	v_bfe_u32 v0, v29, 3, 1
	v_lshlrev_b32_e32 v30, 6, v0
	v_lshlrev_b32_e32 v1, 3, v29
	v_or_b32_e32 v24, v30, v131
	v_ashrrev_i32_e32 v26, 4, v29
	v_and_b32_e32 v27, 56, v1
	v_lshlrev_b32_e32 v28, 8, v0
	v_ashrrev_i32_e32 v25, 31, v24
	v_cmp_gt_i32_e32 vcc, s23, v26
	s_and_saveexec_b64 s[0:1], vcc
	s_cbranch_execz .LBB0_545
	v_lshlrev_b64 v[16:17], 2, v[24:25]
	v_lshl_add_u64 v[0:1], s[6:7], 0, v[16:17]
	v_lshlrev_b32_e32 v128, 2, v27
	v_lshl_add_u64 v[8:9], s[4:5], 0, v[16:17]
	v_lshl_add_u64 v[16:17], s[86:87], 0, v[16:17]
	v_lshl_add_u64 v[4:5], v[0:1], 0, v[128:129]
	v_lshl_add_u64 v[12:13], v[8:9], 0, v[128:129]
	v_lshl_add_u64 v[20:21], v[16:17], 0, v[128:129]
	s_waitcnt vmcnt(0)
	v_mov_b32_e32 v0, v208
	v_mov_b32_e32 v1, v209
	v_mov_b32_e32 v2, v210
	v_mov_b32_e32 v3, v211
	v_mov_b32_e32 v4, v212
	v_mov_b32_e32 v5, v213
	v_mov_b32_e32 v6, v214
	v_mov_b32_e32 v7, v215
	v_mov_b32_e32 v8, v216
	v_mov_b32_e32 v9, v217
	v_mov_b32_e32 v10, v218
	v_mov_b32_e32 v11, v219
	v_mov_b32_e32 v12, v220
	v_mov_b32_e32 v13, v221
	v_mov_b32_e32 v14, v222
	v_mov_b32_e32 v15, v223
	v_mov_b32_e32 v16, v224
	v_mov_b32_e32 v17, v225
	v_mov_b32_e32 v18, v226
	v_mov_b32_e32 v19, v227
	v_mov_b32_e32 v20, v228
	v_mov_b32_e32 v21, v229
	v_mov_b32_e32 v22, v230
	v_mov_b32_e32 v23, v231
	v_lshlrev_b32_e32 v33, 4, v29
	v_mad_i64_i32 v[34:35], s[14:15], v26, s24, 0
	v_mul_lo_u32 v31, v26, s21
	v_and_b32_e32 v36, 0x70, v33
	v_mad_i64_i32 v[34:35], s[14:15], v130, s25, v[34:35]
	v_add_u32_e32 v30, v131, v30
	v_add3_u32 v33, v31, v28, v36
	v_or_b32_e32 v34, v34, v36
	v_ashrrev_i32_e32 v31, 31, v30
	v_readlane_b32 s10, v246, 51
	v_lshl_add_u64 v[30:31], v[30:31], 1, v[34:35]
	v_readlane_b32 s11, v246, 52
	v_subrev_u32_e32 v32, 32, v26
	s_mov_b64 s[14:15], 0
	v_lshl_add_u64 v[30:31], s[10:11], 0, v[30:31]
	s_waitcnt vmcnt(0)

;   DI u32x4 operator()(int r, int k) const {
;     int row = row0 + r;
;     row = row < nrows ? row : nrows - 1;
;     return ldg16(base + (size_t)row * ld + k);
;   }
; DI void phase_gemm_plain256(const Sched& sc, const bf16_t* A, int lda, const bf16_t* Wt, int K, int N, bf16_t* C, int ldc, char* smem) {
;   const int NT = (N + 255) >> 8, MT = T / 256;
;   for (int round = 0;; ++round) {
;     int mt = 0, nt = 0;
;     const int st = sched_tile(sc, round, MT, NT, mt, nt);
;     if (st == 2) break;
;     if (st == 1) continue;
;     LoadRows al{A, lda, mt * 256, T};
;     LoadRows bl{Wt, K, nt * 256, N};
;     EpStore256 ep{C, ldc, mt * 256, nt * 256, N};
;     gemm_tile256(al, bl, ep, K, smem);
.LBB0_653:
	s_cmp_lg_u32 s14, 1
	s_mov_b64 s[0:1], -1
	s_cbranch_scc0 .LBB0_672
	v_mov_b32_e32 v42, v196
	v_readlane_b32 s40, v246, 17
	v_ashrrev_i32_e32 v43, 3, v42
	v_add_u32_e32 v12, s27, v43
	v_lshlrev_b32_e32 v0, 4, v42
	v_add_u32_e32 v26, s26, v43
	v_and_b32_e32 v160, 0x70, v0
	v_min_i32_e32 v44, 0x7fff, v12
	v_add_u32_e32 v2, 64, v12
	v_add_u32_e32 v10, 0x80, v12
	v_add_u32_e32 v12, 0xc0, v12
	v_add_u32_e32 v27, 0x80, v26
	v_lshl_add_u64 v[8:9], s[72:73], 0, v[160:161]
	v_min_i32_e32 v45, 0x7fff, v2
	v_min_i32_e32 v46, 0x7fff, v10
	v_min_i32_e32 v47, 0x7fff, v12
	v_lshl_add_u64 v[24:25], s[2:3], 0, v[160:161]
	v_min_i32_e32 v48, 0x3ff, v26
	v_add_u32_e32 v16, 64, v26
	v_min_i32_e32 v50, 0x3ff, v27
	v_add_u32_e32 v26, 0xc0, v26
	v_mad_i64_i32 v[0:1], s[0:1], v44, s17, v[8:9]
	v_mad_i64_i32 v[4:5], s[0:1], v45, s17, v[8:9]
	v_mad_i64_i32 v[10:11], s[0:1], v46, s17, v[8:9]
	v_mad_i64_i32 v[12:13], s[0:1], v47, s17, v[8:9]
	v_mad_i64_i32 v[32:33], s[0:1], v48, s17, v[24:25]
	v_min_i32_e32 v49, 0x3ff, v16
	v_mad_i64_i32 v[36:37], s[0:1], v50, s17, v[24:25]
	v_min_i32_e32 v51, 0x3ff, v26
	v_mov_b32_e32 v254, v0
	v_mov_b32_e32 v255, v1
	s_nop 0
	s_nop 0
	s_nop 0
	v_mad_i64_i32 v[34:35], s[0:1], v49, s17, v[24:25]
	v_mov_b32_e32 v252, v32
	v_mov_b32_e32 v253, v33
	v_mad_i64_i32 v[38:39], s[0:1], v51, s17, v[24:25]
	v_bfe_u32 v198, v42, 6, 2
	v_and_b32_e32 v52, 31, v42
	v_ashrrev_i32_e32 v53, 1, v42
	v_lshrrev_b32_e32 v42, 2, v42
	v_mul_lo_u32 v43, v43, s18
	v_and_or_b32 v199, v53, s19, v52
	v_and_b32_e32 v200, 8, v42
	v_lshl_or_b32 v52, v198, 6, v52
	v_readlane_b32 s54, v246, 31
	v_readlane_b32 s55, v246, 32
	v_add_u32_e32 v201, v160, v43
	v_or_b32_e32 v53, 0x12000, v160
	v_lshlrev_b32_e32 v42, 1, v200
	v_mul_u32_u24_e32 v52, 0x48, v52
	v_mov_b64_e32 v[40:41], s[54:55]
	v_or_b32_e32 v54, 0x1b000, v160
	v_add_u32_e32 v202, v53, v43
	v_mad_u64_u32 v[162:163], s[0:1], v199, s18, v[42:43]
	v_lshl_add_u32 v42, v52, 1, v42
	v_mad_i64_i32 v[164:165], s[0:1], v48, s17, v[40:41]
	v_add_u32_e32 v163, 0x12000, v42
	v_add_u32_e32 v203, 0x1b000, v42
	v_mad_i64_i32 v[166:167], s[0:1], v49, s17, v[40:41]
	v_mad_i64_i32 v[168:169], s[0:1], v50, s17, v[40:41]
	v_mad_i64_i32 v[170:171], s[0:1], v51, s17, v[40:41]
	v_mad_i64_i32 v[172:173], s[0:1], v44, s17, v[40:41]
	v_mad_i64_i32 v[174:175], s[0:1], v45, s17, v[40:41]
	v_mad_i64_i32 v[176:177], s[0:1], v46, s17, v[40:41]
	v_mad_i64_i32 v[178:179], s[0:1], v47, s17, v[40:41]
	s_mov_b32 s28, 0
	v_add_u32_e32 v204, v54, v43
	v_readlane_b32 s41, v246, 18
	v_readlane_b32 s42, v246, 19
	v_readlane_b32 s43, v246, 20
	v_readlane_b32 s44, v246, 21
	v_readlane_b32 s45, v246, 22
	v_readlane_b32 s46, v246, 23
	v_readlane_b32 s47, v246, 24
	v_readlane_b32 s48, v246, 25
	v_readlane_b32 s49, v246, 26
	v_readlane_b32 s50, v246, 27
	v_readlane_b32 s51, v246, 28
	v_readlane_b32 s52, v246, 29
	v_readlane_b32 s53, v246, 30
	v_lshrrev_b32_e32 v228, 6, v196
	s_mov_b32 s6, 64
	v_readfirstlane_b32 s29, v228
	s_mov_b32 s7, 0
	s_mov_b32 s10, 0xb0000
	s_mov_b32 s11, 0
	v_bfe_u32 v226, v196, 2, 4
	s_lshl_b32 s30, s29, 3
	v_add_u32_e32 v226, s30, v226
	s_mov_b32 s30, 0x1600
	v_mul_lo_u32 v226, v226, s30
	v_bfe_u32 v228, v196, 4, 2
	v_and_b32_e32 v227, 3, v196
	v_xor_b32_e32 v228, v227, v228
	v_lshl_add_u32 v226, v228, 4, v226
	v_mov_b32_e32 v227, 0
	v_readlane_b32 s14, v254, 0
	v_readlane_b32 s15, v255, 0
	s_nop 1
	v_lshl_add_u64 v[218:219], s[14:15], 0, v[226:227]
	v_lshl_add_u64 v[220:221], v[218:219], 0, s[10:11]
	v_readlane_b32 s14, v252, 0
	v_readlane_b32 s15, v253, 0
	s_nop 1
	v_lshl_add_u64 v[222:223], s[14:15], 0, v[226:227]
	v_lshl_add_u64 v[224:225], v[222:223], 0, s[10:11]
	v_and_b32_e32 v226, 31, v196
	v_bfe_u32 v228, v196, 2, 2
	v_bfe_u32 v227, v196, 5, 1
	v_xor_b32_e32 v228, v227, v228
	v_lshlrev_b32_e32 v228, 4, v228
	v_lshl_or_b32 v226, v226, 6, v228
	s_lshr_b32 s30, s29, 2
	s_lshl_b32 s30, s30, 13
	v_add_u32_e32 v128, s30, v226
	s_and_b32 s30, s29, 3
	s_lshl_b32 s30, s30, 12
	s_add_u32 s30, s30, 0x4000
	v_add_u32_e32 v131, s30, v226
	v_xor_b32_e32 v130, 0x20, v128
	v_xor_b32_e32 v205, 0x20, v131
	v_add_u32_e32 v206, 0x10000, v128
	v_add_u32_e32 v212, 0x10000, v131
	v_add_u32_e32 v214, 0x20000, v128
	v_add_u32_e32 v216, 0x20000, v131
	v_add_u32_e32 v207, 0x10000, v130
	v_add_u32_e32 v213, 0x10000, v205
	v_add_u32_e32 v215, 0x20000, v130
	v_add_u32_e32 v217, 0x20000, v205
	s_lshl_b32 s29, s29, 10
	s_waitcnt lgkmcnt(0)
	s_barrier
; #define G_LOADA(kt_) { _Pragma("unroll") for (int i = 0; i < 4; ++i) ra[i] = al(lrow + 64 * i, (kt_) * 64 + lck * 8); }
; #define G_LOADB(kt_) { _Pragma("unroll") for (int i = 0; i < 4; ++i) rb[i] = bl(lrow + 64 * i, (kt_) * 64 + lck * 8); }
; #define G_STOREA(buf_) { bf16_t* nA = sA + (buf_) * 256 * GLD; _Pragma("unroll") for (int i = 0; i < 4; ++i) *(u32x4*)(nA + (lrow + 64 * i) * GLD + lck * 8) = ra[i]; }
; #define G_STOREB(buf_) { bf16_t* nB = sB + (buf_) * 256 * GLD; _Pragma("unroll") for (int i = 0; i < 4; ++i) *(u32x4*)(nB + (lrow + 64 * i) * GLD + lck * 8) = rb[i]; }
; template <class AL, class BL, class EP>
; DI void gemm_tile256(AL al, BL bl, EP ep, int K, char* smem) {
;     ...
; #pragma unroll
;   for (int i = 0; i < 4; ++i)
; #pragma unroll
;     for (int j = 0; j < 2; ++j)
; #pragma unroll
;       for (int q = 0; q < 16; ++q) acc[i][j][q] = 0.f;
;   u32x4 ra[4], rb[4];
;   const int KT = K >> 6;
;     ...
;   G_LOADA(0); G_LOADB(0);
;   __syncthreads();
;   G_STOREA(0); G_STOREB(0);
;   if (KT > 1) G_LOADB(1);
;   __syncthreads();
	s_add_u32 m0, s29, 0x0
	s_nop 0
	global_load_lds_dwordx4 v[218:219], off
	v_lshl_add_u64 v[218:219], v[218:219], 0, s[6:7]
	s_add_u32 m0, s29, 0x4000
	s_nop 0
	global_load_lds_dwordx4 v[222:223], off
	v_lshl_add_u64 v[222:223], v[222:223], 0, s[6:7]
	s_add_u32 m0, s29, 0x2000
	s_nop 0
	global_load_lds_dwordx4 v[220:221], off
	v_lshl_add_u64 v[220:221], v[220:221], 0, s[6:7]
	s_add_u32 m0, s29, 0x6000
	s_nop 0
	global_load_lds_dwordx4 v[224:225], off
	v_lshl_add_u64 v[224:225], v[224:225], 0, s[6:7]
	s_add_u32 m0, s29, 0x8000
	s_nop 0
	global_load_lds_dwordx4 v[218:219], off
	v_lshl_add_u64 v[218:219], v[218:219], 0, s[6:7]
	s_add_u32 m0, s29, 0xc000
	s_nop 0
	global_load_lds_dwordx4 v[222:223], off
	v_lshl_add_u64 v[222:223], v[222:223], 0, s[6:7]
	s_add_u32 m0, s29, 0xa000
	s_nop 0
	global_load_lds_dwordx4 v[220:221], off
	v_lshl_add_u64 v[220:221], v[220:221], 0, s[6:7]
	s_add_u32 m0, s29, 0xe000
	s_nop 0
	global_load_lds_dwordx4 v[224:225], off
	v_lshl_add_u64 v[224:225], v[224:225], 0, s[6:7]
	s_add_u32 m0, s29, 0x10000
	s_nop 0
	global_load_lds_dwordx4 v[218:219], off
	v_lshl_add_u64 v[218:219], v[218:219], 0, s[6:7]
	s_add_u32 m0, s29, 0x14000
	s_nop 0
	global_load_lds_dwordx4 v[222:223], off
	v_lshl_add_u64 v[222:223], v[222:223], 0, s[6:7]
	s_add_u32 m0, s29, 0x12000
	s_nop 0
	global_load_lds_dwordx4 v[220:221], off
	v_lshl_add_u64 v[220:221], v[220:221], 0, s[6:7]
	s_add_u32 m0, s29, 0x16000
	s_nop 0
	global_load_lds_dwordx4 v[224:225], off
	v_lshl_add_u64 v[224:225], v[224:225], 0, s[6:7]
	s_add_u32 m0, s29, 0x18000
	s_nop 0
	global_load_lds_dwordx4 v[218:219], off
	v_lshl_add_u64 v[218:219], v[218:219], 0, s[6:7]
	s_add_u32 m0, s29, 0x1c000
	s_nop 0
	global_load_lds_dwordx4 v[222:223], off
	v_lshl_add_u64 v[222:223], v[222:223], 0, s[6:7]
	s_add_u32 m0, s29, 0x1a000
	s_nop 0
	global_load_lds_dwordx4 v[220:221], off
	v_lshl_add_u64 v[220:221], v[220:221], 0, s[6:7]
	s_add_u32 m0, s29, 0x1e000
	s_nop 0
	global_load_lds_dwordx4 v[224:225], off
	v_lshl_add_u64 v[224:225], v[224:225], 0, s[6:7]
	s_add_u32 m0, s29, 0x20000
	s_nop 0
	global_load_lds_dwordx4 v[218:219], off
	v_lshl_add_u64 v[218:219], v[218:219], 0, s[6:7]
	s_add_u32 m0, s29, 0x24000
	s_nop 0
	global_load_lds_dwordx4 v[222:223], off
	v_lshl_add_u64 v[222:223], v[222:223], 0, s[6:7]
	v_mov_b64_e32 v[112:113], 0
	v_mov_b64_e32 v[114:115], 0
	v_mov_b64_e32 v[116:117], 0
	v_mov_b64_e32 v[118:119], 0
	v_mov_b64_e32 v[120:121], 0
	v_mov_b64_e32 v[122:123], 0
	v_mov_b64_e32 v[124:125], 0
	v_mov_b64_e32 v[126:127], 0
	v_mov_b64_e32 v[96:97], 0
	v_mov_b64_e32 v[98:99], 0
	v_mov_b64_e32 v[100:101], 0
	v_mov_b64_e32 v[102:103], 0
	v_mov_b64_e32 v[104:105], 0
	v_mov_b64_e32 v[106:107], 0
	v_mov_b64_e32 v[108:109], 0
	v_mov_b64_e32 v[110:111], 0
	v_mov_b64_e32 v[80:81], 0
	v_mov_b64_e32 v[82:83], 0
	v_mov_b64_e32 v[84:85], 0
	v_mov_b64_e32 v[86:87], 0
	v_mov_b64_e32 v[88:89], 0
	v_mov_b64_e32 v[90:91], 0
	v_mov_b64_e32 v[92:93], 0
	v_mov_b64_e32 v[94:95], 0
	v_mov_b64_e32 v[64:65], 0
	v_mov_b64_e32 v[66:67], 0
	v_mov_b64_e32 v[68:69], 0
	v_mov_b64_e32 v[70:71], 0
	v_mov_b64_e32 v[72:73], 0
	v_mov_b64_e32 v[74:75], 0
	v_mov_b64_e32 v[76:77], 0
	v_mov_b64_e32 v[78:79], 0
	v_mov_b64_e32 v[48:49], 0
	v_mov_b64_e32 v[50:51], 0
	v_mov_b64_e32 v[52:53], 0
	v_mov_b64_e32 v[54:55], 0
	v_mov_b64_e32 v[56:57], 0
	v_mov_b64_e32 v[58:59], 0
	v_mov_b64_e32 v[60:61], 0
	v_mov_b64_e32 v[62:63], 0
	v_mov_b64_e32 v[32:33], 0
	v_mov_b64_e32 v[34:35], 0
	v_mov_b64_e32 v[36:37], 0
	v_mov_b64_e32 v[38:39], 0
	v_mov_b64_e32 v[40:41], 0
	v_mov_b64_e32 v[42:43], 0
	v_mov_b64_e32 v[44:45], 0
	v_mov_b64_e32 v[46:47], 0
	v_mov_b64_e32 v[16:17], 0
	v_mov_b64_e32 v[18:19], 0
	v_mov_b64_e32 v[20:21], 0
	v_mov_b64_e32 v[22:23], 0
	v_mov_b64_e32 v[24:25], 0
	v_mov_b64_e32 v[26:27], 0
	v_mov_b64_e32 v[28:29], 0
	v_mov_b64_e32 v[30:31], 0
	v_mov_b64_e32 v[0:1], 0
	v_mov_b64_e32 v[2:3], 0
	v_mov_b64_e32 v[4:5], 0
	v_mov_b64_e32 v[6:7], 0
	v_mov_b64_e32 v[8:9], 0
	v_mov_b64_e32 v[10:11], 0
	v_mov_b64_e32 v[12:13], 0
	v_mov_b64_e32 v[14:15], 0
	s_lshr_b32 s30, s29, 2
	s_xor_b32 s30, s30, s29
	s_bitcmp1_b32 s30, 10
	s_cbranch_scc0 .Lgk_ph7_np
	s_setprio 1
.Lgk_ph7_np:
	s_mov_b32 s30, 16
	s_waitcnt vmcnt(14)
	s_barrier
	ds_read_b128 v[184:187], v131
	ds_read_b128 v[132:135], v128
	ds_read_b128 v[188:191], v131 offset:2048
	ds_read_b128 v[136:139], v128 offset:2048
	ds_read_b128 v[140:143], v128 offset:4096
	ds_read_b128 v[144:147], v128 offset:6144
; #define G_LOADA(kt_) { _Pragma("unroll") for (int i = 0; i < 4; ++i) ra[i] = al(lrow + 64 * i, (kt_) * 64 + lck * 8); }
; #define G_LOADB(kt_) { _Pragma("unroll") for (int i = 0; i < 4; ++i) rb[i] = bl(lrow + 64 * i, (kt_) * 64 + lck * 8); }
; #define G_STOREA(buf_) { bf16_t* nA = sA + (buf_) * 256 * GLD; _Pragma("unroll") for (int i = 0; i < 4; ++i) *(u32x4*)(nA + (lrow + 64 * i) * GLD + lck * 8) = ra[i]; }
; #define G_STOREB(buf_) { bf16_t* nB = sB + (buf_) * 256 * GLD; _Pragma("unroll") for (int i = 0; i < 4; ++i) *(u32x4*)(nB + (lrow + 64 * i) * GLD + lck * 8) = rb[i]; }
; template <class AL, class BL, class EP>
; DI void gemm_tile256(AL al, BL bl, EP ep, int K, char* smem) {
;     ...
;   G_LOADA(0); G_LOADB(0);
;   __syncthreads();
;   G_STOREA(0); G_STOREB(0);
;   if (KT > 1) G_LOADB(1);
;   __syncthreads();
;   for (int kt = 0; kt < KT; kt += 2) {
;     G_STEP(0, kt);
;     if (kt + 1 >= KT) break;
;     G_STEP(1, kt + 1);
;   }
.Lgk_ph7_loop:
	s_waitcnt lgkmcnt(0)
	v_mfma_f32_32x32x16_bf16 v[112:127], v[184:187], v[132:135], v[112:127]
	ds_read_b128 v[192:195], v205
	ds_read_b128 v[148:151], v130
	v_mfma_f32_32x32x16_bf16 v[96:111], v[188:191], v[132:135], v[96:111]
	ds_read_b128 v[208:211], v205 offset:2048
	ds_read_b128 v[152:155], v130 offset:2048
	v_mfma_f32_32x32x16_bf16 v[80:95], v[184:187], v[136:139], v[80:95]
	ds_read_b128 v[156:159], v130 offset:4096
	ds_read_b128 v[180:183], v130 offset:6144
	v_mfma_f32_32x32x16_bf16 v[64:79], v[188:191], v[136:139], v[64:79]
	s_add_u32 m0, s29, 0x22000
	s_nop 0
	global_load_lds_dwordx4 v[220:221], off
	v_lshl_add_u64 v[220:221], v[220:221], 0, s[6:7]
	v_mfma_f32_32x32x16_bf16 v[48:63], v[184:187], v[140:143], v[48:63]
	v_mfma_f32_32x32x16_bf16 v[32:47], v[188:191], v[140:143], v[32:47]
	v_mfma_f32_32x32x16_bf16 v[16:31], v[184:187], v[144:147], v[16:31]
	v_mfma_f32_32x32x16_bf16 v[0:15], v[188:191], v[144:147], v[0:15]
	s_add_u32 m0, s29, 0x26000
	s_nop 0
	global_load_lds_dwordx4 v[224:225], off
	v_lshl_add_u64 v[224:225], v[224:225], 0, s[6:7]
	s_waitcnt lgkmcnt(0)
	s_waitcnt vmcnt(12)
	s_barrier
	s_waitcnt lgkmcnt(0)
	v_mfma_f32_32x32x16_bf16 v[112:127], v[192:195], v[148:151], v[112:127]
	ds_read_b128 v[184:187], v131 offset:32768
	ds_read_b128 v[132:135], v128 offset:32768
	v_mfma_f32_32x32x16_bf16 v[96:111], v[208:211], v[148:151], v[96:111]
	ds_read_b128 v[188:191], v131 offset:34816
	ds_read_b128 v[136:139], v128 offset:34816
	v_mfma_f32_32x32x16_bf16 v[80:95], v[192:195], v[152:155], v[80:95]
	ds_read_b128 v[140:143], v128 offset:36864
	ds_read_b128 v[144:147], v128 offset:38912
	v_mfma_f32_32x32x16_bf16 v[64:79], v[208:211], v[152:155], v[64:79]
	s_add_u32 m0, s29, 0x0
	s_nop 0
	global_load_lds_dwordx4 v[218:219], off
	v_lshl_add_u64 v[218:219], v[218:219], 0, s[6:7]
	v_mfma_f32_32x32x16_bf16 v[48:63], v[192:195], v[156:159], v[48:63]
	v_mfma_f32_32x32x16_bf16 v[32:47], v[208:211], v[156:159], v[32:47]
	v_mfma_f32_32x32x16_bf16 v[16:31], v[192:195], v[180:183], v[16:31]
	v_mfma_f32_32x32x16_bf16 v[0:15], v[208:211], v[180:183], v[0:15]
	s_add_u32 m0, s29, 0x4000
	s_nop 0
	global_load_lds_dwordx4 v[222:223], off
	v_lshl_add_u64 v[222:223], v[222:223], 0, s[6:7]
	s_waitcnt lgkmcnt(0)
	v_mfma_f32_32x32x16_bf16 v[112:127], v[184:187], v[132:135], v[112:127]
	ds_read_b128 v[192:195], v205 offset:32768
	ds_read_b128 v[148:151], v130 offset:32768
	v_mfma_f32_32x32x16_bf16 v[96:111], v[188:191], v[132:135], v[96:111]
	ds_read_b128 v[208:211], v205 offset:34816
	ds_read_b128 v[152:155], v130 offset:34816
	v_mfma_f32_32x32x16_bf16 v[80:95], v[184:187], v[136:139], v[80:95]
	ds_read_b128 v[156:159], v130 offset:36864
	ds_read_b128 v[180:183], v130 offset:38912
	v_mfma_f32_32x32x16_bf16 v[64:79], v[188:191], v[136:139], v[64:79]
	s_add_u32 m0, s29, 0x2000
	s_nop 0
	global_load_lds_dwordx4 v[220:221], off
	v_lshl_add_u64 v[220:221], v[220:221], 0, s[6:7]
	v_mfma_f32_32x32x16_bf16 v[48:63], v[184:187], v[140:143], v[48:63]
	v_mfma_f32_32x32x16_bf16 v[32:47], v[188:191], v[140:143], v[32:47]
	v_mfma_f32_32x32x16_bf16 v[16:31], v[184:187], v[144:147], v[16:31]
	v_mfma_f32_32x32x16_bf16 v[0:15], v[188:191], v[144:147], v[0:15]
	s_add_u32 m0, s29, 0x6000
	s_nop 0
	global_load_lds_dwordx4 v[224:225], off
	v_lshl_add_u64 v[224:225], v[224:225], 0, s[6:7]
	s_waitcnt lgkmcnt(0)
	s_waitcnt vmcnt(12)
	s_barrier
	s_waitcnt lgkmcnt(0)
	v_mfma_f32_32x32x16_bf16 v[112:127], v[192:195], v[148:151], v[112:127]
	ds_read_b128 v[184:187], v212
	ds_read_b128 v[132:135], v206
	v_mfma_f32_32x32x16_bf16 v[96:111], v[208:211], v[148:151], v[96:111]
	ds_read_b128 v[188:191], v212 offset:2048
	ds_read_b128 v[136:139], v206 offset:2048
	v_mfma_f32_32x32x16_bf16 v[80:95], v[192:195], v[152:155], v[80:95]
	ds_read_b128 v[140:143], v206 offset:4096
	ds_read_b128 v[144:147], v206 offset:6144
	v_mfma_f32_32x32x16_bf16 v[64:79], v[208:211], v[152:155], v[64:79]
	s_add_u32 m0, s29, 0x8000
	s_nop 0
	global_load_lds_dwordx4 v[218:219], off
	v_lshl_add_u64 v[218:219], v[218:219], 0, s[6:7]
	v_mfma_f32_32x32x16_bf16 v[48:63], v[192:195], v[156:159], v[48:63]
	v_mfma_f32_32x32x16_bf16 v[32:47], v[208:211], v[156:159], v[32:47]
	v_mfma_f32_32x32x16_bf16 v[16:31], v[192:195], v[180:183], v[16:31]
	v_mfma_f32_32x32x16_bf16 v[0:15], v[208:211], v[180:183], v[0:15]
	s_add_u32 m0, s29, 0xc000
	s_nop 0
	global_load_lds_dwordx4 v[222:223], off
	v_lshl_add_u64 v[222:223], v[222:223], 0, s[6:7]
	s_waitcnt lgkmcnt(0)
	v_mfma_f32_32x32x16_bf16 v[112:127], v[184:187], v[132:135], v[112:127]
	ds_read_b128 v[192:195], v213
	ds_read_b128 v[148:151], v207
	v_mfma_f32_32x32x16_bf16 v[96:111], v[188:191], v[132:135], v[96:111]
	ds_read_b128 v[208:211], v213 offset:2048
	ds_read_b128 v[152:155], v207 offset:2048
	v_mfma_f32_32x32x16_bf16 v[80:95], v[184:187], v[136:139], v[80:95]
	ds_read_b128 v[156:159], v207 offset:4096
	ds_read_b128 v[180:183], v207 offset:6144
	v_mfma_f32_32x32x16_bf16 v[64:79], v[188:191], v[136:139], v[64:79]
	s_add_u32 m0, s29, 0xa000
	s_nop 0
	global_load_lds_dwordx4 v[220:221], off
	v_lshl_add_u64 v[220:221], v[220:221], 0, s[6:7]
	v_mfma_f32_32x32x16_bf16 v[48:63], v[184:187], v[140:143], v[48:63]
	v_mfma_f32_32x32x16_bf16 v[32:47], v[188:191], v[140:143], v[32:47]
	v_mfma_f32_32x32x16_bf16 v[16:31], v[184:187], v[144:147], v[16:31]
	v_mfma_f32_32x32x16_bf16 v[0:15], v[188:191], v[144:147], v[0:15]
	s_add_u32 m0, s29, 0xe000
	s_nop 0
	global_load_lds_dwordx4 v[224:225], off
	v_lshl_add_u64 v[224:225], v[224:225], 0, s[6:7]
	s_waitcnt lgkmcnt(0)
	s_waitcnt vmcnt(12)
	s_barrier
; #define G_LOADA(kt_) { _Pragma("unroll") for (int i = 0; i < 4; ++i) ra[i] = al(lrow + 64 * i, (kt_) * 64 + lck * 8); }
; #define G_LOADB(kt_) { _Pragma("unroll") for (int i = 0; i < 4; ++i) rb[i] = bl(lrow + 64 * i, (kt_) * 64 + lck * 8); }
; #define G_STOREA(buf_) { bf16_t* nA = sA + (buf_) * 256 * GLD; _Pragma("unroll") for (int i = 0; i < 4; ++i) *(u32x4*)(nA + (lrow + 64 * i) * GLD + lck * 8) = ra[i]; }
; #define G_STOREB(buf_) { bf16_t* nB = sB + (buf_) * 256 * GLD; _Pragma("unroll") for (int i = 0; i < 4; ++i) *(u32x4*)(nB + (lrow + 64 * i) * GLD + lck * 8) = rb[i]; }
; template <class AL, class BL, class EP>
; DI void gemm_tile256(AL al, BL bl, EP ep, int K, char* smem) {
;     ...
;   G_LOADA(0); G_LOADB(0);
;   __syncthreads();
;   G_STOREA(0); G_STOREB(0);
;   if (KT > 1) G_LOADB(1);
;   __syncthreads();
;   for (int kt = 0; kt < KT; kt += 2) {
;     G_STEP(0, kt);
;     if (kt + 1 >= KT) break;
;     G_STEP(1, kt + 1);
;   }
	s_waitcnt lgkmcnt(0)
	v_mfma_f32_32x32x16_bf16 v[112:127], v[192:195], v[148:151], v[112:127]
	ds_read_b128 v[184:187], v212 offset:32768
	ds_read_b128 v[132:135], v206 offset:32768
	v_mfma_f32_32x32x16_bf16 v[96:111], v[208:211], v[148:151], v[96:111]
	ds_read_b128 v[188:191], v212 offset:34816
	ds_read_b128 v[136:139], v206 offset:34816
	v_mfma_f32_32x32x16_bf16 v[80:95], v[192:195], v[152:155], v[80:95]
	ds_read_b128 v[140:143], v206 offset:36864
	ds_read_b128 v[144:147], v206 offset:38912
	v_mfma_f32_32x32x16_bf16 v[64:79], v[208:211], v[152:155], v[64:79]
	s_add_u32 m0, s29, 0x10000
	s_nop 0
	global_load_lds_dwordx4 v[218:219], off
	v_lshl_add_u64 v[218:219], v[218:219], 0, s[6:7]
	v_mfma_f32_32x32x16_bf16 v[48:63], v[192:195], v[156:159], v[48:63]
	v_mfma_f32_32x32x16_bf16 v[32:47], v[208:211], v[156:159], v[32:47]
	v_mfma_f32_32x32x16_bf16 v[16:31], v[192:195], v[180:183], v[16:31]
	v_mfma_f32_32x32x16_bf16 v[0:15], v[208:211], v[180:183], v[0:15]
	s_add_u32 m0, s29, 0x14000
	s_nop 0
	global_load_lds_dwordx4 v[222:223], off
	v_lshl_add_u64 v[222:223], v[222:223], 0, s[6:7]
	s_waitcnt lgkmcnt(0)
	v_mfma_f32_32x32x16_bf16 v[112:127], v[184:187], v[132:135], v[112:127]
	ds_read_b128 v[192:195], v213 offset:32768
	ds_read_b128 v[148:151], v207 offset:32768
	v_mfma_f32_32x32x16_bf16 v[96:111], v[188:191], v[132:135], v[96:111]
	ds_read_b128 v[208:211], v213 offset:34816
	ds_read_b128 v[152:155], v207 offset:34816
	v_mfma_f32_32x32x16_bf16 v[80:95], v[184:187], v[136:139], v[80:95]
	ds_read_b128 v[156:159], v207 offset:36864
	ds_read_b128 v[180:183], v207 offset:38912
	v_mfma_f32_32x32x16_bf16 v[64:79], v[188:191], v[136:139], v[64:79]
	s_add_u32 m0, s29, 0x12000
	s_nop 0
	global_load_lds_dwordx4 v[220:221], off
	v_lshl_add_u64 v[220:221], v[220:221], 0, s[6:7]
	v_mfma_f32_32x32x16_bf16 v[48:63], v[184:187], v[140:143], v[48:63]
	v_mfma_f32_32x32x16_bf16 v[32:47], v[188:191], v[140:143], v[32:47]
	v_mfma_f32_32x32x16_bf16 v[16:31], v[184:187], v[144:147], v[16:31]
	v_mfma_f32_32x32x16_bf16 v[0:15], v[188:191], v[144:147], v[0:15]
	s_add_u32 m0, s29, 0x16000
	s_nop 0
	global_load_lds_dwordx4 v[224:225], off
	v_lshl_add_u64 v[224:225], v[224:225], 0, s[6:7]
	s_waitcnt lgkmcnt(0)
	s_waitcnt vmcnt(12)
	s_barrier
	s_waitcnt lgkmcnt(0)
	v_mfma_f32_32x32x16_bf16 v[112:127], v[192:195], v[148:151], v[112:127]
	ds_read_b128 v[184:187], v216
	ds_read_b128 v[132:135], v214
	v_mfma_f32_32x32x16_bf16 v[96:111], v[208:211], v[148:151], v[96:111]
	ds_read_b128 v[188:191], v216 offset:2048
	ds_read_b128 v[136:139], v214 offset:2048
	v_mfma_f32_32x32x16_bf16 v[80:95], v[192:195], v[152:155], v[80:95]
	ds_read_b128 v[140:143], v214 offset:4096
	ds_read_b128 v[144:147], v214 offset:6144
	v_mfma_f32_32x32x16_bf16 v[64:79], v[208:211], v[152:155], v[64:79]
	s_add_u32 m0, s29, 0x18000
	s_nop 0
	global_load_lds_dwordx4 v[218:219], off
	v_lshl_add_u64 v[218:219], v[218:219], 0, s[6:7]
	v_mfma_f32_32x32x16_bf16 v[48:63], v[192:195], v[156:159], v[48:63]
	v_mfma_f32_32x32x16_bf16 v[32:47], v[208:211], v[156:159], v[32:47]
	v_mfma_f32_32x32x16_bf16 v[16:31], v[192:195], v[180:183], v[16:31]
	v_mfma_f32_32x32x16_bf16 v[0:15], v[208:211], v[180:183], v[0:15]
	s_add_u32 m0, s29, 0x1c000
	s_nop 0
	global_load_lds_dwordx4 v[222:223], off
	v_lshl_add_u64 v[222:223], v[222:223], 0, s[6:7]
	s_waitcnt lgkmcnt(0)
	v_mfma_f32_32x32x16_bf16 v[112:127], v[184:187], v[132:135], v[112:127]
	ds_read_b128 v[192:195], v217
	ds_read_b128 v[148:151], v215
	v_mfma_f32_32x32x16_bf16 v[96:111], v[188:191], v[132:135], v[96:111]
	ds_read_b128 v[208:211], v217 offset:2048
	ds_read_b128 v[152:155], v215 offset:2048
	v_mfma_f32_32x32x16_bf16 v[80:95], v[184:187], v[136:139], v[80:95]
	ds_read_b128 v[156:159], v215 offset:4096
	ds_read_b128 v[180:183], v215 offset:6144
	v_mfma_f32_32x32x16_bf16 v[64:79], v[188:191], v[136:139], v[64:79]
	s_add_u32 m0, s29, 0x1a000
	s_nop 0
	global_load_lds_dwordx4 v[220:221], off
	v_lshl_add_u64 v[220:221], v[220:221], 0, s[6:7]
	v_mfma_f32_32x32x16_bf16 v[48:63], v[184:187], v[140:143], v[48:63]
	v_mfma_f32_32x32x16_bf16 v[32:47], v[188:191], v[140:143], v[32:47]
	v_mfma_f32_32x32x16_bf16 v[16:31], v[184:187], v[144:147], v[16:31]
	v_mfma_f32_32x32x16_bf16 v[0:15], v[188:191], v[144:147], v[0:15]
	s_add_u32 m0, s29, 0x1e000
	s_nop 0
	global_load_lds_dwordx4 v[224:225], off
	v_lshl_add_u64 v[224:225], v[224:225], 0, s[6:7]
	s_waitcnt lgkmcnt(0)
	s_waitcnt vmcnt(12)
	s_barrier
	s_waitcnt lgkmcnt(0)
	v_mfma_f32_32x32x16_bf16 v[112:127], v[192:195], v[148:151], v[112:127]
	ds_read_b128 v[184:187], v131
	ds_read_b128 v[132:135], v128
	v_mfma_f32_32x32x16_bf16 v[96:111], v[208:211], v[148:151], v[96:111]
	ds_read_b128 v[188:191], v131 offset:2048
	ds_read_b128 v[136:139], v128 offset:2048
	v_mfma_f32_32x32x16_bf16 v[80:95], v[192:195], v[152:155], v[80:95]
	ds_read_b128 v[140:143], v128 offset:4096
	ds_read_b128 v[144:147], v128 offset:6144
	v_mfma_f32_32x32x16_bf16 v[64:79], v[208:211], v[152:155], v[64:79]
	s_add_u32 m0, s29, 0x20000
	s_nop 0
	global_load_lds_dwordx4 v[218:219], off
	v_lshl_add_u64 v[218:219], v[218:219], 0, s[6:7]
	v_mfma_f32_32x32x16_bf16 v[48:63], v[192:195], v[156:159], v[48:63]
	v_mfma_f32_32x32x16_bf16 v[32:47], v[208:211], v[156:159], v[32:47]
	v_mfma_f32_32x32x16_bf16 v[16:31], v[192:195], v[180:183], v[16:31]
	v_mfma_f32_32x32x16_bf16 v[0:15], v[208:211], v[180:183], v[0:15]
	s_add_u32 m0, s29, 0x24000
	s_nop 0
	global_load_lds_dwordx4 v[222:223], off
	v_lshl_add_u64 v[222:223], v[222:223], 0, s[6:7]
	s_sub_u32 s30, s30, 1
	s_cmp_lg_u32 s30, 0
	s_cbranch_scc1 .Lgk_ph7_loop
; #define G_LOADA(kt_) { _Pragma("unroll") for (int i = 0; i < 4; ++i) ra[i] = al(lrow + 64 * i, (kt_) * 64 + lck * 8); }
; #define G_LOADB(kt_) { _Pragma("unroll") for (int i = 0; i < 4; ++i) rb[i] = bl(lrow + 64 * i, (kt_) * 64 + lck * 8); }
; #define G_STOREA(buf_) { bf16_t* nA = sA + (buf_) * 256 * GLD; _Pragma("unroll") for (int i = 0; i < 4; ++i) *(u32x4*)(nA + (lrow + 64 * i) * GLD + lck * 8) = ra[i]; }
; #define G_STOREB(buf_) { bf16_t* nB = sB + (buf_) * 256 * GLD; _Pragma("unroll") for (int i = 0; i < 4; ++i) *(u32x4*)(nB + (lrow + 64 * i) * GLD + lck * 8) = rb[i]; }
; template <class AL, class BL, class EP>
; DI void gemm_tile256(AL al, BL bl, EP ep, int K, char* smem) {
;     ...
;   G_LOADA(0); G_LOADB(0);
;   __syncthreads();
;   G_STOREA(0); G_STOREB(0);
;   if (KT > 1) G_LOADB(1);
;   __syncthreads();
;   for (int kt = 0; kt < KT; kt += 2) {
;     G_STEP(0, kt);
;     if (kt + 1 >= KT) break;
;     G_STEP(1, kt + 1);
;   }
	s_waitcnt lgkmcnt(0)
	v_mfma_f32_32x32x16_bf16 v[112:127], v[184:187], v[132:135], v[112:127]
	ds_read_b128 v[192:195], v205
	ds_read_b128 v[148:151], v130
	v_mfma_f32_32x32x16_bf16 v[96:111], v[188:191], v[132:135], v[96:111]
	ds_read_b128 v[208:211], v205 offset:2048
	ds_read_b128 v[152:155], v130 offset:2048
	v_mfma_f32_32x32x16_bf16 v[80:95], v[184:187], v[136:139], v[80:95]
	ds_read_b128 v[156:159], v130 offset:4096
	ds_read_b128 v[180:183], v130 offset:6144
	v_mfma_f32_32x32x16_bf16 v[64:79], v[188:191], v[136:139], v[64:79]
	s_add_u32 m0, s29, 0x22000
	s_nop 0
	global_load_lds_dwordx4 v[220:221], off
	v_lshl_add_u64 v[220:221], v[220:221], 0, s[6:7]
	v_mfma_f32_32x32x16_bf16 v[48:63], v[184:187], v[140:143], v[48:63]
	v_mfma_f32_32x32x16_bf16 v[32:47], v[188:191], v[140:143], v[32:47]
	v_mfma_f32_32x32x16_bf16 v[16:31], v[184:187], v[144:147], v[16:31]
	v_mfma_f32_32x32x16_bf16 v[0:15], v[188:191], v[144:147], v[0:15]
	s_add_u32 m0, s29, 0x26000
	s_nop 0
	global_load_lds_dwordx4 v[224:225], off
	v_lshl_add_u64 v[224:225], v[224:225], 0, s[6:7]
	s_waitcnt lgkmcnt(0)
	s_waitcnt vmcnt(12)
	s_barrier
	s_waitcnt lgkmcnt(0)
	v_mfma_f32_32x32x16_bf16 v[112:127], v[192:195], v[148:151], v[112:127]
	ds_read_b128 v[184:187], v131 offset:32768
	ds_read_b128 v[132:135], v128 offset:32768
	v_mfma_f32_32x32x16_bf16 v[96:111], v[208:211], v[148:151], v[96:111]
	ds_read_b128 v[188:191], v131 offset:34816
	ds_read_b128 v[136:139], v128 offset:34816
	v_mfma_f32_32x32x16_bf16 v[80:95], v[192:195], v[152:155], v[80:95]
	ds_read_b128 v[140:143], v128 offset:36864
	ds_read_b128 v[144:147], v128 offset:38912
	v_mfma_f32_32x32x16_bf16 v[64:79], v[208:211], v[152:155], v[64:79]
	s_add_u32 m0, s29, 0x0
	s_nop 0
	global_load_lds_dwordx4 v[218:219], off
	v_lshl_add_u64 v[218:219], v[218:219], 0, s[6:7]
	v_mfma_f32_32x32x16_bf16 v[48:63], v[192:195], v[156:159], v[48:63]
	v_mfma_f32_32x32x16_bf16 v[32:47], v[208:211], v[156:159], v[32:47]
	v_mfma_f32_32x32x16_bf16 v[16:31], v[192:195], v[180:183], v[16:31]
	v_mfma_f32_32x32x16_bf16 v[0:15], v[208:211], v[180:183], v[0:15]
	s_add_u32 m0, s29, 0x4000
	s_nop 0
	global_load_lds_dwordx4 v[222:223], off
	v_lshl_add_u64 v[222:223], v[222:223], 0, s[6:7]
	s_waitcnt lgkmcnt(0)
	v_mfma_f32_32x32x16_bf16 v[112:127], v[184:187], v[132:135], v[112:127]
	ds_read_b128 v[192:195], v205 offset:32768
	ds_read_b128 v[148:151], v130 offset:32768
	v_mfma_f32_32x32x16_bf16 v[96:111], v[188:191], v[132:135], v[96:111]
	ds_read_b128 v[208:211], v205 offset:34816
	ds_read_b128 v[152:155], v130 offset:34816
	v_mfma_f32_32x32x16_bf16 v[80:95], v[184:187], v[136:139], v[80:95]
	ds_read_b128 v[156:159], v130 offset:36864
	ds_read_b128 v[180:183], v130 offset:38912
	v_mfma_f32_32x32x16_bf16 v[64:79], v[188:191], v[136:139], v[64:79]
	s_add_u32 m0, s29, 0x2000
	s_nop 0
	global_load_lds_dwordx4 v[220:221], off
	v_lshl_add_u64 v[220:221], v[220:221], 0, s[6:7]
	v_mfma_f32_32x32x16_bf16 v[48:63], v[184:187], v[140:143], v[48:63]
	v_mfma_f32_32x32x16_bf16 v[32:47], v[188:191], v[140:143], v[32:47]
	v_mfma_f32_32x32x16_bf16 v[16:31], v[184:187], v[144:147], v[16:31]
	v_mfma_f32_32x32x16_bf16 v[0:15], v[188:191], v[144:147], v[0:15]
	s_add_u32 m0, s29, 0x6000
	s_nop 0
	global_load_lds_dwordx4 v[224:225], off
	v_lshl_add_u64 v[224:225], v[224:225], 0, s[6:7]
	s_waitcnt lgkmcnt(0)
	s_waitcnt vmcnt(12)
	s_barrier
	s_waitcnt lgkmcnt(0)
	v_mfma_f32_32x32x16_bf16 v[112:127], v[192:195], v[148:151], v[112:127]
	ds_read_b128 v[184:187], v212
	ds_read_b128 v[132:135], v206
	v_mfma_f32_32x32x16_bf16 v[96:111], v[208:211], v[148:151], v[96:111]
	ds_read_b128 v[188:191], v212 offset:2048
	ds_read_b128 v[136:139], v206 offset:2048
	v_mfma_f32_32x32x16_bf16 v[80:95], v[192:195], v[152:155], v[80:95]
	ds_read_b128 v[140:143], v206 offset:4096
	ds_read_b128 v[144:147], v206 offset:6144
	v_mfma_f32_32x32x16_bf16 v[64:79], v[208:211], v[152:155], v[64:79]
	s_add_u32 m0, s29, 0x8000
	s_nop 0
	global_load_lds_dwordx4 v[218:219], off
	v_lshl_add_u64 v[218:219], v[218:219], 0, s[6:7]
	v_mfma_f32_32x32x16_bf16 v[48:63], v[192:195], v[156:159], v[48:63]
	v_mfma_f32_32x32x16_bf16 v[32:47], v[208:211], v[156:159], v[32:47]
	v_mfma_f32_32x32x16_bf16 v[16:31], v[192:195], v[180:183], v[16:31]
	v_mfma_f32_32x32x16_bf16 v[0:15], v[208:211], v[180:183], v[0:15]
	s_add_u32 m0, s29, 0xc000
	s_nop 0
	global_load_lds_dwordx4 v[222:223], off
	v_lshl_add_u64 v[222:223], v[222:223], 0, s[6:7]
	s_waitcnt lgkmcnt(0)
	v_mfma_f32_32x32x16_bf16 v[112:127], v[184:187], v[132:135], v[112:127]
	ds_read_b128 v[192:195], v213
	ds_read_b128 v[148:151], v207
	v_mfma_f32_32x32x16_bf16 v[96:111], v[188:191], v[132:135], v[96:111]
	ds_read_b128 v[208:211], v213 offset:2048
	ds_read_b128 v[152:155], v207 offset:2048
	v_mfma_f32_32x32x16_bf16 v[80:95], v[184:187], v[136:139], v[80:95]
	ds_read_b128 v[156:159], v207 offset:4096
	ds_read_b128 v[180:183], v207 offset:6144
	v_mfma_f32_32x32x16_bf16 v[64:79], v[188:191], v[136:139], v[64:79]
	s_add_u32 m0, s29, 0xa000
	s_nop 0
	global_load_lds_dwordx4 v[220:221], off
	v_lshl_add_u64 v[220:221], v[220:221], 0, s[6:7]
	v_mfma_f32_32x32x16_bf16 v[48:63], v[184:187], v[140:143], v[48:63]
	v_mfma_f32_32x32x16_bf16 v[32:47], v[188:191], v[140:143], v[32:47]
	v_mfma_f32_32x32x16_bf16 v[16:31], v[184:187], v[144:147], v[16:31]
	v_mfma_f32_32x32x16_bf16 v[0:15], v[188:191], v[144:147], v[0:15]
	s_add_u32 m0, s29, 0xe000
	s_nop 0
	global_load_lds_dwordx4 v[224:225], off
	v_lshl_add_u64 v[224:225], v[224:225], 0, s[6:7]
	s_waitcnt lgkmcnt(0)
	s_waitcnt vmcnt(12)
	s_barrier
; #define G_LOADA(kt_) { _Pragma("unroll") for (int i = 0; i < 4; ++i) ra[i] = al(lrow + 64 * i, (kt_) * 64 + lck * 8); }
; #define G_LOADB(kt_) { _Pragma("unroll") for (int i = 0; i < 4; ++i) rb[i] = bl(lrow + 64 * i, (kt_) * 64 + lck * 8); }
; #define G_STOREA(buf_) { bf16_t* nA = sA + (buf_) * 256 * GLD; _Pragma("unroll") for (int i = 0; i < 4; ++i) *(u32x4*)(nA + (lrow + 64 * i) * GLD + lck * 8) = ra[i]; }
; #define G_STOREB(buf_) { bf16_t* nB = sB + (buf_) * 256 * GLD; _Pragma("unroll") for (int i = 0; i < 4; ++i) *(u32x4*)(nB + (lrow + 64 * i) * GLD + lck * 8) = rb[i]; }
; template <class AL, class BL, class EP>
; DI void gemm_tile256(AL al, BL bl, EP ep, int K, char* smem) {
;     ...
;   G_LOADA(0); G_LOADB(0);
;   __syncthreads();
;   G_STOREA(0); G_STOREB(0);
;   if (KT > 1) G_LOADB(1);
;   __syncthreads();
;   for (int kt = 0; kt < KT; kt += 2) {
;     G_STEP(0, kt);
;     if (kt + 1 >= KT) break;
;     G_STEP(1, kt + 1);
;   }
	s_waitcnt lgkmcnt(0)
	v_mfma_f32_32x32x16_bf16 v[112:127], v[192:195], v[148:151], v[112:127]
	ds_read_b128 v[184:187], v212 offset:32768
	ds_read_b128 v[132:135], v206 offset:32768
	v_mfma_f32_32x32x16_bf16 v[96:111], v[208:211], v[148:151], v[96:111]
	ds_read_b128 v[188:191], v212 offset:34816
	ds_read_b128 v[136:139], v206 offset:34816
	v_mfma_f32_32x32x16_bf16 v[80:95], v[192:195], v[152:155], v[80:95]
	ds_read_b128 v[140:143], v206 offset:36864
	ds_read_b128 v[144:147], v206 offset:38912
	v_mfma_f32_32x32x16_bf16 v[64:79], v[208:211], v[152:155], v[64:79]
	s_add_u32 m0, s29, 0x10000
	s_nop 0
	global_load_lds_dwordx4 v[218:219], off
	v_lshl_add_u64 v[218:219], v[218:219], 0, s[6:7]
	v_mfma_f32_32x32x16_bf16 v[48:63], v[192:195], v[156:159], v[48:63]
	v_mfma_f32_32x32x16_bf16 v[32:47], v[208:211], v[156:159], v[32:47]
	v_mfma_f32_32x32x16_bf16 v[16:31], v[192:195], v[180:183], v[16:31]
	v_mfma_f32_32x32x16_bf16 v[0:15], v[208:211], v[180:183], v[0:15]
	s_add_u32 m0, s29, 0x14000
	s_nop 0
	global_load_lds_dwordx4 v[222:223], off
	v_lshl_add_u64 v[222:223], v[222:223], 0, s[6:7]
	s_waitcnt lgkmcnt(0)
	v_mfma_f32_32x32x16_bf16 v[112:127], v[184:187], v[132:135], v[112:127]
	ds_read_b128 v[192:195], v213 offset:32768
	ds_read_b128 v[148:151], v207 offset:32768
	v_mfma_f32_32x32x16_bf16 v[96:111], v[188:191], v[132:135], v[96:111]
	ds_read_b128 v[208:211], v213 offset:34816
	ds_read_b128 v[152:155], v207 offset:34816
	v_mfma_f32_32x32x16_bf16 v[80:95], v[184:187], v[136:139], v[80:95]
	ds_read_b128 v[156:159], v207 offset:36864
	ds_read_b128 v[180:183], v207 offset:38912
	v_mfma_f32_32x32x16_bf16 v[64:79], v[188:191], v[136:139], v[64:79]
	s_add_u32 m0, s29, 0x12000
	s_nop 0
	global_load_lds_dwordx4 v[220:221], off
	v_lshl_add_u64 v[220:221], v[220:221], 0, s[6:7]
	v_mfma_f32_32x32x16_bf16 v[48:63], v[184:187], v[140:143], v[48:63]
	v_mfma_f32_32x32x16_bf16 v[32:47], v[188:191], v[140:143], v[32:47]
	v_mfma_f32_32x32x16_bf16 v[16:31], v[184:187], v[144:147], v[16:31]
	v_mfma_f32_32x32x16_bf16 v[0:15], v[188:191], v[144:147], v[0:15]
	s_add_u32 m0, s29, 0x16000
	s_nop 0
	global_load_lds_dwordx4 v[224:225], off
	v_lshl_add_u64 v[224:225], v[224:225], 0, s[6:7]
	s_waitcnt lgkmcnt(0)
	s_waitcnt vmcnt(12)
	s_barrier
	s_waitcnt lgkmcnt(0)
	v_mfma_f32_32x32x16_bf16 v[112:127], v[192:195], v[148:151], v[112:127]
	ds_read_b128 v[184:187], v216
	ds_read_b128 v[132:135], v214
	v_mfma_f32_32x32x16_bf16 v[96:111], v[208:211], v[148:151], v[96:111]
	ds_read_b128 v[188:191], v216 offset:2048
	ds_read_b128 v[136:139], v214 offset:2048
	v_mfma_f32_32x32x16_bf16 v[80:95], v[192:195], v[152:155], v[80:95]
	ds_read_b128 v[140:143], v214 offset:4096
	ds_read_b128 v[144:147], v214 offset:6144
	v_mfma_f32_32x32x16_bf16 v[64:79], v[208:211], v[152:155], v[64:79]
	v_mfma_f32_32x32x16_bf16 v[48:63], v[192:195], v[156:159], v[48:63]
	v_mfma_f32_32x32x16_bf16 v[32:47], v[208:211], v[156:159], v[32:47]
	v_mfma_f32_32x32x16_bf16 v[16:31], v[192:195], v[180:183], v[16:31]
	v_mfma_f32_32x32x16_bf16 v[0:15], v[208:211], v[180:183], v[0:15]
	s_waitcnt lgkmcnt(0)
	v_mfma_f32_32x32x16_bf16 v[112:127], v[184:187], v[132:135], v[112:127]
	ds_read_b128 v[192:195], v217
	ds_read_b128 v[148:151], v215
	v_mfma_f32_32x32x16_bf16 v[96:111], v[188:191], v[132:135], v[96:111]
	ds_read_b128 v[208:211], v217 offset:2048
	ds_read_b128 v[152:155], v215 offset:2048
	v_mfma_f32_32x32x16_bf16 v[80:95], v[184:187], v[136:139], v[80:95]
	ds_read_b128 v[156:159], v215 offset:4096
	ds_read_b128 v[180:183], v215 offset:6144
	v_mfma_f32_32x32x16_bf16 v[64:79], v[188:191], v[136:139], v[64:79]
	v_mfma_f32_32x32x16_bf16 v[48:63], v[184:187], v[140:143], v[48:63]
	v_mfma_f32_32x32x16_bf16 v[32:47], v[188:191], v[140:143], v[32:47]
	v_mfma_f32_32x32x16_bf16 v[16:31], v[184:187], v[144:147], v[16:31]
	v_mfma_f32_32x32x16_bf16 v[0:15], v[188:191], v[144:147], v[0:15]
	s_waitcnt lgkmcnt(0)
	s_waitcnt vmcnt(8)
	s_barrier
	s_waitcnt lgkmcnt(0)
	v_mfma_f32_32x32x16_bf16 v[112:127], v[192:195], v[148:151], v[112:127]
	ds_read_b128 v[184:187], v131
	ds_read_b128 v[132:135], v128
	v_mfma_f32_32x32x16_bf16 v[96:111], v[208:211], v[148:151], v[96:111]
	ds_read_b128 v[188:191], v131 offset:2048
	ds_read_b128 v[136:139], v128 offset:2048
	v_mfma_f32_32x32x16_bf16 v[80:95], v[192:195], v[152:155], v[80:95]
	ds_read_b128 v[140:143], v128 offset:4096
	ds_read_b128 v[144:147], v128 offset:6144
	v_mfma_f32_32x32x16_bf16 v[64:79], v[208:211], v[152:155], v[64:79]
	v_mfma_f32_32x32x16_bf16 v[48:63], v[192:195], v[156:159], v[48:63]
	v_mfma_f32_32x32x16_bf16 v[32:47], v[208:211], v[156:159], v[32:47]
	v_mfma_f32_32x32x16_bf16 v[16:31], v[192:195], v[180:183], v[16:31]
	v_mfma_f32_32x32x16_bf16 v[0:15], v[208:211], v[180:183], v[0:15]
	s_waitcnt lgkmcnt(0)
	v_mfma_f32_32x32x16_bf16 v[112:127], v[184:187], v[132:135], v[112:127]
	ds_read_b128 v[192:195], v205
	ds_read_b128 v[148:151], v130
	v_mfma_f32_32x32x16_bf16 v[96:111], v[188:191], v[132:135], v[96:111]
	ds_read_b128 v[208:211], v205 offset:2048
	ds_read_b128 v[152:155], v130 offset:2048
	v_mfma_f32_32x32x16_bf16 v[80:95], v[184:187], v[136:139], v[80:95]
	ds_read_b128 v[156:159], v130 offset:4096
	ds_read_b128 v[180:183], v130 offset:6144
	v_mfma_f32_32x32x16_bf16 v[64:79], v[188:191], v[136:139], v[64:79]
	v_mfma_f32_32x32x16_bf16 v[48:63], v[184:187], v[140:143], v[48:63]
	v_mfma_f32_32x32x16_bf16 v[32:47], v[188:191], v[140:143], v[32:47]
	v_mfma_f32_32x32x16_bf16 v[16:31], v[184:187], v[144:147], v[16:31]
	v_mfma_f32_32x32x16_bf16 v[0:15], v[188:191], v[144:147], v[0:15]
	s_waitcnt lgkmcnt(0)
	s_waitcnt vmcnt(4)
	s_barrier
; #define G_LOADA(kt_) { _Pragma("unroll") for (int i = 0; i < 4; ++i) ra[i] = al(lrow + 64 * i, (kt_) * 64 + lck * 8); }
; #define G_LOADB(kt_) { _Pragma("unroll") for (int i = 0; i < 4; ++i) rb[i] = bl(lrow + 64 * i, (kt_) * 64 + lck * 8); }
; #define G_STOREA(buf_) { bf16_t* nA = sA + (buf_) * 256 * GLD; _Pragma("unroll") for (int i = 0; i < 4; ++i) *(u32x4*)(nA + (lrow + 64 * i) * GLD + lck * 8) = ra[i]; }
; #define G_STOREB(buf_) { bf16_t* nB = sB + (buf_) * 256 * GLD; _Pragma("unroll") for (int i = 0; i < 4; ++i) *(u32x4*)(nB + (lrow + 64 * i) * GLD + lck * 8) = rb[i]; }
; template <class AL, class BL, class EP>
; DI void gemm_tile256(AL al, BL bl, EP ep, int K, char* smem) {
;     ...
;   G_LOADA(0); G_LOADB(0);
;   __syncthreads();
;   G_STOREA(0); G_STOREB(0);
;   if (KT > 1) G_LOADB(1);
;   __syncthreads();
;   for (int kt = 0; kt < KT; kt += 2) {
;     G_STEP(0, kt);
;     if (kt + 1 >= KT) break;
;     G_STEP(1, kt + 1);
;   }
	s_waitcnt lgkmcnt(0)
	v_mfma_f32_32x32x16_bf16 v[112:127], v[192:195], v[148:151], v[112:127]
	ds_read_b128 v[184:187], v131 offset:32768
	ds_read_b128 v[132:135], v128 offset:32768
	v_mfma_f32_32x32x16_bf16 v[96:111], v[208:211], v[148:151], v[96:111]
	ds_read_b128 v[188:191], v131 offset:34816
	ds_read_b128 v[136:139], v128 offset:34816
	v_mfma_f32_32x32x16_bf16 v[80:95], v[192:195], v[152:155], v[80:95]
	ds_read_b128 v[140:143], v128 offset:36864
	ds_read_b128 v[144:147], v128 offset:38912
	v_mfma_f32_32x32x16_bf16 v[64:79], v[208:211], v[152:155], v[64:79]
	v_mfma_f32_32x32x16_bf16 v[48:63], v[192:195], v[156:159], v[48:63]
	v_mfma_f32_32x32x16_bf16 v[32:47], v[208:211], v[156:159], v[32:47]
	v_mfma_f32_32x32x16_bf16 v[16:31], v[192:195], v[180:183], v[16:31]
	v_mfma_f32_32x32x16_bf16 v[0:15], v[208:211], v[180:183], v[0:15]
	s_waitcnt lgkmcnt(0)
	v_mfma_f32_32x32x16_bf16 v[112:127], v[184:187], v[132:135], v[112:127]
	ds_read_b128 v[192:195], v205 offset:32768
	ds_read_b128 v[148:151], v130 offset:32768
	v_mfma_f32_32x32x16_bf16 v[96:111], v[188:191], v[132:135], v[96:111]
	ds_read_b128 v[208:211], v205 offset:34816
	ds_read_b128 v[152:155], v130 offset:34816
	v_mfma_f32_32x32x16_bf16 v[80:95], v[184:187], v[136:139], v[80:95]
	ds_read_b128 v[156:159], v130 offset:36864
	ds_read_b128 v[180:183], v130 offset:38912
	v_mfma_f32_32x32x16_bf16 v[64:79], v[188:191], v[136:139], v[64:79]
	v_mfma_f32_32x32x16_bf16 v[48:63], v[184:187], v[140:143], v[48:63]
	v_mfma_f32_32x32x16_bf16 v[32:47], v[188:191], v[140:143], v[32:47]
	v_mfma_f32_32x32x16_bf16 v[16:31], v[184:187], v[144:147], v[16:31]
	v_mfma_f32_32x32x16_bf16 v[0:15], v[188:191], v[144:147], v[0:15]
	s_waitcnt lgkmcnt(0)
	s_waitcnt vmcnt(0)
	s_barrier
	s_waitcnt lgkmcnt(0)
	v_mfma_f32_32x32x16_bf16 v[112:127], v[192:195], v[148:151], v[112:127]
	ds_read_b128 v[184:187], v212
	ds_read_b128 v[132:135], v206
	v_mfma_f32_32x32x16_bf16 v[96:111], v[208:211], v[148:151], v[96:111]
	ds_read_b128 v[188:191], v212 offset:2048
	ds_read_b128 v[136:139], v206 offset:2048
	v_mfma_f32_32x32x16_bf16 v[80:95], v[192:195], v[152:155], v[80:95]
	ds_read_b128 v[140:143], v206 offset:4096
	ds_read_b128 v[144:147], v206 offset:6144
	v_mfma_f32_32x32x16_bf16 v[64:79], v[208:211], v[152:155], v[64:79]
	v_mfma_f32_32x32x16_bf16 v[48:63], v[192:195], v[156:159], v[48:63]
	v_mfma_f32_32x32x16_bf16 v[32:47], v[208:211], v[156:159], v[32:47]
	v_mfma_f32_32x32x16_bf16 v[16:31], v[192:195], v[180:183], v[16:31]
	v_mfma_f32_32x32x16_bf16 v[0:15], v[208:211], v[180:183], v[0:15]
	s_waitcnt lgkmcnt(0)
	v_mfma_f32_32x32x16_bf16 v[112:127], v[184:187], v[132:135], v[112:127]
	ds_read_b128 v[192:195], v213
	ds_read_b128 v[148:151], v207
	v_mfma_f32_32x32x16_bf16 v[96:111], v[188:191], v[132:135], v[96:111]
	ds_read_b128 v[208:211], v213 offset:2048
	ds_read_b128 v[152:155], v207 offset:2048
	v_mfma_f32_32x32x16_bf16 v[80:95], v[184:187], v[136:139], v[80:95]
	ds_read_b128 v[156:159], v207 offset:4096
	ds_read_b128 v[180:183], v207 offset:6144
	v_mfma_f32_32x32x16_bf16 v[64:79], v[188:191], v[136:139], v[64:79]
	v_mfma_f32_32x32x16_bf16 v[48:63], v[184:187], v[140:143], v[48:63]
	v_mfma_f32_32x32x16_bf16 v[32:47], v[188:191], v[140:143], v[32:47]
	v_mfma_f32_32x32x16_bf16 v[16:31], v[184:187], v[144:147], v[16:31]
	v_mfma_f32_32x32x16_bf16 v[0:15], v[188:191], v[144:147], v[0:15]
	s_waitcnt lgkmcnt(0)
	s_waitcnt lgkmcnt(0)
	v_mfma_f32_32x32x16_bf16 v[112:127], v[192:195], v[148:151], v[112:127]
	v_mfma_f32_32x32x16_bf16 v[96:111], v[208:211], v[148:151], v[96:111]
	v_mfma_f32_32x32x16_bf16 v[80:95], v[192:195], v[152:155], v[80:95]
	v_mfma_f32_32x32x16_bf16 v[64:79], v[208:211], v[152:155], v[64:79]
	v_mfma_f32_32x32x16_bf16 v[48:63], v[192:195], v[156:159], v[48:63]
	v_mfma_f32_32x32x16_bf16 v[32:47], v[208:211], v[156:159], v[32:47]
	v_mfma_f32_32x32x16_bf16 v[16:31], v[192:195], v[180:183], v[16:31]
	v_mfma_f32_32x32x16_bf16 v[0:15], v[208:211], v[180:183], v[0:15]
	s_nop 15
	s_nop 3
	s_setprio 0
	s_barrier
	s_branch .LBB0_666

;   DI u32x4 operator()(int r, int k) const {
;     int row = row0 + r;
;     row = row < nrows ? row : nrows - 1;
;     return ldg16(base + (size_t)row * ld + k);
;   }
; DI void phase_in1_256(const Sched& sc, const Params& p, char* smem) {
;   const bf16_t* H = (const bf16_t*)(p.hbuf);
;   const bf16_t* Wt = (const bf16_t*)(p.ws + OFF_WT_IN1);
;   for (int round = 0;; ++round) {
;     int mt = 0, nt = 0;
;     const int st = sched_tile(sc, round, 128, 14, mt, nt);
;     if (st == 2) break;
;     if (st == 1) continue;
;     LoadRows al{H, 1024, mt * 256, T};
;     LoadRows bl{Wt, 1024, nt * 256, 3584};
;     EpIn1_256 ep{&p, mt * 256, nt};
;     gemm_tile256(al, bl, ep, 1024, smem);
.LBB0_765:
	v_cmp_ne_u32_e32 vcc, 1, v0
	s_mov_b64 s[4:5], -1
	s_cbranch_vccz .LBB0_797
	v_mov_b32_e32 v32, v196
	s_nop 0
	v_ashrrev_i32_e32 v33, 3, v32
	v_add_u32_e32 v12, s52, v33
	v_lshlrev_b32_e32 v0, 4, v32
	v_add_u32_e32 v10, 0x80, v12
	v_lshl_add_u32 v28, s20, 8, v33
	v_and_b32_e32 v128, 0x70, v0
	v_min_i32_e32 v0, 0x7fff, v12
	v_min_i32_e32 v10, 0x7fff, v10
	v_add_u32_e32 v26, 0x80, v28
	v_ashrrev_i32_e32 v1, 31, v0
	v_ashrrev_i32_e32 v11, 31, v10
	v_min_i32_e32 v16, 0xdff, v28
	v_min_i32_e32 v26, 0xdff, v26
	v_lshl_add_u64 v[8:9], s[84:85], 0, v[128:129]
	v_lshlrev_b64 v[0:1], 11, v[0:1]
	v_lshlrev_b64 v[10:11], 11, v[10:11]
	v_ashrrev_i32_e32 v17, 31, v16
	v_ashrrev_i32_e32 v27, 31, v26
	v_lshl_add_u64 v[134:135], v[8:9], 0, v[0:1]
	v_add_u32_e32 v0, 64, v12
	v_lshl_add_u64 v[138:139], v[8:9], 0, v[10:11]
	v_add_u32_e32 v10, 0xc0, v12
	v_lshlrev_b64 v[188:189], 11, v[16:17]
	v_add_u32_e32 v16, 64, v28
	v_lshlrev_b64 v[192:193], 11, v[26:27]
	v_add_u32_e32 v26, 0xc0, v28
	v_min_i32_e32 v0, 0x7fff, v0
	v_min_i32_e32 v10, 0x7fff, v10
	v_min_i32_e32 v16, 0xdff, v16
	v_min_i32_e32 v26, 0xdff, v26
	v_ashrrev_i32_e32 v1, 31, v0
	v_ashrrev_i32_e32 v11, 31, v10
	v_lshl_add_u64 v[24:25], s[0:1], 0, v[128:129]
	v_ashrrev_i32_e32 v17, 31, v16
	v_ashrrev_i32_e32 v27, 31, v26
	v_lshlrev_b64 v[0:1], 11, v[0:1]
	v_lshlrev_b64 v[10:11], 11, v[10:11]
	v_lshl_add_u64 v[142:143], v[24:25], 0, v[188:189]
	v_lshlrev_b64 v[190:191], 11, v[16:17]
	v_lshl_add_u64 v[146:147], v[24:25], 0, v[192:193]
	v_lshlrev_b64 v[194:195], 11, v[26:27]
	v_lshl_add_u64 v[136:137], v[8:9], 0, v[0:1]
	v_lshl_add_u64 v[140:141], v[8:9], 0, v[10:11]
	v_lshl_add_u64 v[144:145], v[24:25], 0, v[190:191]
	v_lshl_add_u64 v[148:149], v[24:25], 0, v[194:195]
	v_mad_u64_u32 v[132:133], s[4:5], v33, s44, v[128:129]
	v_add_u32_e32 v155, 0x12000, v132
	v_bfe_u32 v133, v32, 6, 2
	v_add_u32_e32 v154, 0x1b000, v132
	v_and_b32_e32 v1, 31, v32
	v_ashrrev_i32_e32 v0, 1, v32
	v_and_or_b32 v151, v0, s45, v1
	v_lshrrev_b32_e32 v0, 2, v32
	v_and_b32_e32 v152, 8, v0
	v_lshlrev_b32_e32 v0, 1, v152
	v_mad_u64_u32 v[130:131], s[4:5], v151, s44, v[0:1]
	v_lshl_or_b32 v1, v133, 6, v1
	v_mul_u32_u24_e32 v1, 0x48, v1
	v_lshl_add_u32 v0, v1, 1, v0
	v_add_u32_e32 v153, 0x12000, v0
	v_add_u32_e32 v131, 0x1b000, v0
	v_lshl_add_u64 v[194:195], s[0:1], 0, v[194:195]
	v_or_b32_e32 v128, 0x100, v128
	v_lshl_add_u64 v[192:193], s[0:1], 0, v[192:193]
	v_lshl_add_u64 v[190:191], s[0:1], 0, v[190:191]
	v_lshl_add_u64 v[188:189], s[0:1], 0, v[188:189]
	v_lshl_add_u64 v[202:203], v[194:195], 0, v[128:129]
	v_lshl_add_u64 v[198:199], v[192:193], 0, v[128:129]
	v_lshl_add_u64 v[192:193], v[190:191], 0, v[128:129]
	v_lshl_add_u64 v[188:189], v[188:189], 0, v[128:129]
	s_nop 0
	s_nop 0
	s_nop 0
	s_nop 0
	s_nop 0
	s_nop 0
	s_nop 0
	s_nop 0
	s_nop 0
	v_lshrrev_b32_e32 v224, 6, v196
	s_mov_b32 s6, 64
	v_readfirstlane_b32 s21, v224
	s_mov_b32 s7, 0
	s_mov_b32 s10, 0x40000
	s_mov_b32 s11, 0
	v_bfe_u32 v222, v196, 2, 4
	s_lshl_b32 s25, s21, 3
	v_add_u32_e32 v222, s25, v222
	s_mov_b32 s25, 0x800
	v_mul_lo_u32 v222, v222, s25
	v_bfe_u32 v224, v196, 4, 2
	v_and_b32_e32 v223, 3, v196
	v_xor_b32_e32 v224, v223, v224
	v_lshl_add_u32 v222, v224, 4, v222
	v_mov_b32_e32 v223, 0
	v_readlane_b32 s22, v134, 0
	v_readlane_b32 s23, v135, 0
	s_nop 1
	v_lshl_add_u64 v[214:215], s[22:23], 0, v[222:223]
	v_lshl_add_u64 v[216:217], v[214:215], 0, s[10:11]
	v_readlane_b32 s22, v142, 0
	v_readlane_b32 s23, v143, 0
	s_nop 1
	v_lshl_add_u64 v[218:219], s[22:23], 0, v[222:223]
	v_lshl_add_u64 v[220:221], v[218:219], 0, s[10:11]
	v_and_b32_e32 v222, 31, v196
	v_bfe_u32 v224, v196, 2, 2
	v_bfe_u32 v223, v196, 5, 1
	v_xor_b32_e32 v224, v223, v224
	v_lshlrev_b32_e32 v224, 4, v224
	v_lshl_or_b32 v222, v222, 6, v224
	s_lshr_b32 s25, s21, 2
	s_lshl_b32 s25, s25, 13
	v_add_u32_e32 v132, s25, v222
	s_and_b32 s25, s21, 3
	s_lshl_b32 s25, s25, 12
	s_add_u32 s25, s25, 0x4000
	v_add_u32_e32 v154, s25, v222
	v_xor_b32_e32 v153, 0x20, v132
	v_xor_b32_e32 v155, 0x20, v154
	v_add_u32_e32 v198, 0x10000, v132
	v_add_u32_e32 v208, 0x10000, v154
	v_add_u32_e32 v210, 0x20000, v132
	v_add_u32_e32 v212, 0x20000, v154
	v_add_u32_e32 v199, 0x10000, v153
	v_add_u32_e32 v209, 0x10000, v155
	v_add_u32_e32 v211, 0x20000, v153
	v_add_u32_e32 v213, 0x20000, v155
	s_lshl_b32 s21, s21, 10
	s_waitcnt lgkmcnt(0)
	s_barrier
; #define G_LOADA(kt_) { _Pragma("unroll") for (int i = 0; i < 4; ++i) ra[i] = al(lrow + 64 * i, (kt_) * 64 + lck * 8); }
; #define G_LOADB(kt_) { _Pragma("unroll") for (int i = 0; i < 4; ++i) rb[i] = bl(lrow + 64 * i, (kt_) * 64 + lck * 8); }
; #define G_STOREA(buf_) { bf16_t* nA = sA + (buf_) * 256 * GLD; _Pragma("unroll") for (int i = 0; i < 4; ++i) *(u32x4*)(nA + (lrow + 64 * i) * GLD + lck * 8) = ra[i]; }
; #define G_STOREB(buf_) { bf16_t* nB = sB + (buf_) * 256 * GLD; _Pragma("unroll") for (int i = 0; i < 4; ++i) *(u32x4*)(nB + (lrow + 64 * i) * GLD + lck * 8) = rb[i]; }
; template <class AL, class BL, class EP>
; DI void gemm_tile256(AL al, BL bl, EP ep, int K, char* smem) {
;     ...
; #pragma unroll
;   for (int i = 0; i < 4; ++i)
; #pragma unroll
;     for (int j = 0; j < 2; ++j)
; #pragma unroll
;       for (int q = 0; q < 16; ++q) acc[i][j][q] = 0.f;
;   u32x4 ra[4], rb[4];
;   const int KT = K >> 6;
;     ...
;   G_LOADA(0); G_LOADB(0);
;   __syncthreads();
;   G_STOREA(0); G_STOREB(0);
;   if (KT > 1) G_LOADB(1);
;   __syncthreads();
	s_add_u32 m0, s21, 0x0
	s_nop 0
	global_load_lds_dwordx4 v[214:215], off
	v_lshl_add_u64 v[214:215], v[214:215], 0, s[6:7]
	s_add_u32 m0, s21, 0x4000
	s_nop 0
	global_load_lds_dwordx4 v[218:219], off
	v_lshl_add_u64 v[218:219], v[218:219], 0, s[6:7]
	s_add_u32 m0, s21, 0x2000
	s_nop 0
	global_load_lds_dwordx4 v[216:217], off
	v_lshl_add_u64 v[216:217], v[216:217], 0, s[6:7]
	s_add_u32 m0, s21, 0x6000
	s_nop 0
	global_load_lds_dwordx4 v[220:221], off
	v_lshl_add_u64 v[220:221], v[220:221], 0, s[6:7]
	s_add_u32 m0, s21, 0x8000
	s_nop 0
	global_load_lds_dwordx4 v[214:215], off
	v_lshl_add_u64 v[214:215], v[214:215], 0, s[6:7]
	s_add_u32 m0, s21, 0xc000
	s_nop 0
	global_load_lds_dwordx4 v[218:219], off
	v_lshl_add_u64 v[218:219], v[218:219], 0, s[6:7]
	s_add_u32 m0, s21, 0xa000
	s_nop 0
	global_load_lds_dwordx4 v[216:217], off
	v_lshl_add_u64 v[216:217], v[216:217], 0, s[6:7]
	s_add_u32 m0, s21, 0xe000
	s_nop 0
	global_load_lds_dwordx4 v[220:221], off
	v_lshl_add_u64 v[220:221], v[220:221], 0, s[6:7]
	s_add_u32 m0, s21, 0x10000
	s_nop 0
	global_load_lds_dwordx4 v[214:215], off
	v_lshl_add_u64 v[214:215], v[214:215], 0, s[6:7]
	s_add_u32 m0, s21, 0x14000
	s_nop 0
	global_load_lds_dwordx4 v[218:219], off
	v_lshl_add_u64 v[218:219], v[218:219], 0, s[6:7]
	s_add_u32 m0, s21, 0x12000
	s_nop 0
	global_load_lds_dwordx4 v[216:217], off
	v_lshl_add_u64 v[216:217], v[216:217], 0, s[6:7]
	s_add_u32 m0, s21, 0x16000
	s_nop 0
	global_load_lds_dwordx4 v[220:221], off
	v_lshl_add_u64 v[220:221], v[220:221], 0, s[6:7]
	s_add_u32 m0, s21, 0x18000
	s_nop 0
	global_load_lds_dwordx4 v[214:215], off
	v_lshl_add_u64 v[214:215], v[214:215], 0, s[6:7]
	s_add_u32 m0, s21, 0x1c000
	s_nop 0
	global_load_lds_dwordx4 v[218:219], off
	v_lshl_add_u64 v[218:219], v[218:219], 0, s[6:7]
	s_add_u32 m0, s21, 0x1a000
	s_nop 0
	global_load_lds_dwordx4 v[216:217], off
	v_lshl_add_u64 v[216:217], v[216:217], 0, s[6:7]
	s_add_u32 m0, s21, 0x1e000
	s_nop 0
	global_load_lds_dwordx4 v[220:221], off
	v_lshl_add_u64 v[220:221], v[220:221], 0, s[6:7]
	s_add_u32 m0, s21, 0x20000
	s_nop 0
	global_load_lds_dwordx4 v[214:215], off
	v_lshl_add_u64 v[214:215], v[214:215], 0, s[6:7]
	s_add_u32 m0, s21, 0x24000
	s_nop 0
	global_load_lds_dwordx4 v[218:219], off
	v_lshl_add_u64 v[218:219], v[218:219], 0, s[6:7]
	v_mov_b64_e32 v[112:113], 0
	v_mov_b64_e32 v[114:115], 0
	v_mov_b64_e32 v[116:117], 0
	v_mov_b64_e32 v[118:119], 0
	v_mov_b64_e32 v[120:121], 0
	v_mov_b64_e32 v[122:123], 0
	v_mov_b64_e32 v[124:125], 0
	v_mov_b64_e32 v[126:127], 0
	v_mov_b64_e32 v[96:97], 0
	v_mov_b64_e32 v[98:99], 0
	v_mov_b64_e32 v[100:101], 0
	v_mov_b64_e32 v[102:103], 0
	v_mov_b64_e32 v[104:105], 0
	v_mov_b64_e32 v[106:107], 0
	v_mov_b64_e32 v[108:109], 0
	v_mov_b64_e32 v[110:111], 0
	v_mov_b64_e32 v[80:81], 0
	v_mov_b64_e32 v[82:83], 0
	v_mov_b64_e32 v[84:85], 0
	v_mov_b64_e32 v[86:87], 0
	v_mov_b64_e32 v[88:89], 0
	v_mov_b64_e32 v[90:91], 0
	v_mov_b64_e32 v[92:93], 0
	v_mov_b64_e32 v[94:95], 0
	v_mov_b64_e32 v[64:65], 0
	v_mov_b64_e32 v[66:67], 0
	v_mov_b64_e32 v[68:69], 0
	v_mov_b64_e32 v[70:71], 0
	v_mov_b64_e32 v[72:73], 0
	v_mov_b64_e32 v[74:75], 0
	v_mov_b64_e32 v[76:77], 0
	v_mov_b64_e32 v[78:79], 0
	v_mov_b64_e32 v[48:49], 0
	v_mov_b64_e32 v[50:51], 0
	v_mov_b64_e32 v[52:53], 0
	v_mov_b64_e32 v[54:55], 0
	v_mov_b64_e32 v[56:57], 0
	v_mov_b64_e32 v[58:59], 0
	v_mov_b64_e32 v[60:61], 0
	v_mov_b64_e32 v[62:63], 0
	v_mov_b64_e32 v[32:33], 0
	v_mov_b64_e32 v[34:35], 0
	v_mov_b64_e32 v[36:37], 0
	v_mov_b64_e32 v[38:39], 0
	v_mov_b64_e32 v[40:41], 0
	v_mov_b64_e32 v[42:43], 0
	v_mov_b64_e32 v[44:45], 0
	v_mov_b64_e32 v[46:47], 0
	v_mov_b64_e32 v[16:17], 0
	v_mov_b64_e32 v[18:19], 0
	v_mov_b64_e32 v[20:21], 0
	v_mov_b64_e32 v[22:23], 0
	v_mov_b64_e32 v[24:25], 0
	v_mov_b64_e32 v[26:27], 0
	v_mov_b64_e32 v[28:29], 0
	v_mov_b64_e32 v[30:31], 0
	v_mov_b64_e32 v[0:1], 0
	v_mov_b64_e32 v[2:3], 0
	v_mov_b64_e32 v[4:5], 0
	v_mov_b64_e32 v[6:7], 0
	v_mov_b64_e32 v[8:9], 0
	v_mov_b64_e32 v[10:11], 0
	v_mov_b64_e32 v[12:13], 0
	v_mov_b64_e32 v[14:15], 0
	s_lshr_b32 s25, s21, 2
	s_xor_b32 s25, s25, s21
	s_bitcmp1_b32 s25, 10
	s_cbranch_scc0 .Lgk_ph9_np
	s_setprio 1
.Lgk_ph9_np:
	s_mov_b32 s25, 5
	s_waitcnt vmcnt(14)
	s_barrier
	ds_read_b128 v[188:191], v154
	ds_read_b128 v[156:159], v132
	ds_read_b128 v[192:195], v154 offset:2048
	ds_read_b128 v[160:163], v132 offset:2048
	ds_read_b128 v[164:167], v132 offset:4096
	ds_read_b128 v[168:171], v132 offset:6144
; #define G_LOADA(kt_) { _Pragma("unroll") for (int i = 0; i < 4; ++i) ra[i] = al(lrow + 64 * i, (kt_) * 64 + lck * 8); }
; #define G_LOADB(kt_) { _Pragma("unroll") for (int i = 0; i < 4; ++i) rb[i] = bl(lrow + 64 * i, (kt_) * 64 + lck * 8); }
; #define G_STOREA(buf_) { bf16_t* nA = sA + (buf_) * 256 * GLD; _Pragma("unroll") for (int i = 0; i < 4; ++i) *(u32x4*)(nA + (lrow + 64 * i) * GLD + lck * 8) = ra[i]; }
; #define G_STOREB(buf_) { bf16_t* nB = sB + (buf_) * 256 * GLD; _Pragma("unroll") for (int i = 0; i < 4; ++i) *(u32x4*)(nB + (lrow + 64 * i) * GLD + lck * 8) = rb[i]; }
; template <class AL, class BL, class EP>
; DI void gemm_tile256(AL al, BL bl, EP ep, int K, char* smem) {
;     ...
;   G_LOADA(0); G_LOADB(0);
;   __syncthreads();
;   G_STOREA(0); G_STOREB(0);
;   if (KT > 1) G_LOADB(1);
;   __syncthreads();
;   for (int kt = 0; kt < KT; kt += 2) {
;     G_STEP(0, kt);
;     if (kt + 1 >= KT) break;
;     G_STEP(1, kt + 1);
;   }
.Lgk_ph9_loop:
	s_waitcnt lgkmcnt(0)
	v_mfma_f32_32x32x16_bf16 v[112:127], v[188:191], v[156:159], v[112:127]
	ds_read_b128 v[200:203], v155
	ds_read_b128 v[172:175], v153
	v_mfma_f32_32x32x16_bf16 v[96:111], v[192:195], v[156:159], v[96:111]
	ds_read_b128 v[204:207], v155 offset:2048
	ds_read_b128 v[176:179], v153 offset:2048
	v_mfma_f32_32x32x16_bf16 v[80:95], v[188:191], v[160:163], v[80:95]
	ds_read_b128 v[180:183], v153 offset:4096
	ds_read_b128 v[184:187], v153 offset:6144
	v_mfma_f32_32x32x16_bf16 v[64:79], v[192:195], v[160:163], v[64:79]
	s_add_u32 m0, s21, 0x22000
	s_nop 0
	global_load_lds_dwordx4 v[216:217], off
	v_lshl_add_u64 v[216:217], v[216:217], 0, s[6:7]
	v_mfma_f32_32x32x16_bf16 v[48:63], v[188:191], v[164:167], v[48:63]
	v_mfma_f32_32x32x16_bf16 v[32:47], v[192:195], v[164:167], v[32:47]
	v_mfma_f32_32x32x16_bf16 v[16:31], v[188:191], v[168:171], v[16:31]
	v_mfma_f32_32x32x16_bf16 v[0:15], v[192:195], v[168:171], v[0:15]
	s_add_u32 m0, s21, 0x26000
	s_nop 0
	global_load_lds_dwordx4 v[220:221], off
	v_lshl_add_u64 v[220:221], v[220:221], 0, s[6:7]
	s_waitcnt lgkmcnt(0)
	s_waitcnt vmcnt(12)
	s_barrier
	s_waitcnt lgkmcnt(0)
	v_mfma_f32_32x32x16_bf16 v[112:127], v[200:203], v[172:175], v[112:127]
	ds_read_b128 v[188:191], v154 offset:32768
	ds_read_b128 v[156:159], v132 offset:32768
	v_mfma_f32_32x32x16_bf16 v[96:111], v[204:207], v[172:175], v[96:111]
	ds_read_b128 v[192:195], v154 offset:34816
	ds_read_b128 v[160:163], v132 offset:34816
	v_mfma_f32_32x32x16_bf16 v[80:95], v[200:203], v[176:179], v[80:95]
	ds_read_b128 v[164:167], v132 offset:36864
	ds_read_b128 v[168:171], v132 offset:38912
	v_mfma_f32_32x32x16_bf16 v[64:79], v[204:207], v[176:179], v[64:79]
	s_add_u32 m0, s21, 0x0
	s_nop 0
	global_load_lds_dwordx4 v[214:215], off
	v_lshl_add_u64 v[214:215], v[214:215], 0, s[6:7]
	v_mfma_f32_32x32x16_bf16 v[48:63], v[200:203], v[180:183], v[48:63]
	v_mfma_f32_32x32x16_bf16 v[32:47], v[204:207], v[180:183], v[32:47]
	v_mfma_f32_32x32x16_bf16 v[16:31], v[200:203], v[184:187], v[16:31]
	v_mfma_f32_32x32x16_bf16 v[0:15], v[204:207], v[184:187], v[0:15]
	s_add_u32 m0, s21, 0x4000
	s_nop 0
	global_load_lds_dwordx4 v[218:219], off
	v_lshl_add_u64 v[218:219], v[218:219], 0, s[6:7]
	s_waitcnt lgkmcnt(0)
	v_mfma_f32_32x32x16_bf16 v[112:127], v[188:191], v[156:159], v[112:127]
	ds_read_b128 v[200:203], v155 offset:32768
	ds_read_b128 v[172:175], v153 offset:32768
	v_mfma_f32_32x32x16_bf16 v[96:111], v[192:195], v[156:159], v[96:111]
	ds_read_b128 v[204:207], v155 offset:34816
	ds_read_b128 v[176:179], v153 offset:34816
	v_mfma_f32_32x32x16_bf16 v[80:95], v[188:191], v[160:163], v[80:95]
	ds_read_b128 v[180:183], v153 offset:36864
	ds_read_b128 v[184:187], v153 offset:38912
	v_mfma_f32_32x32x16_bf16 v[64:79], v[192:195], v[160:163], v[64:79]
	s_add_u32 m0, s21, 0x2000
	s_nop 0
	global_load_lds_dwordx4 v[216:217], off
	v_lshl_add_u64 v[216:217], v[216:217], 0, s[6:7]
	v_mfma_f32_32x32x16_bf16 v[48:63], v[188:191], v[164:167], v[48:63]
	v_mfma_f32_32x32x16_bf16 v[32:47], v[192:195], v[164:167], v[32:47]
	v_mfma_f32_32x32x16_bf16 v[16:31], v[188:191], v[168:171], v[16:31]
	v_mfma_f32_32x32x16_bf16 v[0:15], v[192:195], v[168:171], v[0:15]
	s_add_u32 m0, s21, 0x6000
	s_nop 0
	global_load_lds_dwordx4 v[220:221], off
	v_lshl_add_u64 v[220:221], v[220:221], 0, s[6:7]
	s_waitcnt lgkmcnt(0)
	s_waitcnt vmcnt(12)
	s_barrier
	s_waitcnt lgkmcnt(0)
	v_mfma_f32_32x32x16_bf16 v[112:127], v[200:203], v[172:175], v[112:127]
	ds_read_b128 v[188:191], v208
	ds_read_b128 v[156:159], v198
	v_mfma_f32_32x32x16_bf16 v[96:111], v[204:207], v[172:175], v[96:111]
	ds_read_b128 v[192:195], v208 offset:2048
	ds_read_b128 v[160:163], v198 offset:2048
	v_mfma_f32_32x32x16_bf16 v[80:95], v[200:203], v[176:179], v[80:95]
	ds_read_b128 v[164:167], v198 offset:4096
	ds_read_b128 v[168:171], v198 offset:6144
	v_mfma_f32_32x32x16_bf16 v[64:79], v[204:207], v[176:179], v[64:79]
	s_add_u32 m0, s21, 0x8000
	s_nop 0
	global_load_lds_dwordx4 v[214:215], off
	v_lshl_add_u64 v[214:215], v[214:215], 0, s[6:7]
	v_mfma_f32_32x32x16_bf16 v[48:63], v[200:203], v[180:183], v[48:63]
	v_mfma_f32_32x32x16_bf16 v[32:47], v[204:207], v[180:183], v[32:47]
	v_mfma_f32_32x32x16_bf16 v[16:31], v[200:203], v[184:187], v[16:31]
	v_mfma_f32_32x32x16_bf16 v[0:15], v[204:207], v[184:187], v[0:15]
	s_add_u32 m0, s21, 0xc000
	s_nop 0
	global_load_lds_dwordx4 v[218:219], off
	v_lshl_add_u64 v[218:219], v[218:219], 0, s[6:7]
	s_waitcnt lgkmcnt(0)
	v_mfma_f32_32x32x16_bf16 v[112:127], v[188:191], v[156:159], v[112:127]
	ds_read_b128 v[200:203], v209
	ds_read_b128 v[172:175], v199
	v_mfma_f32_32x32x16_bf16 v[96:111], v[192:195], v[156:159], v[96:111]
	ds_read_b128 v[204:207], v209 offset:2048
	ds_read_b128 v[176:179], v199 offset:2048
	v_mfma_f32_32x32x16_bf16 v[80:95], v[188:191], v[160:163], v[80:95]
	ds_read_b128 v[180:183], v199 offset:4096
	ds_read_b128 v[184:187], v199 offset:6144
	v_mfma_f32_32x32x16_bf16 v[64:79], v[192:195], v[160:163], v[64:79]
	s_add_u32 m0, s21, 0xa000
	s_nop 0
	global_load_lds_dwordx4 v[216:217], off
	v_lshl_add_u64 v[216:217], v[216:217], 0, s[6:7]
	v_mfma_f32_32x32x16_bf16 v[48:63], v[188:191], v[164:167], v[48:63]
	v_mfma_f32_32x32x16_bf16 v[32:47], v[192:195], v[164:167], v[32:47]
	v_mfma_f32_32x32x16_bf16 v[16:31], v[188:191], v[168:171], v[16:31]
	v_mfma_f32_32x32x16_bf16 v[0:15], v[192:195], v[168:171], v[0:15]
	s_add_u32 m0, s21, 0xe000
	s_nop 0
	global_load_lds_dwordx4 v[220:221], off
	v_lshl_add_u64 v[220:221], v[220:221], 0, s[6:7]
	s_waitcnt lgkmcnt(0)
	s_waitcnt vmcnt(12)
	s_barrier
; #define G_LOADA(kt_) { _Pragma("unroll") for (int i = 0; i < 4; ++i) ra[i] = al(lrow + 64 * i, (kt_) * 64 + lck * 8); }
; #define G_LOADB(kt_) { _Pragma("unroll") for (int i = 0; i < 4; ++i) rb[i] = bl(lrow + 64 * i, (kt_) * 64 + lck * 8); }
; #define G_STOREA(buf_) { bf16_t* nA = sA + (buf_) * 256 * GLD; _Pragma("unroll") for (int i = 0; i < 4; ++i) *(u32x4*)(nA + (lrow + 64 * i) * GLD + lck * 8) = ra[i]; }
; #define G_STOREB(buf_) { bf16_t* nB = sB + (buf_) * 256 * GLD; _Pragma("unroll") for (int i = 0; i < 4; ++i) *(u32x4*)(nB + (lrow + 64 * i) * GLD + lck * 8) = rb[i]; }
; template <class AL, class BL, class EP>
; DI void gemm_tile256(AL al, BL bl, EP ep, int K, char* smem) {
;     ...
;   G_LOADA(0); G_LOADB(0);
;   __syncthreads();
;   G_STOREA(0); G_STOREB(0);
;   if (KT > 1) G_LOADB(1);
;   __syncthreads();
;   for (int kt = 0; kt < KT; kt += 2) {
;     G_STEP(0, kt);
;     if (kt + 1 >= KT) break;
;     G_STEP(1, kt + 1);
;   }
	s_waitcnt lgkmcnt(0)
	v_mfma_f32_32x32x16_bf16 v[112:127], v[200:203], v[172:175], v[112:127]
	ds_read_b128 v[188:191], v208 offset:32768
	ds_read_b128 v[156:159], v198 offset:32768
	v_mfma_f32_32x32x16_bf16 v[96:111], v[204:207], v[172:175], v[96:111]
	ds_read_b128 v[192:195], v208 offset:34816
	ds_read_b128 v[160:163], v198 offset:34816
	v_mfma_f32_32x32x16_bf16 v[80:95], v[200:203], v[176:179], v[80:95]
	ds_read_b128 v[164:167], v198 offset:36864
	ds_read_b128 v[168:171], v198 offset:38912
	v_mfma_f32_32x32x16_bf16 v[64:79], v[204:207], v[176:179], v[64:79]
	s_add_u32 m0, s21, 0x10000
	s_nop 0
	global_load_lds_dwordx4 v[214:215], off
	v_lshl_add_u64 v[214:215], v[214:215], 0, s[6:7]
	v_mfma_f32_32x32x16_bf16 v[48:63], v[200:203], v[180:183], v[48:63]
	v_mfma_f32_32x32x16_bf16 v[32:47], v[204:207], v[180:183], v[32:47]
	v_mfma_f32_32x32x16_bf16 v[16:31], v[200:203], v[184:187], v[16:31]
	v_mfma_f32_32x32x16_bf16 v[0:15], v[204:207], v[184:187], v[0:15]
	s_add_u32 m0, s21, 0x14000
	s_nop 0
	global_load_lds_dwordx4 v[218:219], off
	v_lshl_add_u64 v[218:219], v[218:219], 0, s[6:7]
	s_waitcnt lgkmcnt(0)
	v_mfma_f32_32x32x16_bf16 v[112:127], v[188:191], v[156:159], v[112:127]
	ds_read_b128 v[200:203], v209 offset:32768
	ds_read_b128 v[172:175], v199 offset:32768
	v_mfma_f32_32x32x16_bf16 v[96:111], v[192:195], v[156:159], v[96:111]
	ds_read_b128 v[204:207], v209 offset:34816
	ds_read_b128 v[176:179], v199 offset:34816
	v_mfma_f32_32x32x16_bf16 v[80:95], v[188:191], v[160:163], v[80:95]
	ds_read_b128 v[180:183], v199 offset:36864
	ds_read_b128 v[184:187], v199 offset:38912
	v_mfma_f32_32x32x16_bf16 v[64:79], v[192:195], v[160:163], v[64:79]
	s_add_u32 m0, s21, 0x12000
	s_nop 0
	global_load_lds_dwordx4 v[216:217], off
	v_lshl_add_u64 v[216:217], v[216:217], 0, s[6:7]
	v_mfma_f32_32x32x16_bf16 v[48:63], v[188:191], v[164:167], v[48:63]
	v_mfma_f32_32x32x16_bf16 v[32:47], v[192:195], v[164:167], v[32:47]
	v_mfma_f32_32x32x16_bf16 v[16:31], v[188:191], v[168:171], v[16:31]
	v_mfma_f32_32x32x16_bf16 v[0:15], v[192:195], v[168:171], v[0:15]
	s_add_u32 m0, s21, 0x16000
	s_nop 0
	global_load_lds_dwordx4 v[220:221], off
	v_lshl_add_u64 v[220:221], v[220:221], 0, s[6:7]
	s_waitcnt lgkmcnt(0)
	s_waitcnt vmcnt(12)
	s_barrier
	s_waitcnt lgkmcnt(0)
	v_mfma_f32_32x32x16_bf16 v[112:127], v[200:203], v[172:175], v[112:127]
	ds_read_b128 v[188:191], v212
	ds_read_b128 v[156:159], v210
	v_mfma_f32_32x32x16_bf16 v[96:111], v[204:207], v[172:175], v[96:111]
	ds_read_b128 v[192:195], v212 offset:2048
	ds_read_b128 v[160:163], v210 offset:2048
	v_mfma_f32_32x32x16_bf16 v[80:95], v[200:203], v[176:179], v[80:95]
	ds_read_b128 v[164:167], v210 offset:4096
	ds_read_b128 v[168:171], v210 offset:6144
	v_mfma_f32_32x32x16_bf16 v[64:79], v[204:207], v[176:179], v[64:79]
	s_add_u32 m0, s21, 0x18000
	s_nop 0
	global_load_lds_dwordx4 v[214:215], off
	v_lshl_add_u64 v[214:215], v[214:215], 0, s[6:7]
	v_mfma_f32_32x32x16_bf16 v[48:63], v[200:203], v[180:183], v[48:63]
	v_mfma_f32_32x32x16_bf16 v[32:47], v[204:207], v[180:183], v[32:47]
	v_mfma_f32_32x32x16_bf16 v[16:31], v[200:203], v[184:187], v[16:31]
	v_mfma_f32_32x32x16_bf16 v[0:15], v[204:207], v[184:187], v[0:15]
	s_add_u32 m0, s21, 0x1c000
	s_nop 0
	global_load_lds_dwordx4 v[218:219], off
	v_lshl_add_u64 v[218:219], v[218:219], 0, s[6:7]
	s_waitcnt lgkmcnt(0)
	v_mfma_f32_32x32x16_bf16 v[112:127], v[188:191], v[156:159], v[112:127]
	ds_read_b128 v[200:203], v213
	ds_read_b128 v[172:175], v211
	v_mfma_f32_32x32x16_bf16 v[96:111], v[192:195], v[156:159], v[96:111]
	ds_read_b128 v[204:207], v213 offset:2048
	ds_read_b128 v[176:179], v211 offset:2048
	v_mfma_f32_32x32x16_bf16 v[80:95], v[188:191], v[160:163], v[80:95]
	ds_read_b128 v[180:183], v211 offset:4096
	ds_read_b128 v[184:187], v211 offset:6144
	v_mfma_f32_32x32x16_bf16 v[64:79], v[192:195], v[160:163], v[64:79]
	s_add_u32 m0, s21, 0x1a000
	s_nop 0
	global_load_lds_dwordx4 v[216:217], off
	v_lshl_add_u64 v[216:217], v[216:217], 0, s[6:7]
	v_mfma_f32_32x32x16_bf16 v[48:63], v[188:191], v[164:167], v[48:63]
	v_mfma_f32_32x32x16_bf16 v[32:47], v[192:195], v[164:167], v[32:47]
	v_mfma_f32_32x32x16_bf16 v[16:31], v[188:191], v[168:171], v[16:31]
	v_mfma_f32_32x32x16_bf16 v[0:15], v[192:195], v[168:171], v[0:15]
	s_add_u32 m0, s21, 0x1e000
	s_nop 0
	global_load_lds_dwordx4 v[220:221], off
	v_lshl_add_u64 v[220:221], v[220:221], 0, s[6:7]
	s_waitcnt lgkmcnt(0)
	s_waitcnt vmcnt(12)
	s_barrier
	s_waitcnt lgkmcnt(0)
	v_mfma_f32_32x32x16_bf16 v[112:127], v[200:203], v[172:175], v[112:127]
	ds_read_b128 v[188:191], v154
	ds_read_b128 v[156:159], v132
	v_mfma_f32_32x32x16_bf16 v[96:111], v[204:207], v[172:175], v[96:111]
	ds_read_b128 v[192:195], v154 offset:2048
	ds_read_b128 v[160:163], v132 offset:2048
	v_mfma_f32_32x32x16_bf16 v[80:95], v[200:203], v[176:179], v[80:95]
	ds_read_b128 v[164:167], v132 offset:4096
	ds_read_b128 v[168:171], v132 offset:6144
	v_mfma_f32_32x32x16_bf16 v[64:79], v[204:207], v[176:179], v[64:79]
	s_add_u32 m0, s21, 0x20000
	s_nop 0
	global_load_lds_dwordx4 v[214:215], off
	v_lshl_add_u64 v[214:215], v[214:215], 0, s[6:7]
	v_mfma_f32_32x32x16_bf16 v[48:63], v[200:203], v[180:183], v[48:63]
	v_mfma_f32_32x32x16_bf16 v[32:47], v[204:207], v[180:183], v[32:47]
	v_mfma_f32_32x32x16_bf16 v[16:31], v[200:203], v[184:187], v[16:31]
	v_mfma_f32_32x32x16_bf16 v[0:15], v[204:207], v[184:187], v[0:15]
	s_add_u32 m0, s21, 0x24000
	s_nop 0
	global_load_lds_dwordx4 v[218:219], off
	v_lshl_add_u64 v[218:219], v[218:219], 0, s[6:7]
	s_sub_u32 s25, s25, 1
	s_cmp_lg_u32 s25, 0
	s_cbranch_scc1 .Lgk_ph9_loop
; #define G_LOADA(kt_) { _Pragma("unroll") for (int i = 0; i < 4; ++i) ra[i] = al(lrow + 64 * i, (kt_) * 64 + lck * 8); }
; #define G_LOADB(kt_) { _Pragma("unroll") for (int i = 0; i < 4; ++i) rb[i] = bl(lrow + 64 * i, (kt_) * 64 + lck * 8); }
; #define G_STOREA(buf_) { bf16_t* nA = sA + (buf_) * 256 * GLD; _Pragma("unroll") for (int i = 0; i < 4; ++i) *(u32x4*)(nA + (lrow + 64 * i) * GLD + lck * 8) = ra[i]; }
; #define G_STOREB(buf_) { bf16_t* nB = sB + (buf_) * 256 * GLD; _Pragma("unroll") for (int i = 0; i < 4; ++i) *(u32x4*)(nB + (lrow + 64 * i) * GLD + lck * 8) = rb[i]; }
; template <class AL, class BL, class EP>
; DI void gemm_tile256(AL al, BL bl, EP ep, int K, char* smem) {
;     ...
;   G_LOADA(0); G_LOADB(0);
;   __syncthreads();
;   G_STOREA(0); G_STOREB(0);
;   if (KT > 1) G_LOADB(1);
;   __syncthreads();
;   for (int kt = 0; kt < KT; kt += 2) {
;     G_STEP(0, kt);
;     if (kt + 1 >= KT) break;
;     G_STEP(1, kt + 1);
;   }
	s_waitcnt lgkmcnt(0)
	v_mfma_f32_32x32x16_bf16 v[112:127], v[188:191], v[156:159], v[112:127]
	ds_read_b128 v[200:203], v155
	ds_read_b128 v[172:175], v153
	v_mfma_f32_32x32x16_bf16 v[96:111], v[192:195], v[156:159], v[96:111]
	ds_read_b128 v[204:207], v155 offset:2048
	ds_read_b128 v[176:179], v153 offset:2048
	v_mfma_f32_32x32x16_bf16 v[80:95], v[188:191], v[160:163], v[80:95]
	ds_read_b128 v[180:183], v153 offset:4096
	ds_read_b128 v[184:187], v153 offset:6144
	v_mfma_f32_32x32x16_bf16 v[64:79], v[192:195], v[160:163], v[64:79]
	s_add_u32 m0, s21, 0x22000
	s_nop 0
	global_load_lds_dwordx4 v[216:217], off
	v_lshl_add_u64 v[216:217], v[216:217], 0, s[6:7]
	v_mfma_f32_32x32x16_bf16 v[48:63], v[188:191], v[164:167], v[48:63]
	v_mfma_f32_32x32x16_bf16 v[32:47], v[192:195], v[164:167], v[32:47]
	v_mfma_f32_32x32x16_bf16 v[16:31], v[188:191], v[168:171], v[16:31]
	v_mfma_f32_32x32x16_bf16 v[0:15], v[192:195], v[168:171], v[0:15]
	s_add_u32 m0, s21, 0x26000
	s_nop 0
	global_load_lds_dwordx4 v[220:221], off
	v_lshl_add_u64 v[220:221], v[220:221], 0, s[6:7]
	s_waitcnt lgkmcnt(0)
	s_waitcnt vmcnt(12)
	s_barrier
	s_waitcnt lgkmcnt(0)
	v_mfma_f32_32x32x16_bf16 v[112:127], v[200:203], v[172:175], v[112:127]
	ds_read_b128 v[188:191], v154 offset:32768
	ds_read_b128 v[156:159], v132 offset:32768
	v_mfma_f32_32x32x16_bf16 v[96:111], v[204:207], v[172:175], v[96:111]
	ds_read_b128 v[192:195], v154 offset:34816
	ds_read_b128 v[160:163], v132 offset:34816
	v_mfma_f32_32x32x16_bf16 v[80:95], v[200:203], v[176:179], v[80:95]
	ds_read_b128 v[164:167], v132 offset:36864
	ds_read_b128 v[168:171], v132 offset:38912
	v_mfma_f32_32x32x16_bf16 v[64:79], v[204:207], v[176:179], v[64:79]
	s_add_u32 m0, s21, 0x0
	s_nop 0
	global_load_lds_dwordx4 v[214:215], off
	v_lshl_add_u64 v[214:215], v[214:215], 0, s[6:7]
	v_mfma_f32_32x32x16_bf16 v[48:63], v[200:203], v[180:183], v[48:63]
	v_mfma_f32_32x32x16_bf16 v[32:47], v[204:207], v[180:183], v[32:47]
	v_mfma_f32_32x32x16_bf16 v[16:31], v[200:203], v[184:187], v[16:31]
	v_mfma_f32_32x32x16_bf16 v[0:15], v[204:207], v[184:187], v[0:15]
	s_add_u32 m0, s21, 0x4000
	s_nop 0
	global_load_lds_dwordx4 v[218:219], off
	v_lshl_add_u64 v[218:219], v[218:219], 0, s[6:7]
	s_waitcnt lgkmcnt(0)
	v_mfma_f32_32x32x16_bf16 v[112:127], v[188:191], v[156:159], v[112:127]
	ds_read_b128 v[200:203], v155 offset:32768
	ds_read_b128 v[172:175], v153 offset:32768
	v_mfma_f32_32x32x16_bf16 v[96:111], v[192:195], v[156:159], v[96:111]
	ds_read_b128 v[204:207], v155 offset:34816
	ds_read_b128 v[176:179], v153 offset:34816
	v_mfma_f32_32x32x16_bf16 v[80:95], v[188:191], v[160:163], v[80:95]
	ds_read_b128 v[180:183], v153 offset:36864
	ds_read_b128 v[184:187], v153 offset:38912
	v_mfma_f32_32x32x16_bf16 v[64:79], v[192:195], v[160:163], v[64:79]
	s_add_u32 m0, s21, 0x2000
	s_nop 0
	global_load_lds_dwordx4 v[216:217], off
	v_lshl_add_u64 v[216:217], v[216:217], 0, s[6:7]
	v_mfma_f32_32x32x16_bf16 v[48:63], v[188:191], v[164:167], v[48:63]
	v_mfma_f32_32x32x16_bf16 v[32:47], v[192:195], v[164:167], v[32:47]
	v_mfma_f32_32x32x16_bf16 v[16:31], v[188:191], v[168:171], v[16:31]
	v_mfma_f32_32x32x16_bf16 v[0:15], v[192:195], v[168:171], v[0:15]
	s_add_u32 m0, s21, 0x6000
	s_nop 0
	global_load_lds_dwordx4 v[220:221], off
	v_lshl_add_u64 v[220:221], v[220:221], 0, s[6:7]
	s_waitcnt lgkmcnt(0)
	s_waitcnt vmcnt(12)
	s_barrier
	s_waitcnt lgkmcnt(0)
	v_mfma_f32_32x32x16_bf16 v[112:127], v[200:203], v[172:175], v[112:127]
	ds_read_b128 v[188:191], v208
	ds_read_b128 v[156:159], v198
	v_mfma_f32_32x32x16_bf16 v[96:111], v[204:207], v[172:175], v[96:111]
	ds_read_b128 v[192:195], v208 offset:2048
	ds_read_b128 v[160:163], v198 offset:2048
	v_mfma_f32_32x32x16_bf16 v[80:95], v[200:203], v[176:179], v[80:95]
	ds_read_b128 v[164:167], v198 offset:4096
	ds_read_b128 v[168:171], v198 offset:6144
	v_mfma_f32_32x32x16_bf16 v[64:79], v[204:207], v[176:179], v[64:79]
	s_add_u32 m0, s21, 0x8000
	s_nop 0
	global_load_lds_dwordx4 v[214:215], off
	v_lshl_add_u64 v[214:215], v[214:215], 0, s[6:7]
	v_mfma_f32_32x32x16_bf16 v[48:63], v[200:203], v[180:183], v[48:63]
	v_mfma_f32_32x32x16_bf16 v[32:47], v[204:207], v[180:183], v[32:47]
	v_mfma_f32_32x32x16_bf16 v[16:31], v[200:203], v[184:187], v[16:31]
	v_mfma_f32_32x32x16_bf16 v[0:15], v[204:207], v[184:187], v[0:15]
	s_add_u32 m0, s21, 0xc000
	s_nop 0
	global_load_lds_dwordx4 v[218:219], off
	v_lshl_add_u64 v[218:219], v[218:219], 0, s[6:7]
	s_waitcnt lgkmcnt(0)
	v_mfma_f32_32x32x16_bf16 v[112:127], v[188:191], v[156:159], v[112:127]
	ds_read_b128 v[200:203], v209
	ds_read_b128 v[172:175], v199
	v_mfma_f32_32x32x16_bf16 v[96:111], v[192:195], v[156:159], v[96:111]
	ds_read_b128 v[204:207], v209 offset:2048
	ds_read_b128 v[176:179], v199 offset:2048
	v_mfma_f32_32x32x16_bf16 v[80:95], v[188:191], v[160:163], v[80:95]
	ds_read_b128 v[180:183], v199 offset:4096
	ds_read_b128 v[184:187], v199 offset:6144
	v_mfma_f32_32x32x16_bf16 v[64:79], v[192:195], v[160:163], v[64:79]
	s_add_u32 m0, s21, 0xa000
	s_nop 0
	global_load_lds_dwordx4 v[216:217], off
	v_lshl_add_u64 v[216:217], v[216:217], 0, s[6:7]
	v_mfma_f32_32x32x16_bf16 v[48:63], v[188:191], v[164:167], v[48:63]
	v_mfma_f32_32x32x16_bf16 v[32:47], v[192:195], v[164:167], v[32:47]
	v_mfma_f32_32x32x16_bf16 v[16:31], v[188:191], v[168:171], v[16:31]
	v_mfma_f32_32x32x16_bf16 v[0:15], v[192:195], v[168:171], v[0:15]
	s_add_u32 m0, s21, 0xe000
	s_nop 0
	global_load_lds_dwordx4 v[220:221], off
	v_lshl_add_u64 v[220:221], v[220:221], 0, s[6:7]
	s_waitcnt lgkmcnt(0)
	s_waitcnt vmcnt(12)
	s_barrier
; #define G_LOADA(kt_) { _Pragma("unroll") for (int i = 0; i < 4; ++i) ra[i] = al(lrow + 64 * i, (kt_) * 64 + lck * 8); }
; #define G_LOADB(kt_) { _Pragma("unroll") for (int i = 0; i < 4; ++i) rb[i] = bl(lrow + 64 * i, (kt_) * 64 + lck * 8); }
; #define G_STOREA(buf_) { bf16_t* nA = sA + (buf_) * 256 * GLD; _Pragma("unroll") for (int i = 0; i < 4; ++i) *(u32x4*)(nA + (lrow + 64 * i) * GLD + lck * 8) = ra[i]; }
; #define G_STOREB(buf_) { bf16_t* nB = sB + (buf_) * 256 * GLD; _Pragma("unroll") for (int i = 0; i < 4; ++i) *(u32x4*)(nB + (lrow + 64 * i) * GLD + lck * 8) = rb[i]; }
; template <class AL, class BL, class EP>
; DI void gemm_tile256(AL al, BL bl, EP ep, int K, char* smem) {
;     ...
;   G_LOADA(0); G_LOADB(0);
;   __syncthreads();
;   G_STOREA(0); G_STOREB(0);
;   if (KT > 1) G_LOADB(1);
;   __syncthreads();
;   for (int kt = 0; kt < KT; kt += 2) {
;     G_STEP(0, kt);
;     if (kt + 1 >= KT) break;
;     G_STEP(1, kt + 1);
;   }
	s_waitcnt lgkmcnt(0)
	v_mfma_f32_32x32x16_bf16 v[112:127], v[200:203], v[172:175], v[112:127]
	ds_read_b128 v[188:191], v208 offset:32768
	ds_read_b128 v[156:159], v198 offset:32768
	v_mfma_f32_32x32x16_bf16 v[96:111], v[204:207], v[172:175], v[96:111]
	ds_read_b128 v[192:195], v208 offset:34816
	ds_read_b128 v[160:163], v198 offset:34816
	v_mfma_f32_32x32x16_bf16 v[80:95], v[200:203], v[176:179], v[80:95]
	ds_read_b128 v[164:167], v198 offset:36864
	ds_read_b128 v[168:171], v198 offset:38912
	v_mfma_f32_32x32x16_bf16 v[64:79], v[204:207], v[176:179], v[64:79]
	v_mfma_f32_32x32x16_bf16 v[48:63], v[200:203], v[180:183], v[48:63]
	v_mfma_f32_32x32x16_bf16 v[32:47], v[204:207], v[180:183], v[32:47]
	v_mfma_f32_32x32x16_bf16 v[16:31], v[200:203], v[184:187], v[16:31]
	v_mfma_f32_32x32x16_bf16 v[0:15], v[204:207], v[184:187], v[0:15]
	s_waitcnt lgkmcnt(0)
	v_mfma_f32_32x32x16_bf16 v[112:127], v[188:191], v[156:159], v[112:127]
	ds_read_b128 v[200:203], v209 offset:32768
	ds_read_b128 v[172:175], v199 offset:32768
	v_mfma_f32_32x32x16_bf16 v[96:111], v[192:195], v[156:159], v[96:111]
	ds_read_b128 v[204:207], v209 offset:34816
	ds_read_b128 v[176:179], v199 offset:34816
	v_mfma_f32_32x32x16_bf16 v[80:95], v[188:191], v[160:163], v[80:95]
	ds_read_b128 v[180:183], v199 offset:36864
	ds_read_b128 v[184:187], v199 offset:38912
	v_mfma_f32_32x32x16_bf16 v[64:79], v[192:195], v[160:163], v[64:79]
	v_mfma_f32_32x32x16_bf16 v[48:63], v[188:191], v[164:167], v[48:63]
	v_mfma_f32_32x32x16_bf16 v[32:47], v[192:195], v[164:167], v[32:47]
	v_mfma_f32_32x32x16_bf16 v[16:31], v[188:191], v[168:171], v[16:31]
	v_mfma_f32_32x32x16_bf16 v[0:15], v[192:195], v[168:171], v[0:15]
	s_waitcnt lgkmcnt(0)
	s_waitcnt vmcnt(8)
	s_barrier
	s_waitcnt lgkmcnt(0)
	v_mfma_f32_32x32x16_bf16 v[112:127], v[200:203], v[172:175], v[112:127]
	ds_read_b128 v[188:191], v212
	ds_read_b128 v[156:159], v210
	v_mfma_f32_32x32x16_bf16 v[96:111], v[204:207], v[172:175], v[96:111]
	ds_read_b128 v[192:195], v212 offset:2048
	ds_read_b128 v[160:163], v210 offset:2048
	v_mfma_f32_32x32x16_bf16 v[80:95], v[200:203], v[176:179], v[80:95]
	ds_read_b128 v[164:167], v210 offset:4096
	ds_read_b128 v[168:171], v210 offset:6144
	v_mfma_f32_32x32x16_bf16 v[64:79], v[204:207], v[176:179], v[64:79]
	v_mfma_f32_32x32x16_bf16 v[48:63], v[200:203], v[180:183], v[48:63]
	v_mfma_f32_32x32x16_bf16 v[32:47], v[204:207], v[180:183], v[32:47]
	v_mfma_f32_32x32x16_bf16 v[16:31], v[200:203], v[184:187], v[16:31]
	v_mfma_f32_32x32x16_bf16 v[0:15], v[204:207], v[184:187], v[0:15]
	s_waitcnt lgkmcnt(0)
	v_mfma_f32_32x32x16_bf16 v[112:127], v[188:191], v[156:159], v[112:127]
	ds_read_b128 v[200:203], v213
	ds_read_b128 v[172:175], v211
	v_mfma_f32_32x32x16_bf16 v[96:111], v[192:195], v[156:159], v[96:111]
	ds_read_b128 v[204:207], v213 offset:2048
	ds_read_b128 v[176:179], v211 offset:2048
	v_mfma_f32_32x32x16_bf16 v[80:95], v[188:191], v[160:163], v[80:95]
	ds_read_b128 v[180:183], v211 offset:4096
	ds_read_b128 v[184:187], v211 offset:6144
	v_mfma_f32_32x32x16_bf16 v[64:79], v[192:195], v[160:163], v[64:79]
	v_mfma_f32_32x32x16_bf16 v[48:63], v[188:191], v[164:167], v[48:63]
	v_mfma_f32_32x32x16_bf16 v[32:47], v[192:195], v[164:167], v[32:47]
	v_mfma_f32_32x32x16_bf16 v[16:31], v[188:191], v[168:171], v[16:31]
	v_mfma_f32_32x32x16_bf16 v[0:15], v[192:195], v[168:171], v[0:15]
	s_waitcnt lgkmcnt(0)
	s_waitcnt vmcnt(4)
	s_barrier
	s_waitcnt lgkmcnt(0)
	v_mfma_f32_32x32x16_bf16 v[112:127], v[200:203], v[172:175], v[112:127]
	ds_read_b128 v[188:191], v154
	ds_read_b128 v[156:159], v132
	v_mfma_f32_32x32x16_bf16 v[96:111], v[204:207], v[172:175], v[96:111]
	ds_read_b128 v[192:195], v154 offset:2048
	ds_read_b128 v[160:163], v132 offset:2048
	v_mfma_f32_32x32x16_bf16 v[80:95], v[200:203], v[176:179], v[80:95]
	ds_read_b128 v[164:167], v132 offset:4096
	ds_read_b128 v[168:171], v132 offset:6144
	v_mfma_f32_32x32x16_bf16 v[64:79], v[204:207], v[176:179], v[64:79]
	v_mfma_f32_32x32x16_bf16 v[48:63], v[200:203], v[180:183], v[48:63]
	v_mfma_f32_32x32x16_bf16 v[32:47], v[204:207], v[180:183], v[32:47]
	v_mfma_f32_32x32x16_bf16 v[16:31], v[200:203], v[184:187], v[16:31]
	v_mfma_f32_32x32x16_bf16 v[0:15], v[204:207], v[184:187], v[0:15]
	s_waitcnt lgkmcnt(0)
	v_mfma_f32_32x32x16_bf16 v[112:127], v[188:191], v[156:159], v[112:127]
	ds_read_b128 v[200:203], v155
	ds_read_b128 v[172:175], v153
	v_mfma_f32_32x32x16_bf16 v[96:111], v[192:195], v[156:159], v[96:111]
	ds_read_b128 v[204:207], v155 offset:2048
	ds_read_b128 v[176:179], v153 offset:2048
	v_mfma_f32_32x32x16_bf16 v[80:95], v[188:191], v[160:163], v[80:95]
	ds_read_b128 v[180:183], v153 offset:4096
	ds_read_b128 v[184:187], v153 offset:6144
	v_mfma_f32_32x32x16_bf16 v[64:79], v[192:195], v[160:163], v[64:79]
	v_mfma_f32_32x32x16_bf16 v[48:63], v[188:191], v[164:167], v[48:63]
	v_mfma_f32_32x32x16_bf16 v[32:47], v[192:195], v[164:167], v[32:47]
	v_mfma_f32_32x32x16_bf16 v[16:31], v[188:191], v[168:171], v[16:31]
	v_mfma_f32_32x32x16_bf16 v[0:15], v[192:195], v[168:171], v[0:15]
	s_waitcnt lgkmcnt(0)
	s_waitcnt vmcnt(0)
	s_barrier
; DI unsigned pack2(float a, float b) { f2_t f = {a, b}; bf2_t r = __builtin_convertvector(f, bf2_t); return __builtin_bit_cast(unsigned, r); }
; template <class AL, class BL, class EP>
; DI void gemm_tile256(AL al, BL bl, EP ep, int K, char* smem) {
;     ...
;   if constexpr (EP::kBf16) {
;     bf16_t* sCb = (bf16_t*)smem;
; #pragma unroll
;     for (int i = 0; i < 4; ++i)
; #pragma unroll
;       for (int j = 0; j < 2; ++j)
; #pragma unroll
;         for (int g = 0; g < 4; ++g) {
;           u32x2 v = {pack2(acc[i][j][4 * g], acc[i][j][4 * g + 1]), pack2(acc[i][j][4 * g + 2], acc[i][j][4 * g + 3])};
;           *(u32x2*)(sCb + (128 * wm + 32 * i + r) * BLD + 64 * wn + 32 * j + 8 * g + 4 * h) = v;
;         }
;     __syncthreads();
	s_waitcnt lgkmcnt(0)
	v_mfma_f32_32x32x16_bf16 v[112:127], v[200:203], v[172:175], v[112:127]
	ds_read_b128 v[188:191], v154 offset:32768
	ds_read_b128 v[156:159], v132 offset:32768
	v_mfma_f32_32x32x16_bf16 v[96:111], v[204:207], v[172:175], v[96:111]
	ds_read_b128 v[192:195], v154 offset:34816
	ds_read_b128 v[160:163], v132 offset:34816
	v_mfma_f32_32x32x16_bf16 v[80:95], v[200:203], v[176:179], v[80:95]
	ds_read_b128 v[164:167], v132 offset:36864
	ds_read_b128 v[168:171], v132 offset:38912
	v_mfma_f32_32x32x16_bf16 v[64:79], v[204:207], v[176:179], v[64:79]
	v_mfma_f32_32x32x16_bf16 v[48:63], v[200:203], v[180:183], v[48:63]
	v_mfma_f32_32x32x16_bf16 v[32:47], v[204:207], v[180:183], v[32:47]
	v_mfma_f32_32x32x16_bf16 v[16:31], v[200:203], v[184:187], v[16:31]
	v_mfma_f32_32x32x16_bf16 v[0:15], v[204:207], v[184:187], v[0:15]
	s_waitcnt lgkmcnt(0)
	v_mfma_f32_32x32x16_bf16 v[112:127], v[188:191], v[156:159], v[112:127]
	ds_read_b128 v[200:203], v155 offset:32768
	ds_read_b128 v[172:175], v153 offset:32768
	v_mfma_f32_32x32x16_bf16 v[96:111], v[192:195], v[156:159], v[96:111]
	ds_read_b128 v[204:207], v155 offset:34816
	ds_read_b128 v[176:179], v153 offset:34816
	v_mfma_f32_32x32x16_bf16 v[80:95], v[188:191], v[160:163], v[80:95]
	ds_read_b128 v[180:183], v153 offset:36864
	ds_read_b128 v[184:187], v153 offset:38912
	v_mfma_f32_32x32x16_bf16 v[64:79], v[192:195], v[160:163], v[64:79]
	v_mfma_f32_32x32x16_bf16 v[48:63], v[188:191], v[164:167], v[48:63]
	v_mfma_f32_32x32x16_bf16 v[32:47], v[192:195], v[164:167], v[32:47]
	v_mfma_f32_32x32x16_bf16 v[16:31], v[188:191], v[168:171], v[16:31]
	v_mfma_f32_32x32x16_bf16 v[0:15], v[192:195], v[168:171], v[0:15]
	s_waitcnt lgkmcnt(0)
	s_waitcnt lgkmcnt(0)
	v_mfma_f32_32x32x16_bf16 v[112:127], v[200:203], v[172:175], v[112:127]
	v_mfma_f32_32x32x16_bf16 v[96:111], v[204:207], v[172:175], v[96:111]
	v_mfma_f32_32x32x16_bf16 v[80:95], v[200:203], v[176:179], v[80:95]
	v_mfma_f32_32x32x16_bf16 v[64:79], v[204:207], v[176:179], v[64:79]
	v_mfma_f32_32x32x16_bf16 v[48:63], v[200:203], v[180:183], v[48:63]
	v_mfma_f32_32x32x16_bf16 v[32:47], v[204:207], v[180:183], v[32:47]
	v_mfma_f32_32x32x16_bf16 v[16:31], v[200:203], v[184:187], v[16:31]
	v_mfma_f32_32x32x16_bf16 v[0:15], v[204:207], v[184:187], v[0:15]
	s_nop 15
	s_nop 3
	s_setprio 0
	v_lshl_or_b32 v128, v133, 7, v152
	s_waitcnt lgkmcnt(4)
	v_mad_u64_u32 v[130:131], s[4:5], v151, s46, v[128:129]
	s_and_b32 s24, s52, 0xf00
	s_waitcnt lgkmcnt(0)
	s_barrier
	s_cmp_gt_i32 s20, 3
	s_nop 5
	v_cvt_pk_bf16_f32 v112, v112, v113
	v_cvt_pk_bf16_f32 v113, v114, v115
	v_cvt_pk_bf16_f32 v114, v116, v117
	v_cvt_pk_bf16_f32 v115, v118, v119
	ds_write2_b64 v130, v[112:113], v[114:115] offset1:2
	v_cvt_pk_bf16_f32 v112, v120, v121
	v_cvt_pk_bf16_f32 v113, v122, v123
	v_cvt_pk_bf16_f32 v96, v96, v97
	v_cvt_pk_bf16_f32 v97, v98, v99
	v_cvt_pk_bf16_f32 v98, v100, v101
	v_cvt_pk_bf16_f32 v99, v102, v103
	v_cvt_pk_bf16_f32 v114, v124, v125
	v_cvt_pk_bf16_f32 v115, v126, v127
	ds_write2_b64 v130, v[96:97], v[98:99] offset0:8 offset1:10
	s_nop 3
	v_cvt_pk_bf16_f32 v80, v80, v81
	v_cvt_pk_bf16_f32 v81, v82, v83
	v_cvt_pk_bf16_f32 v82, v84, v85
	v_cvt_pk_bf16_f32 v83, v86, v87
	v_add_u32_e32 v84, 0x4000, v130
	v_cvt_pk_bf16_f32 v96, v104, v105
	v_cvt_pk_bf16_f32 v97, v106, v107
	v_cvt_pk_bf16_f32 v64, v64, v65
	v_cvt_pk_bf16_f32 v65, v66, v67
	v_cvt_pk_bf16_f32 v66, v68, v69
	v_cvt_pk_bf16_f32 v67, v70, v71
	v_cvt_pk_bf16_f32 v98, v108, v109
	v_cvt_pk_bf16_f32 v99, v110, v111
	ds_write2_b64 v84, v[80:81], v[82:83] offset0:64 offset1:66
	s_nop 3
	v_cvt_pk_bf16_f32 v48, v48, v49
	v_cvt_pk_bf16_f32 v49, v50, v51
	v_cvt_pk_bf16_f32 v50, v52, v53
	v_cvt_pk_bf16_f32 v51, v54, v55
	v_add_u32_e32 v52, 0x8000, v130
	v_cvt_pk_bf16_f32 v80, v88, v89
	v_cvt_pk_bf16_f32 v81, v90, v91
	v_cvt_pk_bf16_f32 v32, v32, v33
	v_cvt_pk_bf16_f32 v33, v34, v35
	v_cvt_pk_bf16_f32 v34, v36, v37
	v_cvt_pk_bf16_f32 v35, v38, v39
	v_cvt_pk_bf16_f32 v82, v92, v93
	v_cvt_pk_bf16_f32 v83, v94, v95
	ds_write2_b64 v84, v[64:65], v[66:67] offset0:72 offset1:74
	s_nop 3
	v_cvt_pk_bf16_f32 v16, v16, v17
	v_cvt_pk_bf16_f32 v17, v18, v19
	v_cvt_pk_bf16_f32 v18, v20, v21
	v_cvt_pk_bf16_f32 v19, v22, v23
	v_add_u32_e32 v20, 0xc000, v130
	v_cvt_pk_bf16_f32 v64, v72, v73
	v_cvt_pk_bf16_f32 v65, v74, v75
	s_nop 0
	v_cvt_pk_bf16_f32 v0, v0, v1
	v_cvt_pk_bf16_f32 v1, v2, v3
	v_cvt_pk_bf16_f32 v2, v4, v5
	v_cvt_pk_bf16_f32 v3, v6, v7
	v_cvt_pk_bf16_f32 v66, v76, v77
	v_cvt_pk_bf16_f32 v67, v78, v79
	ds_write2_b64 v52, v[48:49], v[50:51] offset0:128 offset1:130
	v_cvt_pk_bf16_f32 v48, v56, v57
	v_cvt_pk_bf16_f32 v49, v58, v59
	v_cvt_pk_bf16_f32 v50, v60, v61
	v_cvt_pk_bf16_f32 v51, v62, v63
	ds_write2_b64 v52, v[32:33], v[34:35] offset0:136 offset1:138
	v_cvt_pk_bf16_f32 v32, v40, v41
	v_cvt_pk_bf16_f32 v33, v42, v43
	v_cvt_pk_bf16_f32 v34, v44, v45
	v_cvt_pk_bf16_f32 v35, v46, v47
	ds_write2_b64 v20, v[16:17], v[18:19] offset0:192 offset1:194
	v_cvt_pk_bf16_f32 v16, v24, v25
	v_cvt_pk_bf16_f32 v17, v26, v27
	v_cvt_pk_bf16_f32 v18, v28, v29
	v_cvt_pk_bf16_f32 v19, v30, v31
	ds_write2_b64 v20, v[0:1], v[2:3] offset0:200 offset1:202
	v_cvt_pk_bf16_f32 v0, v8, v9
	v_cvt_pk_bf16_f32 v1, v10, v11
	v_cvt_pk_bf16_f32 v2, v12, v13
	v_cvt_pk_bf16_f32 v3, v14, v15
	ds_write2_b64 v130, v[112:113], v[114:115] offset0:4 offset1:6
	ds_write2_b64 v130, v[96:97], v[98:99] offset0:12 offset1:14
	ds_write2_b64 v84, v[80:81], v[82:83] offset0:68 offset1:70
	ds_write2_b64 v84, v[64:65], v[66:67] offset0:76 offset1:78
	ds_write2_b64 v52, v[48:49], v[50:51] offset0:132 offset1:134
	ds_write2_b64 v52, v[32:33], v[34:35] offset0:140 offset1:142
	ds_write2_b64 v20, v[16:17], v[18:19] offset0:196 offset1:198
	ds_write2_b64 v20, v[0:1], v[2:3] offset0:204 offset1:206
	s_waitcnt lgkmcnt(0)
	s_barrier
; DI float bf2f(bf16_t v) { return __uint_as_float(((unsigned)v) << 16); }
; DI bf16_t f2bf(float x) { return (bf16_t)(pack2(x, 0.f) & 0xffffu); }
; DI int tid512() { int t = threadIdx_x_raw(); asm volatile("" : "+v"(t)); return t; }
;   DI void operator()(bf16_t* sCb) const {
;     ...
;     if (nt2 < 4) {
;       const float2* rope = (const float2*)(ws + OFF_ROPER);
;       const float sc = (nt2 >= 2) ? 0.08838834764831845f : 1.f;
;       for (int id = tid512(); id < 256 * 128; id += 512) {
;         int row = id >> 7, hf = (id >> 6) & 1, i = id & 63;
;         float2 cs = rope[(size_t)(s0 + row) * 64 + i];
;         bf16_t* q1 = sCb + row * BLD + 128 * hf + i;
;         float x1 = bf2f(q1[0]), x2 = bf2f(q1[64]);
;         q1[0] = f2bf((x1 * cs.x - x2 * cs.y) * sc);
;         q1[64] = f2bf((x1 * cs.y + x2 * cs.x) * sc);
;       }
;       __syncthreads();
	s_cbranch_scc1 .LBB0_771
	v_mov_b32_e32 v2, v196
	s_nop 0
	v_cmp_gt_i32_e32 vcc, s47, v2
	s_and_saveexec_b64 s[4:5], vcc
	s_cbranch_execz .LBB0_770
	s_cmp_gt_i32 s20, 1
	v_and_b32_e32 v4, 63, v196
	s_cselect_b64 vcc, -1, 0
	v_lshrrev_b32_e32 v8, 7, v196
	v_cndmask_b32_e32 v3, 1.0, v150, vcc
	v_mul_lo_u32 v12, v8, s46
	v_lshlrev_b32_e32 v13, 1, v196
	v_and_b32_e32 v13, 0x80, v13
	v_lshlrev_b32_e32 v13, 1, v13
	v_lshlrev_b32_e32 v14, 1, v4
	v_add3_u32 v12, v12, v13, v14
	v_add_u32_e32 v15, s24, v8
	v_lshlrev_b32_e32 v15, 9, v15
	v_lshl_add_u32 v16, v4, 3, v15
	v_add_u32_e32 v17, 0x1000, v16
	v_add_u32_e32 v18, 0x2000, v16
	v_add_u32_e32 v19, 0x3000, v16
	v_add_u32_e32 v20, 0x4000, v16
	v_add_u32_e32 v21, 0x5000, v16
	v_add_u32_e32 v22, 0x6000, v16
	v_add_u32_e32 v23, 0x7000, v16
	s_lshl_b32 s10, s46, 2
	global_load_dwordx2 v[200:201], v16, s[2:3]
	global_load_dwordx2 v[202:203], v16, s[2:3] offset:2048
	global_load_dwordx2 v[204:205], v17, s[2:3]
	global_load_dwordx2 v[206:207], v17, s[2:3] offset:2048
	global_load_dwordx2 v[208:209], v18, s[2:3]
	global_load_dwordx2 v[210:211], v18, s[2:3] offset:2048
	global_load_dwordx2 v[212:213], v19, s[2:3]
	global_load_dwordx2 v[214:215], v19, s[2:3] offset:2048
	global_load_dwordx2 v[216:217], v20, s[2:3]
	global_load_dwordx2 v[218:219], v20, s[2:3] offset:2048
	global_load_dwordx2 v[220:221], v21, s[2:3]
	global_load_dwordx2 v[222:223], v21, s[2:3] offset:2048
	global_load_dwordx2 v[224:225], v22, s[2:3]
	global_load_dwordx2 v[226:227], v22, s[2:3] offset:2048
	global_load_dwordx2 v[228:229], v23, s[2:3]
	global_load_dwordx2 v[230:231], v23, s[2:3] offset:2048
	ds_read_u16 v9, v12
	ds_read_u16 v10, v12 offset:128
	v_add_u32_e32 v26, s10, v12
	ds_read_u16 v24, v26
	ds_read_u16 v25, v26 offset:128
	s_waitcnt vmcnt(15) lgkmcnt(2)
	v_lshlrev_b32_e32 v9, 16, v9
	v_lshlrev_b32_e32 v10, 16, v10
	v_mul_f32_e32 v11, v201, v10
	v_mul_f32_e32 v10, v200, v10
	v_fma_f32 v6, v200, v9, -v11
	v_fmac_f32_e32 v10, v201, v9
	v_mul_f32_e32 v6, v3, v6
	v_mul_f32_e32 v7, v3, v10
	v_cvt_pk_bf16_f32 v6, v6, s0
	v_cvt_pk_bf16_f32 v7, v7, s0
	ds_write_b16 v12, v6
	ds_write_b16 v12, v7 offset:128
	v_add_u32_e32 v16, 0x8000, v16
	global_load_dwordx2 v[200:201], v16, s[2:3]
	v_add_u32_e32 v12, s10, v12
	v_add_u32_e32 v26, s10, v12
	ds_read_u16 v9, v26
	ds_read_u16 v10, v26 offset:128
	s_waitcnt vmcnt(15) lgkmcnt(4)
	v_lshlrev_b32_e32 v24, 16, v24
	v_lshlrev_b32_e32 v25, 16, v25
	v_mul_f32_e32 v11, v203, v25
	v_mul_f32_e32 v25, v202, v25
	v_fma_f32 v6, v202, v24, -v11
	v_fmac_f32_e32 v25, v203, v24
	v_mul_f32_e32 v6, v3, v6
	v_mul_f32_e32 v7, v3, v25
	v_cvt_pk_bf16_f32 v6, v6, s0
	v_cvt_pk_bf16_f32 v7, v7, s0
	ds_write_b16 v12, v6
	ds_write_b16 v12, v7 offset:128
	global_load_dwordx2 v[202:203], v16, s[2:3] offset:2048
	v_add_u32_e32 v12, s10, v12
	v_add_u32_e32 v26, s10, v12
	ds_read_u16 v24, v26
	ds_read_u16 v25, v26 offset:128
	s_waitcnt vmcnt(15) lgkmcnt(4)
	v_lshlrev_b32_e32 v9, 16, v9
	v_lshlrev_b32_e32 v10, 16, v10
	v_mul_f32_e32 v11, v205, v10
	v_mul_f32_e32 v10, v204, v10
	v_fma_f32 v6, v204, v9, -v11
	v_fmac_f32_e32 v10, v205, v9
	v_mul_f32_e32 v6, v3, v6
	v_mul_f32_e32 v7, v3, v10
	v_cvt_pk_bf16_f32 v6, v6, s0
	v_cvt_pk_bf16_f32 v7, v7, s0
	ds_write_b16 v12, v6
	ds_write_b16 v12, v7 offset:128
	v_add_u32_e32 v17, 0x8000, v17
	global_load_dwordx2 v[204:205], v17, s[2:3]
	v_add_u32_e32 v12, s10, v12
	v_add_u32_e32 v26, s10, v12
	ds_read_u16 v9, v26
	ds_read_u16 v10, v26 offset:128
	s_waitcnt vmcnt(15) lgkmcnt(4)
	v_lshlrev_b32_e32 v24, 16, v24
	v_lshlrev_b32_e32 v25, 16, v25
	v_mul_f32_e32 v11, v207, v25
	v_mul_f32_e32 v25, v206, v25
	v_fma_f32 v6, v206, v24, -v11
	v_fmac_f32_e32 v25, v207, v24
	v_mul_f32_e32 v6, v3, v6
	v_mul_f32_e32 v7, v3, v25
	v_cvt_pk_bf16_f32 v6, v6, s0
	v_cvt_pk_bf16_f32 v7, v7, s0
	ds_write_b16 v12, v6
	ds_write_b16 v12, v7 offset:128
	global_load_dwordx2 v[206:207], v17, s[2:3] offset:2048
	v_add_u32_e32 v12, s10, v12
	v_add_u32_e32 v26, s10, v12
	ds_read_u16 v24, v26
	ds_read_u16 v25, v26 offset:128
	s_waitcnt vmcnt(15) lgkmcnt(4)
	v_lshlrev_b32_e32 v9, 16, v9
	v_lshlrev_b32_e32 v10, 16, v10
	v_mul_f32_e32 v11, v209, v10
	v_mul_f32_e32 v10, v208, v10
	v_fma_f32 v6, v208, v9, -v11
	v_fmac_f32_e32 v10, v209, v9
	v_mul_f32_e32 v6, v3, v6
	v_mul_f32_e32 v7, v3, v10
	v_cvt_pk_bf16_f32 v6, v6, s0
	v_cvt_pk_bf16_f32 v7, v7, s0
	ds_write_b16 v12, v6
	ds_write_b16 v12, v7 offset:128
	v_add_u32_e32 v18, 0x8000, v18
	global_load_dwordx2 v[208:209], v18, s[2:3]
	v_add_u32_e32 v12, s10, v12
	v_add_u32_e32 v26, s10, v12
	ds_read_u16 v9, v26
	ds_read_u16 v10, v26 offset:128
	s_waitcnt vmcnt(15) lgkmcnt(4)
	v_lshlrev_b32_e32 v24, 16, v24
	v_lshlrev_b32_e32 v25, 16, v25
	v_mul_f32_e32 v11, v211, v25
	v_mul_f32_e32 v25, v210, v25
	v_fma_f32 v6, v210, v24, -v11
	v_fmac_f32_e32 v25, v211, v24
	v_mul_f32_e32 v6, v3, v6
	v_mul_f32_e32 v7, v3, v25
	v_cvt_pk_bf16_f32 v6, v6, s0
	v_cvt_pk_bf16_f32 v7, v7, s0
	ds_write_b16 v12, v6
	ds_write_b16 v12, v7 offset:128
	global_load_dwordx2 v[210:211], v18, s[2:3] offset:2048
	v_add_u32_e32 v12, s10, v12
	v_add_u32_e32 v26, s10, v12
	ds_read_u16 v24, v26
	ds_read_u16 v25, v26 offset:128
	s_waitcnt vmcnt(15) lgkmcnt(4)
	v_lshlrev_b32_e32 v9, 16, v9
	v_lshlrev_b32_e32 v10, 16, v10
	v_mul_f32_e32 v11, v213, v10
	v_mul_f32_e32 v10, v212, v10
	v_fma_f32 v6, v212, v9, -v11
	v_fmac_f32_e32 v10, v213, v9
	v_mul_f32_e32 v6, v3, v6
	v_mul_f32_e32 v7, v3, v10
	v_cvt_pk_bf16_f32 v6, v6, s0
	v_cvt_pk_bf16_f32 v7, v7, s0
	ds_write_b16 v12, v6
	ds_write_b16 v12, v7 offset:128
	v_add_u32_e32 v19, 0x8000, v19
	global_load_dwordx2 v[212:213], v19, s[2:3]
	v_add_u32_e32 v12, s10, v12
	v_add_u32_e32 v26, s10, v12
	ds_read_u16 v9, v26
	ds_read_u16 v10, v26 offset:128
	s_waitcnt vmcnt(15) lgkmcnt(4)
; DI float bf2f(bf16_t v) { return __uint_as_float(((unsigned)v) << 16); }
; DI bf16_t f2bf(float x) { return (bf16_t)(pack2(x, 0.f) & 0xffffu); }
; DI int tid512() { int t = threadIdx_x_raw(); asm volatile("" : "+v"(t)); return t; }
;   DI void operator()(bf16_t* sCb) const {
;     ...
;       for (int id = tid512(); id < 256 * 128; id += 512) {
;         int row = id >> 7, hf = (id >> 6) & 1, i = id & 63;
;         float2 cs = rope[(size_t)(s0 + row) * 64 + i];
;         bf16_t* q1 = sCb + row * BLD + 128 * hf + i;
;         float x1 = bf2f(q1[0]), x2 = bf2f(q1[64]);
;         q1[0] = f2bf((x1 * cs.x - x2 * cs.y) * sc);
;         q1[64] = f2bf((x1 * cs.y + x2 * cs.x) * sc);
;       }
	v_lshlrev_b32_e32 v24, 16, v24
	v_lshlrev_b32_e32 v25, 16, v25
	v_mul_f32_e32 v11, v215, v25
	v_mul_f32_e32 v25, v214, v25
	v_fma_f32 v6, v214, v24, -v11
	v_fmac_f32_e32 v25, v215, v24
	v_mul_f32_e32 v6, v3, v6
	v_mul_f32_e32 v7, v3, v25
	v_cvt_pk_bf16_f32 v6, v6, s0
	v_cvt_pk_bf16_f32 v7, v7, s0
	ds_write_b16 v12, v6
	ds_write_b16 v12, v7 offset:128
	global_load_dwordx2 v[214:215], v19, s[2:3] offset:2048
	v_add_u32_e32 v12, s10, v12
	v_add_u32_e32 v26, s10, v12
	ds_read_u16 v24, v26
	ds_read_u16 v25, v26 offset:128
	s_waitcnt vmcnt(15) lgkmcnt(4)
	v_lshlrev_b32_e32 v9, 16, v9
	v_lshlrev_b32_e32 v10, 16, v10
	v_mul_f32_e32 v11, v217, v10
	v_mul_f32_e32 v10, v216, v10
	v_fma_f32 v6, v216, v9, -v11
	v_fmac_f32_e32 v10, v217, v9
	v_mul_f32_e32 v6, v3, v6
	v_mul_f32_e32 v7, v3, v10
	v_cvt_pk_bf16_f32 v6, v6, s0
	v_cvt_pk_bf16_f32 v7, v7, s0
	ds_write_b16 v12, v6
	ds_write_b16 v12, v7 offset:128
	v_add_u32_e32 v20, 0x8000, v20
	global_load_dwordx2 v[216:217], v20, s[2:3]
	v_add_u32_e32 v12, s10, v12
	v_add_u32_e32 v26, s10, v12
	ds_read_u16 v9, v26
	ds_read_u16 v10, v26 offset:128
	s_waitcnt vmcnt(15) lgkmcnt(4)
	v_lshlrev_b32_e32 v24, 16, v24
	v_lshlrev_b32_e32 v25, 16, v25
	v_mul_f32_e32 v11, v219, v25
	v_mul_f32_e32 v25, v218, v25
	v_fma_f32 v6, v218, v24, -v11
	v_fmac_f32_e32 v25, v219, v24
	v_mul_f32_e32 v6, v3, v6
	v_mul_f32_e32 v7, v3, v25
	v_cvt_pk_bf16_f32 v6, v6, s0
	v_cvt_pk_bf16_f32 v7, v7, s0
	ds_write_b16 v12, v6
	ds_write_b16 v12, v7 offset:128
	global_load_dwordx2 v[218:219], v20, s[2:3] offset:2048
	v_add_u32_e32 v12, s10, v12
	v_add_u32_e32 v26, s10, v12
	ds_read_u16 v24, v26
	ds_read_u16 v25, v26 offset:128
	s_waitcnt vmcnt(15) lgkmcnt(4)
	v_lshlrev_b32_e32 v9, 16, v9
	v_lshlrev_b32_e32 v10, 16, v10
	v_mul_f32_e32 v11, v221, v10
	v_mul_f32_e32 v10, v220, v10
	v_fma_f32 v6, v220, v9, -v11
	v_fmac_f32_e32 v10, v221, v9
	v_mul_f32_e32 v6, v3, v6
	v_mul_f32_e32 v7, v3, v10
	v_cvt_pk_bf16_f32 v6, v6, s0
	v_cvt_pk_bf16_f32 v7, v7, s0
	ds_write_b16 v12, v6
	ds_write_b16 v12, v7 offset:128
	v_add_u32_e32 v21, 0x8000, v21
	global_load_dwordx2 v[220:221], v21, s[2:3]
	v_add_u32_e32 v12, s10, v12
	v_add_u32_e32 v26, s10, v12
	ds_read_u16 v9, v26
	ds_read_u16 v10, v26 offset:128
	s_waitcnt vmcnt(15) lgkmcnt(4)
	v_lshlrev_b32_e32 v24, 16, v24
	v_lshlrev_b32_e32 v25, 16, v25
	v_mul_f32_e32 v11, v223, v25
	v_mul_f32_e32 v25, v222, v25
	v_fma_f32 v6, v222, v24, -v11
	v_fmac_f32_e32 v25, v223, v24
	v_mul_f32_e32 v6, v3, v6
	v_mul_f32_e32 v7, v3, v25
	v_cvt_pk_bf16_f32 v6, v6, s0
	v_cvt_pk_bf16_f32 v7, v7, s0
	ds_write_b16 v12, v6
	ds_write_b16 v12, v7 offset:128
	global_load_dwordx2 v[222:223], v21, s[2:3] offset:2048
	v_add_u32_e32 v12, s10, v12
	v_add_u32_e32 v26, s10, v12
	ds_read_u16 v24, v26
	ds_read_u16 v25, v26 offset:128
	s_waitcnt vmcnt(15) lgkmcnt(4)
	v_lshlrev_b32_e32 v9, 16, v9
	v_lshlrev_b32_e32 v10, 16, v10
	v_mul_f32_e32 v11, v225, v10
	v_mul_f32_e32 v10, v224, v10
	v_fma_f32 v6, v224, v9, -v11
	v_fmac_f32_e32 v10, v225, v9
	v_mul_f32_e32 v6, v3, v6
	v_mul_f32_e32 v7, v3, v10
	v_cvt_pk_bf16_f32 v6, v6, s0
	v_cvt_pk_bf16_f32 v7, v7, s0
	ds_write_b16 v12, v6
	ds_write_b16 v12, v7 offset:128
	v_add_u32_e32 v22, 0x8000, v22
	global_load_dwordx2 v[224:225], v22, s[2:3]
	v_add_u32_e32 v12, s10, v12
	v_add_u32_e32 v26, s10, v12
	ds_read_u16 v9, v26
	ds_read_u16 v10, v26 offset:128
	s_waitcnt vmcnt(15) lgkmcnt(4)
	v_lshlrev_b32_e32 v24, 16, v24
	v_lshlrev_b32_e32 v25, 16, v25
	v_mul_f32_e32 v11, v227, v25
	v_mul_f32_e32 v25, v226, v25
	v_fma_f32 v6, v226, v24, -v11
	v_fmac_f32_e32 v25, v227, v24
	v_mul_f32_e32 v6, v3, v6
	v_mul_f32_e32 v7, v3, v25
	v_cvt_pk_bf16_f32 v6, v6, s0
	v_cvt_pk_bf16_f32 v7, v7, s0
	ds_write_b16 v12, v6
	ds_write_b16 v12, v7 offset:128
	global_load_dwordx2 v[226:227], v22, s[2:3] offset:2048
	v_add_u32_e32 v12, s10, v12
	v_add_u32_e32 v26, s10, v12
	ds_read_u16 v24, v26
	ds_read_u16 v25, v26 offset:128
	s_waitcnt vmcnt(15) lgkmcnt(4)
	v_lshlrev_b32_e32 v9, 16, v9
	v_lshlrev_b32_e32 v10, 16, v10
	v_mul_f32_e32 v11, v229, v10
	v_mul_f32_e32 v10, v228, v10
	v_fma_f32 v6, v228, v9, -v11
	v_fmac_f32_e32 v10, v229, v9
	v_mul_f32_e32 v6, v3, v6
	v_mul_f32_e32 v7, v3, v10
	v_cvt_pk_bf16_f32 v6, v6, s0
	v_cvt_pk_bf16_f32 v7, v7, s0
	ds_write_b16 v12, v6
	ds_write_b16 v12, v7 offset:128
	v_add_u32_e32 v23, 0x8000, v23
	global_load_dwordx2 v[228:229], v23, s[2:3]
	v_add_u32_e32 v12, s10, v12
	v_add_u32_e32 v26, s10, v12
	ds_read_u16 v9, v26
	ds_read_u16 v10, v26 offset:128
	s_waitcnt vmcnt(15) lgkmcnt(4)
	v_lshlrev_b32_e32 v24, 16, v24
	v_lshlrev_b32_e32 v25, 16, v25
	v_mul_f32_e32 v11, v231, v25
	v_mul_f32_e32 v25, v230, v25
	v_fma_f32 v6, v230, v24, -v11
	v_fmac_f32_e32 v25, v231, v24
	v_mul_f32_e32 v6, v3, v6
	v_mul_f32_e32 v7, v3, v25
	v_cvt_pk_bf16_f32 v6, v6, s0
	v_cvt_pk_bf16_f32 v7, v7, s0
	ds_write_b16 v12, v6
	ds_write_b16 v12, v7 offset:128
	global_load_dwordx2 v[230:231], v23, s[2:3] offset:2048
	v_add_u32_e32 v12, s10, v12
	v_add_u32_e32 v26, s10, v12
	ds_read_u16 v24, v26
	ds_read_u16 v25, v26 offset:128
	s_waitcnt vmcnt(15) lgkmcnt(4)
	v_lshlrev_b32_e32 v9, 16, v9
	v_lshlrev_b32_e32 v10, 16, v10
	v_mul_f32_e32 v11, v201, v10
	v_mul_f32_e32 v10, v200, v10
	v_fma_f32 v6, v200, v9, -v11
	v_fmac_f32_e32 v10, v201, v9
	v_mul_f32_e32 v6, v3, v6
	v_mul_f32_e32 v7, v3, v10
	v_cvt_pk_bf16_f32 v6, v6, s0
	v_cvt_pk_bf16_f32 v7, v7, s0
	ds_write_b16 v12, v6
	ds_write_b16 v12, v7 offset:128
	v_add_u32_e32 v16, 0x8000, v16
	global_load_dwordx2 v[200:201], v16, s[2:3]
	v_add_u32_e32 v12, s10, v12
	v_add_u32_e32 v26, s10, v12
	ds_read_u16 v9, v26
	ds_read_u16 v10, v26 offset:128
	s_waitcnt vmcnt(15) lgkmcnt(4)
; DI float bf2f(bf16_t v) { return __uint_as_float(((unsigned)v) << 16); }
; DI bf16_t f2bf(float x) { return (bf16_t)(pack2(x, 0.f) & 0xffffu); }
; DI int tid512() { int t = threadIdx_x_raw(); asm volatile("" : "+v"(t)); return t; }
;   DI void operator()(bf16_t* sCb) const {
;     ...
;       for (int id = tid512(); id < 256 * 128; id += 512) {
;         int row = id >> 7, hf = (id >> 6) & 1, i = id & 63;
;         float2 cs = rope[(size_t)(s0 + row) * 64 + i];
;         bf16_t* q1 = sCb + row * BLD + 128 * hf + i;
;         float x1 = bf2f(q1[0]), x2 = bf2f(q1[64]);
;         q1[0] = f2bf((x1 * cs.x - x2 * cs.y) * sc);
;         q1[64] = f2bf((x1 * cs.y + x2 * cs.x) * sc);
;       }
	v_lshlrev_b32_e32 v24, 16, v24
	v_lshlrev_b32_e32 v25, 16, v25
	v_mul_f32_e32 v11, v203, v25
	v_mul_f32_e32 v25, v202, v25
	v_fma_f32 v6, v202, v24, -v11
	v_fmac_f32_e32 v25, v203, v24
	v_mul_f32_e32 v6, v3, v6
	v_mul_f32_e32 v7, v3, v25
	v_cvt_pk_bf16_f32 v6, v6, s0
	v_cvt_pk_bf16_f32 v7, v7, s0
	ds_write_b16 v12, v6
	ds_write_b16 v12, v7 offset:128
	global_load_dwordx2 v[202:203], v16, s[2:3] offset:2048
	v_add_u32_e32 v12, s10, v12
	v_add_u32_e32 v26, s10, v12
	ds_read_u16 v24, v26
	ds_read_u16 v25, v26 offset:128
	s_waitcnt vmcnt(15) lgkmcnt(4)
	v_lshlrev_b32_e32 v9, 16, v9
	v_lshlrev_b32_e32 v10, 16, v10
	v_mul_f32_e32 v11, v205, v10
	v_mul_f32_e32 v10, v204, v10
	v_fma_f32 v6, v204, v9, -v11
	v_fmac_f32_e32 v10, v205, v9
	v_mul_f32_e32 v6, v3, v6
	v_mul_f32_e32 v7, v3, v10
	v_cvt_pk_bf16_f32 v6, v6, s0
	v_cvt_pk_bf16_f32 v7, v7, s0
	ds_write_b16 v12, v6
	ds_write_b16 v12, v7 offset:128
	v_add_u32_e32 v17, 0x8000, v17
	global_load_dwordx2 v[204:205], v17, s[2:3]
	v_add_u32_e32 v12, s10, v12
	v_add_u32_e32 v26, s10, v12
	ds_read_u16 v9, v26
	ds_read_u16 v10, v26 offset:128
	s_waitcnt vmcnt(15) lgkmcnt(4)
	v_lshlrev_b32_e32 v24, 16, v24
	v_lshlrev_b32_e32 v25, 16, v25
	v_mul_f32_e32 v11, v207, v25
	v_mul_f32_e32 v25, v206, v25
	v_fma_f32 v6, v206, v24, -v11
	v_fmac_f32_e32 v25, v207, v24
	v_mul_f32_e32 v6, v3, v6
	v_mul_f32_e32 v7, v3, v25
	v_cvt_pk_bf16_f32 v6, v6, s0
	v_cvt_pk_bf16_f32 v7, v7, s0
	ds_write_b16 v12, v6
	ds_write_b16 v12, v7 offset:128
	global_load_dwordx2 v[206:207], v17, s[2:3] offset:2048
	v_add_u32_e32 v12, s10, v12
	v_add_u32_e32 v26, s10, v12
	ds_read_u16 v24, v26
	ds_read_u16 v25, v26 offset:128
	s_waitcnt vmcnt(15) lgkmcnt(4)
	v_lshlrev_b32_e32 v9, 16, v9
	v_lshlrev_b32_e32 v10, 16, v10
	v_mul_f32_e32 v11, v209, v10
	v_mul_f32_e32 v10, v208, v10
	v_fma_f32 v6, v208, v9, -v11
	v_fmac_f32_e32 v10, v209, v9
	v_mul_f32_e32 v6, v3, v6
	v_mul_f32_e32 v7, v3, v10
	v_cvt_pk_bf16_f32 v6, v6, s0
	v_cvt_pk_bf16_f32 v7, v7, s0
	ds_write_b16 v12, v6
	ds_write_b16 v12, v7 offset:128
	v_add_u32_e32 v18, 0x8000, v18
	global_load_dwordx2 v[208:209], v18, s[2:3]
	v_add_u32_e32 v12, s10, v12
	v_add_u32_e32 v26, s10, v12
	ds_read_u16 v9, v26
	ds_read_u16 v10, v26 offset:128
	s_waitcnt vmcnt(15) lgkmcnt(4)
	v_lshlrev_b32_e32 v24, 16, v24
	v_lshlrev_b32_e32 v25, 16, v25
	v_mul_f32_e32 v11, v211, v25
	v_mul_f32_e32 v25, v210, v25
	v_fma_f32 v6, v210, v24, -v11
	v_fmac_f32_e32 v25, v211, v24
	v_mul_f32_e32 v6, v3, v6
	v_mul_f32_e32 v7, v3, v25
	v_cvt_pk_bf16_f32 v6, v6, s0
	v_cvt_pk_bf16_f32 v7, v7, s0
	ds_write_b16 v12, v6
	ds_write_b16 v12, v7 offset:128
	global_load_dwordx2 v[210:211], v18, s[2:3] offset:2048
	v_add_u32_e32 v12, s10, v12
	v_add_u32_e32 v26, s10, v12
	ds_read_u16 v24, v26
	ds_read_u16 v25, v26 offset:128
	s_waitcnt vmcnt(15) lgkmcnt(4)
	v_lshlrev_b32_e32 v9, 16, v9
	v_lshlrev_b32_e32 v10, 16, v10
	v_mul_f32_e32 v11, v213, v10
	v_mul_f32_e32 v10, v212, v10
	v_fma_f32 v6, v212, v9, -v11
	v_fmac_f32_e32 v10, v213, v9
	v_mul_f32_e32 v6, v3, v6
	v_mul_f32_e32 v7, v3, v10
	v_cvt_pk_bf16_f32 v6, v6, s0
	v_cvt_pk_bf16_f32 v7, v7, s0
	ds_write_b16 v12, v6
	ds_write_b16 v12, v7 offset:128
	v_add_u32_e32 v19, 0x8000, v19
	global_load_dwordx2 v[212:213], v19, s[2:3]
	v_add_u32_e32 v12, s10, v12
	v_add_u32_e32 v26, s10, v12
	ds_read_u16 v9, v26
	ds_read_u16 v10, v26 offset:128
	s_waitcnt vmcnt(15) lgkmcnt(4)
	v_lshlrev_b32_e32 v24, 16, v24
	v_lshlrev_b32_e32 v25, 16, v25
	v_mul_f32_e32 v11, v215, v25
	v_mul_f32_e32 v25, v214, v25
	v_fma_f32 v6, v214, v24, -v11
	v_fmac_f32_e32 v25, v215, v24
	v_mul_f32_e32 v6, v3, v6
	v_mul_f32_e32 v7, v3, v25
	v_cvt_pk_bf16_f32 v6, v6, s0
	v_cvt_pk_bf16_f32 v7, v7, s0
	ds_write_b16 v12, v6
	ds_write_b16 v12, v7 offset:128
	global_load_dwordx2 v[214:215], v19, s[2:3] offset:2048
	v_add_u32_e32 v12, s10, v12
	v_add_u32_e32 v26, s10, v12
	ds_read_u16 v24, v26
	ds_read_u16 v25, v26 offset:128
	s_waitcnt vmcnt(15) lgkmcnt(4)
	v_lshlrev_b32_e32 v9, 16, v9
	v_lshlrev_b32_e32 v10, 16, v10
	v_mul_f32_e32 v11, v217, v10
	v_mul_f32_e32 v10, v216, v10
	v_fma_f32 v6, v216, v9, -v11
	v_fmac_f32_e32 v10, v217, v9
	v_mul_f32_e32 v6, v3, v6
	v_mul_f32_e32 v7, v3, v10
	v_cvt_pk_bf16_f32 v6, v6, s0
	v_cvt_pk_bf16_f32 v7, v7, s0
	ds_write_b16 v12, v6
	ds_write_b16 v12, v7 offset:128
	v_add_u32_e32 v20, 0x8000, v20
	global_load_dwordx2 v[216:217], v20, s[2:3]
	v_add_u32_e32 v12, s10, v12
	v_add_u32_e32 v26, s10, v12
	ds_read_u16 v9, v26
	ds_read_u16 v10, v26 offset:128
	s_waitcnt vmcnt(15) lgkmcnt(4)
	v_lshlrev_b32_e32 v24, 16, v24
	v_lshlrev_b32_e32 v25, 16, v25
	v_mul_f32_e32 v11, v219, v25
	v_mul_f32_e32 v25, v218, v25
	v_fma_f32 v6, v218, v24, -v11
	v_fmac_f32_e32 v25, v219, v24
	v_mul_f32_e32 v6, v3, v6
	v_mul_f32_e32 v7, v3, v25
	v_cvt_pk_bf16_f32 v6, v6, s0
	v_cvt_pk_bf16_f32 v7, v7, s0
	ds_write_b16 v12, v6
	ds_write_b16 v12, v7 offset:128
	global_load_dwordx2 v[218:219], v20, s[2:3] offset:2048
	v_add_u32_e32 v12, s10, v12
	v_add_u32_e32 v26, s10, v12
	ds_read_u16 v24, v26
	ds_read_u16 v25, v26 offset:128
	s_waitcnt vmcnt(15) lgkmcnt(4)
	v_lshlrev_b32_e32 v9, 16, v9
	v_lshlrev_b32_e32 v10, 16, v10
	v_mul_f32_e32 v11, v221, v10
	v_mul_f32_e32 v10, v220, v10
	v_fma_f32 v6, v220, v9, -v11
	v_fmac_f32_e32 v10, v221, v9
	v_mul_f32_e32 v6, v3, v6
	v_mul_f32_e32 v7, v3, v10
	v_cvt_pk_bf16_f32 v6, v6, s0
	v_cvt_pk_bf16_f32 v7, v7, s0
	ds_write_b16 v12, v6
	ds_write_b16 v12, v7 offset:128
	v_add_u32_e32 v21, 0x8000, v21
	global_load_dwordx2 v[220:221], v21, s[2:3]
	v_add_u32_e32 v12, s10, v12
	v_add_u32_e32 v26, s10, v12
	ds_read_u16 v9, v26
	ds_read_u16 v10, v26 offset:128
	s_waitcnt vmcnt(15) lgkmcnt(4)
; DI float bf2f(bf16_t v) { return __uint_as_float(((unsigned)v) << 16); }
; DI bf16_t f2bf(float x) { return (bf16_t)(pack2(x, 0.f) & 0xffffu); }
; DI int tid512() { int t = threadIdx_x_raw(); asm volatile("" : "+v"(t)); return t; }
;   DI void operator()(bf16_t* sCb) const {
;     ...
;       for (int id = tid512(); id < 256 * 128; id += 512) {
;         int row = id >> 7, hf = (id >> 6) & 1, i = id & 63;
;         float2 cs = rope[(size_t)(s0 + row) * 64 + i];
;         bf16_t* q1 = sCb + row * BLD + 128 * hf + i;
;         float x1 = bf2f(q1[0]), x2 = bf2f(q1[64]);
;         q1[0] = f2bf((x1 * cs.x - x2 * cs.y) * sc);
;         q1[64] = f2bf((x1 * cs.y + x2 * cs.x) * sc);
;       }
	v_lshlrev_b32_e32 v24, 16, v24
	v_lshlrev_b32_e32 v25, 16, v25
	v_mul_f32_e32 v11, v223, v25
	v_mul_f32_e32 v25, v222, v25
	v_fma_f32 v6, v222, v24, -v11
	v_fmac_f32_e32 v25, v223, v24
	v_mul_f32_e32 v6, v3, v6
	v_mul_f32_e32 v7, v3, v25
	v_cvt_pk_bf16_f32 v6, v6, s0
	v_cvt_pk_bf16_f32 v7, v7, s0
	ds_write_b16 v12, v6
	ds_write_b16 v12, v7 offset:128
	global_load_dwordx2 v[222:223], v21, s[2:3] offset:2048
	v_add_u32_e32 v12, s10, v12
	v_add_u32_e32 v26, s10, v12
	ds_read_u16 v24, v26
	ds_read_u16 v25, v26 offset:128
	s_waitcnt vmcnt(15) lgkmcnt(4)
	v_lshlrev_b32_e32 v9, 16, v9
	v_lshlrev_b32_e32 v10, 16, v10
	v_mul_f32_e32 v11, v225, v10
	v_mul_f32_e32 v10, v224, v10
	v_fma_f32 v6, v224, v9, -v11
	v_fmac_f32_e32 v10, v225, v9
	v_mul_f32_e32 v6, v3, v6
	v_mul_f32_e32 v7, v3, v10
	v_cvt_pk_bf16_f32 v6, v6, s0
	v_cvt_pk_bf16_f32 v7, v7, s0
	ds_write_b16 v12, v6
	ds_write_b16 v12, v7 offset:128
	v_add_u32_e32 v22, 0x8000, v22
	global_load_dwordx2 v[224:225], v22, s[2:3]
	v_add_u32_e32 v12, s10, v12
	v_add_u32_e32 v26, s10, v12
	ds_read_u16 v9, v26
	ds_read_u16 v10, v26 offset:128
	s_waitcnt vmcnt(15) lgkmcnt(4)
	v_lshlrev_b32_e32 v24, 16, v24
	v_lshlrev_b32_e32 v25, 16, v25
	v_mul_f32_e32 v11, v227, v25
	v_mul_f32_e32 v25, v226, v25
	v_fma_f32 v6, v226, v24, -v11
	v_fmac_f32_e32 v25, v227, v24
	v_mul_f32_e32 v6, v3, v6
	v_mul_f32_e32 v7, v3, v25
	v_cvt_pk_bf16_f32 v6, v6, s0
	v_cvt_pk_bf16_f32 v7, v7, s0
	ds_write_b16 v12, v6
	ds_write_b16 v12, v7 offset:128
	global_load_dwordx2 v[226:227], v22, s[2:3] offset:2048
	v_add_u32_e32 v12, s10, v12
	v_add_u32_e32 v26, s10, v12
	ds_read_u16 v24, v26
	ds_read_u16 v25, v26 offset:128
	s_waitcnt vmcnt(15) lgkmcnt(4)
	v_lshlrev_b32_e32 v9, 16, v9
	v_lshlrev_b32_e32 v10, 16, v10
	v_mul_f32_e32 v11, v229, v10
	v_mul_f32_e32 v10, v228, v10
	v_fma_f32 v6, v228, v9, -v11
	v_fmac_f32_e32 v10, v229, v9
	v_mul_f32_e32 v6, v3, v6
	v_mul_f32_e32 v7, v3, v10
	v_cvt_pk_bf16_f32 v6, v6, s0
	v_cvt_pk_bf16_f32 v7, v7, s0
	ds_write_b16 v12, v6
	ds_write_b16 v12, v7 offset:128
	v_add_u32_e32 v23, 0x8000, v23
	global_load_dwordx2 v[228:229], v23, s[2:3]
	v_add_u32_e32 v12, s10, v12
	v_add_u32_e32 v26, s10, v12
	ds_read_u16 v9, v26
	ds_read_u16 v10, v26 offset:128
	s_waitcnt vmcnt(15) lgkmcnt(4)
	v_lshlrev_b32_e32 v24, 16, v24
	v_lshlrev_b32_e32 v25, 16, v25
	v_mul_f32_e32 v11, v231, v25
	v_mul_f32_e32 v25, v230, v25
	v_fma_f32 v6, v230, v24, -v11
	v_fmac_f32_e32 v25, v231, v24
	v_mul_f32_e32 v6, v3, v6
	v_mul_f32_e32 v7, v3, v25
	v_cvt_pk_bf16_f32 v6, v6, s0
	v_cvt_pk_bf16_f32 v7, v7, s0
	ds_write_b16 v12, v6
	ds_write_b16 v12, v7 offset:128
	global_load_dwordx2 v[230:231], v23, s[2:3] offset:2048
	v_add_u32_e32 v12, s10, v12
	v_add_u32_e32 v26, s10, v12
	ds_read_u16 v24, v26
	ds_read_u16 v25, v26 offset:128
	s_waitcnt vmcnt(15) lgkmcnt(4)
	v_lshlrev_b32_e32 v9, 16, v9
	v_lshlrev_b32_e32 v10, 16, v10
	v_mul_f32_e32 v11, v201, v10
	v_mul_f32_e32 v10, v200, v10
	v_fma_f32 v6, v200, v9, -v11
	v_fmac_f32_e32 v10, v201, v9
	v_mul_f32_e32 v6, v3, v6
	v_mul_f32_e32 v7, v3, v10
	v_cvt_pk_bf16_f32 v6, v6, s0
	v_cvt_pk_bf16_f32 v7, v7, s0
	ds_write_b16 v12, v6
	ds_write_b16 v12, v7 offset:128
	v_add_u32_e32 v16, 0x8000, v16
	global_load_dwordx2 v[200:201], v16, s[2:3]
	v_add_u32_e32 v12, s10, v12
	v_add_u32_e32 v26, s10, v12
	ds_read_u16 v9, v26
	ds_read_u16 v10, v26 offset:128
	s_waitcnt vmcnt(15) lgkmcnt(4)
	v_lshlrev_b32_e32 v24, 16, v24
	v_lshlrev_b32_e32 v25, 16, v25
	v_mul_f32_e32 v11, v203, v25
	v_mul_f32_e32 v25, v202, v25
	v_fma_f32 v6, v202, v24, -v11
	v_fmac_f32_e32 v25, v203, v24
	v_mul_f32_e32 v6, v3, v6
	v_mul_f32_e32 v7, v3, v25
	v_cvt_pk_bf16_f32 v6, v6, s0
	v_cvt_pk_bf16_f32 v7, v7, s0
	ds_write_b16 v12, v6
	ds_write_b16 v12, v7 offset:128
	global_load_dwordx2 v[202:203], v16, s[2:3] offset:2048
	v_add_u32_e32 v12, s10, v12
	v_add_u32_e32 v26, s10, v12
	ds_read_u16 v24, v26
	ds_read_u16 v25, v26 offset:128
	s_waitcnt vmcnt(15) lgkmcnt(4)
	v_lshlrev_b32_e32 v9, 16, v9
	v_lshlrev_b32_e32 v10, 16, v10
	v_mul_f32_e32 v11, v205, v10
	v_mul_f32_e32 v10, v204, v10
	v_fma_f32 v6, v204, v9, -v11
	v_fmac_f32_e32 v10, v205, v9
	v_mul_f32_e32 v6, v3, v6
	v_mul_f32_e32 v7, v3, v10
	v_cvt_pk_bf16_f32 v6, v6, s0
	v_cvt_pk_bf16_f32 v7, v7, s0
	ds_write_b16 v12, v6
	ds_write_b16 v12, v7 offset:128
	v_add_u32_e32 v17, 0x8000, v17
	global_load_dwordx2 v[204:205], v17, s[2:3]
	v_add_u32_e32 v12, s10, v12
	v_add_u32_e32 v26, s10, v12
	ds_read_u16 v9, v26
	ds_read_u16 v10, v26 offset:128
	s_waitcnt vmcnt(15) lgkmcnt(4)
	v_lshlrev_b32_e32 v24, 16, v24
	v_lshlrev_b32_e32 v25, 16, v25
	v_mul_f32_e32 v11, v207, v25
	v_mul_f32_e32 v25, v206, v25
	v_fma_f32 v6, v206, v24, -v11
	v_fmac_f32_e32 v25, v207, v24
	v_mul_f32_e32 v6, v3, v6
	v_mul_f32_e32 v7, v3, v25
	v_cvt_pk_bf16_f32 v6, v6, s0
	v_cvt_pk_bf16_f32 v7, v7, s0
	ds_write_b16 v12, v6
	ds_write_b16 v12, v7 offset:128
	global_load_dwordx2 v[206:207], v17, s[2:3] offset:2048
	v_add_u32_e32 v12, s10, v12
	v_add_u32_e32 v26, s10, v12
	ds_read_u16 v24, v26
	ds_read_u16 v25, v26 offset:128
	s_waitcnt vmcnt(15) lgkmcnt(4)
	v_lshlrev_b32_e32 v9, 16, v9
	v_lshlrev_b32_e32 v10, 16, v10
	v_mul_f32_e32 v11, v209, v10
	v_mul_f32_e32 v10, v208, v10
	v_fma_f32 v6, v208, v9, -v11
	v_fmac_f32_e32 v10, v209, v9
	v_mul_f32_e32 v6, v3, v6
	v_mul_f32_e32 v7, v3, v10
	v_cvt_pk_bf16_f32 v6, v6, s0
	v_cvt_pk_bf16_f32 v7, v7, s0
	ds_write_b16 v12, v6
	ds_write_b16 v12, v7 offset:128
	v_add_u32_e32 v18, 0x8000, v18
	global_load_dwordx2 v[208:209], v18, s[2:3]
	v_add_u32_e32 v12, s10, v12
	v_add_u32_e32 v26, s10, v12
	ds_read_u16 v9, v26
	ds_read_u16 v10, v26 offset:128
	s_waitcnt vmcnt(15) lgkmcnt(4)
; DI float bf2f(bf16_t v) { return __uint_as_float(((unsigned)v) << 16); }
; DI bf16_t f2bf(float x) { return (bf16_t)(pack2(x, 0.f) & 0xffffu); }
; DI int tid512() { int t = threadIdx_x_raw(); asm volatile("" : "+v"(t)); return t; }
;   DI void operator()(bf16_t* sCb) const {
;     ...
;       for (int id = tid512(); id < 256 * 128; id += 512) {
;         int row = id >> 7, hf = (id >> 6) & 1, i = id & 63;
;         float2 cs = rope[(size_t)(s0 + row) * 64 + i];
;         bf16_t* q1 = sCb + row * BLD + 128 * hf + i;
;         float x1 = bf2f(q1[0]), x2 = bf2f(q1[64]);
;         q1[0] = f2bf((x1 * cs.x - x2 * cs.y) * sc);
;         q1[64] = f2bf((x1 * cs.y + x2 * cs.x) * sc);
;       }
	v_lshlrev_b32_e32 v24, 16, v24
	v_lshlrev_b32_e32 v25, 16, v25
	v_mul_f32_e32 v11, v211, v25
	v_mul_f32_e32 v25, v210, v25
	v_fma_f32 v6, v210, v24, -v11
	v_fmac_f32_e32 v25, v211, v24
	v_mul_f32_e32 v6, v3, v6
	v_mul_f32_e32 v7, v3, v25
	v_cvt_pk_bf16_f32 v6, v6, s0
	v_cvt_pk_bf16_f32 v7, v7, s0
	ds_write_b16 v12, v6
	ds_write_b16 v12, v7 offset:128
	global_load_dwordx2 v[210:211], v18, s[2:3] offset:2048
	v_add_u32_e32 v12, s10, v12
	v_add_u32_e32 v26, s10, v12
	ds_read_u16 v24, v26
	ds_read_u16 v25, v26 offset:128
	s_waitcnt vmcnt(15) lgkmcnt(4)
	v_lshlrev_b32_e32 v9, 16, v9
	v_lshlrev_b32_e32 v10, 16, v10
	v_mul_f32_e32 v11, v213, v10
	v_mul_f32_e32 v10, v212, v10
	v_fma_f32 v6, v212, v9, -v11
	v_fmac_f32_e32 v10, v213, v9
	v_mul_f32_e32 v6, v3, v6
	v_mul_f32_e32 v7, v3, v10
	v_cvt_pk_bf16_f32 v6, v6, s0
	v_cvt_pk_bf16_f32 v7, v7, s0
	ds_write_b16 v12, v6
	ds_write_b16 v12, v7 offset:128
	v_add_u32_e32 v19, 0x8000, v19
	global_load_dwordx2 v[212:213], v19, s[2:3]
	v_add_u32_e32 v12, s10, v12
	v_add_u32_e32 v26, s10, v12
	ds_read_u16 v9, v26
	ds_read_u16 v10, v26 offset:128
	s_waitcnt vmcnt(15) lgkmcnt(4)
	v_lshlrev_b32_e32 v24, 16, v24
	v_lshlrev_b32_e32 v25, 16, v25
	v_mul_f32_e32 v11, v215, v25
	v_mul_f32_e32 v25, v214, v25
	v_fma_f32 v6, v214, v24, -v11
	v_fmac_f32_e32 v25, v215, v24
	v_mul_f32_e32 v6, v3, v6
	v_mul_f32_e32 v7, v3, v25
	v_cvt_pk_bf16_f32 v6, v6, s0
	v_cvt_pk_bf16_f32 v7, v7, s0
	ds_write_b16 v12, v6
	ds_write_b16 v12, v7 offset:128
	global_load_dwordx2 v[214:215], v19, s[2:3] offset:2048
	v_add_u32_e32 v12, s10, v12
	v_add_u32_e32 v26, s10, v12
	ds_read_u16 v24, v26
	ds_read_u16 v25, v26 offset:128
	s_waitcnt vmcnt(15) lgkmcnt(4)
	v_lshlrev_b32_e32 v9, 16, v9
	v_lshlrev_b32_e32 v10, 16, v10
	v_mul_f32_e32 v11, v217, v10
	v_mul_f32_e32 v10, v216, v10
	v_fma_f32 v6, v216, v9, -v11
	v_fmac_f32_e32 v10, v217, v9
	v_mul_f32_e32 v6, v3, v6
	v_mul_f32_e32 v7, v3, v10
	v_cvt_pk_bf16_f32 v6, v6, s0
	v_cvt_pk_bf16_f32 v7, v7, s0
	ds_write_b16 v12, v6
	ds_write_b16 v12, v7 offset:128
	v_add_u32_e32 v20, 0x8000, v20
	global_load_dwordx2 v[216:217], v20, s[2:3]
	v_add_u32_e32 v12, s10, v12
	v_add_u32_e32 v26, s10, v12
	ds_read_u16 v9, v26
	ds_read_u16 v10, v26 offset:128
	s_waitcnt vmcnt(15) lgkmcnt(4)
	v_lshlrev_b32_e32 v24, 16, v24
	v_lshlrev_b32_e32 v25, 16, v25
	v_mul_f32_e32 v11, v219, v25
	v_mul_f32_e32 v25, v218, v25
	v_fma_f32 v6, v218, v24, -v11
	v_fmac_f32_e32 v25, v219, v24
	v_mul_f32_e32 v6, v3, v6
	v_mul_f32_e32 v7, v3, v25
	v_cvt_pk_bf16_f32 v6, v6, s0
	v_cvt_pk_bf16_f32 v7, v7, s0
	ds_write_b16 v12, v6
	ds_write_b16 v12, v7 offset:128
	global_load_dwordx2 v[218:219], v20, s[2:3] offset:2048
	v_add_u32_e32 v12, s10, v12
	v_add_u32_e32 v26, s10, v12
	ds_read_u16 v24, v26
	ds_read_u16 v25, v26 offset:128
	s_waitcnt vmcnt(15) lgkmcnt(4)
	v_lshlrev_b32_e32 v9, 16, v9
	v_lshlrev_b32_e32 v10, 16, v10
	v_mul_f32_e32 v11, v221, v10
	v_mul_f32_e32 v10, v220, v10
	v_fma_f32 v6, v220, v9, -v11
	v_fmac_f32_e32 v10, v221, v9
	v_mul_f32_e32 v6, v3, v6
	v_mul_f32_e32 v7, v3, v10
	v_cvt_pk_bf16_f32 v6, v6, s0
	v_cvt_pk_bf16_f32 v7, v7, s0
	ds_write_b16 v12, v6
	ds_write_b16 v12, v7 offset:128
	v_add_u32_e32 v21, 0x8000, v21
	global_load_dwordx2 v[220:221], v21, s[2:3]
	v_add_u32_e32 v12, s10, v12
	v_add_u32_e32 v26, s10, v12
	ds_read_u16 v9, v26
	ds_read_u16 v10, v26 offset:128
	s_waitcnt vmcnt(15) lgkmcnt(4)
	v_lshlrev_b32_e32 v24, 16, v24
	v_lshlrev_b32_e32 v25, 16, v25
	v_mul_f32_e32 v11, v223, v25
	v_mul_f32_e32 v25, v222, v25
	v_fma_f32 v6, v222, v24, -v11
	v_fmac_f32_e32 v25, v223, v24
	v_mul_f32_e32 v6, v3, v6
	v_mul_f32_e32 v7, v3, v25
	v_cvt_pk_bf16_f32 v6, v6, s0
	v_cvt_pk_bf16_f32 v7, v7, s0
	ds_write_b16 v12, v6
	ds_write_b16 v12, v7 offset:128
	global_load_dwordx2 v[222:223], v21, s[2:3] offset:2048
	v_add_u32_e32 v12, s10, v12
	v_add_u32_e32 v26, s10, v12
	ds_read_u16 v24, v26
	ds_read_u16 v25, v26 offset:128
	s_waitcnt vmcnt(15) lgkmcnt(4)
	v_lshlrev_b32_e32 v9, 16, v9
	v_lshlrev_b32_e32 v10, 16, v10
	v_mul_f32_e32 v11, v225, v10
	v_mul_f32_e32 v10, v224, v10
	v_fma_f32 v6, v224, v9, -v11
	v_fmac_f32_e32 v10, v225, v9
	v_mul_f32_e32 v6, v3, v6
	v_mul_f32_e32 v7, v3, v10
	v_cvt_pk_bf16_f32 v6, v6, s0
	v_cvt_pk_bf16_f32 v7, v7, s0
	ds_write_b16 v12, v6
	ds_write_b16 v12, v7 offset:128
	v_add_u32_e32 v22, 0x8000, v22
	global_load_dwordx2 v[224:225], v22, s[2:3]
	v_add_u32_e32 v12, s10, v12
	v_add_u32_e32 v26, s10, v12
	ds_read_u16 v9, v26
	ds_read_u16 v10, v26 offset:128
	s_waitcnt vmcnt(15) lgkmcnt(4)
	v_lshlrev_b32_e32 v24, 16, v24
	v_lshlrev_b32_e32 v25, 16, v25
	v_mul_f32_e32 v11, v227, v25
	v_mul_f32_e32 v25, v226, v25
	v_fma_f32 v6, v226, v24, -v11
	v_fmac_f32_e32 v25, v227, v24
	v_mul_f32_e32 v6, v3, v6
	v_mul_f32_e32 v7, v3, v25
	v_cvt_pk_bf16_f32 v6, v6, s0
	v_cvt_pk_bf16_f32 v7, v7, s0
	ds_write_b16 v12, v6
	ds_write_b16 v12, v7 offset:128
	global_load_dwordx2 v[226:227], v22, s[2:3] offset:2048
	v_add_u32_e32 v12, s10, v12
	v_add_u32_e32 v26, s10, v12
	ds_read_u16 v24, v26
	ds_read_u16 v25, v26 offset:128
	s_waitcnt vmcnt(15) lgkmcnt(4)
	v_lshlrev_b32_e32 v9, 16, v9
	v_lshlrev_b32_e32 v10, 16, v10
	v_mul_f32_e32 v11, v229, v10
	v_mul_f32_e32 v10, v228, v10
	v_fma_f32 v6, v228, v9, -v11
	v_fmac_f32_e32 v10, v229, v9
	v_mul_f32_e32 v6, v3, v6
	v_mul_f32_e32 v7, v3, v10
	v_cvt_pk_bf16_f32 v6, v6, s0
	v_cvt_pk_bf16_f32 v7, v7, s0
	ds_write_b16 v12, v6
	ds_write_b16 v12, v7 offset:128
	v_add_u32_e32 v23, 0x8000, v23
	global_load_dwordx2 v[228:229], v23, s[2:3]
	v_add_u32_e32 v12, s10, v12
	v_add_u32_e32 v26, s10, v12
	ds_read_u16 v9, v26
	ds_read_u16 v10, v26 offset:128
	s_waitcnt vmcnt(15) lgkmcnt(4)
; DI float bf2f(bf16_t v) { return __uint_as_float(((unsigned)v) << 16); }
; DI bf16_t f2bf(float x) { return (bf16_t)(pack2(x, 0.f) & 0xffffu); }
; DI int tid512() { int t = threadIdx_x_raw(); asm volatile("" : "+v"(t)); return t; }
;   DI void operator()(bf16_t* sCb) const {
;     ...
;       for (int id = tid512(); id < 256 * 128; id += 512) {
;         int row = id >> 7, hf = (id >> 6) & 1, i = id & 63;
;         float2 cs = rope[(size_t)(s0 + row) * 64 + i];
;         bf16_t* q1 = sCb + row * BLD + 128 * hf + i;
;         float x1 = bf2f(q1[0]), x2 = bf2f(q1[64]);
;         q1[0] = f2bf((x1 * cs.x - x2 * cs.y) * sc);
;         q1[64] = f2bf((x1 * cs.y + x2 * cs.x) * sc);
;       }
	v_lshlrev_b32_e32 v24, 16, v24
	v_lshlrev_b32_e32 v25, 16, v25
	v_mul_f32_e32 v11, v231, v25
	v_mul_f32_e32 v25, v230, v25
	v_fma_f32 v6, v230, v24, -v11
	v_fmac_f32_e32 v25, v231, v24
	v_mul_f32_e32 v6, v3, v6
	v_mul_f32_e32 v7, v3, v25
	v_cvt_pk_bf16_f32 v6, v6, s0
	v_cvt_pk_bf16_f32 v7, v7, s0
	ds_write_b16 v12, v6
	ds_write_b16 v12, v7 offset:128
	global_load_dwordx2 v[230:231], v23, s[2:3] offset:2048
	v_add_u32_e32 v12, s10, v12
	v_add_u32_e32 v26, s10, v12
	ds_read_u16 v24, v26
	ds_read_u16 v25, v26 offset:128
	s_waitcnt vmcnt(15) lgkmcnt(4)
	v_lshlrev_b32_e32 v9, 16, v9
	v_lshlrev_b32_e32 v10, 16, v10
	v_mul_f32_e32 v11, v201, v10
	v_mul_f32_e32 v10, v200, v10
	v_fma_f32 v6, v200, v9, -v11
	v_fmac_f32_e32 v10, v201, v9
	v_mul_f32_e32 v6, v3, v6
	v_mul_f32_e32 v7, v3, v10
	v_cvt_pk_bf16_f32 v6, v6, s0
	v_cvt_pk_bf16_f32 v7, v7, s0
	ds_write_b16 v12, v6
	ds_write_b16 v12, v7 offset:128
	v_add_u32_e32 v12, s10, v12
	v_add_u32_e32 v26, s10, v12
	ds_read_u16 v9, v26
	ds_read_u16 v10, v26 offset:128
	s_waitcnt vmcnt(14) lgkmcnt(4)
	v_lshlrev_b32_e32 v24, 16, v24
	v_lshlrev_b32_e32 v25, 16, v25
	v_mul_f32_e32 v11, v203, v25
	v_mul_f32_e32 v25, v202, v25
	v_fma_f32 v6, v202, v24, -v11
	v_fmac_f32_e32 v25, v203, v24
	v_mul_f32_e32 v6, v3, v6
	v_mul_f32_e32 v7, v3, v25
	v_cvt_pk_bf16_f32 v6, v6, s0
	v_cvt_pk_bf16_f32 v7, v7, s0
	ds_write_b16 v12, v6
	ds_write_b16 v12, v7 offset:128
	v_add_u32_e32 v12, s10, v12
	v_add_u32_e32 v26, s10, v12
	ds_read_u16 v24, v26
	ds_read_u16 v25, v26 offset:128
	s_waitcnt vmcnt(13) lgkmcnt(4)
	v_lshlrev_b32_e32 v9, 16, v9
	v_lshlrev_b32_e32 v10, 16, v10
	v_mul_f32_e32 v11, v205, v10
	v_mul_f32_e32 v10, v204, v10
	v_fma_f32 v6, v204, v9, -v11
	v_fmac_f32_e32 v10, v205, v9
	v_mul_f32_e32 v6, v3, v6
	v_mul_f32_e32 v7, v3, v10
	v_cvt_pk_bf16_f32 v6, v6, s0
	v_cvt_pk_bf16_f32 v7, v7, s0
	ds_write_b16 v12, v6
	ds_write_b16 v12, v7 offset:128
	v_add_u32_e32 v12, s10, v12
	v_add_u32_e32 v26, s10, v12
	ds_read_u16 v9, v26
	ds_read_u16 v10, v26 offset:128
	s_waitcnt vmcnt(12) lgkmcnt(4)
	v_lshlrev_b32_e32 v24, 16, v24
	v_lshlrev_b32_e32 v25, 16, v25
	v_mul_f32_e32 v11, v207, v25
	v_mul_f32_e32 v25, v206, v25
	v_fma_f32 v6, v206, v24, -v11
	v_fmac_f32_e32 v25, v207, v24
	v_mul_f32_e32 v6, v3, v6
	v_mul_f32_e32 v7, v3, v25
	v_cvt_pk_bf16_f32 v6, v6, s0
	v_cvt_pk_bf16_f32 v7, v7, s0
	ds_write_b16 v12, v6
	ds_write_b16 v12, v7 offset:128
	v_add_u32_e32 v12, s10, v12
	v_add_u32_e32 v26, s10, v12
	ds_read_u16 v24, v26
	ds_read_u16 v25, v26 offset:128
	s_waitcnt vmcnt(11) lgkmcnt(4)
	v_lshlrev_b32_e32 v9, 16, v9
	v_lshlrev_b32_e32 v10, 16, v10
	v_mul_f32_e32 v11, v209, v10
	v_mul_f32_e32 v10, v208, v10
	v_fma_f32 v6, v208, v9, -v11
	v_fmac_f32_e32 v10, v209, v9
	v_mul_f32_e32 v6, v3, v6
	v_mul_f32_e32 v7, v3, v10
	v_cvt_pk_bf16_f32 v6, v6, s0
	v_cvt_pk_bf16_f32 v7, v7, s0
	ds_write_b16 v12, v6
	ds_write_b16 v12, v7 offset:128
	v_add_u32_e32 v12, s10, v12
	v_add_u32_e32 v26, s10, v12
	ds_read_u16 v9, v26
	ds_read_u16 v10, v26 offset:128
	s_waitcnt vmcnt(10) lgkmcnt(4)
	v_lshlrev_b32_e32 v24, 16, v24
	v_lshlrev_b32_e32 v25, 16, v25
	v_mul_f32_e32 v11, v211, v25
	v_mul_f32_e32 v25, v210, v25
	v_fma_f32 v6, v210, v24, -v11
	v_fmac_f32_e32 v25, v211, v24
	v_mul_f32_e32 v6, v3, v6
	v_mul_f32_e32 v7, v3, v25
	v_cvt_pk_bf16_f32 v6, v6, s0
	v_cvt_pk_bf16_f32 v7, v7, s0
	ds_write_b16 v12, v6
	ds_write_b16 v12, v7 offset:128
	v_add_u32_e32 v12, s10, v12
	v_add_u32_e32 v26, s10, v12
	ds_read_u16 v24, v26
	ds_read_u16 v25, v26 offset:128
	s_waitcnt vmcnt(9) lgkmcnt(4)
	v_lshlrev_b32_e32 v9, 16, v9
	v_lshlrev_b32_e32 v10, 16, v10
	v_mul_f32_e32 v11, v213, v10
	v_mul_f32_e32 v10, v212, v10
	v_fma_f32 v6, v212, v9, -v11
	v_fmac_f32_e32 v10, v213, v9
	v_mul_f32_e32 v6, v3, v6
	v_mul_f32_e32 v7, v3, v10
	v_cvt_pk_bf16_f32 v6, v6, s0
	v_cvt_pk_bf16_f32 v7, v7, s0
	ds_write_b16 v12, v6
	ds_write_b16 v12, v7 offset:128
	v_add_u32_e32 v12, s10, v12
	v_add_u32_e32 v26, s10, v12
	ds_read_u16 v9, v26
	ds_read_u16 v10, v26 offset:128
	s_waitcnt vmcnt(8) lgkmcnt(4)
; DI float bf2f(bf16_t v) { return __uint_as_float(((unsigned)v) << 16); }
; DI bf16_t f2bf(float x) { return (bf16_t)(pack2(x, 0.f) & 0xffffu); }
; DI int tid512() { int t = threadIdx_x_raw(); asm volatile("" : "+v"(t)); return t; }
;   DI void operator()(bf16_t* sCb) const {
;     ...
;       for (int id = tid512(); id < 256 * 128; id += 512) {
;         int row = id >> 7, hf = (id >> 6) & 1, i = id & 63;
;         float2 cs = rope[(size_t)(s0 + row) * 64 + i];
;         bf16_t* q1 = sCb + row * BLD + 128 * hf + i;
;         float x1 = bf2f(q1[0]), x2 = bf2f(q1[64]);
;         q1[0] = f2bf((x1 * cs.x - x2 * cs.y) * sc);
;         q1[64] = f2bf((x1 * cs.y + x2 * cs.x) * sc);
;       }
	v_lshlrev_b32_e32 v24, 16, v24
	v_lshlrev_b32_e32 v25, 16, v25
	v_mul_f32_e32 v11, v215, v25
	v_mul_f32_e32 v25, v214, v25
	v_fma_f32 v6, v214, v24, -v11
	v_fmac_f32_e32 v25, v215, v24
	v_mul_f32_e32 v6, v3, v6
	v_mul_f32_e32 v7, v3, v25
	v_cvt_pk_bf16_f32 v6, v6, s0
	v_cvt_pk_bf16_f32 v7, v7, s0
	ds_write_b16 v12, v6
	ds_write_b16 v12, v7 offset:128
	v_add_u32_e32 v12, s10, v12
	v_add_u32_e32 v26, s10, v12
	ds_read_u16 v24, v26
	ds_read_u16 v25, v26 offset:128
	s_waitcnt vmcnt(7) lgkmcnt(4)
	v_lshlrev_b32_e32 v9, 16, v9
	v_lshlrev_b32_e32 v10, 16, v10
	v_mul_f32_e32 v11, v217, v10
	v_mul_f32_e32 v10, v216, v10
	v_fma_f32 v6, v216, v9, -v11
	v_fmac_f32_e32 v10, v217, v9
	v_mul_f32_e32 v6, v3, v6
	v_mul_f32_e32 v7, v3, v10
	v_cvt_pk_bf16_f32 v6, v6, s0
	v_cvt_pk_bf16_f32 v7, v7, s0
	ds_write_b16 v12, v6
	ds_write_b16 v12, v7 offset:128
	v_add_u32_e32 v12, s10, v12
	v_add_u32_e32 v26, s10, v12
	ds_read_u16 v9, v26
	ds_read_u16 v10, v26 offset:128
	s_waitcnt vmcnt(6) lgkmcnt(4)
	v_lshlrev_b32_e32 v24, 16, v24
	v_lshlrev_b32_e32 v25, 16, v25
	v_mul_f32_e32 v11, v219, v25
	v_mul_f32_e32 v25, v218, v25
	v_fma_f32 v6, v218, v24, -v11
	v_fmac_f32_e32 v25, v219, v24
	v_mul_f32_e32 v6, v3, v6
	v_mul_f32_e32 v7, v3, v25
	v_cvt_pk_bf16_f32 v6, v6, s0
	v_cvt_pk_bf16_f32 v7, v7, s0
	ds_write_b16 v12, v6
	ds_write_b16 v12, v7 offset:128
	v_add_u32_e32 v12, s10, v12
	v_add_u32_e32 v26, s10, v12
	ds_read_u16 v24, v26
	ds_read_u16 v25, v26 offset:128
	s_waitcnt vmcnt(5) lgkmcnt(4)
	v_lshlrev_b32_e32 v9, 16, v9
	v_lshlrev_b32_e32 v10, 16, v10
	v_mul_f32_e32 v11, v221, v10
	v_mul_f32_e32 v10, v220, v10
	v_fma_f32 v6, v220, v9, -v11
	v_fmac_f32_e32 v10, v221, v9
	v_mul_f32_e32 v6, v3, v6
	v_mul_f32_e32 v7, v3, v10
	v_cvt_pk_bf16_f32 v6, v6, s0
	v_cvt_pk_bf16_f32 v7, v7, s0
	ds_write_b16 v12, v6
	ds_write_b16 v12, v7 offset:128
	v_add_u32_e32 v12, s10, v12
	v_add_u32_e32 v26, s10, v12
	ds_read_u16 v9, v26
	ds_read_u16 v10, v26 offset:128
	s_waitcnt vmcnt(4) lgkmcnt(4)
	v_lshlrev_b32_e32 v24, 16, v24
	v_lshlrev_b32_e32 v25, 16, v25
	v_mul_f32_e32 v11, v223, v25
	v_mul_f32_e32 v25, v222, v25
	v_fma_f32 v6, v222, v24, -v11
	v_fmac_f32_e32 v25, v223, v24
	v_mul_f32_e32 v6, v3, v6
	v_mul_f32_e32 v7, v3, v25
	v_cvt_pk_bf16_f32 v6, v6, s0
	v_cvt_pk_bf16_f32 v7, v7, s0
	ds_write_b16 v12, v6
	ds_write_b16 v12, v7 offset:128
	v_add_u32_e32 v12, s10, v12
	v_add_u32_e32 v26, s10, v12
	ds_read_u16 v24, v26
	ds_read_u16 v25, v26 offset:128
	s_waitcnt vmcnt(3) lgkmcnt(4)
	v_lshlrev_b32_e32 v9, 16, v9
	v_lshlrev_b32_e32 v10, 16, v10
	v_mul_f32_e32 v11, v225, v10
	v_mul_f32_e32 v10, v224, v10
	v_fma_f32 v6, v224, v9, -v11
	v_fmac_f32_e32 v10, v225, v9
	v_mul_f32_e32 v6, v3, v6
	v_mul_f32_e32 v7, v3, v10
	v_cvt_pk_bf16_f32 v6, v6, s0
	v_cvt_pk_bf16_f32 v7, v7, s0
	ds_write_b16 v12, v6
	ds_write_b16 v12, v7 offset:128
	v_add_u32_e32 v12, s10, v12
	v_add_u32_e32 v26, s10, v12
	ds_read_u16 v9, v26
	ds_read_u16 v10, v26 offset:128
	s_waitcnt vmcnt(2) lgkmcnt(4)
	v_lshlrev_b32_e32 v24, 16, v24
	v_lshlrev_b32_e32 v25, 16, v25
	v_mul_f32_e32 v11, v227, v25
	v_mul_f32_e32 v25, v226, v25
	v_fma_f32 v6, v226, v24, -v11
	v_fmac_f32_e32 v25, v227, v24
	v_mul_f32_e32 v6, v3, v6
	v_mul_f32_e32 v7, v3, v25
	v_cvt_pk_bf16_f32 v6, v6, s0
	v_cvt_pk_bf16_f32 v7, v7, s0
	ds_write_b16 v12, v6
	ds_write_b16 v12, v7 offset:128
	v_add_u32_e32 v12, s10, v12
	v_add_u32_e32 v26, s10, v12
	ds_read_u16 v24, v26
	ds_read_u16 v25, v26 offset:128
	s_waitcnt vmcnt(1) lgkmcnt(4)
	v_lshlrev_b32_e32 v9, 16, v9
	v_lshlrev_b32_e32 v10, 16, v10
	v_mul_f32_e32 v11, v229, v10
	v_mul_f32_e32 v10, v228, v10
	v_fma_f32 v6, v228, v9, -v11
	v_fmac_f32_e32 v10, v229, v9
	v_mul_f32_e32 v6, v3, v6
	v_mul_f32_e32 v7, v3, v10
	v_cvt_pk_bf16_f32 v6, v6, s0
	v_cvt_pk_bf16_f32 v7, v7, s0
	ds_write_b16 v12, v6
	ds_write_b16 v12, v7 offset:128
	v_add_u32_e32 v12, s10, v12
	s_waitcnt vmcnt(0) lgkmcnt(2)
	v_lshlrev_b32_e32 v24, 16, v24
	v_lshlrev_b32_e32 v25, 16, v25
	v_mul_f32_e32 v11, v231, v25
	v_mul_f32_e32 v25, v230, v25
	v_fma_f32 v6, v230, v24, -v11
	v_fmac_f32_e32 v25, v231, v24
	v_mul_f32_e32 v6, v3, v6
	v_mul_f32_e32 v7, v3, v25
	v_cvt_pk_bf16_f32 v6, v6, s0
	v_cvt_pk_bf16_f32 v7, v7, s0
	ds_write_b16 v12, v6
	ds_write_b16 v12, v7 offset:128
	v_add_u32_e32 v12, s10, v12

; DI int tid512() { int t = threadIdx_x_raw(); asm volatile("" : "+v"(t)); return t; }
; template <class AL, class BL, class EP>
; DI void gemm_tile256(AL al, BL bl, EP ep, int K, char* smem) {
;   bf16_t* sA = (bf16_t*)smem;
;   bf16_t* sB = sA + 2 * 256 * GLD;
;   const int tid = tid512(), lane = tid & 63, w = tid >> 6, wm = w >> 2, wn = w & 3, r = lane & 31, h = lane >> 5;
;   const int lrow = tid >> 3, lck = tid & 7;
;   f32x16 acc[4][2];
; #pragma unroll
;   for (int i = 0; i < 4; ++i)
; #pragma unroll
;     for (int j = 0; j < 2; ++j)
; #pragma unroll
;       for (int q = 0; q < 16; ++q) acc[i][j][q] = 0.f;
;   u32x4 ra[4], rb[4];
;   const int KT = K >> 6;
;   DI u32x4 operator()(int r, int k) const {
;     int row = row0 + r;
;     row = row < nrows ? row : nrows - 1;
;     return ldg16(base + (size_t)row * ld + k);
;   }
; DI void phase_gemm_plain256(const Sched& sc, const bf16_t* A, int lda, const bf16_t* Wt, int K, int N, bf16_t* C, int ldc, char* smem) {
;   const int NT = (N + 255) >> 8, MT = T / 256;
;   for (int round = 0;; ++round) {
;     int mt = 0, nt = 0;
;     const int st = sched_tile(sc, round, MT, NT, mt, nt);
;     if (st == 2) break;
;     if (st == 1) continue;
;     LoadRows al{A, lda, mt * 256, T};
;     LoadRows bl{Wt, K, nt * 256, N};
;     EpStore256 ep{C, ldc, mt * 256, nt * 256, N};
;     gemm_tile256(al, bl, ep, K, smem);
.LBB0_1040:
	s_cmp_lg_u32 s6, 1
	s_mov_b64 s[2:3], -1
	s_cbranch_scc0 .LBB0_1047
	v_mov_b32_e32 v32, v196
	v_readlane_b32 s2, v246, 36
	v_ashrrev_i32_e32 v33, 3, v32
	v_add_u32_e32 v12, s22, v33
	v_add_u32_e32 v28, s21, v33
	v_lshlrev_b32_e32 v0, 4, v32
	v_add_u32_e32 v10, 0x80, v12
	v_add_u32_e32 v26, 0x80, v28
	v_and_b32_e32 v128, 0x70, v0
	v_min_i32_e32 v0, 0x7fff, v12
	v_min_i32_e32 v10, 0x7fff, v10
	v_min_i32_e32 v16, 0x3ff, v28
	v_min_i32_e32 v26, 0x3ff, v26
	v_readlane_b32 s3, v246, 37
	v_ashrrev_i32_e32 v1, 31, v0
	v_ashrrev_i32_e32 v11, 31, v10
	v_ashrrev_i32_e32 v17, 31, v16
	v_ashrrev_i32_e32 v27, 31, v26
	v_lshl_add_u64 v[8:9], s[2:3], 0, v[128:129]
	v_lshlrev_b64 v[0:1], 11, v[0:1]
	v_lshlrev_b64 v[10:11], 11, v[10:11]
	v_lshl_add_u64 v[24:25], s[0:1], 0, v[128:129]
	v_lshlrev_b64 v[16:17], 11, v[16:17]
	v_lshlrev_b64 v[26:27], 11, v[26:27]
	v_lshl_add_u64 v[134:135], v[8:9], 0, v[0:1]
	v_add_u32_e32 v0, 64, v12
	v_lshl_add_u64 v[138:139], v[8:9], 0, v[10:11]
	v_add_u32_e32 v10, 0xc0, v12
	v_lshl_add_u64 v[142:143], v[24:25], 0, v[16:17]
	v_add_u32_e32 v16, 64, v28
	v_lshl_add_u64 v[146:147], v[24:25], 0, v[26:27]
	v_add_u32_e32 v26, 0xc0, v28
	v_min_i32_e32 v0, 0x7fff, v0
	v_min_i32_e32 v10, 0x7fff, v10
	v_min_i32_e32 v16, 0x3ff, v16
	v_min_i32_e32 v26, 0x3ff, v26
	v_ashrrev_i32_e32 v1, 31, v0
	v_ashrrev_i32_e32 v11, 31, v10
	v_ashrrev_i32_e32 v17, 31, v16
	v_ashrrev_i32_e32 v27, 31, v26
	v_lshlrev_b64 v[0:1], 11, v[0:1]
	v_lshlrev_b64 v[10:11], 11, v[10:11]
	v_lshlrev_b64 v[16:17], 11, v[16:17]
	v_lshlrev_b64 v[26:27], 11, v[26:27]
	v_lshl_add_u64 v[136:137], v[8:9], 0, v[0:1]
	v_lshl_add_u64 v[140:141], v[8:9], 0, v[10:11]
	v_lshl_add_u64 v[144:145], v[24:25], 0, v[16:17]
	v_lshl_add_u64 v[148:149], v[24:25], 0, v[26:27]
	v_mad_u64_u32 v[132:133], s[2:3], v33, s15, v[128:129]
	v_add_u32_e32 v153, 0x12000, v132
	v_bfe_u32 v128, v32, 6, 2
	v_add_u32_e32 v152, 0x1b000, v132
	v_and_b32_e32 v1, 31, v32
	v_ashrrev_i32_e32 v0, 1, v32
	v_and_or_b32 v133, v0, s16, v1
	v_lshrrev_b32_e32 v0, 2, v32
	v_and_b32_e32 v150, 8, v0
	v_lshlrev_b32_e32 v0, 1, v150
	v_mad_u64_u32 v[130:131], s[2:3], v133, s15, v[0:1]
	v_lshl_or_b32 v1, v128, 6, v1
	v_mul_u32_u24_e32 v1, 0x48, v1
	v_lshl_add_u32 v0, v1, 1, v0
	v_add_u32_e32 v151, 0x12000, v0
	v_add_u32_e32 v131, 0x1b000, v0
	s_nop 0
	s_nop 0
	s_nop 0
	s_nop 0
	s_nop 0
	s_nop 0
	v_lshrrev_b32_e32 v222, 6, v196
	s_mov_b32 s4, 64
	v_readfirstlane_b32 s23, v222
	s_mov_b32 s5, 0
	s_mov_b32 s6, 0x40000
	s_mov_b32 s7, 0
	v_bfe_u32 v220, v196, 2, 4
	s_lshl_b32 s24, s23, 3
	v_add_u32_e32 v220, s24, v220
	s_mov_b32 s24, 0x800
	v_mul_lo_u32 v220, v220, s24
	v_bfe_u32 v222, v196, 4, 2
	v_and_b32_e32 v221, 3, v196
	v_xor_b32_e32 v222, v221, v222
	v_lshl_add_u32 v220, v222, 4, v220
	v_mov_b32_e32 v221, 0
	v_readlane_b32 s10, v134, 0
	v_readlane_b32 s11, v135, 0
	s_nop 1
	v_lshl_add_u64 v[212:213], s[10:11], 0, v[220:221]
	v_lshl_add_u64 v[214:215], v[212:213], 0, s[6:7]
	v_readlane_b32 s10, v142, 0
	v_readlane_b32 s11, v143, 0
	s_nop 1
	v_lshl_add_u64 v[216:217], s[10:11], 0, v[220:221]
	v_lshl_add_u64 v[218:219], v[216:217], 0, s[6:7]
	v_and_b32_e32 v220, 31, v196
	v_bfe_u32 v222, v196, 2, 2
	v_bfe_u32 v221, v196, 5, 1
	v_xor_b32_e32 v222, v221, v222
	v_lshlrev_b32_e32 v222, 4, v222
	v_lshl_or_b32 v220, v220, 6, v222
	s_lshr_b32 s24, s23, 2
	s_lshl_b32 s24, s24, 13
	v_add_u32_e32 v132, s24, v220
	s_and_b32 s24, s23, 3
	s_lshl_b32 s24, s24, 12
	s_add_u32 s24, s24, 0x4000
	v_add_u32_e32 v198, s24, v220
	v_xor_b32_e32 v151, 0x20, v132
	v_xor_b32_e32 v199, 0x20, v198
	v_add_u32_e32 v204, 0x10000, v132
	v_add_u32_e32 v206, 0x10000, v198
	v_add_u32_e32 v208, 0x20000, v132
	v_add_u32_e32 v210, 0x20000, v198
	v_add_u32_e32 v205, 0x10000, v151
	v_add_u32_e32 v207, 0x10000, v199
	v_add_u32_e32 v209, 0x20000, v151
	v_add_u32_e32 v211, 0x20000, v199
	s_lshl_b32 s23, s23, 10
	s_waitcnt lgkmcnt(0)
	s_barrier
	s_add_u32 m0, s23, 0x0
	s_nop 0
	global_load_lds_dwordx4 v[212:213], off
	v_lshl_add_u64 v[212:213], v[212:213], 0, s[4:5]
	s_add_u32 m0, s23, 0x4000
	s_nop 0
	global_load_lds_dwordx4 v[216:217], off
	v_lshl_add_u64 v[216:217], v[216:217], 0, s[4:5]
	s_add_u32 m0, s23, 0x2000
	s_nop 0
	global_load_lds_dwordx4 v[214:215], off
	v_lshl_add_u64 v[214:215], v[214:215], 0, s[4:5]
	s_add_u32 m0, s23, 0x6000
	s_nop 0
	global_load_lds_dwordx4 v[218:219], off
	v_lshl_add_u64 v[218:219], v[218:219], 0, s[4:5]
	s_add_u32 m0, s23, 0x8000
	s_nop 0
	global_load_lds_dwordx4 v[212:213], off
	v_lshl_add_u64 v[212:213], v[212:213], 0, s[4:5]
	s_add_u32 m0, s23, 0xc000
	s_nop 0
	global_load_lds_dwordx4 v[216:217], off
	v_lshl_add_u64 v[216:217], v[216:217], 0, s[4:5]
	s_add_u32 m0, s23, 0xa000
	s_nop 0
	global_load_lds_dwordx4 v[214:215], off
	v_lshl_add_u64 v[214:215], v[214:215], 0, s[4:5]
	s_add_u32 m0, s23, 0xe000
	s_nop 0
	global_load_lds_dwordx4 v[218:219], off
	v_lshl_add_u64 v[218:219], v[218:219], 0, s[4:5]
	s_add_u32 m0, s23, 0x10000
	s_nop 0
	global_load_lds_dwordx4 v[212:213], off
	v_lshl_add_u64 v[212:213], v[212:213], 0, s[4:5]
	s_add_u32 m0, s23, 0x14000
	s_nop 0
	global_load_lds_dwordx4 v[216:217], off
	v_lshl_add_u64 v[216:217], v[216:217], 0, s[4:5]
	s_add_u32 m0, s23, 0x12000
	s_nop 0
	global_load_lds_dwordx4 v[214:215], off
	v_lshl_add_u64 v[214:215], v[214:215], 0, s[4:5]
	s_add_u32 m0, s23, 0x16000
	s_nop 0
	global_load_lds_dwordx4 v[218:219], off
	v_lshl_add_u64 v[218:219], v[218:219], 0, s[4:5]
	s_add_u32 m0, s23, 0x18000
	s_nop 0
	global_load_lds_dwordx4 v[212:213], off
	v_lshl_add_u64 v[212:213], v[212:213], 0, s[4:5]
	s_add_u32 m0, s23, 0x1c000
	s_nop 0
	global_load_lds_dwordx4 v[216:217], off
; #define G_LOADA(kt_) { _Pragma("unroll") for (int i = 0; i < 4; ++i) ra[i] = al(lrow + 64 * i, (kt_) * 64 + lck * 8); }
; #define G_LOADB(kt_) { _Pragma("unroll") for (int i = 0; i < 4; ++i) rb[i] = bl(lrow + 64 * i, (kt_) * 64 + lck * 8); }
; #define G_STOREA(buf_) { bf16_t* nA = sA + (buf_) * 256 * GLD; _Pragma("unroll") for (int i = 0; i < 4; ++i) *(u32x4*)(nA + (lrow + 64 * i) * GLD + lck * 8) = ra[i]; }
; #define G_STOREB(buf_) { bf16_t* nB = sB + (buf_) * 256 * GLD; _Pragma("unroll") for (int i = 0; i < 4; ++i) *(u32x4*)(nB + (lrow + 64 * i) * GLD + lck * 8) = rb[i]; }
; template <class AL, class BL, class EP>
; DI void gemm_tile256(AL al, BL bl, EP ep, int K, char* smem) {
;     ...
; #pragma unroll
;   for (int i = 0; i < 4; ++i)
; #pragma unroll
;     for (int j = 0; j < 2; ++j)
; #pragma unroll
;       for (int q = 0; q < 16; ++q) acc[i][j][q] = 0.f;
;     ...
;   G_LOADA(0); G_LOADB(0);
;   __syncthreads();
;   G_STOREA(0); G_STOREB(0);
;   if (KT > 1) G_LOADB(1);
;   __syncthreads();
;   for (int kt = 0; kt < KT; kt += 2) {
;     G_STEP(0, kt);
;     if (kt + 1 >= KT) break;
;     G_STEP(1, kt + 1);
;   }
	v_lshl_add_u64 v[216:217], v[216:217], 0, s[4:5]
	s_add_u32 m0, s23, 0x1a000
	s_nop 0
	global_load_lds_dwordx4 v[214:215], off
	v_lshl_add_u64 v[214:215], v[214:215], 0, s[4:5]
	s_add_u32 m0, s23, 0x1e000
	s_nop 0
	global_load_lds_dwordx4 v[218:219], off
	v_lshl_add_u64 v[218:219], v[218:219], 0, s[4:5]
	s_add_u32 m0, s23, 0x20000
	s_nop 0
	global_load_lds_dwordx4 v[212:213], off
	v_lshl_add_u64 v[212:213], v[212:213], 0, s[4:5]
	s_add_u32 m0, s23, 0x24000
	s_nop 0
	global_load_lds_dwordx4 v[216:217], off
	v_lshl_add_u64 v[216:217], v[216:217], 0, s[4:5]
	v_mov_b64_e32 v[112:113], 0
	v_mov_b64_e32 v[114:115], 0
	v_mov_b64_e32 v[116:117], 0
	v_mov_b64_e32 v[118:119], 0
	v_mov_b64_e32 v[120:121], 0
	v_mov_b64_e32 v[122:123], 0
	v_mov_b64_e32 v[124:125], 0
	v_mov_b64_e32 v[126:127], 0
	v_mov_b64_e32 v[96:97], 0
	v_mov_b64_e32 v[98:99], 0
	v_mov_b64_e32 v[100:101], 0
	v_mov_b64_e32 v[102:103], 0
	v_mov_b64_e32 v[104:105], 0
	v_mov_b64_e32 v[106:107], 0
	v_mov_b64_e32 v[108:109], 0
	v_mov_b64_e32 v[110:111], 0
	v_mov_b64_e32 v[80:81], 0
	v_mov_b64_e32 v[82:83], 0
	v_mov_b64_e32 v[84:85], 0
	v_mov_b64_e32 v[86:87], 0
	v_mov_b64_e32 v[88:89], 0
	v_mov_b64_e32 v[90:91], 0
	v_mov_b64_e32 v[92:93], 0
	v_mov_b64_e32 v[94:95], 0
	v_mov_b64_e32 v[64:65], 0
	v_mov_b64_e32 v[66:67], 0
	v_mov_b64_e32 v[68:69], 0
	v_mov_b64_e32 v[70:71], 0
	v_mov_b64_e32 v[72:73], 0
	v_mov_b64_e32 v[74:75], 0
	v_mov_b64_e32 v[76:77], 0
	v_mov_b64_e32 v[78:79], 0
	v_mov_b64_e32 v[48:49], 0
	v_mov_b64_e32 v[50:51], 0
	v_mov_b64_e32 v[52:53], 0
	v_mov_b64_e32 v[54:55], 0
	v_mov_b64_e32 v[56:57], 0
	v_mov_b64_e32 v[58:59], 0
	v_mov_b64_e32 v[60:61], 0
	v_mov_b64_e32 v[62:63], 0
	v_mov_b64_e32 v[32:33], 0
	v_mov_b64_e32 v[34:35], 0
	v_mov_b64_e32 v[36:37], 0
	v_mov_b64_e32 v[38:39], 0
	v_mov_b64_e32 v[40:41], 0
	v_mov_b64_e32 v[42:43], 0
	v_mov_b64_e32 v[44:45], 0
	v_mov_b64_e32 v[46:47], 0
	v_mov_b64_e32 v[16:17], 0
	v_mov_b64_e32 v[18:19], 0
	v_mov_b64_e32 v[20:21], 0
	v_mov_b64_e32 v[22:23], 0
	v_mov_b64_e32 v[24:25], 0
	v_mov_b64_e32 v[26:27], 0
	v_mov_b64_e32 v[28:29], 0
	v_mov_b64_e32 v[30:31], 0
	v_mov_b64_e32 v[0:1], 0
	v_mov_b64_e32 v[2:3], 0
	v_mov_b64_e32 v[4:5], 0
	v_mov_b64_e32 v[6:7], 0
	v_mov_b64_e32 v[8:9], 0
	v_mov_b64_e32 v[10:11], 0
	v_mov_b64_e32 v[12:13], 0
	v_mov_b64_e32 v[14:15], 0
	s_lshr_b32 s24, s23, 2
	s_xor_b32 s24, s24, s23
	s_bitcmp1_b32 s24, 10
	s_cbranch_scc0 .Lgk_ph13_np
	s_setprio 1
.Lgk_ph13_np:
	s_mov_b32 s24, 5
	s_waitcnt vmcnt(14)
	s_barrier
	ds_read_b128 v[184:187], v198
	ds_read_b128 v[152:155], v132
	ds_read_b128 v[188:191], v198 offset:2048
	ds_read_b128 v[156:159], v132 offset:2048
	ds_read_b128 v[160:163], v132 offset:4096
	ds_read_b128 v[164:167], v132 offset:6144
.Lgk_ph13_loop:
	s_waitcnt lgkmcnt(0)
	v_mfma_f32_32x32x16_bf16 v[112:127], v[184:187], v[152:155], v[112:127]
	ds_read_b128 v[192:195], v199
	ds_read_b128 v[168:171], v151
	v_mfma_f32_32x32x16_bf16 v[96:111], v[188:191], v[152:155], v[96:111]
	ds_read_b128 v[200:203], v199 offset:2048
	ds_read_b128 v[172:175], v151 offset:2048
	v_mfma_f32_32x32x16_bf16 v[80:95], v[184:187], v[156:159], v[80:95]
	ds_read_b128 v[176:179], v151 offset:4096
	ds_read_b128 v[180:183], v151 offset:6144
	v_mfma_f32_32x32x16_bf16 v[64:79], v[188:191], v[156:159], v[64:79]
	s_add_u32 m0, s23, 0x22000
	s_nop 0
	global_load_lds_dwordx4 v[214:215], off
	v_lshl_add_u64 v[214:215], v[214:215], 0, s[4:5]
	v_mfma_f32_32x32x16_bf16 v[48:63], v[184:187], v[160:163], v[48:63]
	v_mfma_f32_32x32x16_bf16 v[32:47], v[188:191], v[160:163], v[32:47]
	v_mfma_f32_32x32x16_bf16 v[16:31], v[184:187], v[164:167], v[16:31]
	v_mfma_f32_32x32x16_bf16 v[0:15], v[188:191], v[164:167], v[0:15]
	s_add_u32 m0, s23, 0x26000
	s_nop 0
	global_load_lds_dwordx4 v[218:219], off
	v_lshl_add_u64 v[218:219], v[218:219], 0, s[4:5]
	s_waitcnt lgkmcnt(0)
	s_waitcnt vmcnt(12)
	s_barrier
	s_waitcnt lgkmcnt(0)
	v_mfma_f32_32x32x16_bf16 v[112:127], v[192:195], v[168:171], v[112:127]
	ds_read_b128 v[184:187], v198 offset:32768
	ds_read_b128 v[152:155], v132 offset:32768
	v_mfma_f32_32x32x16_bf16 v[96:111], v[200:203], v[168:171], v[96:111]
	ds_read_b128 v[188:191], v198 offset:34816
	ds_read_b128 v[156:159], v132 offset:34816
	v_mfma_f32_32x32x16_bf16 v[80:95], v[192:195], v[172:175], v[80:95]
	ds_read_b128 v[160:163], v132 offset:36864
	ds_read_b128 v[164:167], v132 offset:38912
	v_mfma_f32_32x32x16_bf16 v[64:79], v[200:203], v[172:175], v[64:79]
	s_add_u32 m0, s23, 0x0
	s_nop 0
	global_load_lds_dwordx4 v[212:213], off
	v_lshl_add_u64 v[212:213], v[212:213], 0, s[4:5]
	v_mfma_f32_32x32x16_bf16 v[48:63], v[192:195], v[176:179], v[48:63]
	v_mfma_f32_32x32x16_bf16 v[32:47], v[200:203], v[176:179], v[32:47]
	v_mfma_f32_32x32x16_bf16 v[16:31], v[192:195], v[180:183], v[16:31]
	v_mfma_f32_32x32x16_bf16 v[0:15], v[200:203], v[180:183], v[0:15]
	s_add_u32 m0, s23, 0x4000
	s_nop 0
	global_load_lds_dwordx4 v[216:217], off
	v_lshl_add_u64 v[216:217], v[216:217], 0, s[4:5]
	s_waitcnt lgkmcnt(0)
	v_mfma_f32_32x32x16_bf16 v[112:127], v[184:187], v[152:155], v[112:127]
	ds_read_b128 v[192:195], v199 offset:32768
	ds_read_b128 v[168:171], v151 offset:32768
	v_mfma_f32_32x32x16_bf16 v[96:111], v[188:191], v[152:155], v[96:111]
	ds_read_b128 v[200:203], v199 offset:34816
	ds_read_b128 v[172:175], v151 offset:34816
	v_mfma_f32_32x32x16_bf16 v[80:95], v[184:187], v[156:159], v[80:95]
	ds_read_b128 v[176:179], v151 offset:36864
	ds_read_b128 v[180:183], v151 offset:38912
	v_mfma_f32_32x32x16_bf16 v[64:79], v[188:191], v[156:159], v[64:79]
	s_add_u32 m0, s23, 0x2000
	s_nop 0
	global_load_lds_dwordx4 v[214:215], off
	v_lshl_add_u64 v[214:215], v[214:215], 0, s[4:5]
	v_mfma_f32_32x32x16_bf16 v[48:63], v[184:187], v[160:163], v[48:63]
	v_mfma_f32_32x32x16_bf16 v[32:47], v[188:191], v[160:163], v[32:47]
	v_mfma_f32_32x32x16_bf16 v[16:31], v[184:187], v[164:167], v[16:31]
	v_mfma_f32_32x32x16_bf16 v[0:15], v[188:191], v[164:167], v[0:15]
	s_add_u32 m0, s23, 0x6000
	s_nop 0
	global_load_lds_dwordx4 v[218:219], off
	v_lshl_add_u64 v[218:219], v[218:219], 0, s[4:5]
	s_waitcnt lgkmcnt(0)
	s_waitcnt vmcnt(12)
	s_barrier
; #define G_LOADA(kt_) { _Pragma("unroll") for (int i = 0; i < 4; ++i) ra[i] = al(lrow + 64 * i, (kt_) * 64 + lck * 8); }
; #define G_LOADB(kt_) { _Pragma("unroll") for (int i = 0; i < 4; ++i) rb[i] = bl(lrow + 64 * i, (kt_) * 64 + lck * 8); }
; #define G_STOREA(buf_) { bf16_t* nA = sA + (buf_) * 256 * GLD; _Pragma("unroll") for (int i = 0; i < 4; ++i) *(u32x4*)(nA + (lrow + 64 * i) * GLD + lck * 8) = ra[i]; }
; #define G_STOREB(buf_) { bf16_t* nB = sB + (buf_) * 256 * GLD; _Pragma("unroll") for (int i = 0; i < 4; ++i) *(u32x4*)(nB + (lrow + 64 * i) * GLD + lck * 8) = rb[i]; }
; template <class AL, class BL, class EP>
; DI void gemm_tile256(AL al, BL bl, EP ep, int K, char* smem) {
;     ...
;   G_LOADA(0); G_LOADB(0);
;   __syncthreads();
;   G_STOREA(0); G_STOREB(0);
;   if (KT > 1) G_LOADB(1);
;   __syncthreads();
;   for (int kt = 0; kt < KT; kt += 2) {
;     G_STEP(0, kt);
;     if (kt + 1 >= KT) break;
;     G_STEP(1, kt + 1);
;   }
	s_waitcnt lgkmcnt(0)
	v_mfma_f32_32x32x16_bf16 v[112:127], v[192:195], v[168:171], v[112:127]
	ds_read_b128 v[184:187], v206
	ds_read_b128 v[152:155], v204
	v_mfma_f32_32x32x16_bf16 v[96:111], v[200:203], v[168:171], v[96:111]
	ds_read_b128 v[188:191], v206 offset:2048
	ds_read_b128 v[156:159], v204 offset:2048
	v_mfma_f32_32x32x16_bf16 v[80:95], v[192:195], v[172:175], v[80:95]
	ds_read_b128 v[160:163], v204 offset:4096
	ds_read_b128 v[164:167], v204 offset:6144
	v_mfma_f32_32x32x16_bf16 v[64:79], v[200:203], v[172:175], v[64:79]
	s_add_u32 m0, s23, 0x8000
	s_nop 0
	global_load_lds_dwordx4 v[212:213], off
	v_lshl_add_u64 v[212:213], v[212:213], 0, s[4:5]
	v_mfma_f32_32x32x16_bf16 v[48:63], v[192:195], v[176:179], v[48:63]
	v_mfma_f32_32x32x16_bf16 v[32:47], v[200:203], v[176:179], v[32:47]
	v_mfma_f32_32x32x16_bf16 v[16:31], v[192:195], v[180:183], v[16:31]
	v_mfma_f32_32x32x16_bf16 v[0:15], v[200:203], v[180:183], v[0:15]
	s_add_u32 m0, s23, 0xc000
	s_nop 0
	global_load_lds_dwordx4 v[216:217], off
	v_lshl_add_u64 v[216:217], v[216:217], 0, s[4:5]
	s_waitcnt lgkmcnt(0)
	v_mfma_f32_32x32x16_bf16 v[112:127], v[184:187], v[152:155], v[112:127]
	ds_read_b128 v[192:195], v207
	ds_read_b128 v[168:171], v205
	v_mfma_f32_32x32x16_bf16 v[96:111], v[188:191], v[152:155], v[96:111]
	ds_read_b128 v[200:203], v207 offset:2048
	ds_read_b128 v[172:175], v205 offset:2048
	v_mfma_f32_32x32x16_bf16 v[80:95], v[184:187], v[156:159], v[80:95]
	ds_read_b128 v[176:179], v205 offset:4096
	ds_read_b128 v[180:183], v205 offset:6144
	v_mfma_f32_32x32x16_bf16 v[64:79], v[188:191], v[156:159], v[64:79]
	s_add_u32 m0, s23, 0xa000
	s_nop 0
	global_load_lds_dwordx4 v[214:215], off
	v_lshl_add_u64 v[214:215], v[214:215], 0, s[4:5]
	v_mfma_f32_32x32x16_bf16 v[48:63], v[184:187], v[160:163], v[48:63]
	v_mfma_f32_32x32x16_bf16 v[32:47], v[188:191], v[160:163], v[32:47]
	v_mfma_f32_32x32x16_bf16 v[16:31], v[184:187], v[164:167], v[16:31]
	v_mfma_f32_32x32x16_bf16 v[0:15], v[188:191], v[164:167], v[0:15]
	s_add_u32 m0, s23, 0xe000
	s_nop 0
	global_load_lds_dwordx4 v[218:219], off
	v_lshl_add_u64 v[218:219], v[218:219], 0, s[4:5]
	s_waitcnt lgkmcnt(0)
	s_waitcnt vmcnt(12)
	s_barrier
	s_waitcnt lgkmcnt(0)
	v_mfma_f32_32x32x16_bf16 v[112:127], v[192:195], v[168:171], v[112:127]
	ds_read_b128 v[184:187], v206 offset:32768
	ds_read_b128 v[152:155], v204 offset:32768
	v_mfma_f32_32x32x16_bf16 v[96:111], v[200:203], v[168:171], v[96:111]
	ds_read_b128 v[188:191], v206 offset:34816
	ds_read_b128 v[156:159], v204 offset:34816
	v_mfma_f32_32x32x16_bf16 v[80:95], v[192:195], v[172:175], v[80:95]
	ds_read_b128 v[160:163], v204 offset:36864
	ds_read_b128 v[164:167], v204 offset:38912
	v_mfma_f32_32x32x16_bf16 v[64:79], v[200:203], v[172:175], v[64:79]
	s_add_u32 m0, s23, 0x10000
	s_nop 0
	global_load_lds_dwordx4 v[212:213], off
	v_lshl_add_u64 v[212:213], v[212:213], 0, s[4:5]
	v_mfma_f32_32x32x16_bf16 v[48:63], v[192:195], v[176:179], v[48:63]
	v_mfma_f32_32x32x16_bf16 v[32:47], v[200:203], v[176:179], v[32:47]
	v_mfma_f32_32x32x16_bf16 v[16:31], v[192:195], v[180:183], v[16:31]
	v_mfma_f32_32x32x16_bf16 v[0:15], v[200:203], v[180:183], v[0:15]
	s_add_u32 m0, s23, 0x14000
	s_nop 0
	global_load_lds_dwordx4 v[216:217], off
	v_lshl_add_u64 v[216:217], v[216:217], 0, s[4:5]
	s_waitcnt lgkmcnt(0)
	v_mfma_f32_32x32x16_bf16 v[112:127], v[184:187], v[152:155], v[112:127]
	ds_read_b128 v[192:195], v207 offset:32768
	ds_read_b128 v[168:171], v205 offset:32768
	v_mfma_f32_32x32x16_bf16 v[96:111], v[188:191], v[152:155], v[96:111]
	ds_read_b128 v[200:203], v207 offset:34816
	ds_read_b128 v[172:175], v205 offset:34816
	v_mfma_f32_32x32x16_bf16 v[80:95], v[184:187], v[156:159], v[80:95]
	ds_read_b128 v[176:179], v205 offset:36864
	ds_read_b128 v[180:183], v205 offset:38912
	v_mfma_f32_32x32x16_bf16 v[64:79], v[188:191], v[156:159], v[64:79]
	s_add_u32 m0, s23, 0x12000
	s_nop 0
	global_load_lds_dwordx4 v[214:215], off
	v_lshl_add_u64 v[214:215], v[214:215], 0, s[4:5]
	v_mfma_f32_32x32x16_bf16 v[48:63], v[184:187], v[160:163], v[48:63]
	v_mfma_f32_32x32x16_bf16 v[32:47], v[188:191], v[160:163], v[32:47]
	v_mfma_f32_32x32x16_bf16 v[16:31], v[184:187], v[164:167], v[16:31]
	v_mfma_f32_32x32x16_bf16 v[0:15], v[188:191], v[164:167], v[0:15]
	s_add_u32 m0, s23, 0x16000
	s_nop 0
	global_load_lds_dwordx4 v[218:219], off
	v_lshl_add_u64 v[218:219], v[218:219], 0, s[4:5]
	s_waitcnt lgkmcnt(0)
	s_waitcnt vmcnt(12)
	s_barrier
	s_waitcnt lgkmcnt(0)
	v_mfma_f32_32x32x16_bf16 v[112:127], v[192:195], v[168:171], v[112:127]
	ds_read_b128 v[184:187], v210
	ds_read_b128 v[152:155], v208
	v_mfma_f32_32x32x16_bf16 v[96:111], v[200:203], v[168:171], v[96:111]
	ds_read_b128 v[188:191], v210 offset:2048
	ds_read_b128 v[156:159], v208 offset:2048
	v_mfma_f32_32x32x16_bf16 v[80:95], v[192:195], v[172:175], v[80:95]
	ds_read_b128 v[160:163], v208 offset:4096
	ds_read_b128 v[164:167], v208 offset:6144
	v_mfma_f32_32x32x16_bf16 v[64:79], v[200:203], v[172:175], v[64:79]
	s_add_u32 m0, s23, 0x18000
	s_nop 0
	global_load_lds_dwordx4 v[212:213], off
	v_lshl_add_u64 v[212:213], v[212:213], 0, s[4:5]
	v_mfma_f32_32x32x16_bf16 v[48:63], v[192:195], v[176:179], v[48:63]
	v_mfma_f32_32x32x16_bf16 v[32:47], v[200:203], v[176:179], v[32:47]
	v_mfma_f32_32x32x16_bf16 v[16:31], v[192:195], v[180:183], v[16:31]
	v_mfma_f32_32x32x16_bf16 v[0:15], v[200:203], v[180:183], v[0:15]
	s_add_u32 m0, s23, 0x1c000
	s_nop 0
	global_load_lds_dwordx4 v[216:217], off
	v_lshl_add_u64 v[216:217], v[216:217], 0, s[4:5]
	s_waitcnt lgkmcnt(0)
	v_mfma_f32_32x32x16_bf16 v[112:127], v[184:187], v[152:155], v[112:127]
	ds_read_b128 v[192:195], v211
	ds_read_b128 v[168:171], v209
	v_mfma_f32_32x32x16_bf16 v[96:111], v[188:191], v[152:155], v[96:111]
	ds_read_b128 v[200:203], v211 offset:2048
	ds_read_b128 v[172:175], v209 offset:2048
	v_mfma_f32_32x32x16_bf16 v[80:95], v[184:187], v[156:159], v[80:95]
	ds_read_b128 v[176:179], v209 offset:4096
	ds_read_b128 v[180:183], v209 offset:6144
	v_mfma_f32_32x32x16_bf16 v[64:79], v[188:191], v[156:159], v[64:79]
	s_add_u32 m0, s23, 0x1a000
	s_nop 0
	global_load_lds_dwordx4 v[214:215], off
	v_lshl_add_u64 v[214:215], v[214:215], 0, s[4:5]
	v_mfma_f32_32x32x16_bf16 v[48:63], v[184:187], v[160:163], v[48:63]
	v_mfma_f32_32x32x16_bf16 v[32:47], v[188:191], v[160:163], v[32:47]
	v_mfma_f32_32x32x16_bf16 v[16:31], v[184:187], v[164:167], v[16:31]
	v_mfma_f32_32x32x16_bf16 v[0:15], v[188:191], v[164:167], v[0:15]
	s_add_u32 m0, s23, 0x1e000
	s_nop 0
	global_load_lds_dwordx4 v[218:219], off
	v_lshl_add_u64 v[218:219], v[218:219], 0, s[4:5]
	s_waitcnt lgkmcnt(0)
	s_waitcnt vmcnt(12)
	s_barrier
; #define G_LOADA(kt_) { _Pragma("unroll") for (int i = 0; i < 4; ++i) ra[i] = al(lrow + 64 * i, (kt_) * 64 + lck * 8); }
; #define G_LOADB(kt_) { _Pragma("unroll") for (int i = 0; i < 4; ++i) rb[i] = bl(lrow + 64 * i, (kt_) * 64 + lck * 8); }
; #define G_STOREA(buf_) { bf16_t* nA = sA + (buf_) * 256 * GLD; _Pragma("unroll") for (int i = 0; i < 4; ++i) *(u32x4*)(nA + (lrow + 64 * i) * GLD + lck * 8) = ra[i]; }
; #define G_STOREB(buf_) { bf16_t* nB = sB + (buf_) * 256 * GLD; _Pragma("unroll") for (int i = 0; i < 4; ++i) *(u32x4*)(nB + (lrow + 64 * i) * GLD + lck * 8) = rb[i]; }
; template <class AL, class BL, class EP>
; DI void gemm_tile256(AL al, BL bl, EP ep, int K, char* smem) {
;     ...
;   G_LOADA(0); G_LOADB(0);
;   __syncthreads();
;   G_STOREA(0); G_STOREB(0);
;   if (KT > 1) G_LOADB(1);
;   __syncthreads();
;   for (int kt = 0; kt < KT; kt += 2) {
;     G_STEP(0, kt);
;     if (kt + 1 >= KT) break;
;     G_STEP(1, kt + 1);
;   }
	s_waitcnt lgkmcnt(0)
	v_mfma_f32_32x32x16_bf16 v[112:127], v[192:195], v[168:171], v[112:127]
	ds_read_b128 v[184:187], v198
	ds_read_b128 v[152:155], v132
	v_mfma_f32_32x32x16_bf16 v[96:111], v[200:203], v[168:171], v[96:111]
	ds_read_b128 v[188:191], v198 offset:2048
	ds_read_b128 v[156:159], v132 offset:2048
	v_mfma_f32_32x32x16_bf16 v[80:95], v[192:195], v[172:175], v[80:95]
	ds_read_b128 v[160:163], v132 offset:4096
	ds_read_b128 v[164:167], v132 offset:6144
	v_mfma_f32_32x32x16_bf16 v[64:79], v[200:203], v[172:175], v[64:79]
	s_add_u32 m0, s23, 0x20000
	s_nop 0
	global_load_lds_dwordx4 v[212:213], off
	v_lshl_add_u64 v[212:213], v[212:213], 0, s[4:5]
	v_mfma_f32_32x32x16_bf16 v[48:63], v[192:195], v[176:179], v[48:63]
	v_mfma_f32_32x32x16_bf16 v[32:47], v[200:203], v[176:179], v[32:47]
	v_mfma_f32_32x32x16_bf16 v[16:31], v[192:195], v[180:183], v[16:31]
	v_mfma_f32_32x32x16_bf16 v[0:15], v[200:203], v[180:183], v[0:15]
	s_add_u32 m0, s23, 0x24000
	s_nop 0
	global_load_lds_dwordx4 v[216:217], off
	v_lshl_add_u64 v[216:217], v[216:217], 0, s[4:5]
	s_sub_u32 s24, s24, 1
	s_cmp_lg_u32 s24, 0
	s_cbranch_scc1 .Lgk_ph13_loop
	s_waitcnt lgkmcnt(0)
	v_mfma_f32_32x32x16_bf16 v[112:127], v[184:187], v[152:155], v[112:127]
	ds_read_b128 v[192:195], v199
	ds_read_b128 v[168:171], v151
	v_mfma_f32_32x32x16_bf16 v[96:111], v[188:191], v[152:155], v[96:111]
	ds_read_b128 v[200:203], v199 offset:2048
	ds_read_b128 v[172:175], v151 offset:2048
	v_mfma_f32_32x32x16_bf16 v[80:95], v[184:187], v[156:159], v[80:95]
	ds_read_b128 v[176:179], v151 offset:4096
	ds_read_b128 v[180:183], v151 offset:6144
	v_mfma_f32_32x32x16_bf16 v[64:79], v[188:191], v[156:159], v[64:79]
	s_add_u32 m0, s23, 0x22000
	s_nop 0
	global_load_lds_dwordx4 v[214:215], off
	v_lshl_add_u64 v[214:215], v[214:215], 0, s[4:5]
	v_mfma_f32_32x32x16_bf16 v[48:63], v[184:187], v[160:163], v[48:63]
	v_mfma_f32_32x32x16_bf16 v[32:47], v[188:191], v[160:163], v[32:47]
	v_mfma_f32_32x32x16_bf16 v[16:31], v[184:187], v[164:167], v[16:31]
	v_mfma_f32_32x32x16_bf16 v[0:15], v[188:191], v[164:167], v[0:15]
	s_add_u32 m0, s23, 0x26000
	s_nop 0
	global_load_lds_dwordx4 v[218:219], off
	v_lshl_add_u64 v[218:219], v[218:219], 0, s[4:5]
	s_waitcnt lgkmcnt(0)
	s_waitcnt vmcnt(12)
	s_barrier
	s_waitcnt lgkmcnt(0)
	v_mfma_f32_32x32x16_bf16 v[112:127], v[192:195], v[168:171], v[112:127]
	ds_read_b128 v[184:187], v198 offset:32768
	ds_read_b128 v[152:155], v132 offset:32768
	v_mfma_f32_32x32x16_bf16 v[96:111], v[200:203], v[168:171], v[96:111]
	ds_read_b128 v[188:191], v198 offset:34816
	ds_read_b128 v[156:159], v132 offset:34816
	v_mfma_f32_32x32x16_bf16 v[80:95], v[192:195], v[172:175], v[80:95]
	ds_read_b128 v[160:163], v132 offset:36864
	ds_read_b128 v[164:167], v132 offset:38912
	v_mfma_f32_32x32x16_bf16 v[64:79], v[200:203], v[172:175], v[64:79]
	s_add_u32 m0, s23, 0x0
	s_nop 0
	global_load_lds_dwordx4 v[212:213], off
	v_lshl_add_u64 v[212:213], v[212:213], 0, s[4:5]
	v_mfma_f32_32x32x16_bf16 v[48:63], v[192:195], v[176:179], v[48:63]
	v_mfma_f32_32x32x16_bf16 v[32:47], v[200:203], v[176:179], v[32:47]
	v_mfma_f32_32x32x16_bf16 v[16:31], v[192:195], v[180:183], v[16:31]
	v_mfma_f32_32x32x16_bf16 v[0:15], v[200:203], v[180:183], v[0:15]
	s_add_u32 m0, s23, 0x4000
	s_nop 0
	global_load_lds_dwordx4 v[216:217], off
	v_lshl_add_u64 v[216:217], v[216:217], 0, s[4:5]
	s_waitcnt lgkmcnt(0)
	v_mfma_f32_32x32x16_bf16 v[112:127], v[184:187], v[152:155], v[112:127]
	ds_read_b128 v[192:195], v199 offset:32768
	ds_read_b128 v[168:171], v151 offset:32768
	v_mfma_f32_32x32x16_bf16 v[96:111], v[188:191], v[152:155], v[96:111]
	ds_read_b128 v[200:203], v199 offset:34816
	ds_read_b128 v[172:175], v151 offset:34816
	v_mfma_f32_32x32x16_bf16 v[80:95], v[184:187], v[156:159], v[80:95]
	ds_read_b128 v[176:179], v151 offset:36864
	ds_read_b128 v[180:183], v151 offset:38912
	v_mfma_f32_32x32x16_bf16 v[64:79], v[188:191], v[156:159], v[64:79]
	s_add_u32 m0, s23, 0x2000
	s_nop 0
	global_load_lds_dwordx4 v[214:215], off
	v_lshl_add_u64 v[214:215], v[214:215], 0, s[4:5]
	v_mfma_f32_32x32x16_bf16 v[48:63], v[184:187], v[160:163], v[48:63]
	v_mfma_f32_32x32x16_bf16 v[32:47], v[188:191], v[160:163], v[32:47]
	v_mfma_f32_32x32x16_bf16 v[16:31], v[184:187], v[164:167], v[16:31]
	v_mfma_f32_32x32x16_bf16 v[0:15], v[188:191], v[164:167], v[0:15]
	s_add_u32 m0, s23, 0x6000
	s_nop 0
	global_load_lds_dwordx4 v[218:219], off
	v_lshl_add_u64 v[218:219], v[218:219], 0, s[4:5]
	s_waitcnt lgkmcnt(0)
	s_waitcnt vmcnt(12)
	s_barrier
	s_waitcnt lgkmcnt(0)
	v_mfma_f32_32x32x16_bf16 v[112:127], v[192:195], v[168:171], v[112:127]
	ds_read_b128 v[184:187], v206
	ds_read_b128 v[152:155], v204
	v_mfma_f32_32x32x16_bf16 v[96:111], v[200:203], v[168:171], v[96:111]
	ds_read_b128 v[188:191], v206 offset:2048
	ds_read_b128 v[156:159], v204 offset:2048
	v_mfma_f32_32x32x16_bf16 v[80:95], v[192:195], v[172:175], v[80:95]
	ds_read_b128 v[160:163], v204 offset:4096
	ds_read_b128 v[164:167], v204 offset:6144
	v_mfma_f32_32x32x16_bf16 v[64:79], v[200:203], v[172:175], v[64:79]
	s_add_u32 m0, s23, 0x8000
	s_nop 0
	global_load_lds_dwordx4 v[212:213], off
	v_lshl_add_u64 v[212:213], v[212:213], 0, s[4:5]
	v_mfma_f32_32x32x16_bf16 v[48:63], v[192:195], v[176:179], v[48:63]
	v_mfma_f32_32x32x16_bf16 v[32:47], v[200:203], v[176:179], v[32:47]
	v_mfma_f32_32x32x16_bf16 v[16:31], v[192:195], v[180:183], v[16:31]
	v_mfma_f32_32x32x16_bf16 v[0:15], v[200:203], v[180:183], v[0:15]
	s_add_u32 m0, s23, 0xc000
	s_nop 0
	global_load_lds_dwordx4 v[216:217], off
	v_lshl_add_u64 v[216:217], v[216:217], 0, s[4:5]
	s_waitcnt lgkmcnt(0)
	v_mfma_f32_32x32x16_bf16 v[112:127], v[184:187], v[152:155], v[112:127]
	ds_read_b128 v[192:195], v207
	ds_read_b128 v[168:171], v205
	v_mfma_f32_32x32x16_bf16 v[96:111], v[188:191], v[152:155], v[96:111]
	ds_read_b128 v[200:203], v207 offset:2048
	ds_read_b128 v[172:175], v205 offset:2048
	v_mfma_f32_32x32x16_bf16 v[80:95], v[184:187], v[156:159], v[80:95]
	ds_read_b128 v[176:179], v205 offset:4096
	ds_read_b128 v[180:183], v205 offset:6144
	v_mfma_f32_32x32x16_bf16 v[64:79], v[188:191], v[156:159], v[64:79]
	s_add_u32 m0, s23, 0xa000
	s_nop 0
	global_load_lds_dwordx4 v[214:215], off
	v_lshl_add_u64 v[214:215], v[214:215], 0, s[4:5]
	v_mfma_f32_32x32x16_bf16 v[48:63], v[184:187], v[160:163], v[48:63]
	v_mfma_f32_32x32x16_bf16 v[32:47], v[188:191], v[160:163], v[32:47]
	v_mfma_f32_32x32x16_bf16 v[16:31], v[184:187], v[164:167], v[16:31]
	v_mfma_f32_32x32x16_bf16 v[0:15], v[188:191], v[164:167], v[0:15]
	s_add_u32 m0, s23, 0xe000
	s_nop 0
	global_load_lds_dwordx4 v[218:219], off
	v_lshl_add_u64 v[218:219], v[218:219], 0, s[4:5]
	s_waitcnt lgkmcnt(0)
	s_waitcnt vmcnt(12)
	s_barrier
; #define G_LOADA(kt_) { _Pragma("unroll") for (int i = 0; i < 4; ++i) ra[i] = al(lrow + 64 * i, (kt_) * 64 + lck * 8); }
; #define G_LOADB(kt_) { _Pragma("unroll") for (int i = 0; i < 4; ++i) rb[i] = bl(lrow + 64 * i, (kt_) * 64 + lck * 8); }
; #define G_STOREA(buf_) { bf16_t* nA = sA + (buf_) * 256 * GLD; _Pragma("unroll") for (int i = 0; i < 4; ++i) *(u32x4*)(nA + (lrow + 64 * i) * GLD + lck * 8) = ra[i]; }
; #define G_STOREB(buf_) { bf16_t* nB = sB + (buf_) * 256 * GLD; _Pragma("unroll") for (int i = 0; i < 4; ++i) *(u32x4*)(nB + (lrow + 64 * i) * GLD + lck * 8) = rb[i]; }
; template <class AL, class BL, class EP>
; DI void gemm_tile256(AL al, BL bl, EP ep, int K, char* smem) {
;     ...
;   G_LOADA(0); G_LOADB(0);
;   __syncthreads();
;   G_STOREA(0); G_STOREB(0);
;   if (KT > 1) G_LOADB(1);
;   __syncthreads();
;   for (int kt = 0; kt < KT; kt += 2) {
;     G_STEP(0, kt);
;     if (kt + 1 >= KT) break;
;     G_STEP(1, kt + 1);
;   }
	s_waitcnt lgkmcnt(0)
	v_mfma_f32_32x32x16_bf16 v[112:127], v[192:195], v[168:171], v[112:127]
	ds_read_b128 v[184:187], v206 offset:32768
	ds_read_b128 v[152:155], v204 offset:32768
	v_mfma_f32_32x32x16_bf16 v[96:111], v[200:203], v[168:171], v[96:111]
	ds_read_b128 v[188:191], v206 offset:34816
	ds_read_b128 v[156:159], v204 offset:34816
	v_mfma_f32_32x32x16_bf16 v[80:95], v[192:195], v[172:175], v[80:95]
	ds_read_b128 v[160:163], v204 offset:36864
	ds_read_b128 v[164:167], v204 offset:38912
	v_mfma_f32_32x32x16_bf16 v[64:79], v[200:203], v[172:175], v[64:79]
	v_mfma_f32_32x32x16_bf16 v[48:63], v[192:195], v[176:179], v[48:63]
	v_mfma_f32_32x32x16_bf16 v[32:47], v[200:203], v[176:179], v[32:47]
	v_mfma_f32_32x32x16_bf16 v[16:31], v[192:195], v[180:183], v[16:31]
	v_mfma_f32_32x32x16_bf16 v[0:15], v[200:203], v[180:183], v[0:15]
	s_waitcnt lgkmcnt(0)
	v_mfma_f32_32x32x16_bf16 v[112:127], v[184:187], v[152:155], v[112:127]
	ds_read_b128 v[192:195], v207 offset:32768
	ds_read_b128 v[168:171], v205 offset:32768
	v_mfma_f32_32x32x16_bf16 v[96:111], v[188:191], v[152:155], v[96:111]
	ds_read_b128 v[200:203], v207 offset:34816
	ds_read_b128 v[172:175], v205 offset:34816
	v_mfma_f32_32x32x16_bf16 v[80:95], v[184:187], v[156:159], v[80:95]
	ds_read_b128 v[176:179], v205 offset:36864
	ds_read_b128 v[180:183], v205 offset:38912
	v_mfma_f32_32x32x16_bf16 v[64:79], v[188:191], v[156:159], v[64:79]
	v_mfma_f32_32x32x16_bf16 v[48:63], v[184:187], v[160:163], v[48:63]
	v_mfma_f32_32x32x16_bf16 v[32:47], v[188:191], v[160:163], v[32:47]
	v_mfma_f32_32x32x16_bf16 v[16:31], v[184:187], v[164:167], v[16:31]
	v_mfma_f32_32x32x16_bf16 v[0:15], v[188:191], v[164:167], v[0:15]
	s_waitcnt lgkmcnt(0)
	s_waitcnt vmcnt(8)
	s_barrier
	s_waitcnt lgkmcnt(0)
	v_mfma_f32_32x32x16_bf16 v[112:127], v[192:195], v[168:171], v[112:127]
	ds_read_b128 v[184:187], v210
	ds_read_b128 v[152:155], v208
	v_mfma_f32_32x32x16_bf16 v[96:111], v[200:203], v[168:171], v[96:111]
	ds_read_b128 v[188:191], v210 offset:2048
	ds_read_b128 v[156:159], v208 offset:2048
	v_mfma_f32_32x32x16_bf16 v[80:95], v[192:195], v[172:175], v[80:95]
	ds_read_b128 v[160:163], v208 offset:4096
	ds_read_b128 v[164:167], v208 offset:6144
	v_mfma_f32_32x32x16_bf16 v[64:79], v[200:203], v[172:175], v[64:79]
	v_mfma_f32_32x32x16_bf16 v[48:63], v[192:195], v[176:179], v[48:63]
	v_mfma_f32_32x32x16_bf16 v[32:47], v[200:203], v[176:179], v[32:47]
	v_mfma_f32_32x32x16_bf16 v[16:31], v[192:195], v[180:183], v[16:31]
	v_mfma_f32_32x32x16_bf16 v[0:15], v[200:203], v[180:183], v[0:15]
	s_waitcnt lgkmcnt(0)
	v_mfma_f32_32x32x16_bf16 v[112:127], v[184:187], v[152:155], v[112:127]
	ds_read_b128 v[192:195], v211
	ds_read_b128 v[168:171], v209
	v_mfma_f32_32x32x16_bf16 v[96:111], v[188:191], v[152:155], v[96:111]
	ds_read_b128 v[200:203], v211 offset:2048
	ds_read_b128 v[172:175], v209 offset:2048
	v_mfma_f32_32x32x16_bf16 v[80:95], v[184:187], v[156:159], v[80:95]
	ds_read_b128 v[176:179], v209 offset:4096
	ds_read_b128 v[180:183], v209 offset:6144
	v_mfma_f32_32x32x16_bf16 v[64:79], v[188:191], v[156:159], v[64:79]
	v_mfma_f32_32x32x16_bf16 v[48:63], v[184:187], v[160:163], v[48:63]
	v_mfma_f32_32x32x16_bf16 v[32:47], v[188:191], v[160:163], v[32:47]
	v_mfma_f32_32x32x16_bf16 v[16:31], v[184:187], v[164:167], v[16:31]
	v_mfma_f32_32x32x16_bf16 v[0:15], v[188:191], v[164:167], v[0:15]
	s_waitcnt lgkmcnt(0)
	s_waitcnt vmcnt(4)
	s_barrier
	s_waitcnt lgkmcnt(0)
	v_mfma_f32_32x32x16_bf16 v[112:127], v[192:195], v[168:171], v[112:127]
	ds_read_b128 v[184:187], v198
	ds_read_b128 v[152:155], v132
	v_mfma_f32_32x32x16_bf16 v[96:111], v[200:203], v[168:171], v[96:111]
	ds_read_b128 v[188:191], v198 offset:2048
	ds_read_b128 v[156:159], v132 offset:2048
	v_mfma_f32_32x32x16_bf16 v[80:95], v[192:195], v[172:175], v[80:95]
	ds_read_b128 v[160:163], v132 offset:4096
	ds_read_b128 v[164:167], v132 offset:6144
	v_mfma_f32_32x32x16_bf16 v[64:79], v[200:203], v[172:175], v[64:79]
	v_mfma_f32_32x32x16_bf16 v[48:63], v[192:195], v[176:179], v[48:63]
	v_mfma_f32_32x32x16_bf16 v[32:47], v[200:203], v[176:179], v[32:47]
	v_mfma_f32_32x32x16_bf16 v[16:31], v[192:195], v[180:183], v[16:31]
	v_mfma_f32_32x32x16_bf16 v[0:15], v[200:203], v[180:183], v[0:15]
	s_waitcnt lgkmcnt(0)
	v_mfma_f32_32x32x16_bf16 v[112:127], v[184:187], v[152:155], v[112:127]
	ds_read_b128 v[192:195], v199
	ds_read_b128 v[168:171], v151
	v_mfma_f32_32x32x16_bf16 v[96:111], v[188:191], v[152:155], v[96:111]
	ds_read_b128 v[200:203], v199 offset:2048
	ds_read_b128 v[172:175], v151 offset:2048
	v_mfma_f32_32x32x16_bf16 v[80:95], v[184:187], v[156:159], v[80:95]
	ds_read_b128 v[176:179], v151 offset:4096
	ds_read_b128 v[180:183], v151 offset:6144
	v_mfma_f32_32x32x16_bf16 v[64:79], v[188:191], v[156:159], v[64:79]
	v_mfma_f32_32x32x16_bf16 v[48:63], v[184:187], v[160:163], v[48:63]
	v_mfma_f32_32x32x16_bf16 v[32:47], v[188:191], v[160:163], v[32:47]
	v_mfma_f32_32x32x16_bf16 v[16:31], v[184:187], v[164:167], v[16:31]
	v_mfma_f32_32x32x16_bf16 v[0:15], v[188:191], v[164:167], v[0:15]
	s_waitcnt lgkmcnt(0)
	s_waitcnt vmcnt(0)
	s_barrier
; DI unsigned pack2(float a, float b) { f2_t f = {a, b}; bf2_t r = __builtin_convertvector(f, bf2_t); return __builtin_bit_cast(unsigned, r); }
; template <class AL, class BL, class EP>
; DI void gemm_tile256(AL al, BL bl, EP ep, int K, char* smem) {
;     ...
;   for (int kt = 0; kt < KT; kt += 2) {
;     G_STEP(0, kt);
;     if (kt + 1 >= KT) break;
;     G_STEP(1, kt + 1);
;   }
;     ...
;   if constexpr (EP::kBf16) {
;     bf16_t* sCb = (bf16_t*)smem;
; #pragma unroll
;     for (int i = 0; i < 4; ++i)
; #pragma unroll
;       for (int j = 0; j < 2; ++j)
; #pragma unroll
;         for (int g = 0; g < 4; ++g) {
;           u32x2 v = {pack2(acc[i][j][4 * g], acc[i][j][4 * g + 1]), pack2(acc[i][j][4 * g + 2], acc[i][j][4 * g + 3])};
;           *(u32x2*)(sCb + (128 * wm + 32 * i + r) * BLD + 64 * wn + 32 * j + 8 * g + 4 * h) = v;
;         }
;     __syncthreads();
	s_waitcnt lgkmcnt(0)
	v_mfma_f32_32x32x16_bf16 v[112:127], v[192:195], v[168:171], v[112:127]
	ds_read_b128 v[184:187], v198 offset:32768
	ds_read_b128 v[152:155], v132 offset:32768
	v_mfma_f32_32x32x16_bf16 v[96:111], v[200:203], v[168:171], v[96:111]
	ds_read_b128 v[188:191], v198 offset:34816
	ds_read_b128 v[156:159], v132 offset:34816
	v_mfma_f32_32x32x16_bf16 v[80:95], v[192:195], v[172:175], v[80:95]
	ds_read_b128 v[160:163], v132 offset:36864
	ds_read_b128 v[164:167], v132 offset:38912
	v_mfma_f32_32x32x16_bf16 v[64:79], v[200:203], v[172:175], v[64:79]
	v_mfma_f32_32x32x16_bf16 v[48:63], v[192:195], v[176:179], v[48:63]
	v_mfma_f32_32x32x16_bf16 v[32:47], v[200:203], v[176:179], v[32:47]
	v_mfma_f32_32x32x16_bf16 v[16:31], v[192:195], v[180:183], v[16:31]
	v_mfma_f32_32x32x16_bf16 v[0:15], v[200:203], v[180:183], v[0:15]
	s_waitcnt lgkmcnt(0)
	v_mfma_f32_32x32x16_bf16 v[112:127], v[184:187], v[152:155], v[112:127]
	ds_read_b128 v[192:195], v199 offset:32768
	ds_read_b128 v[168:171], v151 offset:32768
	v_mfma_f32_32x32x16_bf16 v[96:111], v[188:191], v[152:155], v[96:111]
	ds_read_b128 v[200:203], v199 offset:34816
	ds_read_b128 v[172:175], v151 offset:34816
	v_mfma_f32_32x32x16_bf16 v[80:95], v[184:187], v[156:159], v[80:95]
	ds_read_b128 v[176:179], v151 offset:36864
	ds_read_b128 v[180:183], v151 offset:38912
	v_mfma_f32_32x32x16_bf16 v[64:79], v[188:191], v[156:159], v[64:79]
	v_mfma_f32_32x32x16_bf16 v[48:63], v[184:187], v[160:163], v[48:63]
	v_mfma_f32_32x32x16_bf16 v[32:47], v[188:191], v[160:163], v[32:47]
	v_mfma_f32_32x32x16_bf16 v[16:31], v[184:187], v[164:167], v[16:31]
	v_mfma_f32_32x32x16_bf16 v[0:15], v[188:191], v[164:167], v[0:15]
	s_waitcnt lgkmcnt(0)
	s_waitcnt lgkmcnt(0)
	v_mfma_f32_32x32x16_bf16 v[112:127], v[192:195], v[168:171], v[112:127]
	v_mfma_f32_32x32x16_bf16 v[96:111], v[200:203], v[168:171], v[96:111]
	v_mfma_f32_32x32x16_bf16 v[80:95], v[192:195], v[172:175], v[80:95]
	v_mfma_f32_32x32x16_bf16 v[64:79], v[200:203], v[172:175], v[64:79]
	v_mfma_f32_32x32x16_bf16 v[48:63], v[192:195], v[176:179], v[48:63]
	v_mfma_f32_32x32x16_bf16 v[32:47], v[200:203], v[176:179], v[32:47]
	v_mfma_f32_32x32x16_bf16 v[16:31], v[192:195], v[180:183], v[16:31]
	v_mfma_f32_32x32x16_bf16 v[0:15], v[200:203], v[180:183], v[0:15]
	s_nop 15
	s_nop 3
	s_setprio 0
	v_lshl_or_b32 v128, v128, 7, v150
	s_waitcnt lgkmcnt(4)
	v_mad_u64_u32 v[130:131], s[2:3], v133, s17, v[128:129]
	s_waitcnt lgkmcnt(0)
	s_barrier
	s_nop 8
	v_cvt_pk_bf16_f32 v112, v112, v113
	v_cvt_pk_bf16_f32 v113, v114, v115
	v_cvt_pk_bf16_f32 v114, v116, v117
	v_cvt_pk_bf16_f32 v115, v118, v119
	ds_write2_b64 v130, v[112:113], v[114:115] offset1:2
	v_cvt_pk_bf16_f32 v112, v120, v121
	v_cvt_pk_bf16_f32 v113, v122, v123
	v_cvt_pk_bf16_f32 v114, v124, v125
	s_nop 3
	v_cvt_pk_bf16_f32 v16, v16, v17
	v_cvt_pk_bf16_f32 v17, v18, v19
	v_cvt_pk_bf16_f32 v18, v20, v21
	v_add_u32_e32 v20, 0xc000, v130
	v_cvt_pk_bf16_f32 v19, v22, v23
	v_cvt_pk_bf16_f32 v115, v126, v127
	ds_write2_b64 v20, v[16:17], v[18:19] offset0:192 offset1:194
	v_cvt_pk_bf16_f32 v0, v0, v1
	v_cvt_pk_bf16_f32 v1, v2, v3
	v_cvt_pk_bf16_f32 v2, v4, v5
	v_cvt_pk_bf16_f32 v3, v6, v7
	ds_write2_b64 v20, v[0:1], v[2:3] offset0:200 offset1:202
	v_cvt_pk_bf16_f32 v0, v8, v9
	v_cvt_pk_bf16_f32 v1, v10, v11
	s_nop 3
	v_cvt_pk_bf16_f32 v96, v96, v97
	v_cvt_pk_bf16_f32 v97, v98, v99
	v_cvt_pk_bf16_f32 v98, v100, v101
	v_cvt_pk_bf16_f32 v99, v102, v103
	v_cvt_pk_bf16_f32 v2, v12, v13
	v_cvt_pk_bf16_f32 v3, v14, v15
	ds_write2_b64 v130, v[96:97], v[98:99] offset0:8 offset1:10
	v_cvt_pk_bf16_f32 v80, v80, v81
	v_cvt_pk_bf16_f32 v81, v82, v83
	v_cvt_pk_bf16_f32 v82, v84, v85
	v_cvt_pk_bf16_f32 v83, v86, v87
	v_add_u32_e32 v84, 0x4000, v130
	v_cvt_pk_bf16_f32 v96, v104, v105
	v_cvt_pk_bf16_f32 v97, v106, v107
	s_nop 3
	v_cvt_pk_bf16_f32 v64, v64, v65
	v_cvt_pk_bf16_f32 v65, v66, v67
	v_cvt_pk_bf16_f32 v66, v68, v69
	v_cvt_pk_bf16_f32 v67, v70, v71
	v_cvt_pk_bf16_f32 v98, v108, v109
	v_cvt_pk_bf16_f32 v99, v110, v111
	ds_write2_b64 v84, v[80:81], v[82:83] offset0:64 offset1:66
	v_cvt_pk_bf16_f32 v48, v48, v49
	v_cvt_pk_bf16_f32 v49, v50, v51
	v_cvt_pk_bf16_f32 v50, v52, v53
	v_cvt_pk_bf16_f32 v51, v54, v55
	v_add_u32_e32 v52, 0x8000, v130
	v_cvt_pk_bf16_f32 v80, v88, v89
	v_cvt_pk_bf16_f32 v81, v90, v91
	s_nop 4
	v_cvt_pk_bf16_f32 v32, v32, v33
	v_cvt_pk_bf16_f32 v33, v34, v35
	v_cvt_pk_bf16_f32 v34, v36, v37
	v_cvt_pk_bf16_f32 v35, v38, v39
	v_cvt_pk_bf16_f32 v82, v92, v93
	v_cvt_pk_bf16_f32 v83, v94, v95
	ds_write2_b64 v84, v[64:65], v[66:67] offset0:72 offset1:74
	v_cvt_pk_bf16_f32 v64, v72, v73
	v_cvt_pk_bf16_f32 v65, v74, v75
	v_cvt_pk_bf16_f32 v66, v76, v77
	v_cvt_pk_bf16_f32 v67, v78, v79
	ds_write2_b64 v52, v[48:49], v[50:51] offset0:128 offset1:130
	v_cvt_pk_bf16_f32 v48, v56, v57
	v_cvt_pk_bf16_f32 v49, v58, v59
	v_cvt_pk_bf16_f32 v50, v60, v61
	v_cvt_pk_bf16_f32 v51, v62, v63
	ds_write2_b64 v52, v[32:33], v[34:35] offset0:136 offset1:138
	v_cvt_pk_bf16_f32 v32, v40, v41
	v_cvt_pk_bf16_f32 v33, v42, v43
	v_cvt_pk_bf16_f32 v34, v44, v45
	v_cvt_pk_bf16_f32 v35, v46, v47
	v_cvt_pk_bf16_f32 v16, v24, v25
	v_cvt_pk_bf16_f32 v17, v26, v27
	v_cvt_pk_bf16_f32 v18, v28, v29
	v_cvt_pk_bf16_f32 v19, v30, v31
	ds_write2_b64 v20, v[0:1], v[2:3] offset0:204 offset1:206
	v_mov_b32_e32 v2, v196
	ds_write2_b64 v130, v[112:113], v[114:115] offset0:4 offset1:6
	ds_write2_b64 v130, v[96:97], v[98:99] offset0:12 offset1:14
	ds_write2_b64 v84, v[80:81], v[82:83] offset0:68 offset1:70
	ds_write2_b64 v84, v[64:65], v[66:67] offset0:76 offset1:78
	ds_write2_b64 v52, v[48:49], v[50:51] offset0:132 offset1:134
	ds_write2_b64 v52, v[32:33], v[34:35] offset0:140 offset1:142
	ds_write2_b64 v20, v[16:17], v[18:19] offset0:196 offset1:198
	s_waitcnt lgkmcnt(0)
	s_barrier
; DI int tid512() { int t = threadIdx_x_raw(); asm volatile("" : "+v"(t)); return t; }
;   DI void operator()(const bf16_t* sCb) const {
;     for (int id = tid512(); id < 8192; id += 512) {
;       int row = id >> 5, c8 = (id & 31) * 8, n = n0 + c8;
;       if (n < N) *(u32x4*)(dst + (size_t)(m0 + row) * ld + n) = *(const u32x4*)(sCb + row * BLD + c8);
	s_nop 0
	v_cmp_gt_i32_e32 vcc, s18, v2
	s_and_saveexec_b64 s[2:3], vcc
	s_cbranch_execz .LBB0_1046
	v_lshlrev_b32_e32 v3, 3, v2
	v_and_b32_e32 v1, 0xf8, v3
	v_or_b32_e32 v0, s21, v1
	v_cmp_gt_i32_e32 vcc, s19, v0
	s_and_saveexec_b64 s[6:7], vcc
	s_cbranch_execz .Lep_done_1046
; DI int tid512() { int t = threadIdx_x_raw(); asm volatile("" : "+v"(t)); return t; }
;   DI void operator()(const bf16_t* sCb) const {
;     for (int id = tid512(); id < 8192; id += 512) {
;       int row = id >> 5, c8 = (id & 31) * 8, n = n0 + c8;
;       if (n < N) *(u32x4*)(dst + (size_t)(m0 + row) * ld + n) = *(const u32x4*)(sCb + row * BLD + c8);
;     }
;   }
	v_ashrrev_i32_e32 v8, 5, v2
	v_mul_lo_u32 v4, v8, s17
	v_lshl_add_u32 v1, v1, 1, v4
	v_add_u32_e32 v10, 0x10800, v1
	ds_read_b128 v[64:67], v1
	ds_read_b128 v[68:71], v1 offset:8448
	ds_read_b128 v[72:75], v1 offset:16896
	ds_read_b128 v[76:79], v1 offset:25344
	ds_read_b128 v[80:83], v1 offset:33792
	ds_read_b128 v[84:87], v1 offset:42240
	ds_read_b128 v[88:91], v1 offset:50688
	ds_read_b128 v[92:95], v1 offset:59136
	ds_read_b128 v[96:99], v10
	ds_read_b128 v[100:103], v10 offset:8448
	ds_read_b128 v[104:107], v10 offset:16896
	ds_read_b128 v[108:111], v10 offset:25344
	ds_read_b128 v[112:115], v10 offset:33792
	ds_read_b128 v[116:119], v10 offset:42240
	ds_read_b128 v[120:123], v10 offset:50688
	ds_read_b128 v[124:127], v10 offset:59136
	v_and_b32_e32 v1, 0xf8, v3
	v_or_b32_e32 v0, s21, v1
	v_ashrrev_i32_e32 v8, 5, v2
	v_add_u32_e32 v8, s22, v8
	v_ashrrev_i32_e32 v9, 31, v8
	v_lshlrev_b64 v[8:9], 11, v[8:9]
	v_lshl_add_u64 v[8:9], s[8:9], 0, v[8:9]
	v_ashrrev_i32_e32 v1, 31, v0
	v_lshl_add_u64 v[0:1], v[0:1], 1, v[8:9]
	s_waitcnt lgkmcnt(15)
	global_store_dwordx4 v[0:1], v[64:67], off
	v_add_u32_e32 v2, 0x200, v2
	v_and_b32_e32 v1, 0xf8, v3
	v_or_b32_e32 v0, s21, v1
	v_ashrrev_i32_e32 v8, 5, v2
	v_add_u32_e32 v8, s22, v8
	v_ashrrev_i32_e32 v9, 31, v8
	v_lshlrev_b64 v[8:9], 11, v[8:9]
	v_lshl_add_u64 v[8:9], s[8:9], 0, v[8:9]
	v_ashrrev_i32_e32 v1, 31, v0
	v_lshl_add_u64 v[0:1], v[0:1], 1, v[8:9]
	s_waitcnt lgkmcnt(14)
	global_store_dwordx4 v[0:1], v[68:71], off
	v_add_u32_e32 v2, 0x200, v2
	v_and_b32_e32 v1, 0xf8, v3
	v_or_b32_e32 v0, s21, v1
	v_ashrrev_i32_e32 v8, 5, v2
	v_add_u32_e32 v8, s22, v8
	v_ashrrev_i32_e32 v9, 31, v8
	v_lshlrev_b64 v[8:9], 11, v[8:9]
	v_lshl_add_u64 v[8:9], s[8:9], 0, v[8:9]
	v_ashrrev_i32_e32 v1, 31, v0
	v_lshl_add_u64 v[0:1], v[0:1], 1, v[8:9]
	s_waitcnt lgkmcnt(13)
	global_store_dwordx4 v[0:1], v[72:75], off
	v_add_u32_e32 v2, 0x200, v2
	v_and_b32_e32 v1, 0xf8, v3
	v_or_b32_e32 v0, s21, v1
	v_ashrrev_i32_e32 v8, 5, v2
	v_add_u32_e32 v8, s22, v8
	v_ashrrev_i32_e32 v9, 31, v8
	v_lshlrev_b64 v[8:9], 11, v[8:9]
	v_lshl_add_u64 v[8:9], s[8:9], 0, v[8:9]
	v_ashrrev_i32_e32 v1, 31, v0
	v_lshl_add_u64 v[0:1], v[0:1], 1, v[8:9]
	s_waitcnt lgkmcnt(12)
	global_store_dwordx4 v[0:1], v[76:79], off
	v_add_u32_e32 v2, 0x200, v2
	v_and_b32_e32 v1, 0xf8, v3
	v_or_b32_e32 v0, s21, v1
	v_ashrrev_i32_e32 v8, 5, v2
	v_add_u32_e32 v8, s22, v8
	v_ashrrev_i32_e32 v9, 31, v8
	v_lshlrev_b64 v[8:9], 11, v[8:9]
	v_lshl_add_u64 v[8:9], s[8:9], 0, v[8:9]
	v_ashrrev_i32_e32 v1, 31, v0
	v_lshl_add_u64 v[0:1], v[0:1], 1, v[8:9]
	s_waitcnt lgkmcnt(11)
	global_store_dwordx4 v[0:1], v[80:83], off
	v_add_u32_e32 v2, 0x200, v2
	v_and_b32_e32 v1, 0xf8, v3
	v_or_b32_e32 v0, s21, v1
	v_ashrrev_i32_e32 v8, 5, v2
	v_add_u32_e32 v8, s22, v8
	v_ashrrev_i32_e32 v9, 31, v8
	v_lshlrev_b64 v[8:9], 11, v[8:9]
	v_lshl_add_u64 v[8:9], s[8:9], 0, v[8:9]
	v_ashrrev_i32_e32 v1, 31, v0
	v_lshl_add_u64 v[0:1], v[0:1], 1, v[8:9]
	s_waitcnt lgkmcnt(10)
	global_store_dwordx4 v[0:1], v[84:87], off
	v_add_u32_e32 v2, 0x200, v2
	v_and_b32_e32 v1, 0xf8, v3
	v_or_b32_e32 v0, s21, v1
	v_ashrrev_i32_e32 v8, 5, v2
	v_add_u32_e32 v8, s22, v8
	v_ashrrev_i32_e32 v9, 31, v8
	v_lshlrev_b64 v[8:9], 11, v[8:9]
	v_lshl_add_u64 v[8:9], s[8:9], 0, v[8:9]
	v_ashrrev_i32_e32 v1, 31, v0
	v_lshl_add_u64 v[0:1], v[0:1], 1, v[8:9]
	s_waitcnt lgkmcnt(9)
	global_store_dwordx4 v[0:1], v[88:91], off
	v_add_u32_e32 v2, 0x200, v2
	v_and_b32_e32 v1, 0xf8, v3
	v_or_b32_e32 v0, s21, v1
	v_ashrrev_i32_e32 v8, 5, v2
	v_add_u32_e32 v8, s22, v8
	v_ashrrev_i32_e32 v9, 31, v8
	v_lshlrev_b64 v[8:9], 11, v[8:9]
	v_lshl_add_u64 v[8:9], s[8:9], 0, v[8:9]
	v_ashrrev_i32_e32 v1, 31, v0
	v_lshl_add_u64 v[0:1], v[0:1], 1, v[8:9]
	s_waitcnt lgkmcnt(8)
	global_store_dwordx4 v[0:1], v[92:95], off
	v_add_u32_e32 v2, 0x200, v2
	v_and_b32_e32 v1, 0xf8, v3
	v_or_b32_e32 v0, s21, v1
	v_ashrrev_i32_e32 v8, 5, v2
	v_add_u32_e32 v8, s22, v8
	v_ashrrev_i32_e32 v9, 31, v8
	v_lshlrev_b64 v[8:9], 11, v[8:9]
	v_lshl_add_u64 v[8:9], s[8:9], 0, v[8:9]
	v_ashrrev_i32_e32 v1, 31, v0
	v_lshl_add_u64 v[0:1], v[0:1], 1, v[8:9]
	s_waitcnt lgkmcnt(7)
	global_store_dwordx4 v[0:1], v[96:99], off
	v_add_u32_e32 v2, 0x200, v2
	v_and_b32_e32 v1, 0xf8, v3
	v_or_b32_e32 v0, s21, v1
	v_ashrrev_i32_e32 v8, 5, v2
	v_add_u32_e32 v8, s22, v8
	v_ashrrev_i32_e32 v9, 31, v8
	v_lshlrev_b64 v[8:9], 11, v[8:9]
	v_lshl_add_u64 v[8:9], s[8:9], 0, v[8:9]
	v_ashrrev_i32_e32 v1, 31, v0
	v_lshl_add_u64 v[0:1], v[0:1], 1, v[8:9]
	s_waitcnt lgkmcnt(6)
	global_store_dwordx4 v[0:1], v[100:103], off
	v_add_u32_e32 v2, 0x200, v2
	v_and_b32_e32 v1, 0xf8, v3
	v_or_b32_e32 v0, s21, v1
	v_ashrrev_i32_e32 v8, 5, v2
	v_add_u32_e32 v8, s22, v8
	v_ashrrev_i32_e32 v9, 31, v8
	v_lshlrev_b64 v[8:9], 11, v[8:9]
	v_lshl_add_u64 v[8:9], s[8:9], 0, v[8:9]
	v_ashrrev_i32_e32 v1, 31, v0
	v_lshl_add_u64 v[0:1], v[0:1], 1, v[8:9]
	s_waitcnt lgkmcnt(5)
	global_store_dwordx4 v[0:1], v[104:107], off
	v_add_u32_e32 v2, 0x200, v2
	v_and_b32_e32 v1, 0xf8, v3
	v_or_b32_e32 v0, s21, v1
	v_ashrrev_i32_e32 v8, 5, v2
	v_add_u32_e32 v8, s22, v8
	v_ashrrev_i32_e32 v9, 31, v8
	v_lshlrev_b64 v[8:9], 11, v[8:9]
	v_lshl_add_u64 v[8:9], s[8:9], 0, v[8:9]
	v_ashrrev_i32_e32 v1, 31, v0
	v_lshl_add_u64 v[0:1], v[0:1], 1, v[8:9]
	s_waitcnt lgkmcnt(4)
	global_store_dwordx4 v[0:1], v[108:111], off
	v_add_u32_e32 v2, 0x200, v2
	v_and_b32_e32 v1, 0xf8, v3
	v_or_b32_e32 v0, s21, v1
	v_ashrrev_i32_e32 v8, 5, v2
	v_add_u32_e32 v8, s22, v8
	v_ashrrev_i32_e32 v9, 31, v8
	v_lshlrev_b64 v[8:9], 11, v[8:9]
	v_lshl_add_u64 v[8:9], s[8:9], 0, v[8:9]
	v_ashrrev_i32_e32 v1, 31, v0
	v_lshl_add_u64 v[0:1], v[0:1], 1, v[8:9]
	s_waitcnt lgkmcnt(3)
	global_store_dwordx4 v[0:1], v[112:115], off
	v_add_u32_e32 v2, 0x200, v2
	v_and_b32_e32 v1, 0xf8, v3
	v_or_b32_e32 v0, s21, v1
	v_ashrrev_i32_e32 v8, 5, v2
	v_add_u32_e32 v8, s22, v8
	v_ashrrev_i32_e32 v9, 31, v8
	v_lshlrev_b64 v[8:9], 11, v[8:9]
	v_lshl_add_u64 v[8:9], s[8:9], 0, v[8:9]
	v_ashrrev_i32_e32 v1, 31, v0
	v_lshl_add_u64 v[0:1], v[0:1], 1, v[8:9]
	s_waitcnt lgkmcnt(2)
	global_store_dwordx4 v[0:1], v[116:119], off
	v_add_u32_e32 v2, 0x200, v2
	v_and_b32_e32 v1, 0xf8, v3
	v_or_b32_e32 v0, s21, v1
	v_ashrrev_i32_e32 v8, 5, v2
	v_add_u32_e32 v8, s22, v8
	v_ashrrev_i32_e32 v9, 31, v8
	v_lshlrev_b64 v[8:9], 11, v[8:9]
	v_lshl_add_u64 v[8:9], s[8:9], 0, v[8:9]
	v_ashrrev_i32_e32 v1, 31, v0
	v_lshl_add_u64 v[0:1], v[0:1], 1, v[8:9]
	s_waitcnt lgkmcnt(1)
	global_store_dwordx4 v[0:1], v[120:123], off
	v_add_u32_e32 v2, 0x200, v2
	v_and_b32_e32 v1, 0xf8, v3
	v_or_b32_e32 v0, s21, v1
	v_ashrrev_i32_e32 v8, 5, v2
	v_add_u32_e32 v8, s22, v8
	v_ashrrev_i32_e32 v9, 31, v8
	v_lshlrev_b64 v[8:9], 11, v[8:9]
	v_lshl_add_u64 v[8:9], s[8:9], 0, v[8:9]
	v_ashrrev_i32_e32 v1, 31, v0
	v_lshl_add_u64 v[0:1], v[0:1], 1, v[8:9]
	s_waitcnt lgkmcnt(0)
	global_store_dwordx4 v[0:1], v[124:127], off

; DI int tid512() { int t = threadIdx_x_raw(); asm volatile("" : "+v"(t)); return t; }
; template <class AL, class BL, class EP>
; DI void gemm_tile256(AL al, BL bl, EP ep, int K, char* smem) {
;   bf16_t* sA = (bf16_t*)smem;
;   bf16_t* sB = sA + 2 * 256 * GLD;
;   const int tid = tid512(), lane = tid & 63, w = tid >> 6, wm = w >> 2, wn = w & 3, r = lane & 31, h = lane >> 5;
;   const int lrow = tid >> 3, lck = tid & 7;
;   f32x16 acc[4][2];
; #pragma unroll
;   for (int i = 0; i < 4; ++i)
; #pragma unroll
;     for (int j = 0; j < 2; ++j)
; #pragma unroll
;       for (int q = 0; q < 16; ++q) acc[i][j][q] = 0.f;
;   u32x4 ra[4], rb[4];
;   const int KT = K >> 6;
; DI void phase_ffn_up256(const Sched& sc, const Params& p, int layer, char* smem) {
;   const bf16_t* H = (const bf16_t*)(p.hbuf);
;   const bf16_t* Wt = (const bf16_t*)(p.ws + (layer ? OFF_WT_GU1 : OFF_WT_GU0));
;   for (int round = 0;; ++round) {
;     int mt = 0, nt = 0;
;     const int st = sched_tile(sc, round, 128, 22, mt, nt);
;     if (st == 2) break;
;     if (st == 1) continue;
;     LoadRows al{H, 1024, mt * 256, T};
;     LoadRows bl{Wt, 1024, nt * 256, 5632};
;     EpFfnUp256 ep{p.ffn_conv + (size_t)layer * 3 * DFF, (bf16_t*)(p.ws + OFF_HID), (bf16_t*)(p.ws + OFF_HG), (bf16_t*)(p.ws + OFF_HU), mt, nt * 128};
;     gemm_tile256(al, bl, ep, 1024, smem);
.LBB0_1143:
	v_cmp_ne_u32_e32 vcc, 1, v0
	s_mov_b64 s[0:1], -1
	s_cbranch_vccz .LBB0_1158
	v_mov_b32_e32 v32, v196
	s_nop 0
	v_ashrrev_i32_e32 v33, 3, v32
	v_lshl_add_u32 v12, v130, 8, v33
	v_lshlrev_b32_e32 v0, 4, v32
	v_add_u32_e32 v10, 0x80, v12
	v_lshl_add_u32 v28, v131, 8, v33
	v_and_b32_e32 v128, 0x70, v0
	v_min_i32_e32 v0, 0x7fff, v12
	v_min_i32_e32 v10, 0x7fff, v10
	v_add_u32_e32 v26, 0x80, v28
	v_ashrrev_i32_e32 v1, 31, v0
	v_ashrrev_i32_e32 v11, 31, v10
	v_min_i32_e32 v16, 0x15ff, v28
	v_min_i32_e32 v26, 0x15ff, v26
	v_lshl_add_u64 v[8:9], s[84:85], 0, v[128:129]
	v_lshlrev_b64 v[0:1], 11, v[0:1]
	v_lshlrev_b64 v[10:11], 11, v[10:11]
	v_ashrrev_i32_e32 v17, 31, v16
	v_ashrrev_i32_e32 v27, 31, v26
	v_lshl_add_u64 v[136:137], v[8:9], 0, v[0:1]
	v_add_u32_e32 v0, 64, v12
	v_lshl_add_u64 v[140:141], v[8:9], 0, v[10:11]
	v_add_u32_e32 v10, 0xc0, v12
	v_lshlrev_b64 v[190:191], 11, v[16:17]
	v_add_u32_e32 v16, 64, v28
	v_lshlrev_b64 v[194:195], 11, v[26:27]
	v_add_u32_e32 v26, 0xc0, v28
	v_min_i32_e32 v0, 0x7fff, v0
	v_min_i32_e32 v10, 0x7fff, v10
	v_min_i32_e32 v16, 0x15ff, v16
	v_min_i32_e32 v26, 0x15ff, v26
	v_ashrrev_i32_e32 v1, 31, v0
	v_ashrrev_i32_e32 v11, 31, v10
	v_lshl_add_u64 v[24:25], s[2:3], 0, v[128:129]
	v_ashrrev_i32_e32 v17, 31, v16
	v_ashrrev_i32_e32 v27, 31, v26
	v_lshlrev_b64 v[0:1], 11, v[0:1]
	v_lshlrev_b64 v[10:11], 11, v[10:11]
	v_lshl_add_u64 v[144:145], v[24:25], 0, v[190:191]
	v_lshlrev_b64 v[192:193], 11, v[16:17]
	v_lshl_add_u64 v[148:149], v[24:25], 0, v[194:195]
	v_lshlrev_b64 v[198:199], 11, v[26:27]
	v_lshl_add_u64 v[138:139], v[8:9], 0, v[0:1]
	v_lshl_add_u64 v[142:143], v[8:9], 0, v[10:11]
	v_lshl_add_u64 v[146:147], v[24:25], 0, v[192:193]
	v_lshl_add_u64 v[150:151], v[24:25], 0, v[198:199]
	v_mad_u64_u32 v[134:135], s[0:1], v33, s23, v[128:129]
	v_add_u32_e32 v157, 0x12000, v134
	v_bfe_u32 v135, v32, 6, 2
	v_add_u32_e32 v156, 0x1b000, v134
	v_and_b32_e32 v1, 31, v32
	v_ashrrev_i32_e32 v0, 1, v32
	v_and_or_b32 v153, v0, s24, v1
	v_lshrrev_b32_e32 v0, 2, v32
	v_and_b32_e32 v154, 8, v0
	v_lshlrev_b32_e32 v0, 1, v154
	v_mad_u64_u32 v[132:133], s[0:1], v153, s23, v[0:1]
	v_lshl_or_b32 v1, v135, 6, v1
	v_mul_u32_u24_e32 v1, 0x48, v1
	v_lshl_add_u32 v0, v1, 1, v0
	v_add_u32_e32 v155, 0x12000, v0
	v_add_u32_e32 v133, 0x1b000, v0
	v_lshl_add_u64 v[198:199], s[2:3], 0, v[198:199]
	v_or_b32_e32 v128, 0x100, v128
	v_lshl_add_u64 v[192:193], s[2:3], 0, v[192:193]
	v_lshl_add_u64 v[190:191], s[2:3], 0, v[190:191]
	v_lshl_add_u64 v[206:207], v[198:199], 0, v[128:129]
	v_lshl_add_u64 v[194:195], s[2:3], 0, v[194:195]
	v_lshl_add_u64 v[198:199], v[192:193], 0, v[128:129]
	v_lshl_add_u64 v[190:191], v[190:191], 0, v[128:129]
	v_lshl_add_u64 v[194:195], v[194:195], 0, v[128:129]
	s_nop 0
	s_nop 0
	s_nop 0
	s_nop 0
	s_nop 0
	s_nop 0
	s_nop 0
	s_nop 0
	s_nop 0
	v_lshrrev_b32_e32 v226, 6, v196
	s_mov_b32 s10, 64
	v_readfirstlane_b32 s32, v226
	s_mov_b32 s11, 0
	s_mov_b32 s18, 0x40000
	s_mov_b32 s19, 0
	v_bfe_u32 v224, v196, 2, 4
	s_lshl_b32 s33, s32, 3
	v_add_u32_e32 v224, s33, v224
	s_mov_b32 s33, 0x800
	v_mul_lo_u32 v224, v224, s33
	v_bfe_u32 v226, v196, 4, 2
	v_and_b32_e32 v225, 3, v196
	v_xor_b32_e32 v226, v225, v226
	v_lshl_add_u32 v224, v226, 4, v224
	v_mov_b32_e32 v225, 0
	v_readlane_b32 s20, v136, 0
	v_readlane_b32 s21, v137, 0
	s_nop 1
	v_lshl_add_u64 v[216:217], s[20:21], 0, v[224:225]
	v_lshl_add_u64 v[218:219], v[216:217], 0, s[18:19]
	v_readlane_b32 s20, v144, 0
	v_readlane_b32 s21, v145, 0
	s_nop 1
	v_lshl_add_u64 v[220:221], s[20:21], 0, v[224:225]
	v_lshl_add_u64 v[222:223], v[220:221], 0, s[18:19]
	v_and_b32_e32 v224, 31, v196
	v_bfe_u32 v226, v196, 2, 2
	v_bfe_u32 v225, v196, 5, 1
	v_xor_b32_e32 v226, v225, v226
	v_lshlrev_b32_e32 v226, 4, v226
	v_lshl_or_b32 v224, v224, 6, v226
	s_lshr_b32 s33, s32, 2
	s_lshl_b32 s33, s33, 13
	v_add_u32_e32 v134, s33, v224
	s_and_b32 s33, s32, 3
	s_lshl_b32 s33, s33, 12
	s_add_u32 s33, s33, 0x4000
	v_add_u32_e32 v198, s33, v224
	v_xor_b32_e32 v155, 0x20, v134
	v_xor_b32_e32 v199, 0x20, v198
	v_add_u32_e32 v208, 0x10000, v134
	v_add_u32_e32 v210, 0x10000, v198
	v_add_u32_e32 v212, 0x20000, v134
	v_add_u32_e32 v214, 0x20000, v198
	v_add_u32_e32 v209, 0x10000, v155
	v_add_u32_e32 v211, 0x10000, v199
	v_add_u32_e32 v213, 0x20000, v155
	v_add_u32_e32 v215, 0x20000, v199
	s_lshl_b32 s32, s32, 10
	s_waitcnt lgkmcnt(0)
	s_barrier
; #define G_LOADA(kt_) { _Pragma("unroll") for (int i = 0; i < 4; ++i) ra[i] = al(lrow + 64 * i, (kt_) * 64 + lck * 8); }
; #define G_LOADB(kt_) { _Pragma("unroll") for (int i = 0; i < 4; ++i) rb[i] = bl(lrow + 64 * i, (kt_) * 64 + lck * 8); }
; #define G_STOREA(buf_) { bf16_t* nA = sA + (buf_) * 256 * GLD; _Pragma("unroll") for (int i = 0; i < 4; ++i) *(u32x4*)(nA + (lrow + 64 * i) * GLD + lck * 8) = ra[i]; }
; #define G_STOREB(buf_) { bf16_t* nB = sB + (buf_) * 256 * GLD; _Pragma("unroll") for (int i = 0; i < 4; ++i) *(u32x4*)(nB + (lrow + 64 * i) * GLD + lck * 8) = rb[i]; }
; template <class AL, class BL, class EP>
; DI void gemm_tile256(AL al, BL bl, EP ep, int K, char* smem) {
;     ...
; #pragma unroll
;   for (int i = 0; i < 4; ++i)
; #pragma unroll
;     for (int j = 0; j < 2; ++j)
; #pragma unroll
;       for (int q = 0; q < 16; ++q) acc[i][j][q] = 0.f;
;     ...
;   G_LOADA(0); G_LOADB(0);
;   __syncthreads();
;   G_STOREA(0); G_STOREB(0);
;   if (KT > 1) G_LOADB(1);
;   __syncthreads();
	s_add_u32 m0, s32, 0x0
	s_nop 0
	global_load_lds_dwordx4 v[216:217], off
	v_lshl_add_u64 v[216:217], v[216:217], 0, s[10:11]
	s_add_u32 m0, s32, 0x4000
	s_nop 0
	global_load_lds_dwordx4 v[220:221], off
	v_lshl_add_u64 v[220:221], v[220:221], 0, s[10:11]
	s_add_u32 m0, s32, 0x2000
	s_nop 0
	global_load_lds_dwordx4 v[218:219], off
	v_lshl_add_u64 v[218:219], v[218:219], 0, s[10:11]
	s_add_u32 m0, s32, 0x6000
	s_nop 0
	global_load_lds_dwordx4 v[222:223], off
	v_lshl_add_u64 v[222:223], v[222:223], 0, s[10:11]
	s_add_u32 m0, s32, 0x8000
	s_nop 0
	global_load_lds_dwordx4 v[216:217], off
	v_lshl_add_u64 v[216:217], v[216:217], 0, s[10:11]
	s_add_u32 m0, s32, 0xc000
	s_nop 0
	global_load_lds_dwordx4 v[220:221], off
	v_lshl_add_u64 v[220:221], v[220:221], 0, s[10:11]
	s_add_u32 m0, s32, 0xa000
	s_nop 0
	global_load_lds_dwordx4 v[218:219], off
	v_lshl_add_u64 v[218:219], v[218:219], 0, s[10:11]
	s_add_u32 m0, s32, 0xe000
	s_nop 0
	global_load_lds_dwordx4 v[222:223], off
	v_lshl_add_u64 v[222:223], v[222:223], 0, s[10:11]
	s_add_u32 m0, s32, 0x10000
	s_nop 0
	global_load_lds_dwordx4 v[216:217], off
	v_lshl_add_u64 v[216:217], v[216:217], 0, s[10:11]
	s_add_u32 m0, s32, 0x14000
	s_nop 0
	global_load_lds_dwordx4 v[220:221], off
	v_lshl_add_u64 v[220:221], v[220:221], 0, s[10:11]
	s_add_u32 m0, s32, 0x12000
	s_nop 0
	global_load_lds_dwordx4 v[218:219], off
	v_lshl_add_u64 v[218:219], v[218:219], 0, s[10:11]
	s_add_u32 m0, s32, 0x16000
	s_nop 0
	global_load_lds_dwordx4 v[222:223], off
	v_lshl_add_u64 v[222:223], v[222:223], 0, s[10:11]
	s_add_u32 m0, s32, 0x18000
	s_nop 0
	global_load_lds_dwordx4 v[216:217], off
	v_lshl_add_u64 v[216:217], v[216:217], 0, s[10:11]
	s_add_u32 m0, s32, 0x1c000
	s_nop 0
	global_load_lds_dwordx4 v[220:221], off
	v_lshl_add_u64 v[220:221], v[220:221], 0, s[10:11]
	s_add_u32 m0, s32, 0x1a000
	s_nop 0
	global_load_lds_dwordx4 v[218:219], off
	v_lshl_add_u64 v[218:219], v[218:219], 0, s[10:11]
	s_add_u32 m0, s32, 0x1e000
	s_nop 0
	global_load_lds_dwordx4 v[222:223], off
	v_lshl_add_u64 v[222:223], v[222:223], 0, s[10:11]
	s_add_u32 m0, s32, 0x20000
	s_nop 0
	global_load_lds_dwordx4 v[216:217], off
	v_lshl_add_u64 v[216:217], v[216:217], 0, s[10:11]
	s_add_u32 m0, s32, 0x24000
	s_nop 0
	global_load_lds_dwordx4 v[220:221], off
	v_lshl_add_u64 v[220:221], v[220:221], 0, s[10:11]
	v_mov_b64_e32 v[112:113], 0
	v_mov_b64_e32 v[114:115], 0
	v_mov_b64_e32 v[116:117], 0
	v_mov_b64_e32 v[118:119], 0
	v_mov_b64_e32 v[120:121], 0
	v_mov_b64_e32 v[122:123], 0
	v_mov_b64_e32 v[124:125], 0
	v_mov_b64_e32 v[126:127], 0
	v_mov_b64_e32 v[96:97], 0
	v_mov_b64_e32 v[98:99], 0
	v_mov_b64_e32 v[100:101], 0
	v_mov_b64_e32 v[102:103], 0
	v_mov_b64_e32 v[104:105], 0
	v_mov_b64_e32 v[106:107], 0
	v_mov_b64_e32 v[108:109], 0
	v_mov_b64_e32 v[110:111], 0
	v_mov_b64_e32 v[80:81], 0
	v_mov_b64_e32 v[82:83], 0
	v_mov_b64_e32 v[84:85], 0
	v_mov_b64_e32 v[86:87], 0
	v_mov_b64_e32 v[88:89], 0
	v_mov_b64_e32 v[90:91], 0
	v_mov_b64_e32 v[92:93], 0
	v_mov_b64_e32 v[94:95], 0
	v_mov_b64_e32 v[64:65], 0
	v_mov_b64_e32 v[66:67], 0
	v_mov_b64_e32 v[68:69], 0
	v_mov_b64_e32 v[70:71], 0
	v_mov_b64_e32 v[72:73], 0
	v_mov_b64_e32 v[74:75], 0
	v_mov_b64_e32 v[76:77], 0
	v_mov_b64_e32 v[78:79], 0
	v_mov_b64_e32 v[48:49], 0
	v_mov_b64_e32 v[50:51], 0
	v_mov_b64_e32 v[52:53], 0
	v_mov_b64_e32 v[54:55], 0
	v_mov_b64_e32 v[56:57], 0
	v_mov_b64_e32 v[58:59], 0
	v_mov_b64_e32 v[60:61], 0
	v_mov_b64_e32 v[62:63], 0
	v_mov_b64_e32 v[32:33], 0
	v_mov_b64_e32 v[34:35], 0
	v_mov_b64_e32 v[36:37], 0
	v_mov_b64_e32 v[38:39], 0
	v_mov_b64_e32 v[40:41], 0
	v_mov_b64_e32 v[42:43], 0
	v_mov_b64_e32 v[44:45], 0
	v_mov_b64_e32 v[46:47], 0
	v_mov_b64_e32 v[16:17], 0
	v_mov_b64_e32 v[18:19], 0
	v_mov_b64_e32 v[20:21], 0
	v_mov_b64_e32 v[22:23], 0
	v_mov_b64_e32 v[24:25], 0
	v_mov_b64_e32 v[26:27], 0
	v_mov_b64_e32 v[28:29], 0
	v_mov_b64_e32 v[30:31], 0
	v_mov_b64_e32 v[0:1], 0
	v_mov_b64_e32 v[2:3], 0
	v_mov_b64_e32 v[4:5], 0
	v_mov_b64_e32 v[6:7], 0
	v_mov_b64_e32 v[8:9], 0
	v_mov_b64_e32 v[10:11], 0
	v_mov_b64_e32 v[12:13], 0
	v_mov_b64_e32 v[14:15], 0
	s_lshr_b32 s33, s32, 2
	s_xor_b32 s33, s33, s32
	s_bitcmp1_b32 s33, 10
	s_cbranch_scc0 .Lgk_ph15_np
	s_setprio 1
.Lgk_ph15_np:
	s_mov_b32 s33, 5
	s_waitcnt vmcnt(14)
	s_barrier
	ds_read_b128 v[188:191], v198
	ds_read_b128 v[156:159], v134
	ds_read_b128 v[192:195], v198 offset:2048
	ds_read_b128 v[160:163], v134 offset:2048
	ds_read_b128 v[164:167], v134 offset:4096
	ds_read_b128 v[168:171], v134 offset:6144
; #define G_LOADA(kt_) { _Pragma("unroll") for (int i = 0; i < 4; ++i) ra[i] = al(lrow + 64 * i, (kt_) * 64 + lck * 8); }
; #define G_LOADB(kt_) { _Pragma("unroll") for (int i = 0; i < 4; ++i) rb[i] = bl(lrow + 64 * i, (kt_) * 64 + lck * 8); }
; #define G_STOREA(buf_) { bf16_t* nA = sA + (buf_) * 256 * GLD; _Pragma("unroll") for (int i = 0; i < 4; ++i) *(u32x4*)(nA + (lrow + 64 * i) * GLD + lck * 8) = ra[i]; }
; #define G_STOREB(buf_) { bf16_t* nB = sB + (buf_) * 256 * GLD; _Pragma("unroll") for (int i = 0; i < 4; ++i) *(u32x4*)(nB + (lrow + 64 * i) * GLD + lck * 8) = rb[i]; }
; template <class AL, class BL, class EP>
; DI void gemm_tile256(AL al, BL bl, EP ep, int K, char* smem) {
;     ...
;   G_LOADA(0); G_LOADB(0);
;   __syncthreads();
;   G_STOREA(0); G_STOREB(0);
;   if (KT > 1) G_LOADB(1);
;   __syncthreads();
;   for (int kt = 0; kt < KT; kt += 2) {
;     G_STEP(0, kt);
;     if (kt + 1 >= KT) break;
;     G_STEP(1, kt + 1);
;   }
.Lgk_ph15_loop:
	s_waitcnt lgkmcnt(0)
	v_mfma_f32_32x32x16_bf16 v[112:127], v[188:191], v[156:159], v[112:127]
	ds_read_b128 v[200:203], v199
	ds_read_b128 v[172:175], v155
	v_mfma_f32_32x32x16_bf16 v[96:111], v[192:195], v[156:159], v[96:111]
	ds_read_b128 v[204:207], v199 offset:2048
	ds_read_b128 v[176:179], v155 offset:2048
	v_mfma_f32_32x32x16_bf16 v[80:95], v[188:191], v[160:163], v[80:95]
	ds_read_b128 v[180:183], v155 offset:4096
	ds_read_b128 v[184:187], v155 offset:6144
	v_mfma_f32_32x32x16_bf16 v[64:79], v[192:195], v[160:163], v[64:79]
	s_add_u32 m0, s32, 0x22000
	s_nop 0
	global_load_lds_dwordx4 v[218:219], off
	v_lshl_add_u64 v[218:219], v[218:219], 0, s[10:11]
	v_mfma_f32_32x32x16_bf16 v[48:63], v[188:191], v[164:167], v[48:63]
	v_mfma_f32_32x32x16_bf16 v[32:47], v[192:195], v[164:167], v[32:47]
	v_mfma_f32_32x32x16_bf16 v[16:31], v[188:191], v[168:171], v[16:31]
	v_mfma_f32_32x32x16_bf16 v[0:15], v[192:195], v[168:171], v[0:15]
	s_add_u32 m0, s32, 0x26000
	s_nop 0
	global_load_lds_dwordx4 v[222:223], off
	v_lshl_add_u64 v[222:223], v[222:223], 0, s[10:11]
	s_waitcnt lgkmcnt(0)
	s_waitcnt vmcnt(12)
	s_barrier
	s_waitcnt lgkmcnt(0)
	v_mfma_f32_32x32x16_bf16 v[112:127], v[200:203], v[172:175], v[112:127]
	ds_read_b128 v[188:191], v198 offset:32768
	ds_read_b128 v[156:159], v134 offset:32768
	v_mfma_f32_32x32x16_bf16 v[96:111], v[204:207], v[172:175], v[96:111]
	ds_read_b128 v[192:195], v198 offset:34816
	ds_read_b128 v[160:163], v134 offset:34816
	v_mfma_f32_32x32x16_bf16 v[80:95], v[200:203], v[176:179], v[80:95]
	ds_read_b128 v[164:167], v134 offset:36864
	ds_read_b128 v[168:171], v134 offset:38912
	v_mfma_f32_32x32x16_bf16 v[64:79], v[204:207], v[176:179], v[64:79]
	s_add_u32 m0, s32, 0x0
	s_nop 0
	global_load_lds_dwordx4 v[216:217], off
	v_lshl_add_u64 v[216:217], v[216:217], 0, s[10:11]
	v_mfma_f32_32x32x16_bf16 v[48:63], v[200:203], v[180:183], v[48:63]
	v_mfma_f32_32x32x16_bf16 v[32:47], v[204:207], v[180:183], v[32:47]
	v_mfma_f32_32x32x16_bf16 v[16:31], v[200:203], v[184:187], v[16:31]
	v_mfma_f32_32x32x16_bf16 v[0:15], v[204:207], v[184:187], v[0:15]
	s_add_u32 m0, s32, 0x4000
	s_nop 0
	global_load_lds_dwordx4 v[220:221], off
	v_lshl_add_u64 v[220:221], v[220:221], 0, s[10:11]
	s_waitcnt lgkmcnt(0)
	v_mfma_f32_32x32x16_bf16 v[112:127], v[188:191], v[156:159], v[112:127]
	ds_read_b128 v[200:203], v199 offset:32768
	ds_read_b128 v[172:175], v155 offset:32768
	v_mfma_f32_32x32x16_bf16 v[96:111], v[192:195], v[156:159], v[96:111]
	ds_read_b128 v[204:207], v199 offset:34816
	ds_read_b128 v[176:179], v155 offset:34816
	v_mfma_f32_32x32x16_bf16 v[80:95], v[188:191], v[160:163], v[80:95]
	ds_read_b128 v[180:183], v155 offset:36864
	ds_read_b128 v[184:187], v155 offset:38912
	v_mfma_f32_32x32x16_bf16 v[64:79], v[192:195], v[160:163], v[64:79]
	s_add_u32 m0, s32, 0x2000
	s_nop 0
	global_load_lds_dwordx4 v[218:219], off
	v_lshl_add_u64 v[218:219], v[218:219], 0, s[10:11]
	v_mfma_f32_32x32x16_bf16 v[48:63], v[188:191], v[164:167], v[48:63]
	v_mfma_f32_32x32x16_bf16 v[32:47], v[192:195], v[164:167], v[32:47]
	v_mfma_f32_32x32x16_bf16 v[16:31], v[188:191], v[168:171], v[16:31]
	v_mfma_f32_32x32x16_bf16 v[0:15], v[192:195], v[168:171], v[0:15]
	s_add_u32 m0, s32, 0x6000
	s_nop 0
	global_load_lds_dwordx4 v[222:223], off
	v_lshl_add_u64 v[222:223], v[222:223], 0, s[10:11]
	s_waitcnt lgkmcnt(0)
	s_waitcnt vmcnt(12)
	s_barrier
	s_waitcnt lgkmcnt(0)
	v_mfma_f32_32x32x16_bf16 v[112:127], v[200:203], v[172:175], v[112:127]
	ds_read_b128 v[188:191], v210
	ds_read_b128 v[156:159], v208
	v_mfma_f32_32x32x16_bf16 v[96:111], v[204:207], v[172:175], v[96:111]
	ds_read_b128 v[192:195], v210 offset:2048
	ds_read_b128 v[160:163], v208 offset:2048
	v_mfma_f32_32x32x16_bf16 v[80:95], v[200:203], v[176:179], v[80:95]
	ds_read_b128 v[164:167], v208 offset:4096
	ds_read_b128 v[168:171], v208 offset:6144
	v_mfma_f32_32x32x16_bf16 v[64:79], v[204:207], v[176:179], v[64:79]
	s_add_u32 m0, s32, 0x8000
	s_nop 0
	global_load_lds_dwordx4 v[216:217], off
	v_lshl_add_u64 v[216:217], v[216:217], 0, s[10:11]
	v_mfma_f32_32x32x16_bf16 v[48:63], v[200:203], v[180:183], v[48:63]
	v_mfma_f32_32x32x16_bf16 v[32:47], v[204:207], v[180:183], v[32:47]
	v_mfma_f32_32x32x16_bf16 v[16:31], v[200:203], v[184:187], v[16:31]
	v_mfma_f32_32x32x16_bf16 v[0:15], v[204:207], v[184:187], v[0:15]
	s_add_u32 m0, s32, 0xc000
	s_nop 0
	global_load_lds_dwordx4 v[220:221], off
	v_lshl_add_u64 v[220:221], v[220:221], 0, s[10:11]
	s_waitcnt lgkmcnt(0)
	v_mfma_f32_32x32x16_bf16 v[112:127], v[188:191], v[156:159], v[112:127]
	ds_read_b128 v[200:203], v211
	ds_read_b128 v[172:175], v209
	v_mfma_f32_32x32x16_bf16 v[96:111], v[192:195], v[156:159], v[96:111]
	ds_read_b128 v[204:207], v211 offset:2048
	ds_read_b128 v[176:179], v209 offset:2048
	v_mfma_f32_32x32x16_bf16 v[80:95], v[188:191], v[160:163], v[80:95]
	ds_read_b128 v[180:183], v209 offset:4096
	ds_read_b128 v[184:187], v209 offset:6144
	v_mfma_f32_32x32x16_bf16 v[64:79], v[192:195], v[160:163], v[64:79]
	s_add_u32 m0, s32, 0xa000
	s_nop 0
	global_load_lds_dwordx4 v[218:219], off
	v_lshl_add_u64 v[218:219], v[218:219], 0, s[10:11]
	v_mfma_f32_32x32x16_bf16 v[48:63], v[188:191], v[164:167], v[48:63]
	v_mfma_f32_32x32x16_bf16 v[32:47], v[192:195], v[164:167], v[32:47]
	v_mfma_f32_32x32x16_bf16 v[16:31], v[188:191], v[168:171], v[16:31]
	v_mfma_f32_32x32x16_bf16 v[0:15], v[192:195], v[168:171], v[0:15]
	s_add_u32 m0, s32, 0xe000
	s_nop 0
	global_load_lds_dwordx4 v[222:223], off
	v_lshl_add_u64 v[222:223], v[222:223], 0, s[10:11]
	s_waitcnt lgkmcnt(0)
	s_waitcnt vmcnt(12)
	s_barrier
; #define G_LOADA(kt_) { _Pragma("unroll") for (int i = 0; i < 4; ++i) ra[i] = al(lrow + 64 * i, (kt_) * 64 + lck * 8); }
; #define G_LOADB(kt_) { _Pragma("unroll") for (int i = 0; i < 4; ++i) rb[i] = bl(lrow + 64 * i, (kt_) * 64 + lck * 8); }
; #define G_STOREA(buf_) { bf16_t* nA = sA + (buf_) * 256 * GLD; _Pragma("unroll") for (int i = 0; i < 4; ++i) *(u32x4*)(nA + (lrow + 64 * i) * GLD + lck * 8) = ra[i]; }
; #define G_STOREB(buf_) { bf16_t* nB = sB + (buf_) * 256 * GLD; _Pragma("unroll") for (int i = 0; i < 4; ++i) *(u32x4*)(nB + (lrow + 64 * i) * GLD + lck * 8) = rb[i]; }
; template <class AL, class BL, class EP>
; DI void gemm_tile256(AL al, BL bl, EP ep, int K, char* smem) {
;     ...
;   G_LOADA(0); G_LOADB(0);
;   __syncthreads();
;   G_STOREA(0); G_STOREB(0);
;   if (KT > 1) G_LOADB(1);
;   __syncthreads();
;   for (int kt = 0; kt < KT; kt += 2) {
;     G_STEP(0, kt);
;     if (kt + 1 >= KT) break;
;     G_STEP(1, kt + 1);
;   }
	s_waitcnt lgkmcnt(0)
	v_mfma_f32_32x32x16_bf16 v[112:127], v[200:203], v[172:175], v[112:127]
	ds_read_b128 v[188:191], v210 offset:32768
	ds_read_b128 v[156:159], v208 offset:32768
	v_mfma_f32_32x32x16_bf16 v[96:111], v[204:207], v[172:175], v[96:111]
	ds_read_b128 v[192:195], v210 offset:34816
	ds_read_b128 v[160:163], v208 offset:34816
	v_mfma_f32_32x32x16_bf16 v[80:95], v[200:203], v[176:179], v[80:95]
	ds_read_b128 v[164:167], v208 offset:36864
	ds_read_b128 v[168:171], v208 offset:38912
	v_mfma_f32_32x32x16_bf16 v[64:79], v[204:207], v[176:179], v[64:79]
	s_add_u32 m0, s32, 0x10000
	s_nop 0
	global_load_lds_dwordx4 v[216:217], off
	v_lshl_add_u64 v[216:217], v[216:217], 0, s[10:11]
	v_mfma_f32_32x32x16_bf16 v[48:63], v[200:203], v[180:183], v[48:63]
	v_mfma_f32_32x32x16_bf16 v[32:47], v[204:207], v[180:183], v[32:47]
	v_mfma_f32_32x32x16_bf16 v[16:31], v[200:203], v[184:187], v[16:31]
	v_mfma_f32_32x32x16_bf16 v[0:15], v[204:207], v[184:187], v[0:15]
	s_add_u32 m0, s32, 0x14000
	s_nop 0
	global_load_lds_dwordx4 v[220:221], off
	v_lshl_add_u64 v[220:221], v[220:221], 0, s[10:11]
	s_waitcnt lgkmcnt(0)
	v_mfma_f32_32x32x16_bf16 v[112:127], v[188:191], v[156:159], v[112:127]
	ds_read_b128 v[200:203], v211 offset:32768
	ds_read_b128 v[172:175], v209 offset:32768
	v_mfma_f32_32x32x16_bf16 v[96:111], v[192:195], v[156:159], v[96:111]
	ds_read_b128 v[204:207], v211 offset:34816
	ds_read_b128 v[176:179], v209 offset:34816
	v_mfma_f32_32x32x16_bf16 v[80:95], v[188:191], v[160:163], v[80:95]
	ds_read_b128 v[180:183], v209 offset:36864
	ds_read_b128 v[184:187], v209 offset:38912
	v_mfma_f32_32x32x16_bf16 v[64:79], v[192:195], v[160:163], v[64:79]
	s_add_u32 m0, s32, 0x12000
	s_nop 0
	global_load_lds_dwordx4 v[218:219], off
	v_lshl_add_u64 v[218:219], v[218:219], 0, s[10:11]
	v_mfma_f32_32x32x16_bf16 v[48:63], v[188:191], v[164:167], v[48:63]
	v_mfma_f32_32x32x16_bf16 v[32:47], v[192:195], v[164:167], v[32:47]
	v_mfma_f32_32x32x16_bf16 v[16:31], v[188:191], v[168:171], v[16:31]
	v_mfma_f32_32x32x16_bf16 v[0:15], v[192:195], v[168:171], v[0:15]
	s_add_u32 m0, s32, 0x16000
	s_nop 0
	global_load_lds_dwordx4 v[222:223], off
	v_lshl_add_u64 v[222:223], v[222:223], 0, s[10:11]
	s_waitcnt lgkmcnt(0)
	s_waitcnt vmcnt(12)
	s_barrier
	s_waitcnt lgkmcnt(0)
	v_mfma_f32_32x32x16_bf16 v[112:127], v[200:203], v[172:175], v[112:127]
	ds_read_b128 v[188:191], v214
	ds_read_b128 v[156:159], v212
	v_mfma_f32_32x32x16_bf16 v[96:111], v[204:207], v[172:175], v[96:111]
	ds_read_b128 v[192:195], v214 offset:2048
	ds_read_b128 v[160:163], v212 offset:2048
	v_mfma_f32_32x32x16_bf16 v[80:95], v[200:203], v[176:179], v[80:95]
	ds_read_b128 v[164:167], v212 offset:4096
	ds_read_b128 v[168:171], v212 offset:6144
	v_mfma_f32_32x32x16_bf16 v[64:79], v[204:207], v[176:179], v[64:79]
	s_add_u32 m0, s32, 0x18000
	s_nop 0
	global_load_lds_dwordx4 v[216:217], off
	v_lshl_add_u64 v[216:217], v[216:217], 0, s[10:11]
	v_mfma_f32_32x32x16_bf16 v[48:63], v[200:203], v[180:183], v[48:63]
	v_mfma_f32_32x32x16_bf16 v[32:47], v[204:207], v[180:183], v[32:47]
	v_mfma_f32_32x32x16_bf16 v[16:31], v[200:203], v[184:187], v[16:31]
	v_mfma_f32_32x32x16_bf16 v[0:15], v[204:207], v[184:187], v[0:15]
	s_add_u32 m0, s32, 0x1c000
	s_nop 0
	global_load_lds_dwordx4 v[220:221], off
	v_lshl_add_u64 v[220:221], v[220:221], 0, s[10:11]
	s_waitcnt lgkmcnt(0)
	v_mfma_f32_32x32x16_bf16 v[112:127], v[188:191], v[156:159], v[112:127]
	ds_read_b128 v[200:203], v215
	ds_read_b128 v[172:175], v213
	v_mfma_f32_32x32x16_bf16 v[96:111], v[192:195], v[156:159], v[96:111]
	ds_read_b128 v[204:207], v215 offset:2048
	ds_read_b128 v[176:179], v213 offset:2048
	v_mfma_f32_32x32x16_bf16 v[80:95], v[188:191], v[160:163], v[80:95]
	ds_read_b128 v[180:183], v213 offset:4096
	ds_read_b128 v[184:187], v213 offset:6144
	v_mfma_f32_32x32x16_bf16 v[64:79], v[192:195], v[160:163], v[64:79]
	s_add_u32 m0, s32, 0x1a000
	s_nop 0
	global_load_lds_dwordx4 v[218:219], off
	v_lshl_add_u64 v[218:219], v[218:219], 0, s[10:11]
	v_mfma_f32_32x32x16_bf16 v[48:63], v[188:191], v[164:167], v[48:63]
	v_mfma_f32_32x32x16_bf16 v[32:47], v[192:195], v[164:167], v[32:47]
	v_mfma_f32_32x32x16_bf16 v[16:31], v[188:191], v[168:171], v[16:31]
	v_mfma_f32_32x32x16_bf16 v[0:15], v[192:195], v[168:171], v[0:15]
	s_add_u32 m0, s32, 0x1e000
	s_nop 0
	global_load_lds_dwordx4 v[222:223], off
	v_lshl_add_u64 v[222:223], v[222:223], 0, s[10:11]
	s_waitcnt lgkmcnt(0)
	s_waitcnt vmcnt(12)
	s_barrier
	s_waitcnt lgkmcnt(0)
	v_mfma_f32_32x32x16_bf16 v[112:127], v[200:203], v[172:175], v[112:127]
	ds_read_b128 v[188:191], v198
	ds_read_b128 v[156:159], v134
	v_mfma_f32_32x32x16_bf16 v[96:111], v[204:207], v[172:175], v[96:111]
	ds_read_b128 v[192:195], v198 offset:2048
	ds_read_b128 v[160:163], v134 offset:2048
	v_mfma_f32_32x32x16_bf16 v[80:95], v[200:203], v[176:179], v[80:95]
	ds_read_b128 v[164:167], v134 offset:4096
	ds_read_b128 v[168:171], v134 offset:6144
	v_mfma_f32_32x32x16_bf16 v[64:79], v[204:207], v[176:179], v[64:79]
	s_add_u32 m0, s32, 0x20000
	s_nop 0
	global_load_lds_dwordx4 v[216:217], off
	v_lshl_add_u64 v[216:217], v[216:217], 0, s[10:11]
	v_mfma_f32_32x32x16_bf16 v[48:63], v[200:203], v[180:183], v[48:63]
	v_mfma_f32_32x32x16_bf16 v[32:47], v[204:207], v[180:183], v[32:47]
	v_mfma_f32_32x32x16_bf16 v[16:31], v[200:203], v[184:187], v[16:31]
	v_mfma_f32_32x32x16_bf16 v[0:15], v[204:207], v[184:187], v[0:15]
	s_add_u32 m0, s32, 0x24000
	s_nop 0
	global_load_lds_dwordx4 v[220:221], off
	v_lshl_add_u64 v[220:221], v[220:221], 0, s[10:11]
	s_sub_u32 s33, s33, 1
	s_cmp_lg_u32 s33, 0
	s_cbranch_scc1 .Lgk_ph15_loop
	s_waitcnt lgkmcnt(0)
	v_mfma_f32_32x32x16_bf16 v[112:127], v[188:191], v[156:159], v[112:127]
	ds_read_b128 v[200:203], v199
	ds_read_b128 v[172:175], v155
	v_mfma_f32_32x32x16_bf16 v[96:111], v[192:195], v[156:159], v[96:111]
	ds_read_b128 v[204:207], v199 offset:2048
	ds_read_b128 v[176:179], v155 offset:2048
	v_mfma_f32_32x32x16_bf16 v[80:95], v[188:191], v[160:163], v[80:95]
	ds_read_b128 v[180:183], v155 offset:4096
	ds_read_b128 v[184:187], v155 offset:6144
	v_mfma_f32_32x32x16_bf16 v[64:79], v[192:195], v[160:163], v[64:79]
	s_add_u32 m0, s32, 0x22000
	s_nop 0
	global_load_lds_dwordx4 v[218:219], off
	v_lshl_add_u64 v[218:219], v[218:219], 0, s[10:11]
	v_mfma_f32_32x32x16_bf16 v[48:63], v[188:191], v[164:167], v[48:63]
	v_mfma_f32_32x32x16_bf16 v[32:47], v[192:195], v[164:167], v[32:47]
	v_mfma_f32_32x32x16_bf16 v[16:31], v[188:191], v[168:171], v[16:31]
	v_mfma_f32_32x32x16_bf16 v[0:15], v[192:195], v[168:171], v[0:15]
	s_add_u32 m0, s32, 0x26000
	s_nop 0
	global_load_lds_dwordx4 v[222:223], off
	v_lshl_add_u64 v[222:223], v[222:223], 0, s[10:11]
	s_waitcnt lgkmcnt(0)
	s_waitcnt vmcnt(12)
	s_barrier
	s_waitcnt lgkmcnt(0)
	v_mfma_f32_32x32x16_bf16 v[112:127], v[200:203], v[172:175], v[112:127]
	ds_read_b128 v[188:191], v198 offset:32768
	ds_read_b128 v[156:159], v134 offset:32768
	v_mfma_f32_32x32x16_bf16 v[96:111], v[204:207], v[172:175], v[96:111]
	ds_read_b128 v[192:195], v198 offset:34816
	ds_read_b128 v[160:163], v134 offset:34816
	v_mfma_f32_32x32x16_bf16 v[80:95], v[200:203], v[176:179], v[80:95]
	ds_read_b128 v[164:167], v134 offset:36864
	ds_read_b128 v[168:171], v134 offset:38912
	v_mfma_f32_32x32x16_bf16 v[64:79], v[204:207], v[176:179], v[64:79]
	s_add_u32 m0, s32, 0x0
	s_nop 0
	global_load_lds_dwordx4 v[216:217], off
	v_lshl_add_u64 v[216:217], v[216:217], 0, s[10:11]
	v_mfma_f32_32x32x16_bf16 v[48:63], v[200:203], v[180:183], v[48:63]
	v_mfma_f32_32x32x16_bf16 v[32:47], v[204:207], v[180:183], v[32:47]
	v_mfma_f32_32x32x16_bf16 v[16:31], v[200:203], v[184:187], v[16:31]
	v_mfma_f32_32x32x16_bf16 v[0:15], v[204:207], v[184:187], v[0:15]
	s_add_u32 m0, s32, 0x4000
	s_nop 0
	global_load_lds_dwordx4 v[220:221], off
	v_lshl_add_u64 v[220:221], v[220:221], 0, s[10:11]
	s_waitcnt lgkmcnt(0)
	v_mfma_f32_32x32x16_bf16 v[112:127], v[188:191], v[156:159], v[112:127]
	ds_read_b128 v[200:203], v199 offset:32768
	ds_read_b128 v[172:175], v155 offset:32768
	v_mfma_f32_32x32x16_bf16 v[96:111], v[192:195], v[156:159], v[96:111]
	ds_read_b128 v[204:207], v199 offset:34816
	ds_read_b128 v[176:179], v155 offset:34816
	v_mfma_f32_32x32x16_bf16 v[80:95], v[188:191], v[160:163], v[80:95]
	ds_read_b128 v[180:183], v155 offset:36864
	ds_read_b128 v[184:187], v155 offset:38912
	v_mfma_f32_32x32x16_bf16 v[64:79], v[192:195], v[160:163], v[64:79]
	s_add_u32 m0, s32, 0x2000
	s_nop 0
	global_load_lds_dwordx4 v[218:219], off
	v_lshl_add_u64 v[218:219], v[218:219], 0, s[10:11]
	v_mfma_f32_32x32x16_bf16 v[48:63], v[188:191], v[164:167], v[48:63]
	v_mfma_f32_32x32x16_bf16 v[32:47], v[192:195], v[164:167], v[32:47]
	v_mfma_f32_32x32x16_bf16 v[16:31], v[188:191], v[168:171], v[16:31]
	v_mfma_f32_32x32x16_bf16 v[0:15], v[192:195], v[168:171], v[0:15]
	s_add_u32 m0, s32, 0x6000
	s_nop 0
	global_load_lds_dwordx4 v[222:223], off
	v_lshl_add_u64 v[222:223], v[222:223], 0, s[10:11]
	s_waitcnt lgkmcnt(0)
	s_waitcnt vmcnt(12)
	s_barrier
	s_waitcnt lgkmcnt(0)
	v_mfma_f32_32x32x16_bf16 v[112:127], v[200:203], v[172:175], v[112:127]
	ds_read_b128 v[188:191], v210
	ds_read_b128 v[156:159], v208
	v_mfma_f32_32x32x16_bf16 v[96:111], v[204:207], v[172:175], v[96:111]
	ds_read_b128 v[192:195], v210 offset:2048
	ds_read_b128 v[160:163], v208 offset:2048
	v_mfma_f32_32x32x16_bf16 v[80:95], v[200:203], v[176:179], v[80:95]
	ds_read_b128 v[164:167], v208 offset:4096
	ds_read_b128 v[168:171], v208 offset:6144
	v_mfma_f32_32x32x16_bf16 v[64:79], v[204:207], v[176:179], v[64:79]
	s_add_u32 m0, s32, 0x8000
	s_nop 0
	global_load_lds_dwordx4 v[216:217], off
	v_lshl_add_u64 v[216:217], v[216:217], 0, s[10:11]
	v_mfma_f32_32x32x16_bf16 v[48:63], v[200:203], v[180:183], v[48:63]
	v_mfma_f32_32x32x16_bf16 v[32:47], v[204:207], v[180:183], v[32:47]
	v_mfma_f32_32x32x16_bf16 v[16:31], v[200:203], v[184:187], v[16:31]
	v_mfma_f32_32x32x16_bf16 v[0:15], v[204:207], v[184:187], v[0:15]
	s_add_u32 m0, s32, 0xc000
	s_nop 0
	global_load_lds_dwordx4 v[220:221], off
	v_lshl_add_u64 v[220:221], v[220:221], 0, s[10:11]
	s_waitcnt lgkmcnt(0)
	v_mfma_f32_32x32x16_bf16 v[112:127], v[188:191], v[156:159], v[112:127]
	ds_read_b128 v[200:203], v211
	ds_read_b128 v[172:175], v209
	v_mfma_f32_32x32x16_bf16 v[96:111], v[192:195], v[156:159], v[96:111]
	ds_read_b128 v[204:207], v211 offset:2048
	ds_read_b128 v[176:179], v209 offset:2048
	v_mfma_f32_32x32x16_bf16 v[80:95], v[188:191], v[160:163], v[80:95]
	ds_read_b128 v[180:183], v209 offset:4096
	ds_read_b128 v[184:187], v209 offset:6144
	v_mfma_f32_32x32x16_bf16 v[64:79], v[192:195], v[160:163], v[64:79]
	s_add_u32 m0, s32, 0xa000
	s_nop 0
	global_load_lds_dwordx4 v[218:219], off
	v_lshl_add_u64 v[218:219], v[218:219], 0, s[10:11]
	v_mfma_f32_32x32x16_bf16 v[48:63], v[188:191], v[164:167], v[48:63]
	v_mfma_f32_32x32x16_bf16 v[32:47], v[192:195], v[164:167], v[32:47]
	v_mfma_f32_32x32x16_bf16 v[16:31], v[188:191], v[168:171], v[16:31]
	v_mfma_f32_32x32x16_bf16 v[0:15], v[192:195], v[168:171], v[0:15]
	s_add_u32 m0, s32, 0xe000
	s_nop 0
	global_load_lds_dwordx4 v[222:223], off
	v_lshl_add_u64 v[222:223], v[222:223], 0, s[10:11]
	s_waitcnt lgkmcnt(0)
	s_waitcnt vmcnt(12)
	s_barrier
	s_waitcnt lgkmcnt(0)
	v_mfma_f32_32x32x16_bf16 v[112:127], v[200:203], v[172:175], v[112:127]
	ds_read_b128 v[188:191], v210 offset:32768
	ds_read_b128 v[156:159], v208 offset:32768
	v_mfma_f32_32x32x16_bf16 v[96:111], v[204:207], v[172:175], v[96:111]
	ds_read_b128 v[192:195], v210 offset:34816
	ds_read_b128 v[160:163], v208 offset:34816
	v_mfma_f32_32x32x16_bf16 v[80:95], v[200:203], v[176:179], v[80:95]
	ds_read_b128 v[164:167], v208 offset:36864
	ds_read_b128 v[168:171], v208 offset:38912
	v_mfma_f32_32x32x16_bf16 v[64:79], v[204:207], v[176:179], v[64:79]
	v_mfma_f32_32x32x16_bf16 v[48:63], v[200:203], v[180:183], v[48:63]
	v_mfma_f32_32x32x16_bf16 v[32:47], v[204:207], v[180:183], v[32:47]
	v_mfma_f32_32x32x16_bf16 v[16:31], v[200:203], v[184:187], v[16:31]
	v_mfma_f32_32x32x16_bf16 v[0:15], v[204:207], v[184:187], v[0:15]
	s_waitcnt lgkmcnt(0)
	v_mfma_f32_32x32x16_bf16 v[112:127], v[188:191], v[156:159], v[112:127]
	ds_read_b128 v[200:203], v211 offset:32768
	ds_read_b128 v[172:175], v209 offset:32768
	v_mfma_f32_32x32x16_bf16 v[96:111], v[192:195], v[156:159], v[96:111]
	ds_read_b128 v[204:207], v211 offset:34816
	ds_read_b128 v[176:179], v209 offset:34816
	v_mfma_f32_32x32x16_bf16 v[80:95], v[188:191], v[160:163], v[80:95]
	ds_read_b128 v[180:183], v209 offset:36864
	ds_read_b128 v[184:187], v209 offset:38912
	v_mfma_f32_32x32x16_bf16 v[64:79], v[192:195], v[160:163], v[64:79]
	v_mfma_f32_32x32x16_bf16 v[48:63], v[188:191], v[164:167], v[48:63]
	v_mfma_f32_32x32x16_bf16 v[32:47], v[192:195], v[164:167], v[32:47]
	v_mfma_f32_32x32x16_bf16 v[16:31], v[188:191], v[168:171], v[16:31]
	v_mfma_f32_32x32x16_bf16 v[0:15], v[192:195], v[168:171], v[0:15]
	s_waitcnt lgkmcnt(0)
	s_waitcnt vmcnt(8)
	s_barrier
	s_waitcnt lgkmcnt(0)
	v_mfma_f32_32x32x16_bf16 v[112:127], v[200:203], v[172:175], v[112:127]
	ds_read_b128 v[188:191], v214
	ds_read_b128 v[156:159], v212
	v_mfma_f32_32x32x16_bf16 v[96:111], v[204:207], v[172:175], v[96:111]
	ds_read_b128 v[192:195], v214 offset:2048
	ds_read_b128 v[160:163], v212 offset:2048
	v_mfma_f32_32x32x16_bf16 v[80:95], v[200:203], v[176:179], v[80:95]
	ds_read_b128 v[164:167], v212 offset:4096
	ds_read_b128 v[168:171], v212 offset:6144
	v_mfma_f32_32x32x16_bf16 v[64:79], v[204:207], v[176:179], v[64:79]
	v_mfma_f32_32x32x16_bf16 v[48:63], v[200:203], v[180:183], v[48:63]
	v_mfma_f32_32x32x16_bf16 v[32:47], v[204:207], v[180:183], v[32:47]
	v_mfma_f32_32x32x16_bf16 v[16:31], v[200:203], v[184:187], v[16:31]
	v_mfma_f32_32x32x16_bf16 v[0:15], v[204:207], v[184:187], v[0:15]
	s_waitcnt lgkmcnt(0)
	v_mfma_f32_32x32x16_bf16 v[112:127], v[188:191], v[156:159], v[112:127]
	ds_read_b128 v[200:203], v215
	ds_read_b128 v[172:175], v213
	v_mfma_f32_32x32x16_bf16 v[96:111], v[192:195], v[156:159], v[96:111]
	ds_read_b128 v[204:207], v215 offset:2048
	ds_read_b128 v[176:179], v213 offset:2048
	v_mfma_f32_32x32x16_bf16 v[80:95], v[188:191], v[160:163], v[80:95]
	ds_read_b128 v[180:183], v213 offset:4096
	ds_read_b128 v[184:187], v213 offset:6144
	v_mfma_f32_32x32x16_bf16 v[64:79], v[192:195], v[160:163], v[64:79]
	v_mfma_f32_32x32x16_bf16 v[48:63], v[188:191], v[164:167], v[48:63]
	v_mfma_f32_32x32x16_bf16 v[32:47], v[192:195], v[164:167], v[32:47]
	v_mfma_f32_32x32x16_bf16 v[16:31], v[188:191], v[168:171], v[16:31]
	v_mfma_f32_32x32x16_bf16 v[0:15], v[192:195], v[168:171], v[0:15]
	s_waitcnt lgkmcnt(0)
	s_waitcnt vmcnt(4)
	s_barrier
	s_waitcnt lgkmcnt(0)
	v_mfma_f32_32x32x16_bf16 v[112:127], v[200:203], v[172:175], v[112:127]
	ds_read_b128 v[188:191], v198
	ds_read_b128 v[156:159], v134
	v_mfma_f32_32x32x16_bf16 v[96:111], v[204:207], v[172:175], v[96:111]
	ds_read_b128 v[192:195], v198 offset:2048
	ds_read_b128 v[160:163], v134 offset:2048
	v_mfma_f32_32x32x16_bf16 v[80:95], v[200:203], v[176:179], v[80:95]
	ds_read_b128 v[164:167], v134 offset:4096
	ds_read_b128 v[168:171], v134 offset:6144
	v_mfma_f32_32x32x16_bf16 v[64:79], v[204:207], v[176:179], v[64:79]
	v_mfma_f32_32x32x16_bf16 v[48:63], v[200:203], v[180:183], v[48:63]
	v_mfma_f32_32x32x16_bf16 v[32:47], v[204:207], v[180:183], v[32:47]
	v_mfma_f32_32x32x16_bf16 v[16:31], v[200:203], v[184:187], v[16:31]
	v_mfma_f32_32x32x16_bf16 v[0:15], v[204:207], v[184:187], v[0:15]
	s_waitcnt lgkmcnt(0)
	v_mfma_f32_32x32x16_bf16 v[112:127], v[188:191], v[156:159], v[112:127]
	ds_read_b128 v[200:203], v199
	ds_read_b128 v[172:175], v155
	v_mfma_f32_32x32x16_bf16 v[96:111], v[192:195], v[156:159], v[96:111]
	ds_read_b128 v[204:207], v199 offset:2048
	ds_read_b128 v[176:179], v155 offset:2048
	v_mfma_f32_32x32x16_bf16 v[80:95], v[188:191], v[160:163], v[80:95]
	ds_read_b128 v[180:183], v155 offset:4096
	ds_read_b128 v[184:187], v155 offset:6144
	v_mfma_f32_32x32x16_bf16 v[64:79], v[192:195], v[160:163], v[64:79]
	v_mfma_f32_32x32x16_bf16 v[48:63], v[188:191], v[164:167], v[48:63]
	v_mfma_f32_32x32x16_bf16 v[32:47], v[192:195], v[164:167], v[32:47]
	v_mfma_f32_32x32x16_bf16 v[16:31], v[188:191], v[168:171], v[16:31]
	v_mfma_f32_32x32x16_bf16 v[0:15], v[192:195], v[168:171], v[0:15]
	s_waitcnt lgkmcnt(0)
	s_waitcnt vmcnt(0)
	s_barrier
; DI unsigned pack2(float a, float b) { f2_t f = {a, b}; bf2_t r = __builtin_convertvector(f, bf2_t); return __builtin_bit_cast(unsigned, r); }
; template <class AL, class BL, class EP>
; DI void gemm_tile256(AL al, BL bl, EP ep, int K, char* smem) {
;     ...
;           u32x2 v = {pack2(acc[i][j][4 * g], acc[i][j][4 * g + 1]), pack2(acc[i][j][4 * g + 2], acc[i][j][4 * g + 3])};
;           *(u32x2*)(sCb + (128 * wm + 32 * i + r) * BLD + 64 * wn + 32 * j + 8 * g + 4 * h) = v;
	s_waitcnt lgkmcnt(0)
	v_mfma_f32_32x32x16_bf16 v[112:127], v[200:203], v[172:175], v[112:127]
	ds_read_b128 v[188:191], v198 offset:32768
	ds_read_b128 v[156:159], v134 offset:32768
	v_mfma_f32_32x32x16_bf16 v[96:111], v[204:207], v[172:175], v[96:111]
	ds_read_b128 v[192:195], v198 offset:34816
	ds_read_b128 v[160:163], v134 offset:34816
	v_mfma_f32_32x32x16_bf16 v[80:95], v[200:203], v[176:179], v[80:95]
	ds_read_b128 v[164:167], v134 offset:36864
	ds_read_b128 v[168:171], v134 offset:38912
	v_mfma_f32_32x32x16_bf16 v[64:79], v[204:207], v[176:179], v[64:79]
	v_mfma_f32_32x32x16_bf16 v[48:63], v[200:203], v[180:183], v[48:63]
	v_mfma_f32_32x32x16_bf16 v[32:47], v[204:207], v[180:183], v[32:47]
	v_mfma_f32_32x32x16_bf16 v[16:31], v[200:203], v[184:187], v[16:31]
	v_mfma_f32_32x32x16_bf16 v[0:15], v[204:207], v[184:187], v[0:15]
	s_waitcnt lgkmcnt(0)
	v_mfma_f32_32x32x16_bf16 v[112:127], v[188:191], v[156:159], v[112:127]
	ds_read_b128 v[200:203], v199 offset:32768
	ds_read_b128 v[172:175], v155 offset:32768
	v_mfma_f32_32x32x16_bf16 v[96:111], v[192:195], v[156:159], v[96:111]
	ds_read_b128 v[204:207], v199 offset:34816
	ds_read_b128 v[176:179], v155 offset:34816
	v_mfma_f32_32x32x16_bf16 v[80:95], v[188:191], v[160:163], v[80:95]
	ds_read_b128 v[180:183], v155 offset:36864
	ds_read_b128 v[184:187], v155 offset:38912
	v_mfma_f32_32x32x16_bf16 v[64:79], v[192:195], v[160:163], v[64:79]
	v_mfma_f32_32x32x16_bf16 v[48:63], v[188:191], v[164:167], v[48:63]
	v_mfma_f32_32x32x16_bf16 v[32:47], v[192:195], v[164:167], v[32:47]
	v_mfma_f32_32x32x16_bf16 v[16:31], v[188:191], v[168:171], v[16:31]
	v_mfma_f32_32x32x16_bf16 v[0:15], v[192:195], v[168:171], v[0:15]
	s_waitcnt lgkmcnt(0)
	s_waitcnt lgkmcnt(0)
	v_mfma_f32_32x32x16_bf16 v[112:127], v[200:203], v[172:175], v[112:127]
	v_mfma_f32_32x32x16_bf16 v[96:111], v[204:207], v[172:175], v[96:111]
	v_mfma_f32_32x32x16_bf16 v[80:95], v[200:203], v[176:179], v[80:95]
	v_mfma_f32_32x32x16_bf16 v[64:79], v[204:207], v[176:179], v[64:79]
	v_mfma_f32_32x32x16_bf16 v[48:63], v[200:203], v[180:183], v[48:63]
	v_mfma_f32_32x32x16_bf16 v[32:47], v[204:207], v[180:183], v[32:47]
	v_mfma_f32_32x32x16_bf16 v[16:31], v[200:203], v[184:187], v[16:31]
	v_mfma_f32_32x32x16_bf16 v[0:15], v[204:207], v[184:187], v[0:15]
	s_nop 15
	s_nop 3
	s_setprio 0
	s_waitcnt lgkmcnt(4)
	v_lshl_or_b32 v128, v135, 7, v154
	v_mad_u64_u32 v[132:133], s[0:1], v153, s25, v[128:129]
	s_waitcnt lgkmcnt(0)
	s_barrier
; DI unsigned pack2(float a, float b) { f2_t f = {a, b}; bf2_t r = __builtin_convertvector(f, bf2_t); return __builtin_bit_cast(unsigned, r); }
; DI int tid512() { int t = threadIdx_x_raw(); asm volatile("" : "+v"(t)); return t; }
; template <class AL, class BL, class EP>
; DI void gemm_tile256(AL al, BL bl, EP ep, int K, char* smem) {
;     ...
;   if constexpr (EP::kBf16) {
;     bf16_t* sCb = (bf16_t*)smem;
; #pragma unroll
;     for (int i = 0; i < 4; ++i)
; #pragma unroll
;       for (int j = 0; j < 2; ++j)
; #pragma unroll
;         for (int g = 0; g < 4; ++g) {
;           u32x2 v = {pack2(acc[i][j][4 * g], acc[i][j][4 * g + 1]), pack2(acc[i][j][4 * g + 2], acc[i][j][4 * g + 3])};
;           *(u32x2*)(sCb + (128 * wm + 32 * i + r) * BLD + 64 * wn + 32 * j + 8 * g + 4 * h) = v;
;         }
;     __syncthreads();
;     ep(sCb);
;   DI void operator()(const bf16_t* sCb) const {
;     const int t = tid512(), hf = (t >> 3) & 1, c8 = (t & 7) * 8;
;     const int cb = c0 + 64 * hf;
;     const bf16_t* base = sCb + 128 * hf;
;     float w0[8], w1[8], w2[8];
;     ld8f(conv + cb + c8, w0); ld8f(conv + DFF + cb + c8, w1); ld8f(conv + 2 * DFF + cb + c8, w2);
;     for (int rr = t >> 4; rr < 254; rr += 32) {
;       const int row = rr + 1;
;       float gm[8], g0[8], gp[8], uu[8], v[8];
;       ld8b(base + (row - 1) * BLD + c8, gm); ld8b(base + row * BLD + c8, g0); ld8b(base + (row + 1) * BLD + c8, gp); ld8b(base + row * BLD + 64 + c8, uu);
; #pragma unroll
;       for (int j = 0; j < 8; ++j) v[j] = gelu_gate(w0[j] * gm[j] + w1[j] * g0[j] + w2[j] * gp[j], uu[j]);
;       store8(hid + ((size_t)mt * 256 + row) * DFF + cb + c8, v);
	v_lshlrev_b32_e32 v131, 7, v131
	v_bfe_u32 v200, v196, 3, 1
	v_lshlrev_b32_e32 v200, 6, v200
	v_or_b32_e32 v200, v200, v131
	v_ashrrev_i32_e32 v201, 31, v200
	v_lshlrev_b64 v[200:201], 2, v[200:201]
	v_lshlrev_b32_e32 v202, 3, v196
	v_and_b32_e32 v202, 56, v202
	v_lshlrev_b32_e32 v202, 2, v202
	v_mov_b32_e32 v203, 0
	v_lshl_add_u64 v[204:205], s[14:15], 0, v[200:201]
	v_lshl_add_u64 v[204:205], v[204:205], 0, v[202:203]
	v_lshl_add_u64 v[206:207], s[6:7], 0, v[200:201]
	v_lshl_add_u64 v[206:207], v[206:207], 0, v[202:203]
	v_lshl_add_u64 v[240:241], s[4:5], 0, v[200:201]
	v_lshl_add_u64 v[240:241], v[240:241], 0, v[202:203]
	global_load_dwordx4 v[208:211], v[204:205], off
	global_load_dwordx4 v[212:215], v[204:205], off offset:16
	global_load_dwordx4 v[216:219], v[206:207], off
	global_load_dwordx4 v[220:223], v[206:207], off offset:16
	global_load_dwordx4 v[224:227], v[240:241], off
	global_load_dwordx4 v[228:231], v[240:241], off offset:16
	s_nop 5
	v_cvt_pk_bf16_f32 v112, v112, v113
	v_cvt_pk_bf16_f32 v113, v114, v115
	v_cvt_pk_bf16_f32 v114, v116, v117
	v_cvt_pk_bf16_f32 v115, v118, v119
	ds_write2_b64 v132, v[112:113], v[114:115] offset1:2
	v_cvt_pk_bf16_f32 v112, v120, v121
	v_cvt_pk_bf16_f32 v113, v122, v123
	v_cvt_pk_bf16_f32 v96, v96, v97
	v_cvt_pk_bf16_f32 v97, v98, v99
	v_cvt_pk_bf16_f32 v98, v100, v101
	v_cvt_pk_bf16_f32 v99, v102, v103
	v_cvt_pk_bf16_f32 v114, v124, v125
	v_cvt_pk_bf16_f32 v115, v126, v127
	ds_write2_b64 v132, v[96:97], v[98:99] offset0:8 offset1:10
	s_nop 3
	v_cvt_pk_bf16_f32 v80, v80, v81
	v_cvt_pk_bf16_f32 v81, v82, v83
	v_cvt_pk_bf16_f32 v82, v84, v85
	v_cvt_pk_bf16_f32 v83, v86, v87
	v_add_u32_e32 v84, 0x4000, v132
	v_cvt_pk_bf16_f32 v96, v104, v105
	v_cvt_pk_bf16_f32 v97, v106, v107
	v_cvt_pk_bf16_f32 v64, v64, v65
	v_cvt_pk_bf16_f32 v65, v66, v67
	v_cvt_pk_bf16_f32 v66, v68, v69
	v_cvt_pk_bf16_f32 v67, v70, v71
	v_cvt_pk_bf16_f32 v98, v108, v109
	v_cvt_pk_bf16_f32 v99, v110, v111
	ds_write2_b64 v84, v[80:81], v[82:83] offset0:64 offset1:66
	s_nop 3
	v_cvt_pk_bf16_f32 v48, v48, v49
	v_cvt_pk_bf16_f32 v49, v50, v51
	v_cvt_pk_bf16_f32 v50, v52, v53
	v_cvt_pk_bf16_f32 v51, v54, v55
	v_add_u32_e32 v52, 0x8000, v132
	v_cvt_pk_bf16_f32 v80, v88, v89
	v_cvt_pk_bf16_f32 v81, v90, v91
	v_cvt_pk_bf16_f32 v32, v32, v33
	v_cvt_pk_bf16_f32 v33, v34, v35
	v_cvt_pk_bf16_f32 v34, v36, v37
	v_cvt_pk_bf16_f32 v35, v38, v39
	v_cvt_pk_bf16_f32 v82, v92, v93
	v_cvt_pk_bf16_f32 v83, v94, v95
	ds_write2_b64 v84, v[64:65], v[66:67] offset0:72 offset1:74
	s_nop 3
	v_cvt_pk_bf16_f32 v16, v16, v17
	v_cvt_pk_bf16_f32 v17, v18, v19
	v_cvt_pk_bf16_f32 v18, v20, v21
	v_cvt_pk_bf16_f32 v19, v22, v23
	v_add_u32_e32 v20, 0xc000, v132
	v_cvt_pk_bf16_f32 v64, v72, v73
	v_cvt_pk_bf16_f32 v65, v74, v75
	s_nop 0
	v_cvt_pk_bf16_f32 v0, v0, v1
	v_cvt_pk_bf16_f32 v1, v2, v3
	v_cvt_pk_bf16_f32 v2, v4, v5
	v_cvt_pk_bf16_f32 v3, v6, v7
	v_cvt_pk_bf16_f32 v66, v76, v77
	v_cvt_pk_bf16_f32 v67, v78, v79
	ds_write2_b64 v52, v[48:49], v[50:51] offset0:128 offset1:130
	v_cvt_pk_bf16_f32 v48, v56, v57
	v_cvt_pk_bf16_f32 v49, v58, v59
	v_cvt_pk_bf16_f32 v50, v60, v61
	v_cvt_pk_bf16_f32 v51, v62, v63
	ds_write2_b64 v52, v[32:33], v[34:35] offset0:136 offset1:138
	v_cvt_pk_bf16_f32 v32, v40, v41
	v_cvt_pk_bf16_f32 v33, v42, v43
	v_cvt_pk_bf16_f32 v34, v44, v45
	v_cvt_pk_bf16_f32 v35, v46, v47
	ds_write2_b64 v20, v[16:17], v[18:19] offset0:192 offset1:194
	v_cvt_pk_bf16_f32 v16, v24, v25
	v_cvt_pk_bf16_f32 v17, v26, v27
	v_cvt_pk_bf16_f32 v18, v28, v29
	v_cvt_pk_bf16_f32 v19, v30, v31
	ds_write2_b64 v20, v[0:1], v[2:3] offset0:200 offset1:202
	v_cvt_pk_bf16_f32 v0, v8, v9
	v_cvt_pk_bf16_f32 v1, v10, v11
	v_cvt_pk_bf16_f32 v2, v12, v13
	v_cvt_pk_bf16_f32 v3, v14, v15
	v_mov_b32_e32 v29, v196
	ds_write2_b64 v132, v[112:113], v[114:115] offset0:4 offset1:6
	ds_write2_b64 v132, v[96:97], v[98:99] offset0:12 offset1:14
	ds_write2_b64 v84, v[80:81], v[82:83] offset0:68 offset1:70
	ds_write2_b64 v84, v[64:65], v[66:67] offset0:76 offset1:78
	ds_write2_b64 v52, v[48:49], v[50:51] offset0:132 offset1:134
	ds_write2_b64 v52, v[32:33], v[34:35] offset0:140 offset1:142
	ds_write2_b64 v20, v[16:17], v[18:19] offset0:196 offset1:198
	ds_write2_b64 v20, v[0:1], v[2:3] offset0:204 offset1:206
	s_waitcnt lgkmcnt(0)
	s_barrier
	s_nop 0
	v_bfe_u32 v0, v29, 3, 1
	v_lshlrev_b32_e32 v30, 6, v0
	v_lshlrev_b32_e32 v1, 3, v29
	v_or_b32_e32 v24, v30, v131
	v_ashrrev_i32_e32 v26, 4, v29
	v_and_b32_e32 v27, 56, v1
	v_lshlrev_b32_e32 v28, 8, v0
	v_ashrrev_i32_e32 v25, 31, v24
	v_cmp_gt_i32_e32 vcc, s26, v26
	s_and_saveexec_b64 s[0:1], vcc
	s_cbranch_execz .LBB0_1147
	v_lshlrev_b64 v[16:17], 2, v[24:25]
	v_lshl_add_u64 v[0:1], s[14:15], 0, v[16:17]
	v_lshlrev_b32_e32 v128, 2, v27
	v_lshl_add_u64 v[8:9], s[6:7], 0, v[16:17]
	v_lshl_add_u64 v[16:17], s[4:5], 0, v[16:17]
	v_lshl_add_u64 v[4:5], v[0:1], 0, v[128:129]
	v_lshl_add_u64 v[12:13], v[8:9], 0, v[128:129]
	v_lshl_add_u64 v[20:21], v[16:17], 0, v[128:129]
	s_waitcnt vmcnt(0)
	v_mov_b32_e32 v0, v208
	v_mov_b32_e32 v1, v209
	v_mov_b32_e32 v2, v210
	v_mov_b32_e32 v3, v211
	v_mov_b32_e32 v4, v212
	v_mov_b32_e32 v5, v213
	v_mov_b32_e32 v6, v214
	v_mov_b32_e32 v7, v215
	v_mov_b32_e32 v8, v216
	v_mov_b32_e32 v9, v217
	v_mov_b32_e32 v10, v218
	v_mov_b32_e32 v11, v219
	v_mov_b32_e32 v12, v220
	v_mov_b32_e32 v13, v221
	v_mov_b32_e32 v14, v222
	v_mov_b32_e32 v15, v223
	v_mov_b32_e32 v16, v224
	v_mov_b32_e32 v17, v225
	v_mov_b32_e32 v18, v226
	v_mov_b32_e32 v19, v227
	v_mov_b32_e32 v20, v228
	v_mov_b32_e32 v21, v229
	v_mov_b32_e32 v22, v230
	v_mov_b32_e32 v23, v231
	v_lshlrev_b32_e32 v33, 4, v29
	v_mad_i64_i32 v[34:35], s[18:19], v26, s27, 0
	v_mul_lo_u32 v31, v26, s25
	v_and_b32_e32 v36, 0x70, v33
	v_mad_i64_i32 v[34:35], s[18:19], v130, s28, v[34:35]
	v_add_u32_e32 v30, v131, v30
	v_add3_u32 v33, v31, v28, v36
	v_or_b32_e32 v34, v34, v36
	v_ashrrev_i32_e32 v31, 31, v30
	v_readlane_b32 s10, v246, 51
	v_lshl_add_u64 v[30:31], v[30:31], 1, v[34:35]
	v_readlane_b32 s11, v246, 52
	v_subrev_u32_e32 v32, 32, v26
	s_mov_b64 s[18:19], 0
	v_lshl_add_u64 v[30:31], s[10:11], 0, v[30:31]
	s_waitcnt vmcnt(0)

;   DI u32x4 operator()(int r, int k) const {
;     int row = row0 + r;
;     row = row < nrows ? row : nrows - 1;
;     return ldg16(base + (size_t)row * ld + k);
;   }
; DI void phase_gemm_plain256(const Sched& sc, const bf16_t* A, int lda, const bf16_t* Wt, int K, int N, bf16_t* C, int ldc, char* smem) {
;   const int NT = (N + 255) >> 8, MT = T / 256;
;   for (int round = 0;; ++round) {
;     int mt = 0, nt = 0;
;     const int st = sched_tile(sc, round, MT, NT, mt, nt);
;     if (st == 2) break;
;     if (st == 1) continue;
;     LoadRows al{A, lda, mt * 256, T};
;     LoadRows bl{Wt, K, nt * 256, N};
;     EpStore256 ep{C, ldc, mt * 256, nt * 256, N};
;     gemm_tile256(al, bl, ep, K, smem);
.LBB0_1255:
	s_cmp_lg_u32 s10, 1
	s_mov_b64 s[0:1], -1
	s_cbranch_scc0 .LBB0_1274
	v_mov_b32_e32 v42, v196
	v_readlane_b32 s40, v246, 17
	v_ashrrev_i32_e32 v43, 3, v42
	v_lshlrev_b32_e32 v0, 4, v42
	v_add_u32_e32 v14, s22, v43
	v_and_b32_e32 v160, 0x70, v0
	v_lshl_add_u64 v[8:9], s[72:73], 0, v[160:161]
	v_min_i32_e32 v44, 0x7fff, v14
	v_add_u32_e32 v0, 64, v14
	v_mad_i64_i32 v[10:11], s[0:1], v44, s13, v[8:9]
	v_min_i32_e32 v45, 0x7fff, v0
	v_mad_i64_i32 v[12:13], s[0:1], v45, s13, v[8:9]
	v_mov_b32_e32 v254, v10
	v_mov_b32_e32 v255, v11
	v_add_u32_e32 v10, 0x80, v14
	v_min_i32_e32 v46, 0x7fff, v10
	v_add_u32_e32 v10, 0xc0, v14
	v_add_u32_e32 v26, s21, v43
	v_mad_i64_i32 v[16:17], s[0:1], v46, s13, v[8:9]
	v_min_i32_e32 v47, 0x7fff, v10
	v_add_u32_e32 v27, 0x80, v26
	v_mad_i64_i32 v[18:19], s[0:1], v47, s13, v[8:9]
	v_lshl_add_u64 v[24:25], s[2:3], 0, v[160:161]
	v_min_i32_e32 v48, 0x3ff, v26
	v_add_u32_e32 v16, 64, v26
	v_min_i32_e32 v50, 0x3ff, v27
	v_add_u32_e32 v26, 0xc0, v26
	v_mad_i64_i32 v[32:33], s[0:1], v48, s13, v[24:25]
	v_min_i32_e32 v49, 0x3ff, v16
	v_mad_i64_i32 v[36:37], s[0:1], v50, s13, v[24:25]
	v_min_i32_e32 v51, 0x3ff, v26
	v_mad_i64_i32 v[34:35], s[0:1], v49, s13, v[24:25]
	v_mov_b32_e32 v252, v32
	v_mov_b32_e32 v253, v33
	v_mad_i64_i32 v[38:39], s[0:1], v51, s13, v[24:25]
	v_bfe_u32 v198, v42, 6, 2
	v_and_b32_e32 v52, 31, v42
	v_ashrrev_i32_e32 v53, 1, v42
	v_lshrrev_b32_e32 v42, 2, v42
	v_mul_lo_u32 v43, v43, s14
	v_and_or_b32 v199, v53, s15, v52
	v_and_b32_e32 v200, 8, v42
	v_lshl_or_b32 v52, v198, 6, v52
	v_readlane_b32 s54, v246, 31
	v_readlane_b32 s55, v246, 32
	v_add_u32_e32 v201, v160, v43
	v_or_b32_e32 v53, 0x12000, v160
	v_lshlrev_b32_e32 v42, 1, v200
	v_mul_u32_u24_e32 v52, 0x48, v52
	v_mov_b64_e32 v[40:41], s[54:55]
	v_or_b32_e32 v54, 0x1b000, v160
	v_add_u32_e32 v202, v53, v43
	v_mad_u64_u32 v[162:163], s[0:1], v199, s14, v[42:43]
	v_lshl_add_u32 v42, v52, 1, v42
	v_mad_i64_i32 v[164:165], s[0:1], v48, s13, v[40:41]
	v_add_u32_e32 v163, 0x12000, v42
	v_add_u32_e32 v203, 0x1b000, v42
	v_mad_i64_i32 v[166:167], s[0:1], v49, s13, v[40:41]
	v_mad_i64_i32 v[168:169], s[0:1], v50, s13, v[40:41]
	v_mad_i64_i32 v[170:171], s[0:1], v51, s13, v[40:41]
	v_mad_i64_i32 v[172:173], s[0:1], v44, s13, v[40:41]
	v_mad_i64_i32 v[174:175], s[0:1], v45, s13, v[40:41]
	v_mad_i64_i32 v[176:177], s[0:1], v46, s13, v[40:41]
	v_mad_i64_i32 v[178:179], s[0:1], v47, s13, v[40:41]
	s_mov_b32 s23, 0
	v_add_u32_e32 v204, v54, v43
	v_readlane_b32 s41, v246, 18
	v_readlane_b32 s42, v246, 19
	v_readlane_b32 s43, v246, 20
	v_readlane_b32 s44, v246, 21
	v_readlane_b32 s45, v246, 22
	v_readlane_b32 s46, v246, 23
	v_readlane_b32 s47, v246, 24
	v_readlane_b32 s48, v246, 25
	v_readlane_b32 s49, v246, 26
	v_readlane_b32 s50, v246, 27
	v_readlane_b32 s51, v246, 28
	v_readlane_b32 s52, v246, 29
	v_readlane_b32 s53, v246, 30
	v_lshrrev_b32_e32 v228, 6, v196
	s_mov_b32 s6, 64
	v_readfirstlane_b32 s26, v228
	s_mov_b32 s7, 0
	s_mov_b32 s10, 0xb0000
	s_mov_b32 s11, 0
	v_bfe_u32 v226, v196, 2, 4
	s_lshl_b32 s27, s26, 3
	v_add_u32_e32 v226, s27, v226
	s_mov_b32 s27, 0x1600
	v_mul_lo_u32 v226, v226, s27
	v_bfe_u32 v228, v196, 4, 2
	v_and_b32_e32 v227, 3, v196
	v_xor_b32_e32 v228, v227, v228
	v_lshl_add_u32 v226, v228, 4, v226
	v_mov_b32_e32 v227, 0
	v_readlane_b32 s24, v254, 0
	v_readlane_b32 s25, v255, 0
	s_nop 1
	v_lshl_add_u64 v[218:219], s[24:25], 0, v[226:227]
	v_lshl_add_u64 v[220:221], v[218:219], 0, s[10:11]
	v_readlane_b32 s24, v252, 0
	v_readlane_b32 s25, v253, 0
	s_nop 1
	v_lshl_add_u64 v[222:223], s[24:25], 0, v[226:227]
	v_lshl_add_u64 v[224:225], v[222:223], 0, s[10:11]
	v_and_b32_e32 v226, 31, v196
	v_bfe_u32 v228, v196, 2, 2
	v_bfe_u32 v227, v196, 5, 1
	v_xor_b32_e32 v228, v227, v228
	v_lshlrev_b32_e32 v228, 4, v228
	v_lshl_or_b32 v226, v226, 6, v228
	s_lshr_b32 s27, s26, 2
	s_lshl_b32 s27, s27, 13
	v_add_u32_e32 v128, s27, v226
	s_and_b32 s27, s26, 3
	s_lshl_b32 s27, s27, 12
	s_add_u32 s27, s27, 0x4000
	v_add_u32_e32 v131, s27, v226
	v_xor_b32_e32 v130, 0x20, v128
	v_xor_b32_e32 v205, 0x20, v131
	v_add_u32_e32 v206, 0x10000, v128
	v_add_u32_e32 v212, 0x10000, v131
	v_add_u32_e32 v214, 0x20000, v128
	v_add_u32_e32 v216, 0x20000, v131
	v_add_u32_e32 v207, 0x10000, v130
	v_add_u32_e32 v213, 0x10000, v205
	v_add_u32_e32 v215, 0x20000, v130
	v_add_u32_e32 v217, 0x20000, v205
	s_lshl_b32 s26, s26, 10
	s_waitcnt lgkmcnt(0)
	s_barrier
; #define G_LOADA(kt_) { _Pragma("unroll") for (int i = 0; i < 4; ++i) ra[i] = al(lrow + 64 * i, (kt_) * 64 + lck * 8); }
; #define G_LOADB(kt_) { _Pragma("unroll") for (int i = 0; i < 4; ++i) rb[i] = bl(lrow + 64 * i, (kt_) * 64 + lck * 8); }
; #define G_STOREA(buf_) { bf16_t* nA = sA + (buf_) * 256 * GLD; _Pragma("unroll") for (int i = 0; i < 4; ++i) *(u32x4*)(nA + (lrow + 64 * i) * GLD + lck * 8) = ra[i]; }
; #define G_STOREB(buf_) { bf16_t* nB = sB + (buf_) * 256 * GLD; _Pragma("unroll") for (int i = 0; i < 4; ++i) *(u32x4*)(nB + (lrow + 64 * i) * GLD + lck * 8) = rb[i]; }
; template <class AL, class BL, class EP>
; DI void gemm_tile256(AL al, BL bl, EP ep, int K, char* smem) {
;     ...
;   f32x16 acc[4][2];
; #pragma unroll
;   for (int i = 0; i < 4; ++i)
; #pragma unroll
;     for (int j = 0; j < 2; ++j)
; #pragma unroll
;       for (int q = 0; q < 16; ++q) acc[i][j][q] = 0.f;
;   u32x4 ra[4], rb[4];
;   const int KT = K >> 6;
;     ...
;   G_LOADA(0); G_LOADB(0);
;   __syncthreads();
;   G_STOREA(0); G_STOREB(0);
;   if (KT > 1) G_LOADB(1);
;   __syncthreads();
	s_add_u32 m0, s26, 0x0
	s_nop 0
	global_load_lds_dwordx4 v[218:219], off
	v_lshl_add_u64 v[218:219], v[218:219], 0, s[6:7]
	s_add_u32 m0, s26, 0x4000
	s_nop 0
	global_load_lds_dwordx4 v[222:223], off
	v_lshl_add_u64 v[222:223], v[222:223], 0, s[6:7]
	s_add_u32 m0, s26, 0x2000
	s_nop 0
	global_load_lds_dwordx4 v[220:221], off
	v_lshl_add_u64 v[220:221], v[220:221], 0, s[6:7]
	s_add_u32 m0, s26, 0x6000
	s_nop 0
	global_load_lds_dwordx4 v[224:225], off
	v_lshl_add_u64 v[224:225], v[224:225], 0, s[6:7]
	s_add_u32 m0, s26, 0x8000
	s_nop 0
	global_load_lds_dwordx4 v[218:219], off
	v_lshl_add_u64 v[218:219], v[218:219], 0, s[6:7]
	s_add_u32 m0, s26, 0xc000
	s_nop 0
	global_load_lds_dwordx4 v[222:223], off
	v_lshl_add_u64 v[222:223], v[222:223], 0, s[6:7]
	s_add_u32 m0, s26, 0xa000
	s_nop 0
	global_load_lds_dwordx4 v[220:221], off
	v_lshl_add_u64 v[220:221], v[220:221], 0, s[6:7]
	s_add_u32 m0, s26, 0xe000
	s_nop 0
	global_load_lds_dwordx4 v[224:225], off
	v_lshl_add_u64 v[224:225], v[224:225], 0, s[6:7]
	s_add_u32 m0, s26, 0x10000
	s_nop 0
	global_load_lds_dwordx4 v[218:219], off
	v_lshl_add_u64 v[218:219], v[218:219], 0, s[6:7]
	s_add_u32 m0, s26, 0x14000
	s_nop 0
	global_load_lds_dwordx4 v[222:223], off
	v_lshl_add_u64 v[222:223], v[222:223], 0, s[6:7]
	s_add_u32 m0, s26, 0x12000
	s_nop 0
	global_load_lds_dwordx4 v[220:221], off
	v_lshl_add_u64 v[220:221], v[220:221], 0, s[6:7]
	s_add_u32 m0, s26, 0x16000
	s_nop 0
	global_load_lds_dwordx4 v[224:225], off
	v_lshl_add_u64 v[224:225], v[224:225], 0, s[6:7]
	s_add_u32 m0, s26, 0x18000
	s_nop 0
	global_load_lds_dwordx4 v[218:219], off
	v_lshl_add_u64 v[218:219], v[218:219], 0, s[6:7]
	s_add_u32 m0, s26, 0x1c000
	s_nop 0
	global_load_lds_dwordx4 v[222:223], off
	v_lshl_add_u64 v[222:223], v[222:223], 0, s[6:7]
	s_add_u32 m0, s26, 0x1a000
	s_nop 0
	global_load_lds_dwordx4 v[220:221], off
	v_lshl_add_u64 v[220:221], v[220:221], 0, s[6:7]
	s_add_u32 m0, s26, 0x1e000
	s_nop 0
	global_load_lds_dwordx4 v[224:225], off
	v_lshl_add_u64 v[224:225], v[224:225], 0, s[6:7]
	s_add_u32 m0, s26, 0x20000
	s_nop 0
	global_load_lds_dwordx4 v[218:219], off
	v_lshl_add_u64 v[218:219], v[218:219], 0, s[6:7]
	s_add_u32 m0, s26, 0x24000
	s_nop 0
	global_load_lds_dwordx4 v[222:223], off
	v_lshl_add_u64 v[222:223], v[222:223], 0, s[6:7]
	v_mov_b64_e32 v[112:113], 0
	v_mov_b64_e32 v[114:115], 0
	v_mov_b64_e32 v[116:117], 0
	v_mov_b64_e32 v[118:119], 0
	v_mov_b64_e32 v[120:121], 0
	v_mov_b64_e32 v[122:123], 0
	v_mov_b64_e32 v[124:125], 0
	v_mov_b64_e32 v[126:127], 0
	v_mov_b64_e32 v[96:97], 0
	v_mov_b64_e32 v[98:99], 0
	v_mov_b64_e32 v[100:101], 0
	v_mov_b64_e32 v[102:103], 0
	v_mov_b64_e32 v[104:105], 0
	v_mov_b64_e32 v[106:107], 0
	v_mov_b64_e32 v[108:109], 0
	v_mov_b64_e32 v[110:111], 0
	v_mov_b64_e32 v[80:81], 0
	v_mov_b64_e32 v[82:83], 0
	v_mov_b64_e32 v[84:85], 0
	v_mov_b64_e32 v[86:87], 0
	v_mov_b64_e32 v[88:89], 0
	v_mov_b64_e32 v[90:91], 0
	v_mov_b64_e32 v[92:93], 0
	v_mov_b64_e32 v[94:95], 0
	v_mov_b64_e32 v[64:65], 0
	v_mov_b64_e32 v[66:67], 0
	v_mov_b64_e32 v[68:69], 0
	v_mov_b64_e32 v[70:71], 0
	v_mov_b64_e32 v[72:73], 0
	v_mov_b64_e32 v[74:75], 0
	v_mov_b64_e32 v[76:77], 0
	v_mov_b64_e32 v[78:79], 0
	v_mov_b64_e32 v[48:49], 0
	v_mov_b64_e32 v[50:51], 0
	v_mov_b64_e32 v[52:53], 0
	v_mov_b64_e32 v[54:55], 0
	v_mov_b64_e32 v[56:57], 0
	v_mov_b64_e32 v[58:59], 0
	v_mov_b64_e32 v[60:61], 0
	v_mov_b64_e32 v[62:63], 0
	v_mov_b64_e32 v[32:33], 0
	v_mov_b64_e32 v[34:35], 0
	v_mov_b64_e32 v[36:37], 0
	v_mov_b64_e32 v[38:39], 0
	v_mov_b64_e32 v[40:41], 0
	v_mov_b64_e32 v[42:43], 0
	v_mov_b64_e32 v[44:45], 0
	v_mov_b64_e32 v[46:47], 0
	v_mov_b64_e32 v[16:17], 0
	v_mov_b64_e32 v[18:19], 0
	v_mov_b64_e32 v[20:21], 0
	v_mov_b64_e32 v[22:23], 0
	v_mov_b64_e32 v[24:25], 0
	v_mov_b64_e32 v[26:27], 0
	v_mov_b64_e32 v[28:29], 0
	v_mov_b64_e32 v[30:31], 0
	v_mov_b64_e32 v[0:1], 0
	v_mov_b64_e32 v[2:3], 0
	v_mov_b64_e32 v[4:5], 0
	v_mov_b64_e32 v[6:7], 0
	v_mov_b64_e32 v[8:9], 0
	v_mov_b64_e32 v[10:11], 0
	v_mov_b64_e32 v[12:13], 0
	v_mov_b64_e32 v[14:15], 0
	s_lshr_b32 s27, s26, 2
	s_xor_b32 s27, s27, s26
	s_bitcmp1_b32 s27, 10
	s_cbranch_scc0 .Lgk_ph16_np
	s_setprio 1
.Lgk_ph16_np:
	s_mov_b32 s27, 16
	s_waitcnt vmcnt(14)
	s_barrier
	ds_read_b128 v[184:187], v131
	ds_read_b128 v[132:135], v128
	ds_read_b128 v[188:191], v131 offset:2048
	ds_read_b128 v[136:139], v128 offset:2048
	ds_read_b128 v[140:143], v128 offset:4096
	ds_read_b128 v[144:147], v128 offset:6144
; #define G_LOADA(kt_) { _Pragma("unroll") for (int i = 0; i < 4; ++i) ra[i] = al(lrow + 64 * i, (kt_) * 64 + lck * 8); }
; #define G_LOADB(kt_) { _Pragma("unroll") for (int i = 0; i < 4; ++i) rb[i] = bl(lrow + 64 * i, (kt_) * 64 + lck * 8); }
; #define G_STOREA(buf_) { bf16_t* nA = sA + (buf_) * 256 * GLD; _Pragma("unroll") for (int i = 0; i < 4; ++i) *(u32x4*)(nA + (lrow + 64 * i) * GLD + lck * 8) = ra[i]; }
; #define G_STOREB(buf_) { bf16_t* nB = sB + (buf_) * 256 * GLD; _Pragma("unroll") for (int i = 0; i < 4; ++i) *(u32x4*)(nB + (lrow + 64 * i) * GLD + lck * 8) = rb[i]; }
; template <class AL, class BL, class EP>
; DI void gemm_tile256(AL al, BL bl, EP ep, int K, char* smem) {
;     ...
;   G_LOADA(0); G_LOADB(0);
;   __syncthreads();
;   G_STOREA(0); G_STOREB(0);
;   if (KT > 1) G_LOADB(1);
;   __syncthreads();
;   for (int kt = 0; kt < KT; kt += 2) {
;     G_STEP(0, kt);
;     if (kt + 1 >= KT) break;
;     G_STEP(1, kt + 1);
;   }
.Lgk_ph16_loop:
	s_waitcnt lgkmcnt(0)
	v_mfma_f32_32x32x16_bf16 v[112:127], v[184:187], v[132:135], v[112:127]
	ds_read_b128 v[192:195], v205
	ds_read_b128 v[148:151], v130
	v_mfma_f32_32x32x16_bf16 v[96:111], v[188:191], v[132:135], v[96:111]
	ds_read_b128 v[208:211], v205 offset:2048
	ds_read_b128 v[152:155], v130 offset:2048
	v_mfma_f32_32x32x16_bf16 v[80:95], v[184:187], v[136:139], v[80:95]
	ds_read_b128 v[156:159], v130 offset:4096
	ds_read_b128 v[180:183], v130 offset:6144
	v_mfma_f32_32x32x16_bf16 v[64:79], v[188:191], v[136:139], v[64:79]
	s_add_u32 m0, s26, 0x22000
	s_nop 0
	global_load_lds_dwordx4 v[220:221], off
	v_lshl_add_u64 v[220:221], v[220:221], 0, s[6:7]
	v_mfma_f32_32x32x16_bf16 v[48:63], v[184:187], v[140:143], v[48:63]
	v_mfma_f32_32x32x16_bf16 v[32:47], v[188:191], v[140:143], v[32:47]
	v_mfma_f32_32x32x16_bf16 v[16:31], v[184:187], v[144:147], v[16:31]
	v_mfma_f32_32x32x16_bf16 v[0:15], v[188:191], v[144:147], v[0:15]
	s_add_u32 m0, s26, 0x26000
	s_nop 0
	global_load_lds_dwordx4 v[224:225], off
	v_lshl_add_u64 v[224:225], v[224:225], 0, s[6:7]
	s_waitcnt lgkmcnt(0)
	s_waitcnt vmcnt(12)
	s_barrier
	s_waitcnt lgkmcnt(0)
	v_mfma_f32_32x32x16_bf16 v[112:127], v[192:195], v[148:151], v[112:127]
	ds_read_b128 v[184:187], v131 offset:32768
	ds_read_b128 v[132:135], v128 offset:32768
	v_mfma_f32_32x32x16_bf16 v[96:111], v[208:211], v[148:151], v[96:111]
	ds_read_b128 v[188:191], v131 offset:34816
	ds_read_b128 v[136:139], v128 offset:34816
	v_mfma_f32_32x32x16_bf16 v[80:95], v[192:195], v[152:155], v[80:95]
	ds_read_b128 v[140:143], v128 offset:36864
	ds_read_b128 v[144:147], v128 offset:38912
	v_mfma_f32_32x32x16_bf16 v[64:79], v[208:211], v[152:155], v[64:79]
	s_add_u32 m0, s26, 0x0
	s_nop 0
	global_load_lds_dwordx4 v[218:219], off
	v_lshl_add_u64 v[218:219], v[218:219], 0, s[6:7]
	v_mfma_f32_32x32x16_bf16 v[48:63], v[192:195], v[156:159], v[48:63]
	v_mfma_f32_32x32x16_bf16 v[32:47], v[208:211], v[156:159], v[32:47]
	v_mfma_f32_32x32x16_bf16 v[16:31], v[192:195], v[180:183], v[16:31]
	v_mfma_f32_32x32x16_bf16 v[0:15], v[208:211], v[180:183], v[0:15]
	s_add_u32 m0, s26, 0x4000
	s_nop 0
	global_load_lds_dwordx4 v[222:223], off
	v_lshl_add_u64 v[222:223], v[222:223], 0, s[6:7]
	s_waitcnt lgkmcnt(0)
	v_mfma_f32_32x32x16_bf16 v[112:127], v[184:187], v[132:135], v[112:127]
	ds_read_b128 v[192:195], v205 offset:32768
	ds_read_b128 v[148:151], v130 offset:32768
	v_mfma_f32_32x32x16_bf16 v[96:111], v[188:191], v[132:135], v[96:111]
	ds_read_b128 v[208:211], v205 offset:34816
	ds_read_b128 v[152:155], v130 offset:34816
	v_mfma_f32_32x32x16_bf16 v[80:95], v[184:187], v[136:139], v[80:95]
	ds_read_b128 v[156:159], v130 offset:36864
	ds_read_b128 v[180:183], v130 offset:38912
	v_mfma_f32_32x32x16_bf16 v[64:79], v[188:191], v[136:139], v[64:79]
	s_add_u32 m0, s26, 0x2000
	s_nop 0
	global_load_lds_dwordx4 v[220:221], off
	v_lshl_add_u64 v[220:221], v[220:221], 0, s[6:7]
	v_mfma_f32_32x32x16_bf16 v[48:63], v[184:187], v[140:143], v[48:63]
	v_mfma_f32_32x32x16_bf16 v[32:47], v[188:191], v[140:143], v[32:47]
	v_mfma_f32_32x32x16_bf16 v[16:31], v[184:187], v[144:147], v[16:31]
	v_mfma_f32_32x32x16_bf16 v[0:15], v[188:191], v[144:147], v[0:15]
	s_add_u32 m0, s26, 0x6000
	s_nop 0
	global_load_lds_dwordx4 v[224:225], off
	v_lshl_add_u64 v[224:225], v[224:225], 0, s[6:7]
	s_waitcnt lgkmcnt(0)
	s_waitcnt vmcnt(12)
	s_barrier
	s_waitcnt lgkmcnt(0)
	v_mfma_f32_32x32x16_bf16 v[112:127], v[192:195], v[148:151], v[112:127]
	ds_read_b128 v[184:187], v212
	ds_read_b128 v[132:135], v206
	v_mfma_f32_32x32x16_bf16 v[96:111], v[208:211], v[148:151], v[96:111]
	ds_read_b128 v[188:191], v212 offset:2048
	ds_read_b128 v[136:139], v206 offset:2048
	v_mfma_f32_32x32x16_bf16 v[80:95], v[192:195], v[152:155], v[80:95]
	ds_read_b128 v[140:143], v206 offset:4096
	ds_read_b128 v[144:147], v206 offset:6144
	v_mfma_f32_32x32x16_bf16 v[64:79], v[208:211], v[152:155], v[64:79]
	s_add_u32 m0, s26, 0x8000
	s_nop 0
	global_load_lds_dwordx4 v[218:219], off
	v_lshl_add_u64 v[218:219], v[218:219], 0, s[6:7]
	v_mfma_f32_32x32x16_bf16 v[48:63], v[192:195], v[156:159], v[48:63]
	v_mfma_f32_32x32x16_bf16 v[32:47], v[208:211], v[156:159], v[32:47]
	v_mfma_f32_32x32x16_bf16 v[16:31], v[192:195], v[180:183], v[16:31]
	v_mfma_f32_32x32x16_bf16 v[0:15], v[208:211], v[180:183], v[0:15]
	s_add_u32 m0, s26, 0xc000
	s_nop 0
	global_load_lds_dwordx4 v[222:223], off
	v_lshl_add_u64 v[222:223], v[222:223], 0, s[6:7]
	s_waitcnt lgkmcnt(0)
	v_mfma_f32_32x32x16_bf16 v[112:127], v[184:187], v[132:135], v[112:127]
	ds_read_b128 v[192:195], v213
	ds_read_b128 v[148:151], v207
	v_mfma_f32_32x32x16_bf16 v[96:111], v[188:191], v[132:135], v[96:111]
	ds_read_b128 v[208:211], v213 offset:2048
	ds_read_b128 v[152:155], v207 offset:2048
	v_mfma_f32_32x32x16_bf16 v[80:95], v[184:187], v[136:139], v[80:95]
	ds_read_b128 v[156:159], v207 offset:4096
	ds_read_b128 v[180:183], v207 offset:6144
	v_mfma_f32_32x32x16_bf16 v[64:79], v[188:191], v[136:139], v[64:79]
	s_add_u32 m0, s26, 0xa000
	s_nop 0
	global_load_lds_dwordx4 v[220:221], off
	v_lshl_add_u64 v[220:221], v[220:221], 0, s[6:7]
	v_mfma_f32_32x32x16_bf16 v[48:63], v[184:187], v[140:143], v[48:63]
	v_mfma_f32_32x32x16_bf16 v[32:47], v[188:191], v[140:143], v[32:47]
	v_mfma_f32_32x32x16_bf16 v[16:31], v[184:187], v[144:147], v[16:31]
	v_mfma_f32_32x32x16_bf16 v[0:15], v[188:191], v[144:147], v[0:15]
	s_add_u32 m0, s26, 0xe000
	s_nop 0
	global_load_lds_dwordx4 v[224:225], off
	v_lshl_add_u64 v[224:225], v[224:225], 0, s[6:7]
	s_waitcnt lgkmcnt(0)
	s_waitcnt vmcnt(12)
	s_barrier
; #define G_LOADA(kt_) { _Pragma("unroll") for (int i = 0; i < 4; ++i) ra[i] = al(lrow + 64 * i, (kt_) * 64 + lck * 8); }
; #define G_LOADB(kt_) { _Pragma("unroll") for (int i = 0; i < 4; ++i) rb[i] = bl(lrow + 64 * i, (kt_) * 64 + lck * 8); }
; #define G_STOREA(buf_) { bf16_t* nA = sA + (buf_) * 256 * GLD; _Pragma("unroll") for (int i = 0; i < 4; ++i) *(u32x4*)(nA + (lrow + 64 * i) * GLD + lck * 8) = ra[i]; }
; #define G_STOREB(buf_) { bf16_t* nB = sB + (buf_) * 256 * GLD; _Pragma("unroll") for (int i = 0; i < 4; ++i) *(u32x4*)(nB + (lrow + 64 * i) * GLD + lck * 8) = rb[i]; }
; template <class AL, class BL, class EP>
; DI void gemm_tile256(AL al, BL bl, EP ep, int K, char* smem) {
;     ...
;   G_LOADA(0); G_LOADB(0);
;   __syncthreads();
;   G_STOREA(0); G_STOREB(0);
;   if (KT > 1) G_LOADB(1);
;   __syncthreads();
;   for (int kt = 0; kt < KT; kt += 2) {
;     G_STEP(0, kt);
;     if (kt + 1 >= KT) break;
;     G_STEP(1, kt + 1);
;   }
	s_waitcnt lgkmcnt(0)
	v_mfma_f32_32x32x16_bf16 v[112:127], v[192:195], v[148:151], v[112:127]
	ds_read_b128 v[184:187], v212 offset:32768
	ds_read_b128 v[132:135], v206 offset:32768
	v_mfma_f32_32x32x16_bf16 v[96:111], v[208:211], v[148:151], v[96:111]
	ds_read_b128 v[188:191], v212 offset:34816
	ds_read_b128 v[136:139], v206 offset:34816
	v_mfma_f32_32x32x16_bf16 v[80:95], v[192:195], v[152:155], v[80:95]
	ds_read_b128 v[140:143], v206 offset:36864
	ds_read_b128 v[144:147], v206 offset:38912
	v_mfma_f32_32x32x16_bf16 v[64:79], v[208:211], v[152:155], v[64:79]
	s_add_u32 m0, s26, 0x10000
	s_nop 0
	global_load_lds_dwordx4 v[218:219], off
	v_lshl_add_u64 v[218:219], v[218:219], 0, s[6:7]
	v_mfma_f32_32x32x16_bf16 v[48:63], v[192:195], v[156:159], v[48:63]
	v_mfma_f32_32x32x16_bf16 v[32:47], v[208:211], v[156:159], v[32:47]
	v_mfma_f32_32x32x16_bf16 v[16:31], v[192:195], v[180:183], v[16:31]
	v_mfma_f32_32x32x16_bf16 v[0:15], v[208:211], v[180:183], v[0:15]
	s_add_u32 m0, s26, 0x14000
	s_nop 0
	global_load_lds_dwordx4 v[222:223], off
	v_lshl_add_u64 v[222:223], v[222:223], 0, s[6:7]
	s_waitcnt lgkmcnt(0)
	v_mfma_f32_32x32x16_bf16 v[112:127], v[184:187], v[132:135], v[112:127]
	ds_read_b128 v[192:195], v213 offset:32768
	ds_read_b128 v[148:151], v207 offset:32768
	v_mfma_f32_32x32x16_bf16 v[96:111], v[188:191], v[132:135], v[96:111]
	ds_read_b128 v[208:211], v213 offset:34816
	ds_read_b128 v[152:155], v207 offset:34816
	v_mfma_f32_32x32x16_bf16 v[80:95], v[184:187], v[136:139], v[80:95]
	ds_read_b128 v[156:159], v207 offset:36864
	ds_read_b128 v[180:183], v207 offset:38912
	v_mfma_f32_32x32x16_bf16 v[64:79], v[188:191], v[136:139], v[64:79]
	s_add_u32 m0, s26, 0x12000
	s_nop 0
	global_load_lds_dwordx4 v[220:221], off
	v_lshl_add_u64 v[220:221], v[220:221], 0, s[6:7]
	v_mfma_f32_32x32x16_bf16 v[48:63], v[184:187], v[140:143], v[48:63]
	v_mfma_f32_32x32x16_bf16 v[32:47], v[188:191], v[140:143], v[32:47]
	v_mfma_f32_32x32x16_bf16 v[16:31], v[184:187], v[144:147], v[16:31]
	v_mfma_f32_32x32x16_bf16 v[0:15], v[188:191], v[144:147], v[0:15]
	s_add_u32 m0, s26, 0x16000
	s_nop 0
	global_load_lds_dwordx4 v[224:225], off
	v_lshl_add_u64 v[224:225], v[224:225], 0, s[6:7]
	s_waitcnt lgkmcnt(0)
	s_waitcnt vmcnt(12)
	s_barrier
	s_waitcnt lgkmcnt(0)
	v_mfma_f32_32x32x16_bf16 v[112:127], v[192:195], v[148:151], v[112:127]
	ds_read_b128 v[184:187], v216
	ds_read_b128 v[132:135], v214
	v_mfma_f32_32x32x16_bf16 v[96:111], v[208:211], v[148:151], v[96:111]
	ds_read_b128 v[188:191], v216 offset:2048
	ds_read_b128 v[136:139], v214 offset:2048
	v_mfma_f32_32x32x16_bf16 v[80:95], v[192:195], v[152:155], v[80:95]
	ds_read_b128 v[140:143], v214 offset:4096
	ds_read_b128 v[144:147], v214 offset:6144
	v_mfma_f32_32x32x16_bf16 v[64:79], v[208:211], v[152:155], v[64:79]
	s_add_u32 m0, s26, 0x18000
	s_nop 0
	global_load_lds_dwordx4 v[218:219], off
	v_lshl_add_u64 v[218:219], v[218:219], 0, s[6:7]
	v_mfma_f32_32x32x16_bf16 v[48:63], v[192:195], v[156:159], v[48:63]
	v_mfma_f32_32x32x16_bf16 v[32:47], v[208:211], v[156:159], v[32:47]
	v_mfma_f32_32x32x16_bf16 v[16:31], v[192:195], v[180:183], v[16:31]
	v_mfma_f32_32x32x16_bf16 v[0:15], v[208:211], v[180:183], v[0:15]
	s_add_u32 m0, s26, 0x1c000
	s_nop 0
	global_load_lds_dwordx4 v[222:223], off
	v_lshl_add_u64 v[222:223], v[222:223], 0, s[6:7]
	s_waitcnt lgkmcnt(0)
	v_mfma_f32_32x32x16_bf16 v[112:127], v[184:187], v[132:135], v[112:127]
	ds_read_b128 v[192:195], v217
	ds_read_b128 v[148:151], v215
	v_mfma_f32_32x32x16_bf16 v[96:111], v[188:191], v[132:135], v[96:111]
	ds_read_b128 v[208:211], v217 offset:2048
	ds_read_b128 v[152:155], v215 offset:2048
	v_mfma_f32_32x32x16_bf16 v[80:95], v[184:187], v[136:139], v[80:95]
	ds_read_b128 v[156:159], v215 offset:4096
	ds_read_b128 v[180:183], v215 offset:6144
	v_mfma_f32_32x32x16_bf16 v[64:79], v[188:191], v[136:139], v[64:79]
	s_add_u32 m0, s26, 0x1a000
	s_nop 0
	global_load_lds_dwordx4 v[220:221], off
	v_lshl_add_u64 v[220:221], v[220:221], 0, s[6:7]
	v_mfma_f32_32x32x16_bf16 v[48:63], v[184:187], v[140:143], v[48:63]
	v_mfma_f32_32x32x16_bf16 v[32:47], v[188:191], v[140:143], v[32:47]
	v_mfma_f32_32x32x16_bf16 v[16:31], v[184:187], v[144:147], v[16:31]
	v_mfma_f32_32x32x16_bf16 v[0:15], v[188:191], v[144:147], v[0:15]
	s_add_u32 m0, s26, 0x1e000
	s_nop 0
	global_load_lds_dwordx4 v[224:225], off
	v_lshl_add_u64 v[224:225], v[224:225], 0, s[6:7]
	s_waitcnt lgkmcnt(0)
	s_waitcnt vmcnt(12)
	s_barrier
	s_waitcnt lgkmcnt(0)
	v_mfma_f32_32x32x16_bf16 v[112:127], v[192:195], v[148:151], v[112:127]
	ds_read_b128 v[184:187], v131
	ds_read_b128 v[132:135], v128
	v_mfma_f32_32x32x16_bf16 v[96:111], v[208:211], v[148:151], v[96:111]
	ds_read_b128 v[188:191], v131 offset:2048
	ds_read_b128 v[136:139], v128 offset:2048
	v_mfma_f32_32x32x16_bf16 v[80:95], v[192:195], v[152:155], v[80:95]
	ds_read_b128 v[140:143], v128 offset:4096
	ds_read_b128 v[144:147], v128 offset:6144
	v_mfma_f32_32x32x16_bf16 v[64:79], v[208:211], v[152:155], v[64:79]
	s_add_u32 m0, s26, 0x20000
	s_nop 0
	global_load_lds_dwordx4 v[218:219], off
	v_lshl_add_u64 v[218:219], v[218:219], 0, s[6:7]
	v_mfma_f32_32x32x16_bf16 v[48:63], v[192:195], v[156:159], v[48:63]
	v_mfma_f32_32x32x16_bf16 v[32:47], v[208:211], v[156:159], v[32:47]
	v_mfma_f32_32x32x16_bf16 v[16:31], v[192:195], v[180:183], v[16:31]
	v_mfma_f32_32x32x16_bf16 v[0:15], v[208:211], v[180:183], v[0:15]
	s_add_u32 m0, s26, 0x24000
	s_nop 0
	global_load_lds_dwordx4 v[222:223], off
	v_lshl_add_u64 v[222:223], v[222:223], 0, s[6:7]
	s_sub_u32 s27, s27, 1
	s_cmp_lg_u32 s27, 0
	s_cbranch_scc1 .Lgk_ph16_loop
; #define G_LOADA(kt_) { _Pragma("unroll") for (int i = 0; i < 4; ++i) ra[i] = al(lrow + 64 * i, (kt_) * 64 + lck * 8); }
; #define G_LOADB(kt_) { _Pragma("unroll") for (int i = 0; i < 4; ++i) rb[i] = bl(lrow + 64 * i, (kt_) * 64 + lck * 8); }
; #define G_STOREA(buf_) { bf16_t* nA = sA + (buf_) * 256 * GLD; _Pragma("unroll") for (int i = 0; i < 4; ++i) *(u32x4*)(nA + (lrow + 64 * i) * GLD + lck * 8) = ra[i]; }
; #define G_STOREB(buf_) { bf16_t* nB = sB + (buf_) * 256 * GLD; _Pragma("unroll") for (int i = 0; i < 4; ++i) *(u32x4*)(nB + (lrow + 64 * i) * GLD + lck * 8) = rb[i]; }
; template <class AL, class BL, class EP>
; DI void gemm_tile256(AL al, BL bl, EP ep, int K, char* smem) {
;     ...
;   G_LOADA(0); G_LOADB(0);
;   __syncthreads();
;   G_STOREA(0); G_STOREB(0);
;   if (KT > 1) G_LOADB(1);
;   __syncthreads();
;   for (int kt = 0; kt < KT; kt += 2) {
;     G_STEP(0, kt);
;     if (kt + 1 >= KT) break;
;     G_STEP(1, kt + 1);
;   }
	s_waitcnt lgkmcnt(0)
	v_mfma_f32_32x32x16_bf16 v[112:127], v[184:187], v[132:135], v[112:127]
	ds_read_b128 v[192:195], v205
	ds_read_b128 v[148:151], v130
	v_mfma_f32_32x32x16_bf16 v[96:111], v[188:191], v[132:135], v[96:111]
	ds_read_b128 v[208:211], v205 offset:2048
	ds_read_b128 v[152:155], v130 offset:2048
	v_mfma_f32_32x32x16_bf16 v[80:95], v[184:187], v[136:139], v[80:95]
	ds_read_b128 v[156:159], v130 offset:4096
	ds_read_b128 v[180:183], v130 offset:6144
	v_mfma_f32_32x32x16_bf16 v[64:79], v[188:191], v[136:139], v[64:79]
	s_add_u32 m0, s26, 0x22000
	s_nop 0
	global_load_lds_dwordx4 v[220:221], off
	v_lshl_add_u64 v[220:221], v[220:221], 0, s[6:7]
	v_mfma_f32_32x32x16_bf16 v[48:63], v[184:187], v[140:143], v[48:63]
	v_mfma_f32_32x32x16_bf16 v[32:47], v[188:191], v[140:143], v[32:47]
	v_mfma_f32_32x32x16_bf16 v[16:31], v[184:187], v[144:147], v[16:31]
	v_mfma_f32_32x32x16_bf16 v[0:15], v[188:191], v[144:147], v[0:15]
	s_add_u32 m0, s26, 0x26000
	s_nop 0
	global_load_lds_dwordx4 v[224:225], off
	v_lshl_add_u64 v[224:225], v[224:225], 0, s[6:7]
	s_waitcnt lgkmcnt(0)
	s_waitcnt vmcnt(12)
	s_barrier
	s_waitcnt lgkmcnt(0)
	v_mfma_f32_32x32x16_bf16 v[112:127], v[192:195], v[148:151], v[112:127]
	ds_read_b128 v[184:187], v131 offset:32768
	ds_read_b128 v[132:135], v128 offset:32768
	v_mfma_f32_32x32x16_bf16 v[96:111], v[208:211], v[148:151], v[96:111]
	ds_read_b128 v[188:191], v131 offset:34816
	ds_read_b128 v[136:139], v128 offset:34816
	v_mfma_f32_32x32x16_bf16 v[80:95], v[192:195], v[152:155], v[80:95]
	ds_read_b128 v[140:143], v128 offset:36864
	ds_read_b128 v[144:147], v128 offset:38912
	v_mfma_f32_32x32x16_bf16 v[64:79], v[208:211], v[152:155], v[64:79]
	s_add_u32 m0, s26, 0x0
	s_nop 0
	global_load_lds_dwordx4 v[218:219], off
	v_lshl_add_u64 v[218:219], v[218:219], 0, s[6:7]
	v_mfma_f32_32x32x16_bf16 v[48:63], v[192:195], v[156:159], v[48:63]
	v_mfma_f32_32x32x16_bf16 v[32:47], v[208:211], v[156:159], v[32:47]
	v_mfma_f32_32x32x16_bf16 v[16:31], v[192:195], v[180:183], v[16:31]
	v_mfma_f32_32x32x16_bf16 v[0:15], v[208:211], v[180:183], v[0:15]
	s_add_u32 m0, s26, 0x4000
	s_nop 0
	global_load_lds_dwordx4 v[222:223], off
	v_lshl_add_u64 v[222:223], v[222:223], 0, s[6:7]
	s_waitcnt lgkmcnt(0)
	v_mfma_f32_32x32x16_bf16 v[112:127], v[184:187], v[132:135], v[112:127]
	ds_read_b128 v[192:195], v205 offset:32768
	ds_read_b128 v[148:151], v130 offset:32768
	v_mfma_f32_32x32x16_bf16 v[96:111], v[188:191], v[132:135], v[96:111]
	ds_read_b128 v[208:211], v205 offset:34816
	ds_read_b128 v[152:155], v130 offset:34816
	v_mfma_f32_32x32x16_bf16 v[80:95], v[184:187], v[136:139], v[80:95]
	ds_read_b128 v[156:159], v130 offset:36864
	ds_read_b128 v[180:183], v130 offset:38912
	v_mfma_f32_32x32x16_bf16 v[64:79], v[188:191], v[136:139], v[64:79]
	s_add_u32 m0, s26, 0x2000
	s_nop 0
	global_load_lds_dwordx4 v[220:221], off
	v_lshl_add_u64 v[220:221], v[220:221], 0, s[6:7]
	v_mfma_f32_32x32x16_bf16 v[48:63], v[184:187], v[140:143], v[48:63]
	v_mfma_f32_32x32x16_bf16 v[32:47], v[188:191], v[140:143], v[32:47]
	v_mfma_f32_32x32x16_bf16 v[16:31], v[184:187], v[144:147], v[16:31]
	v_mfma_f32_32x32x16_bf16 v[0:15], v[188:191], v[144:147], v[0:15]
	s_add_u32 m0, s26, 0x6000
	s_nop 0
	global_load_lds_dwordx4 v[224:225], off
	v_lshl_add_u64 v[224:225], v[224:225], 0, s[6:7]
	s_waitcnt lgkmcnt(0)
	s_waitcnt vmcnt(12)
	s_barrier
	s_waitcnt lgkmcnt(0)
	v_mfma_f32_32x32x16_bf16 v[112:127], v[192:195], v[148:151], v[112:127]
	ds_read_b128 v[184:187], v212
	ds_read_b128 v[132:135], v206
	v_mfma_f32_32x32x16_bf16 v[96:111], v[208:211], v[148:151], v[96:111]
	ds_read_b128 v[188:191], v212 offset:2048
	ds_read_b128 v[136:139], v206 offset:2048
	v_mfma_f32_32x32x16_bf16 v[80:95], v[192:195], v[152:155], v[80:95]
	ds_read_b128 v[140:143], v206 offset:4096
	ds_read_b128 v[144:147], v206 offset:6144
	v_mfma_f32_32x32x16_bf16 v[64:79], v[208:211], v[152:155], v[64:79]
	s_add_u32 m0, s26, 0x8000
	s_nop 0
	global_load_lds_dwordx4 v[218:219], off
	v_lshl_add_u64 v[218:219], v[218:219], 0, s[6:7]
	v_mfma_f32_32x32x16_bf16 v[48:63], v[192:195], v[156:159], v[48:63]
	v_mfma_f32_32x32x16_bf16 v[32:47], v[208:211], v[156:159], v[32:47]
	v_mfma_f32_32x32x16_bf16 v[16:31], v[192:195], v[180:183], v[16:31]
	v_mfma_f32_32x32x16_bf16 v[0:15], v[208:211], v[180:183], v[0:15]
	s_add_u32 m0, s26, 0xc000
	s_nop 0
	global_load_lds_dwordx4 v[222:223], off
	v_lshl_add_u64 v[222:223], v[222:223], 0, s[6:7]
	s_waitcnt lgkmcnt(0)
	v_mfma_f32_32x32x16_bf16 v[112:127], v[184:187], v[132:135], v[112:127]
	ds_read_b128 v[192:195], v213
	ds_read_b128 v[148:151], v207
	v_mfma_f32_32x32x16_bf16 v[96:111], v[188:191], v[132:135], v[96:111]
	ds_read_b128 v[208:211], v213 offset:2048
	ds_read_b128 v[152:155], v207 offset:2048
	v_mfma_f32_32x32x16_bf16 v[80:95], v[184:187], v[136:139], v[80:95]
	ds_read_b128 v[156:159], v207 offset:4096
	ds_read_b128 v[180:183], v207 offset:6144
	v_mfma_f32_32x32x16_bf16 v[64:79], v[188:191], v[136:139], v[64:79]
	s_add_u32 m0, s26, 0xa000
	s_nop 0
	global_load_lds_dwordx4 v[220:221], off
	v_lshl_add_u64 v[220:221], v[220:221], 0, s[6:7]
	v_mfma_f32_32x32x16_bf16 v[48:63], v[184:187], v[140:143], v[48:63]
	v_mfma_f32_32x32x16_bf16 v[32:47], v[188:191], v[140:143], v[32:47]
	v_mfma_f32_32x32x16_bf16 v[16:31], v[184:187], v[144:147], v[16:31]
	v_mfma_f32_32x32x16_bf16 v[0:15], v[188:191], v[144:147], v[0:15]
	s_add_u32 m0, s26, 0xe000
	s_nop 0
	global_load_lds_dwordx4 v[224:225], off
	v_lshl_add_u64 v[224:225], v[224:225], 0, s[6:7]
	s_waitcnt lgkmcnt(0)
	s_waitcnt vmcnt(12)
	s_barrier
; #define G_LOADA(kt_) { _Pragma("unroll") for (int i = 0; i < 4; ++i) ra[i] = al(lrow + 64 * i, (kt_) * 64 + lck * 8); }
; #define G_LOADB(kt_) { _Pragma("unroll") for (int i = 0; i < 4; ++i) rb[i] = bl(lrow + 64 * i, (kt_) * 64 + lck * 8); }
; #define G_STOREA(buf_) { bf16_t* nA = sA + (buf_) * 256 * GLD; _Pragma("unroll") for (int i = 0; i < 4; ++i) *(u32x4*)(nA + (lrow + 64 * i) * GLD + lck * 8) = ra[i]; }
; #define G_STOREB(buf_) { bf16_t* nB = sB + (buf_) * 256 * GLD; _Pragma("unroll") for (int i = 0; i < 4; ++i) *(u32x4*)(nB + (lrow + 64 * i) * GLD + lck * 8) = rb[i]; }
; template <class AL, class BL, class EP>
; DI void gemm_tile256(AL al, BL bl, EP ep, int K, char* smem) {
;     ...
;   G_LOADA(0); G_LOADB(0);
;   __syncthreads();
;   G_STOREA(0); G_STOREB(0);
;   if (KT > 1) G_LOADB(1);
;   __syncthreads();
;   for (int kt = 0; kt < KT; kt += 2) {
;     G_STEP(0, kt);
;     if (kt + 1 >= KT) break;
;     G_STEP(1, kt + 1);
;   }
	s_waitcnt lgkmcnt(0)
	v_mfma_f32_32x32x16_bf16 v[112:127], v[192:195], v[148:151], v[112:127]
	ds_read_b128 v[184:187], v212 offset:32768
	ds_read_b128 v[132:135], v206 offset:32768
	v_mfma_f32_32x32x16_bf16 v[96:111], v[208:211], v[148:151], v[96:111]
	ds_read_b128 v[188:191], v212 offset:34816
	ds_read_b128 v[136:139], v206 offset:34816
	v_mfma_f32_32x32x16_bf16 v[80:95], v[192:195], v[152:155], v[80:95]
	ds_read_b128 v[140:143], v206 offset:36864
	ds_read_b128 v[144:147], v206 offset:38912
	v_mfma_f32_32x32x16_bf16 v[64:79], v[208:211], v[152:155], v[64:79]
	s_add_u32 m0, s26, 0x10000
	s_nop 0
	global_load_lds_dwordx4 v[218:219], off
	v_lshl_add_u64 v[218:219], v[218:219], 0, s[6:7]
	v_mfma_f32_32x32x16_bf16 v[48:63], v[192:195], v[156:159], v[48:63]
	v_mfma_f32_32x32x16_bf16 v[32:47], v[208:211], v[156:159], v[32:47]
	v_mfma_f32_32x32x16_bf16 v[16:31], v[192:195], v[180:183], v[16:31]
	v_mfma_f32_32x32x16_bf16 v[0:15], v[208:211], v[180:183], v[0:15]
	s_add_u32 m0, s26, 0x14000
	s_nop 0
	global_load_lds_dwordx4 v[222:223], off
	v_lshl_add_u64 v[222:223], v[222:223], 0, s[6:7]
	s_waitcnt lgkmcnt(0)
	v_mfma_f32_32x32x16_bf16 v[112:127], v[184:187], v[132:135], v[112:127]
	ds_read_b128 v[192:195], v213 offset:32768
	ds_read_b128 v[148:151], v207 offset:32768
	v_mfma_f32_32x32x16_bf16 v[96:111], v[188:191], v[132:135], v[96:111]
	ds_read_b128 v[208:211], v213 offset:34816
	ds_read_b128 v[152:155], v207 offset:34816
	v_mfma_f32_32x32x16_bf16 v[80:95], v[184:187], v[136:139], v[80:95]
	ds_read_b128 v[156:159], v207 offset:36864
	ds_read_b128 v[180:183], v207 offset:38912
	v_mfma_f32_32x32x16_bf16 v[64:79], v[188:191], v[136:139], v[64:79]
	s_add_u32 m0, s26, 0x12000
	s_nop 0
	global_load_lds_dwordx4 v[220:221], off
	v_lshl_add_u64 v[220:221], v[220:221], 0, s[6:7]
	v_mfma_f32_32x32x16_bf16 v[48:63], v[184:187], v[140:143], v[48:63]
	v_mfma_f32_32x32x16_bf16 v[32:47], v[188:191], v[140:143], v[32:47]
	v_mfma_f32_32x32x16_bf16 v[16:31], v[184:187], v[144:147], v[16:31]
	v_mfma_f32_32x32x16_bf16 v[0:15], v[188:191], v[144:147], v[0:15]
	s_add_u32 m0, s26, 0x16000
	s_nop 0
	global_load_lds_dwordx4 v[224:225], off
	v_lshl_add_u64 v[224:225], v[224:225], 0, s[6:7]
	s_waitcnt lgkmcnt(0)
	s_waitcnt vmcnt(12)
	s_barrier
	s_waitcnt lgkmcnt(0)
	v_mfma_f32_32x32x16_bf16 v[112:127], v[192:195], v[148:151], v[112:127]
	ds_read_b128 v[184:187], v216
	ds_read_b128 v[132:135], v214
	v_mfma_f32_32x32x16_bf16 v[96:111], v[208:211], v[148:151], v[96:111]
	ds_read_b128 v[188:191], v216 offset:2048
	ds_read_b128 v[136:139], v214 offset:2048
	v_mfma_f32_32x32x16_bf16 v[80:95], v[192:195], v[152:155], v[80:95]
	ds_read_b128 v[140:143], v214 offset:4096
	ds_read_b128 v[144:147], v214 offset:6144
	v_mfma_f32_32x32x16_bf16 v[64:79], v[208:211], v[152:155], v[64:79]
	v_mfma_f32_32x32x16_bf16 v[48:63], v[192:195], v[156:159], v[48:63]
	v_mfma_f32_32x32x16_bf16 v[32:47], v[208:211], v[156:159], v[32:47]
	v_mfma_f32_32x32x16_bf16 v[16:31], v[192:195], v[180:183], v[16:31]
	v_mfma_f32_32x32x16_bf16 v[0:15], v[208:211], v[180:183], v[0:15]
	s_waitcnt lgkmcnt(0)
	v_mfma_f32_32x32x16_bf16 v[112:127], v[184:187], v[132:135], v[112:127]
	ds_read_b128 v[192:195], v217
	ds_read_b128 v[148:151], v215
	v_mfma_f32_32x32x16_bf16 v[96:111], v[188:191], v[132:135], v[96:111]
	ds_read_b128 v[208:211], v217 offset:2048
	ds_read_b128 v[152:155], v215 offset:2048
	v_mfma_f32_32x32x16_bf16 v[80:95], v[184:187], v[136:139], v[80:95]
	ds_read_b128 v[156:159], v215 offset:4096
	ds_read_b128 v[180:183], v215 offset:6144
	v_mfma_f32_32x32x16_bf16 v[64:79], v[188:191], v[136:139], v[64:79]
	v_mfma_f32_32x32x16_bf16 v[48:63], v[184:187], v[140:143], v[48:63]
	v_mfma_f32_32x32x16_bf16 v[32:47], v[188:191], v[140:143], v[32:47]
	v_mfma_f32_32x32x16_bf16 v[16:31], v[184:187], v[144:147], v[16:31]
	v_mfma_f32_32x32x16_bf16 v[0:15], v[188:191], v[144:147], v[0:15]
	s_waitcnt lgkmcnt(0)
	s_waitcnt vmcnt(8)
	s_barrier
	s_waitcnt lgkmcnt(0)
	v_mfma_f32_32x32x16_bf16 v[112:127], v[192:195], v[148:151], v[112:127]
	ds_read_b128 v[184:187], v131
	ds_read_b128 v[132:135], v128
	v_mfma_f32_32x32x16_bf16 v[96:111], v[208:211], v[148:151], v[96:111]
	ds_read_b128 v[188:191], v131 offset:2048
	ds_read_b128 v[136:139], v128 offset:2048
	v_mfma_f32_32x32x16_bf16 v[80:95], v[192:195], v[152:155], v[80:95]
	ds_read_b128 v[140:143], v128 offset:4096
	ds_read_b128 v[144:147], v128 offset:6144
	v_mfma_f32_32x32x16_bf16 v[64:79], v[208:211], v[152:155], v[64:79]
	v_mfma_f32_32x32x16_bf16 v[48:63], v[192:195], v[156:159], v[48:63]
	v_mfma_f32_32x32x16_bf16 v[32:47], v[208:211], v[156:159], v[32:47]
	v_mfma_f32_32x32x16_bf16 v[16:31], v[192:195], v[180:183], v[16:31]
	v_mfma_f32_32x32x16_bf16 v[0:15], v[208:211], v[180:183], v[0:15]
	s_waitcnt lgkmcnt(0)
	v_mfma_f32_32x32x16_bf16 v[112:127], v[184:187], v[132:135], v[112:127]
	ds_read_b128 v[192:195], v205
	ds_read_b128 v[148:151], v130
	v_mfma_f32_32x32x16_bf16 v[96:111], v[188:191], v[132:135], v[96:111]
	ds_read_b128 v[208:211], v205 offset:2048
	ds_read_b128 v[152:155], v130 offset:2048
	v_mfma_f32_32x32x16_bf16 v[80:95], v[184:187], v[136:139], v[80:95]
	ds_read_b128 v[156:159], v130 offset:4096
	ds_read_b128 v[180:183], v130 offset:6144
	v_mfma_f32_32x32x16_bf16 v[64:79], v[188:191], v[136:139], v[64:79]
	v_mfma_f32_32x32x16_bf16 v[48:63], v[184:187], v[140:143], v[48:63]
	v_mfma_f32_32x32x16_bf16 v[32:47], v[188:191], v[140:143], v[32:47]
	v_mfma_f32_32x32x16_bf16 v[16:31], v[184:187], v[144:147], v[16:31]
	v_mfma_f32_32x32x16_bf16 v[0:15], v[188:191], v[144:147], v[0:15]
	s_waitcnt lgkmcnt(0)
	s_waitcnt vmcnt(4)
	s_barrier
; #define G_LOADA(kt_) { _Pragma("unroll") for (int i = 0; i < 4; ++i) ra[i] = al(lrow + 64 * i, (kt_) * 64 + lck * 8); }
; #define G_LOADB(kt_) { _Pragma("unroll") for (int i = 0; i < 4; ++i) rb[i] = bl(lrow + 64 * i, (kt_) * 64 + lck * 8); }
; #define G_STOREA(buf_) { bf16_t* nA = sA + (buf_) * 256 * GLD; _Pragma("unroll") for (int i = 0; i < 4; ++i) *(u32x4*)(nA + (lrow + 64 * i) * GLD + lck * 8) = ra[i]; }
; #define G_STOREB(buf_) { bf16_t* nB = sB + (buf_) * 256 * GLD; _Pragma("unroll") for (int i = 0; i < 4; ++i) *(u32x4*)(nB + (lrow + 64 * i) * GLD + lck * 8) = rb[i]; }
; template <class AL, class BL, class EP>
; DI void gemm_tile256(AL al, BL bl, EP ep, int K, char* smem) {
;     ...
;   G_LOADA(0); G_LOADB(0);
;   __syncthreads();
;   G_STOREA(0); G_STOREB(0);
;   if (KT > 1) G_LOADB(1);
;   __syncthreads();
;   for (int kt = 0; kt < KT; kt += 2) {
;     G_STEP(0, kt);
;     if (kt + 1 >= KT) break;
;     G_STEP(1, kt + 1);
;   }
	s_waitcnt lgkmcnt(0)
	v_mfma_f32_32x32x16_bf16 v[112:127], v[192:195], v[148:151], v[112:127]
	ds_read_b128 v[184:187], v131 offset:32768
	ds_read_b128 v[132:135], v128 offset:32768
	v_mfma_f32_32x32x16_bf16 v[96:111], v[208:211], v[148:151], v[96:111]
	ds_read_b128 v[188:191], v131 offset:34816
	ds_read_b128 v[136:139], v128 offset:34816
	v_mfma_f32_32x32x16_bf16 v[80:95], v[192:195], v[152:155], v[80:95]
	ds_read_b128 v[140:143], v128 offset:36864
	ds_read_b128 v[144:147], v128 offset:38912
	v_mfma_f32_32x32x16_bf16 v[64:79], v[208:211], v[152:155], v[64:79]
	v_mfma_f32_32x32x16_bf16 v[48:63], v[192:195], v[156:159], v[48:63]
	v_mfma_f32_32x32x16_bf16 v[32:47], v[208:211], v[156:159], v[32:47]
	v_mfma_f32_32x32x16_bf16 v[16:31], v[192:195], v[180:183], v[16:31]
	v_mfma_f32_32x32x16_bf16 v[0:15], v[208:211], v[180:183], v[0:15]
	s_waitcnt lgkmcnt(0)
	v_mfma_f32_32x32x16_bf16 v[112:127], v[184:187], v[132:135], v[112:127]
	ds_read_b128 v[192:195], v205 offset:32768
	ds_read_b128 v[148:151], v130 offset:32768
	v_mfma_f32_32x32x16_bf16 v[96:111], v[188:191], v[132:135], v[96:111]
	ds_read_b128 v[208:211], v205 offset:34816
	ds_read_b128 v[152:155], v130 offset:34816
	v_mfma_f32_32x32x16_bf16 v[80:95], v[184:187], v[136:139], v[80:95]
	ds_read_b128 v[156:159], v130 offset:36864
	ds_read_b128 v[180:183], v130 offset:38912
	v_mfma_f32_32x32x16_bf16 v[64:79], v[188:191], v[136:139], v[64:79]
	v_mfma_f32_32x32x16_bf16 v[48:63], v[184:187], v[140:143], v[48:63]
	v_mfma_f32_32x32x16_bf16 v[32:47], v[188:191], v[140:143], v[32:47]
	v_mfma_f32_32x32x16_bf16 v[16:31], v[184:187], v[144:147], v[16:31]
	v_mfma_f32_32x32x16_bf16 v[0:15], v[188:191], v[144:147], v[0:15]
	s_waitcnt lgkmcnt(0)
	s_waitcnt vmcnt(0)
	s_barrier
	s_waitcnt lgkmcnt(0)
	v_mfma_f32_32x32x16_bf16 v[112:127], v[192:195], v[148:151], v[112:127]
	ds_read_b128 v[184:187], v212
	ds_read_b128 v[132:135], v206
	v_mfma_f32_32x32x16_bf16 v[96:111], v[208:211], v[148:151], v[96:111]
	ds_read_b128 v[188:191], v212 offset:2048
	ds_read_b128 v[136:139], v206 offset:2048
	v_mfma_f32_32x32x16_bf16 v[80:95], v[192:195], v[152:155], v[80:95]
	ds_read_b128 v[140:143], v206 offset:4096
	ds_read_b128 v[144:147], v206 offset:6144
	v_mfma_f32_32x32x16_bf16 v[64:79], v[208:211], v[152:155], v[64:79]
	v_mfma_f32_32x32x16_bf16 v[48:63], v[192:195], v[156:159], v[48:63]
	v_mfma_f32_32x32x16_bf16 v[32:47], v[208:211], v[156:159], v[32:47]
	v_mfma_f32_32x32x16_bf16 v[16:31], v[192:195], v[180:183], v[16:31]
	v_mfma_f32_32x32x16_bf16 v[0:15], v[208:211], v[180:183], v[0:15]
	s_waitcnt lgkmcnt(0)
	v_mfma_f32_32x32x16_bf16 v[112:127], v[184:187], v[132:135], v[112:127]
	ds_read_b128 v[192:195], v213
	ds_read_b128 v[148:151], v207
	v_mfma_f32_32x32x16_bf16 v[96:111], v[188:191], v[132:135], v[96:111]
	ds_read_b128 v[208:211], v213 offset:2048
	ds_read_b128 v[152:155], v207 offset:2048
	v_mfma_f32_32x32x16_bf16 v[80:95], v[184:187], v[136:139], v[80:95]
	ds_read_b128 v[156:159], v207 offset:4096
	ds_read_b128 v[180:183], v207 offset:6144
	v_mfma_f32_32x32x16_bf16 v[64:79], v[188:191], v[136:139], v[64:79]
	v_mfma_f32_32x32x16_bf16 v[48:63], v[184:187], v[140:143], v[48:63]
	v_mfma_f32_32x32x16_bf16 v[32:47], v[188:191], v[140:143], v[32:47]
	v_mfma_f32_32x32x16_bf16 v[16:31], v[184:187], v[144:147], v[16:31]
	v_mfma_f32_32x32x16_bf16 v[0:15], v[188:191], v[144:147], v[0:15]
	s_waitcnt lgkmcnt(0)
	s_waitcnt lgkmcnt(0)
	v_mfma_f32_32x32x16_bf16 v[112:127], v[192:195], v[148:151], v[112:127]
	v_mfma_f32_32x32x16_bf16 v[96:111], v[208:211], v[148:151], v[96:111]
	v_mfma_f32_32x32x16_bf16 v[80:95], v[192:195], v[152:155], v[80:95]
	v_mfma_f32_32x32x16_bf16 v[64:79], v[208:211], v[152:155], v[64:79]
	v_mfma_f32_32x32x16_bf16 v[48:63], v[192:195], v[156:159], v[48:63]
	v_mfma_f32_32x32x16_bf16 v[32:47], v[208:211], v[156:159], v[32:47]
	v_mfma_f32_32x32x16_bf16 v[16:31], v[192:195], v[180:183], v[16:31]
	v_mfma_f32_32x32x16_bf16 v[0:15], v[208:211], v[180:183], v[0:15]
	s_nop 15
	s_nop 3
	s_setprio 0
	s_barrier
	s_branch .LBB0_1268
